# GEMM K-loops: redundant s_setprio 0/1 pair between the two MFMA sub-clusters removed (timing only)
# baseline (speedup 1.0000x reference)
; #define PG8_STAGE(bufoff, gbase, voff) do { _Pragma("unroll") for (int _i = 0; _i < 2; ++_i) \
;         __builtin_amdgcn_global_load_lds((const unsigned*)((const char*)(gbase) + (voff)[_i]), (PG8_LAS unsigned*)(lds + (bufoff) + ldsw + _i * 8192), 16, 0, 0); } while (0)
; #define PG8_LDA(dst, b, h) do { _Pragma("unroll") for (int m = 0; m < 4; ++m) _Pragma("unroll") for (int k = 0; k < 2; ++k) dst[m][k] = *(const PG8_LAS bf16x8*)(lds + PG8_SA(b, h) + aoff + m * 2048 + k * 1024); } while (0)
; #define PG8_LDB(dst, b, h) do { _Pragma("unroll") for (int n = 0; n < 2; ++n) _Pragma("unroll") for (int k = 0; k < 2; ++k) dst[n][k] = *(const PG8_LAS bf16x8*)(lds + PG8_SB(b, h) + boff + n * 2048 + k * 1024); } while (0)
; #define PG8_SCHED __builtin_amdgcn_sched_barrier(0)
; template <class Epi, class Sched, bool ALIGN_EPI = false, bool SP2 = false>
; __device__ __forceinline__ void gemm_phase(PG8_LAS unsigned char* lds, const Gemm g, const Sched& S, const Epi& E) {
;     ...
;         const bool has_next = S.next(ui + 1, nxt);
;         const char* nA = has_next ? (const char*)g.A + (size_t)nxt.pm * tstep : cA; const char* nB = has_next ? (const char*)g.Bt + (size_t)nxt.pn * tstep : cB;
; #pragma nounroll
;         for (int t = 0; t < nt; t += 2) {
;             const bool last = (t == nt - 2);
;             const char* a1 = cA + (size_t)(t + 1) * kstep;
;             const char* a2 = last ? nA : cA + (size_t)(t + 2) * kstep; const char* b2 = last ? nB : cB + (size_t)(t + 2) * kstep;
;             const char* a3 = a2 + kstep; const char* b3 = b2 + kstep;
;             if (last && has_next) S.a_ready(nxt);
;             if constexpr (SP2) {
;             PG8_LDB(B0, 0, 0); PG8_LDB(B1, 0, 1); PG8_SCHED; PG8_LDA(At, 0, 0); PG8_STAGE(PG8_SA(1, 1), a1 + hstep, voffA);
.LBB0_490:
	s_ashr_i32 s11, s10, 31
	s_lshl_b64 s[12:13], s[10:11], 19
	s_add_u32 s12, s24, s12
	s_addc_u32 s13, s25, s13
	s_and_b64 s[14:15], s[2:3], exec
	s_cselect_b32 s11, s13, s19
	s_cselect_b32 s52, s12, s18
	s_ashr_i32 s9, s8, 31
	s_lshl_b64 s[14:15], s[8:9], 19
	s_add_u32 s14, s26, s14
	s_addc_u32 s15, s27, s15
	s_and_b64 s[22:23], s[2:3], exec
	s_cselect_b32 s9, s15, s21
	s_cselect_b32 s53, s14, s20
	s_add_u32 s18, s18, 0x40080
	s_addc_u32 s19, s19, 0
	s_add_u32 s56, s20, 0x100
	s_addc_u32 s57, s21, 0
	s_mov_b32 s60, -2
	ds_read_b128 v[156:159], v151
	ds_read_b128 v[160:163], v151 offset:1024
	ds_read_b128 v[164:167], v151 offset:2048
	ds_read_b128 v[168:171], v151 offset:3072
	ds_read_b128 v[174:177], v152
	ds_read_b128 v[178:181], v152 offset:1024
	ds_read_b128 v[182:185], v152 offset:2048
	ds_read_b128 v[186:189], v152 offset:3072
	s_add_u32 s20, s18, 0xfffc0080
	s_addc_u32 s21, s19, -1
	s_cmp_eq_u32 s60, 12
	s_cselect_b32 s23, s11, s21
	s_cselect_b32 s22, s52, s20
	s_cselect_b32 s21, s9, s57
	s_cselect_b32 s20, s53, s56

; #define PG8_STAGE(bufoff, gbase, voff) do { _Pragma("unroll") for (int _i = 0; _i < 2; ++_i) \
;         __builtin_amdgcn_global_load_lds((const unsigned*)((const char*)(gbase) + (voff)[_i]), (PG8_LAS unsigned*)(lds + (bufoff) + ldsw + _i * 8192), 16, 0, 0); } while (0)
; #define PG8_LDA(dst, b, h) do { _Pragma("unroll") for (int m = 0; m < 4; ++m) _Pragma("unroll") for (int k = 0; k < 2; ++k) dst[m][k] = *(const PG8_LAS bf16x8*)(lds + PG8_SA(b, h) + aoff + m * 2048 + k * 1024); } while (0)
; #define PG8_LDB(dst, b, h) do { _Pragma("unroll") for (int n = 0; n < 2; ++n) _Pragma("unroll") for (int k = 0; k < 2; ++k) dst[n][k] = *(const PG8_LAS bf16x8*)(lds + PG8_SB(b, h) + boff + n * 2048 + k * 1024); } while (0)
; #define PG8_MMA(ai, bj, At, Bt) do { __builtin_amdgcn_s_setprio(1); _Pragma("unroll") for (int m = 0; m < 4; ++m) _Pragma("unroll") for (int n = 0; n < 2; ++n) _Pragma("unroll") for (int k = 0; k < 2; ++k) \
;         acc[ai][bj][m][n] = __builtin_amdgcn_mfma_f32_16x16x32_bf16(Bt[n][k], At[m][k], acc[ai][bj][m][n], 0, 0, 0); __builtin_amdgcn_s_setprio(0); } while (0)
; #define PG8_WAIT_V(n) asm volatile("s_waitcnt vmcnt(" #n ")" ::: "memory")
; #define PG8_WAIT_L(n) asm volatile("s_waitcnt lgkmcnt(" #n ")" ::: "memory")
; #define PG8_BAR __builtin_amdgcn_s_barrier()
; #define PG8_SCHED __builtin_amdgcn_sched_barrier(0)
; template <class Epi, class Sched, bool ALIGN_EPI = false, bool SP2 = false>
; __device__ __forceinline__ void gemm_phase(PG8_LAS unsigned char* lds, const Gemm g, const Sched& S, const Epi& E) {
;     ...
;             PG8_LDB(B0, 0, 0); PG8_LDB(B1, 0, 1); PG8_SCHED; PG8_LDA(At, 0, 0); PG8_STAGE(PG8_SA(1, 1), a1 + hstep, voffA);
;             PG8_WAIT_V(8); PG8_WAIT_L(0); PG8_BAR; PG8_MMA(0, 0, At, B0); PG8_MMA(0, 1, At, B1); PG8_BAR; PG8_SCHED;
	v_lshl_add_u64 v[222:223], s[18:19], 0, v[142:143]
	s_add_i32 m0, s31, 0xc000
	ds_read_b128 v[190:193], v153
	ds_read_b128 v[194:197], v153 offset:1024
	ds_read_b128 v[198:201], v153 offset:2048
	ds_read_b128 v[202:205], v153 offset:3072
	ds_read_b128 v[206:209], v153 offset:4096
	ds_read_b128 v[210:213], v153 offset:5120
	ds_read_b128 v[214:217], v153 offset:6144
	ds_read_b128 v[218:221], v153 offset:7168
	global_load_lds_dwordx4 v[222:223], off
	v_lshl_add_u64 v[222:223], s[18:19], 0, v[144:145]
	s_add_i32 m0, s31, 0xe000
	s_nop 0
	global_load_lds_dwordx4 v[222:223], off
	s_waitcnt vmcnt(24)
	s_waitcnt lgkmcnt(0)
	s_barrier
	s_setprio 1
	s_waitcnt lgkmcnt(0)
	v_mfma_f32_16x16x32_bf16 v[126:129], v[156:159], v[190:193], 0
	v_mfma_f32_16x16x32_bf16 v[122:125], v[164:167], v[190:193], 0
	v_mfma_f32_16x16x32_bf16 v[114:117], v[156:159], v[198:201], 0
	v_mfma_f32_16x16x32_bf16 v[106:109], v[164:167], v[198:201], 0
	v_mfma_f32_16x16x32_bf16 v[98:101], v[156:159], v[206:209], 0
	v_mfma_f32_16x16x32_bf16 v[90:93], v[164:167], v[206:209], 0
	v_mfma_f32_16x16x32_bf16 v[82:85], v[156:159], v[214:217], 0
	v_mfma_f32_16x16x32_bf16 v[74:77], v[164:167], v[214:217], 0
	v_mfma_f32_16x16x32_bf16 v[126:129], v[160:163], v[194:197], v[126:129]
	v_mfma_f32_16x16x32_bf16 v[122:125], v[168:171], v[194:197], v[122:125]
	v_mfma_f32_16x16x32_bf16 v[114:117], v[160:163], v[202:205], v[114:117]
	v_mfma_f32_16x16x32_bf16 v[106:109], v[168:171], v[202:205], v[106:109]
	v_mfma_f32_16x16x32_bf16 v[98:101], v[160:163], v[210:213], v[98:101]
	v_mfma_f32_16x16x32_bf16 v[90:93], v[168:171], v[210:213], v[90:93]
	v_mfma_f32_16x16x32_bf16 v[82:85], v[160:163], v[218:221], v[82:85]
	v_mfma_f32_16x16x32_bf16 v[74:77], v[168:171], v[218:221], v[74:77]
	v_mfma_f32_16x16x32_bf16 v[118:121], v[174:177], v[190:193], 0
	v_mfma_f32_16x16x32_bf16 v[110:113], v[182:185], v[190:193], 0
	v_mfma_f32_16x16x32_bf16 v[102:105], v[174:177], v[198:201], 0
	v_mfma_f32_16x16x32_bf16 v[94:97], v[182:185], v[198:201], 0
	v_mfma_f32_16x16x32_bf16 v[86:89], v[174:177], v[206:209], 0
	v_mfma_f32_16x16x32_bf16 v[78:81], v[182:185], v[206:209], 0
	v_mfma_f32_16x16x32_bf16 v[70:73], v[174:177], v[214:217], 0
	v_mfma_f32_16x16x32_bf16 v[66:69], v[182:185], v[214:217], 0
	v_mfma_f32_16x16x32_bf16 v[118:121], v[178:181], v[194:197], v[118:121]
	v_mfma_f32_16x16x32_bf16 v[110:113], v[186:189], v[194:197], v[110:113]
	v_mfma_f32_16x16x32_bf16 v[102:105], v[178:181], v[202:205], v[102:105]
	v_mfma_f32_16x16x32_bf16 v[94:97], v[186:189], v[202:205], v[94:97]
	v_mfma_f32_16x16x32_bf16 v[86:89], v[178:181], v[210:213], v[86:89]
	v_mfma_f32_16x16x32_bf16 v[78:81], v[186:189], v[210:213], v[78:81]
	v_mfma_f32_16x16x32_bf16 v[70:73], v[178:181], v[218:221], v[70:73]
	v_mfma_f32_16x16x32_bf16 v[66:69], v[186:189], v[218:221], v[66:69]
	s_setprio 0
	s_barrier

; #define PG8_STAGE(bufoff, gbase, voff) do { _Pragma("unroll") for (int _i = 0; _i < 2; ++_i) \
;         __builtin_amdgcn_global_load_lds((const unsigned*)((const char*)(gbase) + (voff)[_i]), (PG8_LAS unsigned*)(lds + (bufoff) + ldsw + _i * 8192), 16, 0, 0); } while (0)
; #define PG8_LDA(dst, b, h) do { _Pragma("unroll") for (int m = 0; m < 4; ++m) _Pragma("unroll") for (int k = 0; k < 2; ++k) dst[m][k] = *(const PG8_LAS bf16x8*)(lds + PG8_SA(b, h) + aoff + m * 2048 + k * 1024); } while (0)
; #define PG8_MMA(ai, bj, At, Bt) do { __builtin_amdgcn_s_setprio(1); _Pragma("unroll") for (int m = 0; m < 4; ++m) _Pragma("unroll") for (int n = 0; n < 2; ++n) _Pragma("unroll") for (int k = 0; k < 2; ++k) \
;         acc[ai][bj][m][n] = __builtin_amdgcn_mfma_f32_16x16x32_bf16(Bt[n][k], At[m][k], acc[ai][bj][m][n], 0, 0, 0); __builtin_amdgcn_s_setprio(0); } while (0)
; #define PG8_WAIT_V(n) asm volatile("s_waitcnt vmcnt(" #n ")" ::: "memory")
; #define PG8_WAIT_L(n) asm volatile("s_waitcnt lgkmcnt(" #n ")" ::: "memory")
; #define PG8_BAR __builtin_amdgcn_s_barrier()
; #define PG8_SCHED __builtin_amdgcn_sched_barrier(0)
; template <class Epi, class Sched, bool ALIGN_EPI = false, bool SP2 = false>
; __device__ __forceinline__ void gemm_phase(PG8_LAS unsigned char* lds, const Gemm g, const Sched& S, const Epi& E) {
;     ...
;             PG8_LDA(At, 0, 1); PG8_STAGE(PG8_SB(0, 0), b2, voffB); PG8_STAGE(PG8_SB(0, 1), b2 + hstep, voffB); PG8_STAGE(PG8_SA(0, 0), a2, voffA);
;             PG8_WAIT_V(8); PG8_WAIT_L(0); PG8_BAR; PG8_MMA(1, 0, At, B0); PG8_MMA(1, 1, At, B1); PG8_BAR; PG8_SCHED;
	s_add_i32 s61, s44, s28
	v_lshl_add_u64 v[222:223], s[20:21], 0, v[134:135]
	s_mov_b32 m0, s61
	ds_read_b128 v[190:193], v153 offset:16384
	ds_read_b128 v[194:197], v153 offset:17408
	ds_read_b128 v[198:201], v153 offset:18432
	ds_read_b128 v[202:205], v153 offset:19456
	ds_read_b128 v[206:209], v153 offset:20480
	ds_read_b128 v[210:213], v153 offset:21504
	ds_read_b128 v[214:217], v153 offset:22528
	ds_read_b128 v[218:221], v153 offset:23552
	global_load_lds_dwordx4 v[222:223], off
	s_add_i32 m0, s61, 0x2000
	s_add_u32 s62, s20, 0x40000
	v_lshl_add_u64 v[224:225], s[20:21], 0, v[130:131]
	s_addc_u32 s63, s21, 0
	s_add_i32 s61, s45, s28
	global_load_lds_dwordx4 v[224:225], off
	v_lshl_add_u64 v[226:227], s[62:63], 0, v[134:135]
	s_mov_b32 m0, s61
	v_lshl_add_u64 v[228:229], s[22:23], 0, v[132:133]
	global_load_lds_dwordx4 v[226:227], off
	v_lshl_add_u64 v[226:227], s[62:63], 0, v[130:131]
	s_add_i32 m0, s61, 0x2000
	s_nop 0
	global_load_lds_dwordx4 v[226:227], off
	v_lshl_add_u64 v[226:227], s[22:23], 0, v[136:137]
	s_mov_b32 m0, s31
	s_nop 0
	global_load_lds_dwordx4 v[226:227], off
	s_mov_b32 m0, s33
	s_nop 0
	global_load_lds_dwordx4 v[228:229], off
	s_waitcnt vmcnt(24)
	s_waitcnt lgkmcnt(0)
	s_barrier
	s_setprio 1
	s_waitcnt lgkmcnt(0)
	v_mfma_f32_16x16x32_bf16 v[62:65], v[156:159], v[190:193], 0
	v_mfma_f32_16x16x32_bf16 v[58:61], v[164:167], v[190:193], 0
	v_mfma_f32_16x16x32_bf16 v[50:53], v[156:159], v[198:201], 0
	v_mfma_f32_16x16x32_bf16 v[42:45], v[164:167], v[198:201], 0
	v_mfma_f32_16x16x32_bf16 v[34:37], v[156:159], v[206:209], 0
	v_mfma_f32_16x16x32_bf16 v[26:29], v[164:167], v[206:209], 0
	v_mfma_f32_16x16x32_bf16 v[18:21], v[156:159], v[214:217], 0
	v_mfma_f32_16x16x32_bf16 v[10:13], v[164:167], v[214:217], 0
	v_mfma_f32_16x16x32_bf16 v[62:65], v[160:163], v[194:197], v[62:65]
	v_mfma_f32_16x16x32_bf16 v[58:61], v[168:171], v[194:197], v[58:61]
	v_mfma_f32_16x16x32_bf16 v[50:53], v[160:163], v[202:205], v[50:53]
	v_mfma_f32_16x16x32_bf16 v[42:45], v[168:171], v[202:205], v[42:45]
	v_mfma_f32_16x16x32_bf16 v[34:37], v[160:163], v[210:213], v[34:37]
	v_mfma_f32_16x16x32_bf16 v[26:29], v[168:171], v[210:213], v[26:29]
	v_mfma_f32_16x16x32_bf16 v[18:21], v[160:163], v[218:221], v[18:21]
	v_mfma_f32_16x16x32_bf16 v[10:13], v[168:171], v[218:221], v[10:13]
	v_mfma_f32_16x16x32_bf16 v[54:57], v[174:177], v[190:193], 0
	v_mfma_f32_16x16x32_bf16 v[46:49], v[182:185], v[190:193], 0
	v_mfma_f32_16x16x32_bf16 v[38:41], v[174:177], v[198:201], 0
	v_mfma_f32_16x16x32_bf16 v[30:33], v[182:185], v[198:201], 0
	v_mfma_f32_16x16x32_bf16 v[22:25], v[174:177], v[206:209], 0
	v_mfma_f32_16x16x32_bf16 v[14:17], v[182:185], v[206:209], 0
	v_mfma_f32_16x16x32_bf16 v[6:9], v[174:177], v[214:217], 0
	v_mfma_f32_16x16x32_bf16 v[2:5], v[182:185], v[214:217], 0
	v_mfma_f32_16x16x32_bf16 v[54:57], v[178:181], v[194:197], v[54:57]
	v_mfma_f32_16x16x32_bf16 v[46:49], v[186:189], v[194:197], v[46:49]
	v_mfma_f32_16x16x32_bf16 v[38:41], v[178:181], v[202:205], v[38:41]
	v_mfma_f32_16x16x32_bf16 v[30:33], v[186:189], v[202:205], v[30:33]
	v_mfma_f32_16x16x32_bf16 v[22:25], v[178:181], v[210:213], v[22:25]
	v_mfma_f32_16x16x32_bf16 v[14:17], v[186:189], v[210:213], v[14:17]
	v_mfma_f32_16x16x32_bf16 v[6:9], v[178:181], v[218:221], v[6:9]
	v_mfma_f32_16x16x32_bf16 v[2:5], v[186:189], v[218:221], v[2:5]
	s_setprio 0
	s_barrier

; #define PG8_STAGE(bufoff, gbase, voff) do { _Pragma("unroll") for (int _i = 0; _i < 2; ++_i) \
;         __builtin_amdgcn_global_load_lds((const unsigned*)((const char*)(gbase) + (voff)[_i]), (PG8_LAS unsigned*)(lds + (bufoff) + ldsw + _i * 8192), 16, 0, 0); } while (0)
; #define PG8_LDA(dst, b, h) do { _Pragma("unroll") for (int m = 0; m < 4; ++m) _Pragma("unroll") for (int k = 0; k < 2; ++k) dst[m][k] = *(const PG8_LAS bf16x8*)(lds + PG8_SA(b, h) + aoff + m * 2048 + k * 1024); } while (0)
; #define PG8_LDB(dst, b, h) do { _Pragma("unroll") for (int n = 0; n < 2; ++n) _Pragma("unroll") for (int k = 0; k < 2; ++k) dst[n][k] = *(const PG8_LAS bf16x8*)(lds + PG8_SB(b, h) + boff + n * 2048 + k * 1024); } while (0)
; #define PG8_SCHED __builtin_amdgcn_sched_barrier(0)
; template <class Epi, class Sched, bool ALIGN_EPI = false, bool SP2 = false>
; __device__ __forceinline__ void gemm_phase(PG8_LAS unsigned char* lds, const Gemm g, const Sched& S, const Epi& E) {
;     ...
;             PG8_LDB(B0, 1, 0); PG8_LDB(B1, 1, 1); PG8_SCHED; PG8_LDA(At, 1, 0); PG8_STAGE(PG8_SA(0, 1), a2 + hstep, voffA);
	s_add_i32 s61, 0, 0x18000
	v_add_u32_e32 v138, s61, v150
	s_add_i32 s62, 0, 0x1c000
	ds_read_b128 v[156:159], v138
	ds_read_b128 v[160:163], v138 offset:1024
	ds_read_b128 v[164:167], v138 offset:2048
	ds_read_b128 v[168:171], v138 offset:3072
	v_add_u32_e32 v138, s62, v150
	ds_read_b128 v[174:177], v138
	ds_read_b128 v[178:181], v138 offset:1024
	ds_read_b128 v[182:185], v138 offset:2048
	ds_read_b128 v[186:189], v138 offset:3072

; #define PG8_STAGE(bufoff, gbase, voff) do { _Pragma("unroll") for (int _i = 0; _i < 2; ++_i) \
;         __builtin_amdgcn_global_load_lds((const unsigned*)((const char*)(gbase) + (voff)[_i]), (PG8_LAS unsigned*)(lds + (bufoff) + ldsw + _i * 8192), 16, 0, 0); } while (0)
; #define PG8_LDA(dst, b, h) do { _Pragma("unroll") for (int m = 0; m < 4; ++m) _Pragma("unroll") for (int k = 0; k < 2; ++k) dst[m][k] = *(const PG8_LAS bf16x8*)(lds + PG8_SA(b, h) + aoff + m * 2048 + k * 1024); } while (0)
; #define PG8_LDB(dst, b, h) do { _Pragma("unroll") for (int n = 0; n < 2; ++n) _Pragma("unroll") for (int k = 0; k < 2; ++k) dst[n][k] = *(const PG8_LAS bf16x8*)(lds + PG8_SB(b, h) + boff + n * 2048 + k * 1024); } while (0)
; #define PG8_MMA(ai, bj, At, Bt) do { __builtin_amdgcn_s_setprio(1); _Pragma("unroll") for (int m = 0; m < 4; ++m) _Pragma("unroll") for (int n = 0; n < 2; ++n) _Pragma("unroll") for (int k = 0; k < 2; ++k) \
;         acc[ai][bj][m][n] = __builtin_amdgcn_mfma_f32_16x16x32_bf16(Bt[n][k], At[m][k], acc[ai][bj][m][n], 0, 0, 0); __builtin_amdgcn_s_setprio(0); } while (0)
; #define PG8_WAIT_V(n) asm volatile("s_waitcnt vmcnt(" #n ")" ::: "memory")
; #define PG8_WAIT_L(n) asm volatile("s_waitcnt lgkmcnt(" #n ")" ::: "memory")
; #define PG8_BAR __builtin_amdgcn_s_barrier()
; #define PG8_SCHED __builtin_amdgcn_sched_barrier(0)
; template <class Epi, class Sched, bool ALIGN_EPI = false, bool SP2 = false>
; __device__ __forceinline__ void gemm_phase(PG8_LAS unsigned char* lds, const Gemm g, const Sched& S, const Epi& E) {
;     ...
;             PG8_LDB(B0, 1, 0); PG8_LDB(B1, 1, 1); PG8_SCHED; PG8_LDA(At, 1, 0); PG8_STAGE(PG8_SA(0, 1), a2 + hstep, voffA);
;             PG8_WAIT_V(8); PG8_WAIT_L(0); PG8_BAR; PG8_MMA(0, 0, At, B0); PG8_MMA(0, 1, At, B1); PG8_BAR; PG8_SCHED;
	s_add_u32 s22, s22, 0x40000
	s_addc_u32 s23, s23, 0
	s_mov_b32 m0, s34
	v_lshl_add_u64 v[230:231], s[22:23], 0, v[136:137]
	ds_read_b128 v[190:193], v153 offset:32768
	ds_read_b128 v[194:197], v153 offset:33792
	ds_read_b128 v[198:201], v153 offset:34816
	ds_read_b128 v[202:205], v153 offset:35840
	ds_read_b128 v[206:209], v153 offset:36864
	ds_read_b128 v[210:213], v153 offset:37888
	ds_read_b128 v[214:217], v153 offset:38912
	ds_read_b128 v[218:221], v153 offset:39936
	global_load_lds_dwordx4 v[230:231], off
	v_lshl_add_u64 v[230:231], s[22:23], 0, v[132:133]
	s_mov_b32 m0, s35
	s_nop 0
	global_load_lds_dwordx4 v[230:231], off
	s_waitcnt vmcnt(8)
	s_waitcnt lgkmcnt(0)
	s_barrier
	s_setprio 1
	s_waitcnt lgkmcnt(0)
	v_mfma_f32_16x16x32_bf16 v[126:129], v[156:159], v[190:193], v[126:129]
	v_mfma_f32_16x16x32_bf16 v[122:125], v[164:167], v[190:193], v[122:125]
	v_mfma_f32_16x16x32_bf16 v[114:117], v[156:159], v[198:201], v[114:117]
	v_mfma_f32_16x16x32_bf16 v[106:109], v[164:167], v[198:201], v[106:109]
	v_mfma_f32_16x16x32_bf16 v[98:101], v[156:159], v[206:209], v[98:101]
	v_mfma_f32_16x16x32_bf16 v[90:93], v[164:167], v[206:209], v[90:93]
	v_mfma_f32_16x16x32_bf16 v[82:85], v[156:159], v[214:217], v[82:85]
	v_mfma_f32_16x16x32_bf16 v[74:77], v[164:167], v[214:217], v[74:77]
	v_mfma_f32_16x16x32_bf16 v[126:129], v[160:163], v[194:197], v[126:129]
	v_mfma_f32_16x16x32_bf16 v[122:125], v[168:171], v[194:197], v[122:125]
	v_mfma_f32_16x16x32_bf16 v[114:117], v[160:163], v[202:205], v[114:117]
	v_mfma_f32_16x16x32_bf16 v[106:109], v[168:171], v[202:205], v[106:109]
	v_mfma_f32_16x16x32_bf16 v[98:101], v[160:163], v[210:213], v[98:101]
	v_mfma_f32_16x16x32_bf16 v[90:93], v[168:171], v[210:213], v[90:93]
	v_mfma_f32_16x16x32_bf16 v[82:85], v[160:163], v[218:221], v[82:85]
	v_mfma_f32_16x16x32_bf16 v[74:77], v[168:171], v[218:221], v[74:77]
	v_mfma_f32_16x16x32_bf16 v[118:121], v[174:177], v[190:193], v[118:121]
	v_mfma_f32_16x16x32_bf16 v[110:113], v[182:185], v[190:193], v[110:113]
	v_mfma_f32_16x16x32_bf16 v[102:105], v[174:177], v[198:201], v[102:105]
	v_mfma_f32_16x16x32_bf16 v[94:97], v[182:185], v[198:201], v[94:97]
	v_mfma_f32_16x16x32_bf16 v[86:89], v[174:177], v[206:209], v[86:89]
	v_mfma_f32_16x16x32_bf16 v[78:81], v[182:185], v[206:209], v[78:81]
	v_mfma_f32_16x16x32_bf16 v[70:73], v[174:177], v[214:217], v[70:73]
	v_mfma_f32_16x16x32_bf16 v[66:69], v[182:185], v[214:217], v[66:69]
	v_mfma_f32_16x16x32_bf16 v[118:121], v[178:181], v[194:197], v[118:121]
	v_mfma_f32_16x16x32_bf16 v[110:113], v[186:189], v[194:197], v[110:113]
	v_mfma_f32_16x16x32_bf16 v[102:105], v[178:181], v[202:205], v[102:105]
	v_mfma_f32_16x16x32_bf16 v[94:97], v[186:189], v[202:205], v[94:97]
	v_mfma_f32_16x16x32_bf16 v[86:89], v[178:181], v[210:213], v[86:89]
	v_mfma_f32_16x16x32_bf16 v[78:81], v[186:189], v[210:213], v[78:81]
	v_mfma_f32_16x16x32_bf16 v[70:73], v[178:181], v[218:221], v[70:73]
	v_mfma_f32_16x16x32_bf16 v[66:69], v[186:189], v[218:221], v[66:69]
	s_setprio 0
	s_barrier

; #define PG8_STAGE(bufoff, gbase, voff) do { _Pragma("unroll") for (int _i = 0; _i < 2; ++_i) \
;         __builtin_amdgcn_global_load_lds((const unsigned*)((const char*)(gbase) + (voff)[_i]), (PG8_LAS unsigned*)(lds + (bufoff) + ldsw + _i * 8192), 16, 0, 0); } while (0)
; #define PG8_LDA(dst, b, h) do { _Pragma("unroll") for (int m = 0; m < 4; ++m) _Pragma("unroll") for (int k = 0; k < 2; ++k) dst[m][k] = *(const PG8_LAS bf16x8*)(lds + PG8_SA(b, h) + aoff + m * 2048 + k * 1024); } while (0)
; #define PG8_MMA(ai, bj, At, Bt) do { __builtin_amdgcn_s_setprio(1); _Pragma("unroll") for (int m = 0; m < 4; ++m) _Pragma("unroll") for (int n = 0; n < 2; ++n) _Pragma("unroll") for (int k = 0; k < 2; ++k) \
;         acc[ai][bj][m][n] = __builtin_amdgcn_mfma_f32_16x16x32_bf16(Bt[n][k], At[m][k], acc[ai][bj][m][n], 0, 0, 0); __builtin_amdgcn_s_setprio(0); } while (0)
; #define PG8_WAIT_V(n) asm volatile("s_waitcnt vmcnt(" #n ")" ::: "memory")
; #define PG8_WAIT_L(n) asm volatile("s_waitcnt lgkmcnt(" #n ")" ::: "memory")
; #define PG8_BAR __builtin_amdgcn_s_barrier()
; #define PG8_SCHED __builtin_amdgcn_sched_barrier(0)
; template <class Epi, class Sched, bool ALIGN_EPI = false, bool SP2 = false>
; __device__ __forceinline__ void gemm_phase(PG8_LAS unsigned char* lds, const Gemm g, const Sched& S, const Epi& E) {
;     ...
;             PG8_LDA(At, 1, 1); PG8_STAGE(PG8_SB(1, 0), b3, voffB); PG8_STAGE(PG8_SB(1, 1), b3 + hstep, voffB); PG8_STAGE(PG8_SA(1, 0), a3, voffA);
;             PG8_WAIT_V(8); PG8_WAIT_L(0); PG8_BAR; PG8_MMA(1, 0, At, B0); PG8_MMA(1, 1, At, B1); PG8_BAR; PG8_SCHED;
	s_add_i32 s22, s61, s28
	v_lshl_add_u64 v[222:223], v[222:223], 0, s[4:5]
	s_mov_b32 m0, s22
	ds_read_b128 v[190:193], v153 offset:49152
	ds_read_b128 v[194:197], v153 offset:50176
	ds_read_b128 v[198:201], v153 offset:51200
	ds_read_b128 v[202:205], v153 offset:52224
	ds_read_b128 v[206:209], v153 offset:53248
	ds_read_b128 v[210:213], v153 offset:54272
	ds_read_b128 v[214:217], v153 offset:55296
	ds_read_b128 v[218:221], v153 offset:56320
	global_load_lds_dwordx4 v[222:223], off
	s_add_i32 m0, s22, 0x2000
	s_add_u32 s20, s20, 0x40080
	v_lshl_add_u64 v[222:223], v[224:225], 0, s[4:5]
	s_addc_u32 s21, s21, 0
	s_add_i32 s22, s62, s28
	global_load_lds_dwordx4 v[222:223], off
	v_lshl_add_u64 v[222:223], s[20:21], 0, v[134:135]
	s_mov_b32 m0, s22
	s_nop 0
	global_load_lds_dwordx4 v[222:223], off
	v_lshl_add_u64 v[222:223], s[20:21], 0, v[130:131]
	s_add_i32 m0, s22, 0x2000
	s_nop 0
	global_load_lds_dwordx4 v[222:223], off
	v_lshl_add_u64 v[222:223], v[226:227], 0, s[4:5]
	s_mov_b32 m0, s39
	s_nop 0
	global_load_lds_dwordx4 v[222:223], off
	v_lshl_add_u64 v[222:223], v[228:229], 0, s[4:5]
	s_mov_b32 m0, s40
	s_nop 0
	global_load_lds_dwordx4 v[222:223], off
	s_waitcnt vmcnt(8)
	s_waitcnt lgkmcnt(0)
	s_barrier
	s_setprio 1
	s_waitcnt lgkmcnt(0)
	v_mfma_f32_16x16x32_bf16 v[62:65], v[156:159], v[190:193], v[62:65]
	v_mfma_f32_16x16x32_bf16 v[58:61], v[164:167], v[190:193], v[58:61]
	v_mfma_f32_16x16x32_bf16 v[50:53], v[156:159], v[198:201], v[50:53]
	v_mfma_f32_16x16x32_bf16 v[42:45], v[164:167], v[198:201], v[42:45]
	v_mfma_f32_16x16x32_bf16 v[34:37], v[156:159], v[206:209], v[34:37]
	v_mfma_f32_16x16x32_bf16 v[26:29], v[164:167], v[206:209], v[26:29]
	v_mfma_f32_16x16x32_bf16 v[18:21], v[156:159], v[214:217], v[18:21]
	v_mfma_f32_16x16x32_bf16 v[10:13], v[164:167], v[214:217], v[10:13]
	v_mfma_f32_16x16x32_bf16 v[62:65], v[160:163], v[194:197], v[62:65]
	v_mfma_f32_16x16x32_bf16 v[58:61], v[168:171], v[194:197], v[58:61]
	v_mfma_f32_16x16x32_bf16 v[50:53], v[160:163], v[202:205], v[50:53]
	v_mfma_f32_16x16x32_bf16 v[42:45], v[168:171], v[202:205], v[42:45]
	v_mfma_f32_16x16x32_bf16 v[34:37], v[160:163], v[210:213], v[34:37]
	v_mfma_f32_16x16x32_bf16 v[26:29], v[168:171], v[210:213], v[26:29]
	v_mfma_f32_16x16x32_bf16 v[18:21], v[160:163], v[218:221], v[18:21]
	v_mfma_f32_16x16x32_bf16 v[10:13], v[168:171], v[218:221], v[10:13]
	v_mfma_f32_16x16x32_bf16 v[54:57], v[174:177], v[190:193], v[54:57]
	v_mfma_f32_16x16x32_bf16 v[46:49], v[182:185], v[190:193], v[46:49]
	v_mfma_f32_16x16x32_bf16 v[38:41], v[174:177], v[198:201], v[38:41]
	v_mfma_f32_16x16x32_bf16 v[30:33], v[182:185], v[198:201], v[30:33]
	v_mfma_f32_16x16x32_bf16 v[22:25], v[174:177], v[206:209], v[22:25]
	v_mfma_f32_16x16x32_bf16 v[14:17], v[182:185], v[206:209], v[14:17]
	v_mfma_f32_16x16x32_bf16 v[6:9], v[174:177], v[214:217], v[6:9]
	v_mfma_f32_16x16x32_bf16 v[2:5], v[182:185], v[214:217], v[2:5]
	v_mfma_f32_16x16x32_bf16 v[54:57], v[178:181], v[194:197], v[54:57]
	v_mfma_f32_16x16x32_bf16 v[46:49], v[186:189], v[194:197], v[46:49]
	v_mfma_f32_16x16x32_bf16 v[38:41], v[178:181], v[202:205], v[38:41]
	v_mfma_f32_16x16x32_bf16 v[30:33], v[186:189], v[202:205], v[30:33]
	v_mfma_f32_16x16x32_bf16 v[22:25], v[178:181], v[210:213], v[22:25]
	v_mfma_f32_16x16x32_bf16 v[14:17], v[186:189], v[210:213], v[14:17]
	v_mfma_f32_16x16x32_bf16 v[6:9], v[178:181], v[218:221], v[6:9]
	v_mfma_f32_16x16x32_bf16 v[2:5], v[186:189], v[218:221], v[2:5]
	s_setprio 0
	s_barrier

; #define PG8_STAGE(bufoff, gbase, voff) do { _Pragma("unroll") for (int _i = 0; _i < 2; ++_i) \
;         __builtin_amdgcn_global_load_lds((const unsigned*)((const char*)(gbase) + (voff)[_i]), (PG8_LAS unsigned*)(lds + (bufoff) + ldsw + _i * 8192), 16, 0, 0); } while (0)
; #define PG8_LDA(dst, b, h) do { _Pragma("unroll") for (int m = 0; m < 4; ++m) _Pragma("unroll") for (int k = 0; k < 2; ++k) dst[m][k] = *(const PG8_LAS bf16x8*)(lds + PG8_SA(b, h) + aoff + m * 2048 + k * 1024); } while (0)
; #define PG8_LDB(dst, b, h) do { _Pragma("unroll") for (int n = 0; n < 2; ++n) _Pragma("unroll") for (int k = 0; k < 2; ++k) dst[n][k] = *(const PG8_LAS bf16x8*)(lds + PG8_SB(b, h) + boff + n * 2048 + k * 1024); } while (0)
; #define PG8_MMA(ai, bj, At, Bt) do { __builtin_amdgcn_s_setprio(1); _Pragma("unroll") for (int m = 0; m < 4; ++m) _Pragma("unroll") for (int n = 0; n < 2; ++n) _Pragma("unroll") for (int k = 0; k < 2; ++k) \
;         acc[ai][bj][m][n] = __builtin_amdgcn_mfma_f32_16x16x32_bf16(Bt[n][k], At[m][k], acc[ai][bj][m][n], 0, 0, 0); __builtin_amdgcn_s_setprio(0); } while (0)
; #define PG8_WAIT_V(n) asm volatile("s_waitcnt vmcnt(" #n ")" ::: "memory")
; #define PG8_BAR __builtin_amdgcn_s_barrier()
; template <class Epi, class Sched, bool ALIGN_EPI = false, bool SP2 = false>
; __device__ __forceinline__ void gemm_phase(PG8_LAS unsigned char* lds, const Gemm g, const Sched& S, const Epi& E) {
;     ...
;         for (int t = 0; t < nt; t += 2) {
;             const bool last = (t == nt - 2);
;             const char* a1 = cA + (size_t)(t + 1) * kstep;
;             const char* a2 = last ? nA : cA + (size_t)(t + 2) * kstep; const char* b2 = last ? nB : cB + (size_t)(t + 2) * kstep;
;             const char* a3 = a2 + kstep; const char* b3 = b2 + kstep;
;             if (last && has_next) S.a_ready(nxt);
;             if constexpr (SP2) {
;             PG8_LDB(B0, 0, 0); PG8_LDB(B1, 0, 1); PG8_SCHED; PG8_LDA(At, 0, 0); PG8_STAGE(PG8_SA(1, 1), a1 + hstep, voffA);
;             PG8_WAIT_V(8); PG8_WAIT_L(0); PG8_BAR; PG8_MMA(0, 0, At, B0); PG8_MMA(0, 1, At, B1); PG8_BAR; PG8_SCHED;
;             PG8_LDA(At, 0, 1); PG8_STAGE(PG8_SB(0, 0), b2, voffB); PG8_STAGE(PG8_SB(0, 1), b2 + hstep, voffB); PG8_STAGE(PG8_SA(0, 0), a2, voffA);
;             PG8_WAIT_V(8); PG8_WAIT_L(0); PG8_BAR; PG8_MMA(1, 0, At, B0); PG8_MMA(1, 1, At, B1); PG8_BAR; PG8_SCHED;
	s_add_i32 s60, s60, 2
	s_add_u32 s18, s18, 0x100
	s_addc_u32 s19, s19, 0
	s_add_u32 s56, s56, 0x100
	s_addc_u32 s57, s57, 0
.LBB0_491:
	ds_read_b128 v[156:159], v151
	ds_read_b128 v[160:163], v151 offset:1024
	ds_read_b128 v[164:167], v151 offset:2048
	ds_read_b128 v[168:171], v151 offset:3072
	ds_read_b128 v[174:177], v152
	ds_read_b128 v[178:181], v152 offset:1024
	ds_read_b128 v[182:185], v152 offset:2048
	ds_read_b128 v[186:189], v152 offset:3072
	s_add_u32 s20, s18, 0xfffc0080
	s_addc_u32 s21, s19, -1
	s_cmp_eq_u32 s60, 12
	s_cselect_b32 s23, s11, s21
	s_cselect_b32 s22, s52, s20
	s_cselect_b32 s21, s9, s57
	s_cselect_b32 s20, s53, s56
	v_lshl_add_u64 v[222:223], s[18:19], 0, v[142:143]
	s_add_i32 m0, s31, 0xc000
	ds_read_b128 v[190:193], v153
	ds_read_b128 v[194:197], v153 offset:1024
	ds_read_b128 v[198:201], v153 offset:2048
	ds_read_b128 v[202:205], v153 offset:3072
	ds_read_b128 v[206:209], v153 offset:4096
	ds_read_b128 v[210:213], v153 offset:5120
	ds_read_b128 v[214:217], v153 offset:6144
	ds_read_b128 v[218:221], v153 offset:7168
	global_load_lds_dwordx4 v[222:223], off
	v_lshl_add_u64 v[222:223], s[18:19], 0, v[144:145]
	s_add_i32 m0, s31, 0xe000
	s_nop 0
	global_load_lds_dwordx4 v[222:223], off
	s_waitcnt vmcnt(8)
	s_waitcnt lgkmcnt(0)
	s_barrier
	s_setprio 1
	s_waitcnt lgkmcnt(0)
	v_mfma_f32_16x16x32_bf16 v[126:129], v[156:159], v[190:193], v[126:129]
	v_mfma_f32_16x16x32_bf16 v[122:125], v[164:167], v[190:193], v[122:125]
	v_mfma_f32_16x16x32_bf16 v[114:117], v[156:159], v[198:201], v[114:117]
	v_mfma_f32_16x16x32_bf16 v[106:109], v[164:167], v[198:201], v[106:109]
	v_mfma_f32_16x16x32_bf16 v[98:101], v[156:159], v[206:209], v[98:101]
	v_mfma_f32_16x16x32_bf16 v[90:93], v[164:167], v[206:209], v[90:93]
	v_mfma_f32_16x16x32_bf16 v[82:85], v[156:159], v[214:217], v[82:85]
	v_mfma_f32_16x16x32_bf16 v[74:77], v[164:167], v[214:217], v[74:77]
	v_mfma_f32_16x16x32_bf16 v[126:129], v[160:163], v[194:197], v[126:129]
	v_mfma_f32_16x16x32_bf16 v[122:125], v[168:171], v[194:197], v[122:125]
	v_mfma_f32_16x16x32_bf16 v[114:117], v[160:163], v[202:205], v[114:117]
	v_mfma_f32_16x16x32_bf16 v[106:109], v[168:171], v[202:205], v[106:109]
	v_mfma_f32_16x16x32_bf16 v[98:101], v[160:163], v[210:213], v[98:101]
	v_mfma_f32_16x16x32_bf16 v[90:93], v[168:171], v[210:213], v[90:93]
	v_mfma_f32_16x16x32_bf16 v[82:85], v[160:163], v[218:221], v[82:85]
	v_mfma_f32_16x16x32_bf16 v[74:77], v[168:171], v[218:221], v[74:77]
	v_mfma_f32_16x16x32_bf16 v[118:121], v[174:177], v[190:193], v[118:121]
	v_mfma_f32_16x16x32_bf16 v[110:113], v[182:185], v[190:193], v[110:113]
	v_mfma_f32_16x16x32_bf16 v[102:105], v[174:177], v[198:201], v[102:105]
	v_mfma_f32_16x16x32_bf16 v[94:97], v[182:185], v[198:201], v[94:97]
	v_mfma_f32_16x16x32_bf16 v[86:89], v[174:177], v[206:209], v[86:89]
	v_mfma_f32_16x16x32_bf16 v[78:81], v[182:185], v[206:209], v[78:81]
	v_mfma_f32_16x16x32_bf16 v[70:73], v[174:177], v[214:217], v[70:73]
	v_mfma_f32_16x16x32_bf16 v[66:69], v[182:185], v[214:217], v[66:69]
	v_mfma_f32_16x16x32_bf16 v[118:121], v[178:181], v[194:197], v[118:121]
	v_mfma_f32_16x16x32_bf16 v[110:113], v[186:189], v[194:197], v[110:113]
	v_mfma_f32_16x16x32_bf16 v[102:105], v[178:181], v[202:205], v[102:105]
	v_mfma_f32_16x16x32_bf16 v[94:97], v[186:189], v[202:205], v[94:97]
	v_mfma_f32_16x16x32_bf16 v[86:89], v[178:181], v[210:213], v[86:89]
	v_mfma_f32_16x16x32_bf16 v[78:81], v[186:189], v[210:213], v[78:81]
	v_mfma_f32_16x16x32_bf16 v[70:73], v[178:181], v[218:221], v[70:73]
	v_mfma_f32_16x16x32_bf16 v[66:69], v[186:189], v[218:221], v[66:69]
	s_setprio 0
	s_barrier
	s_add_i32 s61, s44, s28
	v_lshl_add_u64 v[222:223], s[20:21], 0, v[134:135]
	s_mov_b32 m0, s61
	ds_read_b128 v[190:193], v153 offset:16384
	ds_read_b128 v[194:197], v153 offset:17408
	ds_read_b128 v[198:201], v153 offset:18432
	ds_read_b128 v[202:205], v153 offset:19456
	ds_read_b128 v[206:209], v153 offset:20480
	ds_read_b128 v[210:213], v153 offset:21504
	ds_read_b128 v[214:217], v153 offset:22528
	ds_read_b128 v[218:221], v153 offset:23552
	global_load_lds_dwordx4 v[222:223], off
	s_add_i32 m0, s61, 0x2000
	s_add_u32 s62, s20, 0x40000
	v_lshl_add_u64 v[224:225], s[20:21], 0, v[130:131]
	s_addc_u32 s63, s21, 0
	s_add_i32 s61, s45, s28
	global_load_lds_dwordx4 v[224:225], off
	v_lshl_add_u64 v[226:227], s[62:63], 0, v[134:135]
	s_mov_b32 m0, s61
	v_lshl_add_u64 v[228:229], s[22:23], 0, v[132:133]
	global_load_lds_dwordx4 v[226:227], off
	v_lshl_add_u64 v[226:227], s[62:63], 0, v[130:131]
	s_add_i32 m0, s61, 0x2000
	s_nop 0
	global_load_lds_dwordx4 v[226:227], off
	v_lshl_add_u64 v[226:227], s[22:23], 0, v[136:137]
	s_mov_b32 m0, s31
	s_nop 0
	global_load_lds_dwordx4 v[226:227], off
	s_mov_b32 m0, s33
	s_nop 0
	global_load_lds_dwordx4 v[228:229], off
	s_waitcnt vmcnt(8)
	s_waitcnt lgkmcnt(0)
	s_barrier
; #define PG8_STAGE(bufoff, gbase, voff) do { _Pragma("unroll") for (int _i = 0; _i < 2; ++_i) \
;         __builtin_amdgcn_global_load_lds((const unsigned*)((const char*)(gbase) + (voff)[_i]), (PG8_LAS unsigned*)(lds + (bufoff) + ldsw + _i * 8192), 16, 0, 0); } while (0)
; #define PG8_LDA(dst, b, h) do { _Pragma("unroll") for (int m = 0; m < 4; ++m) _Pragma("unroll") for (int k = 0; k < 2; ++k) dst[m][k] = *(const PG8_LAS bf16x8*)(lds + PG8_SA(b, h) + aoff + m * 2048 + k * 1024); } while (0)
; #define PG8_LDB(dst, b, h) do { _Pragma("unroll") for (int n = 0; n < 2; ++n) _Pragma("unroll") for (int k = 0; k < 2; ++k) dst[n][k] = *(const PG8_LAS bf16x8*)(lds + PG8_SB(b, h) + boff + n * 2048 + k * 1024); } while (0)
; #define PG8_MMA(ai, bj, At, Bt) do { __builtin_amdgcn_s_setprio(1); _Pragma("unroll") for (int m = 0; m < 4; ++m) _Pragma("unroll") for (int n = 0; n < 2; ++n) _Pragma("unroll") for (int k = 0; k < 2; ++k) \
;         acc[ai][bj][m][n] = __builtin_amdgcn_mfma_f32_16x16x32_bf16(Bt[n][k], At[m][k], acc[ai][bj][m][n], 0, 0, 0); __builtin_amdgcn_s_setprio(0); } while (0)
; #define PG8_WAIT_V(n) asm volatile("s_waitcnt vmcnt(" #n ")" ::: "memory")
; #define PG8_WAIT_L(n) asm volatile("s_waitcnt lgkmcnt(" #n ")" ::: "memory")
; #define PG8_BAR __builtin_amdgcn_s_barrier()
; #define PG8_SCHED __builtin_amdgcn_sched_barrier(0)
; template <class Epi, class Sched, bool ALIGN_EPI = false, bool SP2 = false>
; __device__ __forceinline__ void gemm_phase(PG8_LAS unsigned char* lds, const Gemm g, const Sched& S, const Epi& E) {
;     ...
;             PG8_WAIT_V(8); PG8_WAIT_L(0); PG8_BAR; PG8_MMA(1, 0, At, B0); PG8_MMA(1, 1, At, B1); PG8_BAR; PG8_SCHED;
;             PG8_LDB(B0, 1, 0); PG8_LDB(B1, 1, 1); PG8_SCHED; PG8_LDA(At, 1, 0); PG8_STAGE(PG8_SA(0, 1), a2 + hstep, voffA);
;             PG8_WAIT_V(8); PG8_WAIT_L(0); PG8_BAR; PG8_MMA(0, 0, At, B0); PG8_MMA(0, 1, At, B1); PG8_BAR; PG8_SCHED;
	s_setprio 1
	s_waitcnt lgkmcnt(0)
	v_mfma_f32_16x16x32_bf16 v[62:65], v[156:159], v[190:193], v[62:65]
	v_mfma_f32_16x16x32_bf16 v[58:61], v[164:167], v[190:193], v[58:61]
	v_mfma_f32_16x16x32_bf16 v[50:53], v[156:159], v[198:201], v[50:53]
	v_mfma_f32_16x16x32_bf16 v[42:45], v[164:167], v[198:201], v[42:45]
	v_mfma_f32_16x16x32_bf16 v[34:37], v[156:159], v[206:209], v[34:37]
	v_mfma_f32_16x16x32_bf16 v[26:29], v[164:167], v[206:209], v[26:29]
	v_mfma_f32_16x16x32_bf16 v[18:21], v[156:159], v[214:217], v[18:21]
	v_mfma_f32_16x16x32_bf16 v[10:13], v[164:167], v[214:217], v[10:13]
	v_mfma_f32_16x16x32_bf16 v[62:65], v[160:163], v[194:197], v[62:65]
	v_mfma_f32_16x16x32_bf16 v[58:61], v[168:171], v[194:197], v[58:61]
	v_mfma_f32_16x16x32_bf16 v[50:53], v[160:163], v[202:205], v[50:53]
	v_mfma_f32_16x16x32_bf16 v[42:45], v[168:171], v[202:205], v[42:45]
	v_mfma_f32_16x16x32_bf16 v[34:37], v[160:163], v[210:213], v[34:37]
	v_mfma_f32_16x16x32_bf16 v[26:29], v[168:171], v[210:213], v[26:29]
	v_mfma_f32_16x16x32_bf16 v[18:21], v[160:163], v[218:221], v[18:21]
	v_mfma_f32_16x16x32_bf16 v[10:13], v[168:171], v[218:221], v[10:13]
	v_mfma_f32_16x16x32_bf16 v[54:57], v[174:177], v[190:193], v[54:57]
	v_mfma_f32_16x16x32_bf16 v[46:49], v[182:185], v[190:193], v[46:49]
	v_mfma_f32_16x16x32_bf16 v[38:41], v[174:177], v[198:201], v[38:41]
	v_mfma_f32_16x16x32_bf16 v[30:33], v[182:185], v[198:201], v[30:33]
	v_mfma_f32_16x16x32_bf16 v[22:25], v[174:177], v[206:209], v[22:25]
	v_mfma_f32_16x16x32_bf16 v[14:17], v[182:185], v[206:209], v[14:17]
	v_mfma_f32_16x16x32_bf16 v[6:9], v[174:177], v[214:217], v[6:9]
	v_mfma_f32_16x16x32_bf16 v[2:5], v[182:185], v[214:217], v[2:5]
	v_mfma_f32_16x16x32_bf16 v[54:57], v[178:181], v[194:197], v[54:57]
	v_mfma_f32_16x16x32_bf16 v[46:49], v[186:189], v[194:197], v[46:49]
	v_mfma_f32_16x16x32_bf16 v[38:41], v[178:181], v[202:205], v[38:41]
	v_mfma_f32_16x16x32_bf16 v[30:33], v[186:189], v[202:205], v[30:33]
	v_mfma_f32_16x16x32_bf16 v[22:25], v[178:181], v[210:213], v[22:25]
	v_mfma_f32_16x16x32_bf16 v[14:17], v[186:189], v[210:213], v[14:17]
	v_mfma_f32_16x16x32_bf16 v[6:9], v[178:181], v[218:221], v[6:9]
	v_mfma_f32_16x16x32_bf16 v[2:5], v[186:189], v[218:221], v[2:5]
	s_setprio 0
	s_barrier
	s_add_i32 s61, 0, 0x18000
	v_add_u32_e32 v138, s61, v150
	s_add_i32 s62, 0, 0x1c000
	ds_read_b128 v[156:159], v138
	ds_read_b128 v[160:163], v138 offset:1024
	ds_read_b128 v[164:167], v138 offset:2048
	ds_read_b128 v[168:171], v138 offset:3072
	v_add_u32_e32 v138, s62, v150
	ds_read_b128 v[174:177], v138
	ds_read_b128 v[178:181], v138 offset:1024
	ds_read_b128 v[182:185], v138 offset:2048
	ds_read_b128 v[186:189], v138 offset:3072
	s_add_u32 s22, s22, 0x40000
	s_addc_u32 s23, s23, 0
	s_mov_b32 m0, s34
	v_lshl_add_u64 v[230:231], s[22:23], 0, v[136:137]
	ds_read_b128 v[190:193], v153 offset:32768
	ds_read_b128 v[194:197], v153 offset:33792
	ds_read_b128 v[198:201], v153 offset:34816
	ds_read_b128 v[202:205], v153 offset:35840
	ds_read_b128 v[206:209], v153 offset:36864
	ds_read_b128 v[210:213], v153 offset:37888
	ds_read_b128 v[214:217], v153 offset:38912
	ds_read_b128 v[218:221], v153 offset:39936
	global_load_lds_dwordx4 v[230:231], off
	v_lshl_add_u64 v[230:231], s[22:23], 0, v[132:133]
	s_mov_b32 m0, s35
	s_nop 0
	global_load_lds_dwordx4 v[230:231], off
	s_waitcnt vmcnt(8)
	s_waitcnt lgkmcnt(0)
	s_barrier
	s_setprio 1
	s_waitcnt lgkmcnt(0)
	v_mfma_f32_16x16x32_bf16 v[126:129], v[156:159], v[190:193], v[126:129]
	v_mfma_f32_16x16x32_bf16 v[122:125], v[164:167], v[190:193], v[122:125]
	v_mfma_f32_16x16x32_bf16 v[114:117], v[156:159], v[198:201], v[114:117]
	v_mfma_f32_16x16x32_bf16 v[106:109], v[164:167], v[198:201], v[106:109]
	v_mfma_f32_16x16x32_bf16 v[98:101], v[156:159], v[206:209], v[98:101]
	v_mfma_f32_16x16x32_bf16 v[90:93], v[164:167], v[206:209], v[90:93]
	v_mfma_f32_16x16x32_bf16 v[82:85], v[156:159], v[214:217], v[82:85]
	v_mfma_f32_16x16x32_bf16 v[74:77], v[164:167], v[214:217], v[74:77]
	v_mfma_f32_16x16x32_bf16 v[126:129], v[160:163], v[194:197], v[126:129]
	v_mfma_f32_16x16x32_bf16 v[122:125], v[168:171], v[194:197], v[122:125]
	v_mfma_f32_16x16x32_bf16 v[114:117], v[160:163], v[202:205], v[114:117]
	v_mfma_f32_16x16x32_bf16 v[106:109], v[168:171], v[202:205], v[106:109]
	v_mfma_f32_16x16x32_bf16 v[98:101], v[160:163], v[210:213], v[98:101]
	v_mfma_f32_16x16x32_bf16 v[90:93], v[168:171], v[210:213], v[90:93]
	v_mfma_f32_16x16x32_bf16 v[82:85], v[160:163], v[218:221], v[82:85]
	v_mfma_f32_16x16x32_bf16 v[74:77], v[168:171], v[218:221], v[74:77]
	v_mfma_f32_16x16x32_bf16 v[118:121], v[174:177], v[190:193], v[118:121]
	v_mfma_f32_16x16x32_bf16 v[110:113], v[182:185], v[190:193], v[110:113]
	v_mfma_f32_16x16x32_bf16 v[102:105], v[174:177], v[198:201], v[102:105]
	v_mfma_f32_16x16x32_bf16 v[94:97], v[182:185], v[198:201], v[94:97]
	v_mfma_f32_16x16x32_bf16 v[86:89], v[174:177], v[206:209], v[86:89]
	v_mfma_f32_16x16x32_bf16 v[78:81], v[182:185], v[206:209], v[78:81]
	v_mfma_f32_16x16x32_bf16 v[70:73], v[174:177], v[214:217], v[70:73]
	v_mfma_f32_16x16x32_bf16 v[66:69], v[182:185], v[214:217], v[66:69]
	v_mfma_f32_16x16x32_bf16 v[118:121], v[178:181], v[194:197], v[118:121]
	v_mfma_f32_16x16x32_bf16 v[110:113], v[186:189], v[194:197], v[110:113]
	v_mfma_f32_16x16x32_bf16 v[102:105], v[178:181], v[202:205], v[102:105]
	v_mfma_f32_16x16x32_bf16 v[94:97], v[186:189], v[202:205], v[94:97]
	v_mfma_f32_16x16x32_bf16 v[86:89], v[178:181], v[210:213], v[86:89]
	v_mfma_f32_16x16x32_bf16 v[78:81], v[186:189], v[210:213], v[78:81]
	v_mfma_f32_16x16x32_bf16 v[70:73], v[178:181], v[218:221], v[70:73]
	v_mfma_f32_16x16x32_bf16 v[66:69], v[186:189], v[218:221], v[66:69]
	s_setprio 0
	s_barrier
; #define PG8_STAGE(bufoff, gbase, voff) do { _Pragma("unroll") for (int _i = 0; _i < 2; ++_i) \
;         __builtin_amdgcn_global_load_lds((const unsigned*)((const char*)(gbase) + (voff)[_i]), (PG8_LAS unsigned*)(lds + (bufoff) + ldsw + _i * 8192), 16, 0, 0); } while (0)
; #define PG8_LDA(dst, b, h) do { _Pragma("unroll") for (int m = 0; m < 4; ++m) _Pragma("unroll") for (int k = 0; k < 2; ++k) dst[m][k] = *(const PG8_LAS bf16x8*)(lds + PG8_SA(b, h) + aoff + m * 2048 + k * 1024); } while (0)
; #define PG8_MMA(ai, bj, At, Bt) do { __builtin_amdgcn_s_setprio(1); _Pragma("unroll") for (int m = 0; m < 4; ++m) _Pragma("unroll") for (int n = 0; n < 2; ++n) _Pragma("unroll") for (int k = 0; k < 2; ++k) \
;         acc[ai][bj][m][n] = __builtin_amdgcn_mfma_f32_16x16x32_bf16(Bt[n][k], At[m][k], acc[ai][bj][m][n], 0, 0, 0); __builtin_amdgcn_s_setprio(0); } while (0)
; #define PG8_WAIT_V(n) asm volatile("s_waitcnt vmcnt(" #n ")" ::: "memory")
; #define PG8_WAIT_L(n) asm volatile("s_waitcnt lgkmcnt(" #n ")" ::: "memory")
; #define PG8_BAR __builtin_amdgcn_s_barrier()
; #define PG8_SCHED __builtin_amdgcn_sched_barrier(0)
; template <class Epi, class Sched, bool ALIGN_EPI = false, bool SP2 = false>
; __device__ __forceinline__ void gemm_phase(PG8_LAS unsigned char* lds, const Gemm g, const Sched& S, const Epi& E) {
;     ...
;             PG8_LDA(At, 1, 1); PG8_STAGE(PG8_SB(1, 0), b3, voffB); PG8_STAGE(PG8_SB(1, 1), b3 + hstep, voffB); PG8_STAGE(PG8_SA(1, 0), a3, voffA);
;             PG8_WAIT_V(8); PG8_WAIT_L(0); PG8_BAR; PG8_MMA(1, 0, At, B0); PG8_MMA(1, 1, At, B1); PG8_BAR; PG8_SCHED;
;     ...
;         if constexpr (ALIGN_EPI) { if (wr == 0) PG8_BAR; }
	s_add_i32 s22, s61, s28
	v_lshl_add_u64 v[222:223], v[222:223], 0, s[4:5]
	s_mov_b32 m0, s22
	ds_read_b128 v[190:193], v153 offset:49152
	ds_read_b128 v[194:197], v153 offset:50176
	ds_read_b128 v[198:201], v153 offset:51200
	ds_read_b128 v[202:205], v153 offset:52224
	ds_read_b128 v[206:209], v153 offset:53248
	ds_read_b128 v[210:213], v153 offset:54272
	ds_read_b128 v[214:217], v153 offset:55296
	ds_read_b128 v[218:221], v153 offset:56320
	global_load_lds_dwordx4 v[222:223], off
	s_add_i32 m0, s22, 0x2000
	s_add_u32 s20, s20, 0x40080
	v_lshl_add_u64 v[222:223], v[224:225], 0, s[4:5]
	s_addc_u32 s21, s21, 0
	s_add_i32 s22, s62, s28
	global_load_lds_dwordx4 v[222:223], off
	v_lshl_add_u64 v[222:223], s[20:21], 0, v[134:135]
	s_mov_b32 m0, s22
	s_nop 0
	global_load_lds_dwordx4 v[222:223], off
	v_lshl_add_u64 v[222:223], s[20:21], 0, v[130:131]
	s_add_i32 m0, s22, 0x2000
	s_nop 0
	global_load_lds_dwordx4 v[222:223], off
	v_lshl_add_u64 v[222:223], v[226:227], 0, s[4:5]
	s_mov_b32 m0, s39
	s_nop 0
	global_load_lds_dwordx4 v[222:223], off
	v_lshl_add_u64 v[222:223], v[228:229], 0, s[4:5]
	s_mov_b32 m0, s40
	s_nop 0
	global_load_lds_dwordx4 v[222:223], off
	s_waitcnt vmcnt(8)
	s_waitcnt lgkmcnt(0)
	s_barrier
	s_setprio 1
	s_waitcnt lgkmcnt(0)
	v_mfma_f32_16x16x32_bf16 v[62:65], v[156:159], v[190:193], v[62:65]
	v_mfma_f32_16x16x32_bf16 v[58:61], v[164:167], v[190:193], v[58:61]
	v_mfma_f32_16x16x32_bf16 v[50:53], v[156:159], v[198:201], v[50:53]
	v_mfma_f32_16x16x32_bf16 v[42:45], v[164:167], v[198:201], v[42:45]
	v_mfma_f32_16x16x32_bf16 v[34:37], v[156:159], v[206:209], v[34:37]
	v_mfma_f32_16x16x32_bf16 v[26:29], v[164:167], v[206:209], v[26:29]
	v_mfma_f32_16x16x32_bf16 v[18:21], v[156:159], v[214:217], v[18:21]
	v_mfma_f32_16x16x32_bf16 v[10:13], v[164:167], v[214:217], v[10:13]
	v_mfma_f32_16x16x32_bf16 v[62:65], v[160:163], v[194:197], v[62:65]
	v_mfma_f32_16x16x32_bf16 v[58:61], v[168:171], v[194:197], v[58:61]
	v_mfma_f32_16x16x32_bf16 v[50:53], v[160:163], v[202:205], v[50:53]
	v_mfma_f32_16x16x32_bf16 v[42:45], v[168:171], v[202:205], v[42:45]
	v_mfma_f32_16x16x32_bf16 v[34:37], v[160:163], v[210:213], v[34:37]
	v_mfma_f32_16x16x32_bf16 v[26:29], v[168:171], v[210:213], v[26:29]
	v_mfma_f32_16x16x32_bf16 v[18:21], v[160:163], v[218:221], v[18:21]
	v_mfma_f32_16x16x32_bf16 v[10:13], v[168:171], v[218:221], v[10:13]
	v_mfma_f32_16x16x32_bf16 v[54:57], v[174:177], v[190:193], v[54:57]
	v_mfma_f32_16x16x32_bf16 v[46:49], v[182:185], v[190:193], v[46:49]
	v_mfma_f32_16x16x32_bf16 v[38:41], v[174:177], v[198:201], v[38:41]
	v_mfma_f32_16x16x32_bf16 v[30:33], v[182:185], v[198:201], v[30:33]
	v_mfma_f32_16x16x32_bf16 v[22:25], v[174:177], v[206:209], v[22:25]
	v_mfma_f32_16x16x32_bf16 v[14:17], v[182:185], v[206:209], v[14:17]
	v_mfma_f32_16x16x32_bf16 v[6:9], v[174:177], v[214:217], v[6:9]
	v_mfma_f32_16x16x32_bf16 v[2:5], v[182:185], v[214:217], v[2:5]
	v_mfma_f32_16x16x32_bf16 v[54:57], v[178:181], v[194:197], v[54:57]
	v_mfma_f32_16x16x32_bf16 v[46:49], v[186:189], v[194:197], v[46:49]
	v_mfma_f32_16x16x32_bf16 v[38:41], v[178:181], v[202:205], v[38:41]
	v_mfma_f32_16x16x32_bf16 v[30:33], v[186:189], v[202:205], v[30:33]
	v_mfma_f32_16x16x32_bf16 v[22:25], v[178:181], v[210:213], v[22:25]
	v_mfma_f32_16x16x32_bf16 v[14:17], v[186:189], v[210:213], v[14:17]
	v_mfma_f32_16x16x32_bf16 v[6:9], v[178:181], v[218:221], v[6:9]
	v_mfma_f32_16x16x32_bf16 v[2:5], v[186:189], v[218:221], v[2:5]
	s_setprio 0
	s_barrier
	s_add_i32 s60, s60, 2
	s_add_u32 s18, s18, 0x100
	s_addc_u32 s19, s19, 0
	s_add_u32 s56, s56, 0x100
	s_addc_u32 s57, s57, 0
	s_cmp_gt_u32 s60, 13
	s_cbranch_scc0 .LBB0_491
	s_and_b64 vcc, exec, s[6:7]
	s_cbranch_vccz .LBB0_494
	s_barrier

; #define PG8_STAGE(bufoff, gbase, voff) do { _Pragma("unroll") for (int _i = 0; _i < 2; ++_i) \
;         __builtin_amdgcn_global_load_lds((const unsigned*)((const char*)(gbase) + (voff)[_i]), (PG8_LAS unsigned*)(lds + (bufoff) + ldsw + _i * 8192), 16, 0, 0); } while (0)
; #define PG8_LDA(dst, b, h) do { _Pragma("unroll") for (int m = 0; m < 4; ++m) _Pragma("unroll") for (int k = 0; k < 2; ++k) dst[m][k] = *(const PG8_LAS bf16x8*)(lds + PG8_SA(b, h) + aoff + m * 2048 + k * 1024); } while (0)
; #define PG8_LDB(dst, b, h) do { _Pragma("unroll") for (int n = 0; n < 2; ++n) _Pragma("unroll") for (int k = 0; k < 2; ++k) dst[n][k] = *(const PG8_LAS bf16x8*)(lds + PG8_SB(b, h) + boff + n * 2048 + k * 1024); } while (0)
; #define PG8_SCHED __builtin_amdgcn_sched_barrier(0)
; template <class Epi, class Sched, bool ALIGN_EPI = false, bool SP2 = false>
; __device__ __forceinline__ void gemm_phase(PG8_LAS unsigned char* lds, const Gemm g, const Sched& S, const Epi& E) {
;     ...
;         const bool has_next = S.next(ui + 1, nxt);
;         const char* nA = has_next ? (const char*)g.A + (size_t)nxt.pm * tstep : cA; const char* nB = has_next ? (const char*)g.Bt + (size_t)nxt.pn * tstep : cB;
; #pragma nounroll
;         for (int t = 0; t < nt; t += 2) {
;             const bool last = (t == nt - 2);
;             const char* a1 = cA + (size_t)(t + 1) * kstep;
;             const char* a2 = last ? nA : cA + (size_t)(t + 2) * kstep; const char* b2 = last ? nB : cB + (size_t)(t + 2) * kstep;
;             const char* a3 = a2 + kstep; const char* b3 = b2 + kstep;
;             if (last && has_next) S.a_ready(nxt);
;             if constexpr (SP2) {
;             PG8_LDB(B0, 0, 0); PG8_LDB(B1, 0, 1); PG8_SCHED; PG8_LDA(At, 0, 0); PG8_STAGE(PG8_SA(1, 1), a1 + hstep, voffA);
.LBB0_688:
	s_ashr_i32 s23, s22, 31
	s_lshl_b64 s[24:25], s[22:23], 19
	s_add_u32 s24, s33, s24
	s_addc_u32 s25, s38, s25
	s_and_b64 s[26:27], s[2:3], exec
	s_cselect_b32 s23, s25, s29
	s_cselect_b32 s70, s24, s28
	s_ashr_i32 s21, s20, 31
	s_lshl_b64 s[26:27], s[20:21], 19
	s_add_u32 s26, s39, s26
	s_addc_u32 s27, s40, s27
	s_and_b64 s[34:35], s[2:3], exec
	s_cselect_b32 s21, s27, s31
	s_cselect_b32 s71, s26, s30
	s_add_u32 s28, s28, 0x40080
	s_addc_u32 s29, s29, 0
	s_add_u32 s72, s30, 0x100
	s_addc_u32 s73, s31, 0
	s_mov_b32 s74, -2
	ds_read_b128 v[148:151], v157
	ds_read_b128 v[152:155], v157 offset:1024
	ds_read_b128 v[160:163], v157 offset:2048
	ds_read_b128 v[164:167], v157 offset:3072
	ds_read_b128 v[168:171], v158
	ds_read_b128 v[174:177], v158 offset:1024
	ds_read_b128 v[178:181], v158 offset:2048
	ds_read_b128 v[182:185], v158 offset:3072
	s_add_u32 s30, s28, 0xfffc0080
	s_addc_u32 s31, s29, -1
	s_cmp_eq_u32 s74, 12
	s_cselect_b32 s35, s23, s31
	s_cselect_b32 s34, s70, s30
	s_cselect_b32 s31, s21, s73
	s_cselect_b32 s30, s71, s72

; #define PG8_STAGE(bufoff, gbase, voff) do { _Pragma("unroll") for (int _i = 0; _i < 2; ++_i) \
;         __builtin_amdgcn_global_load_lds((const unsigned*)((const char*)(gbase) + (voff)[_i]), (PG8_LAS unsigned*)(lds + (bufoff) + ldsw + _i * 8192), 16, 0, 0); } while (0)
; #define PG8_LDA(dst, b, h) do { _Pragma("unroll") for (int m = 0; m < 4; ++m) _Pragma("unroll") for (int k = 0; k < 2; ++k) dst[m][k] = *(const PG8_LAS bf16x8*)(lds + PG8_SA(b, h) + aoff + m * 2048 + k * 1024); } while (0)
; #define PG8_LDB(dst, b, h) do { _Pragma("unroll") for (int n = 0; n < 2; ++n) _Pragma("unroll") for (int k = 0; k < 2; ++k) dst[n][k] = *(const PG8_LAS bf16x8*)(lds + PG8_SB(b, h) + boff + n * 2048 + k * 1024); } while (0)
; #define PG8_MMA(ai, bj, At, Bt) do { __builtin_amdgcn_s_setprio(1); _Pragma("unroll") for (int m = 0; m < 4; ++m) _Pragma("unroll") for (int n = 0; n < 2; ++n) _Pragma("unroll") for (int k = 0; k < 2; ++k) \
;         acc[ai][bj][m][n] = __builtin_amdgcn_mfma_f32_16x16x32_bf16(Bt[n][k], At[m][k], acc[ai][bj][m][n], 0, 0, 0); __builtin_amdgcn_s_setprio(0); } while (0)
; #define PG8_WAIT_V(n) asm volatile("s_waitcnt vmcnt(" #n ")" ::: "memory")
; #define PG8_WAIT_L(n) asm volatile("s_waitcnt lgkmcnt(" #n ")" ::: "memory")
; #define PG8_BAR __builtin_amdgcn_s_barrier()
; #define PG8_SCHED __builtin_amdgcn_sched_barrier(0)
; template <class Epi, class Sched, bool ALIGN_EPI = false, bool SP2 = false>
; __device__ __forceinline__ void gemm_phase(PG8_LAS unsigned char* lds, const Gemm g, const Sched& S, const Epi& E) {
;     ...
;             PG8_LDB(B0, 0, 0); PG8_LDB(B1, 0, 1); PG8_SCHED; PG8_LDA(At, 0, 0); PG8_STAGE(PG8_SA(1, 1), a1 + hstep, voffA);
;             PG8_WAIT_V(8); PG8_WAIT_L(0); PG8_BAR; PG8_MMA(0, 0, At, B0); PG8_MMA(0, 1, At, B1); PG8_BAR; PG8_SCHED;
	v_lshl_add_u64 v[218:219], s[28:29], 0, v[140:141]
	s_add_i32 m0, s44, 0xc000
	ds_read_b128 v[186:189], v159
	ds_read_b128 v[190:193], v159 offset:1024
	ds_read_b128 v[194:197], v159 offset:2048
	ds_read_b128 v[198:201], v159 offset:3072
	ds_read_b128 v[202:205], v159 offset:4096
	ds_read_b128 v[206:209], v159 offset:5120
	ds_read_b128 v[210:213], v159 offset:6144
	ds_read_b128 v[214:217], v159 offset:7168
	global_load_lds_dwordx4 v[218:219], off
	v_lshl_add_u64 v[218:219], s[28:29], 0, v[142:143]
	s_add_i32 m0, s44, 0xe000
	s_nop 0
	global_load_lds_dwordx4 v[218:219], off
	s_waitcnt vmcnt(24)
	s_waitcnt lgkmcnt(0)
	s_barrier
	s_setprio 1
	s_waitcnt lgkmcnt(0)
	v_mfma_f32_16x16x32_bf16 v[126:129], v[148:151], v[186:189], 0
	v_mfma_f32_16x16x32_bf16 v[122:125], v[160:163], v[186:189], 0
	v_mfma_f32_16x16x32_bf16 v[114:117], v[148:151], v[194:197], 0
	v_mfma_f32_16x16x32_bf16 v[106:109], v[160:163], v[194:197], 0
	v_mfma_f32_16x16x32_bf16 v[98:101], v[148:151], v[202:205], 0
	v_mfma_f32_16x16x32_bf16 v[90:93], v[160:163], v[202:205], 0
	v_mfma_f32_16x16x32_bf16 v[82:85], v[148:151], v[210:213], 0
	v_mfma_f32_16x16x32_bf16 v[74:77], v[160:163], v[210:213], 0
	v_mfma_f32_16x16x32_bf16 v[126:129], v[152:155], v[190:193], v[126:129]
	v_mfma_f32_16x16x32_bf16 v[122:125], v[164:167], v[190:193], v[122:125]
	v_mfma_f32_16x16x32_bf16 v[114:117], v[152:155], v[198:201], v[114:117]
	v_mfma_f32_16x16x32_bf16 v[106:109], v[164:167], v[198:201], v[106:109]
	v_mfma_f32_16x16x32_bf16 v[98:101], v[152:155], v[206:209], v[98:101]
	v_mfma_f32_16x16x32_bf16 v[90:93], v[164:167], v[206:209], v[90:93]
	v_mfma_f32_16x16x32_bf16 v[82:85], v[152:155], v[214:217], v[82:85]
	v_mfma_f32_16x16x32_bf16 v[74:77], v[164:167], v[214:217], v[74:77]
	v_mfma_f32_16x16x32_bf16 v[118:121], v[168:171], v[186:189], 0
	v_mfma_f32_16x16x32_bf16 v[110:113], v[178:181], v[186:189], 0
	v_mfma_f32_16x16x32_bf16 v[102:105], v[168:171], v[194:197], 0
	v_mfma_f32_16x16x32_bf16 v[94:97], v[178:181], v[194:197], 0
	v_mfma_f32_16x16x32_bf16 v[86:89], v[168:171], v[202:205], 0
	v_mfma_f32_16x16x32_bf16 v[78:81], v[178:181], v[202:205], 0
	v_mfma_f32_16x16x32_bf16 v[70:73], v[168:171], v[210:213], 0
	v_mfma_f32_16x16x32_bf16 v[66:69], v[178:181], v[210:213], 0
	v_mfma_f32_16x16x32_bf16 v[118:121], v[174:177], v[190:193], v[118:121]
	v_mfma_f32_16x16x32_bf16 v[110:113], v[182:185], v[190:193], v[110:113]
	v_mfma_f32_16x16x32_bf16 v[102:105], v[174:177], v[198:201], v[102:105]
	v_mfma_f32_16x16x32_bf16 v[94:97], v[182:185], v[198:201], v[94:97]
	v_mfma_f32_16x16x32_bf16 v[86:89], v[174:177], v[206:209], v[86:89]
	v_mfma_f32_16x16x32_bf16 v[78:81], v[182:185], v[206:209], v[78:81]
	v_mfma_f32_16x16x32_bf16 v[70:73], v[174:177], v[214:217], v[70:73]
	v_mfma_f32_16x16x32_bf16 v[66:69], v[182:185], v[214:217], v[66:69]
	s_setprio 0
	s_barrier

; #define PG8_STAGE(bufoff, gbase, voff) do { _Pragma("unroll") for (int _i = 0; _i < 2; ++_i) \
;         __builtin_amdgcn_global_load_lds((const unsigned*)((const char*)(gbase) + (voff)[_i]), (PG8_LAS unsigned*)(lds + (bufoff) + ldsw + _i * 8192), 16, 0, 0); } while (0)
; #define PG8_LDA(dst, b, h) do { _Pragma("unroll") for (int m = 0; m < 4; ++m) _Pragma("unroll") for (int k = 0; k < 2; ++k) dst[m][k] = *(const PG8_LAS bf16x8*)(lds + PG8_SA(b, h) + aoff + m * 2048 + k * 1024); } while (0)
; #define PG8_MMA(ai, bj, At, Bt) do { __builtin_amdgcn_s_setprio(1); _Pragma("unroll") for (int m = 0; m < 4; ++m) _Pragma("unroll") for (int n = 0; n < 2; ++n) _Pragma("unroll") for (int k = 0; k < 2; ++k) \
;         acc[ai][bj][m][n] = __builtin_amdgcn_mfma_f32_16x16x32_bf16(Bt[n][k], At[m][k], acc[ai][bj][m][n], 0, 0, 0); __builtin_amdgcn_s_setprio(0); } while (0)
; #define PG8_WAIT_V(n) asm volatile("s_waitcnt vmcnt(" #n ")" ::: "memory")
; #define PG8_WAIT_L(n) asm volatile("s_waitcnt lgkmcnt(" #n ")" ::: "memory")
; #define PG8_BAR __builtin_amdgcn_s_barrier()
; #define PG8_SCHED __builtin_amdgcn_sched_barrier(0)
; template <class Epi, class Sched, bool ALIGN_EPI = false, bool SP2 = false>
; __device__ __forceinline__ void gemm_phase(PG8_LAS unsigned char* lds, const Gemm g, const Sched& S, const Epi& E) {
;     ...
;             PG8_LDA(At, 0, 1); PG8_STAGE(PG8_SB(0, 0), b2, voffB); PG8_STAGE(PG8_SB(0, 1), b2 + hstep, voffB); PG8_STAGE(PG8_SA(0, 0), a2, voffA);
;             PG8_WAIT_V(8); PG8_WAIT_L(0); PG8_BAR; PG8_MMA(1, 0, At, B0); PG8_MMA(1, 1, At, B1); PG8_BAR; PG8_SCHED;
	s_add_i32 s75, s63, s41
	v_lshl_add_u64 v[218:219], s[30:31], 0, v[136:137]
	s_mov_b32 m0, s75
	ds_read_b128 v[186:189], v159 offset:16384
	ds_read_b128 v[190:193], v159 offset:17408
	ds_read_b128 v[194:197], v159 offset:18432
	ds_read_b128 v[198:201], v159 offset:19456
	ds_read_b128 v[202:205], v159 offset:20480
	ds_read_b128 v[206:209], v159 offset:21504
	ds_read_b128 v[210:213], v159 offset:22528
	ds_read_b128 v[214:217], v159 offset:23552
	global_load_lds_dwordx4 v[218:219], off
	s_add_i32 m0, s75, 0x2000
	s_add_u32 s76, s30, 0x40000
	v_lshl_add_u64 v[220:221], s[30:31], 0, v[132:133]
	s_addc_u32 s77, s31, 0
	s_add_i32 s75, s66, s41
	global_load_lds_dwordx4 v[220:221], off
	v_lshl_add_u64 v[222:223], s[76:77], 0, v[136:137]
	s_mov_b32 m0, s75
	v_lshl_add_u64 v[224:225], s[34:35], 0, v[134:135]
	global_load_lds_dwordx4 v[222:223], off
	v_lshl_add_u64 v[222:223], s[76:77], 0, v[132:133]
	s_add_i32 m0, s75, 0x2000
	s_nop 0
	global_load_lds_dwordx4 v[222:223], off
	v_lshl_add_u64 v[222:223], s[34:35], 0, v[138:139]
	s_mov_b32 m0, s44
	s_nop 0
	global_load_lds_dwordx4 v[222:223], off
	s_mov_b32 m0, s45
	s_nop 0
	global_load_lds_dwordx4 v[224:225], off
	s_waitcnt vmcnt(24)
	s_waitcnt lgkmcnt(0)
	s_barrier
	s_setprio 1
	s_waitcnt lgkmcnt(0)
	v_mfma_f32_16x16x32_bf16 v[62:65], v[148:151], v[186:189], 0
	v_mfma_f32_16x16x32_bf16 v[58:61], v[160:163], v[186:189], 0
	v_mfma_f32_16x16x32_bf16 v[50:53], v[148:151], v[194:197], 0
	v_mfma_f32_16x16x32_bf16 v[42:45], v[160:163], v[194:197], 0
	v_mfma_f32_16x16x32_bf16 v[34:37], v[148:151], v[202:205], 0
	v_mfma_f32_16x16x32_bf16 v[26:29], v[160:163], v[202:205], 0
	v_mfma_f32_16x16x32_bf16 v[18:21], v[148:151], v[210:213], 0
	v_mfma_f32_16x16x32_bf16 v[10:13], v[160:163], v[210:213], 0
	v_mfma_f32_16x16x32_bf16 v[62:65], v[152:155], v[190:193], v[62:65]
	v_mfma_f32_16x16x32_bf16 v[58:61], v[164:167], v[190:193], v[58:61]
	v_mfma_f32_16x16x32_bf16 v[50:53], v[152:155], v[198:201], v[50:53]
	v_mfma_f32_16x16x32_bf16 v[42:45], v[164:167], v[198:201], v[42:45]
	v_mfma_f32_16x16x32_bf16 v[34:37], v[152:155], v[206:209], v[34:37]
	v_mfma_f32_16x16x32_bf16 v[26:29], v[164:167], v[206:209], v[26:29]
	v_mfma_f32_16x16x32_bf16 v[18:21], v[152:155], v[214:217], v[18:21]
	v_mfma_f32_16x16x32_bf16 v[10:13], v[164:167], v[214:217], v[10:13]
	v_mfma_f32_16x16x32_bf16 v[54:57], v[168:171], v[186:189], 0
	v_mfma_f32_16x16x32_bf16 v[46:49], v[178:181], v[186:189], 0
	v_mfma_f32_16x16x32_bf16 v[38:41], v[168:171], v[194:197], 0
	v_mfma_f32_16x16x32_bf16 v[30:33], v[178:181], v[194:197], 0
	v_mfma_f32_16x16x32_bf16 v[22:25], v[168:171], v[202:205], 0
	v_mfma_f32_16x16x32_bf16 v[14:17], v[178:181], v[202:205], 0
	v_mfma_f32_16x16x32_bf16 v[6:9], v[168:171], v[210:213], 0
	v_mfma_f32_16x16x32_bf16 v[2:5], v[178:181], v[210:213], 0
	v_mfma_f32_16x16x32_bf16 v[54:57], v[174:177], v[190:193], v[54:57]
	v_mfma_f32_16x16x32_bf16 v[46:49], v[182:185], v[190:193], v[46:49]
	v_mfma_f32_16x16x32_bf16 v[38:41], v[174:177], v[198:201], v[38:41]
	v_mfma_f32_16x16x32_bf16 v[30:33], v[182:185], v[198:201], v[30:33]
	v_mfma_f32_16x16x32_bf16 v[22:25], v[174:177], v[206:209], v[22:25]
	v_mfma_f32_16x16x32_bf16 v[14:17], v[182:185], v[206:209], v[14:17]
	v_mfma_f32_16x16x32_bf16 v[6:9], v[174:177], v[214:217], v[6:9]
	v_mfma_f32_16x16x32_bf16 v[2:5], v[182:185], v[214:217], v[2:5]
	s_setprio 0
	s_barrier

; #define PG8_STAGE(bufoff, gbase, voff) do { _Pragma("unroll") for (int _i = 0; _i < 2; ++_i) \
;         __builtin_amdgcn_global_load_lds((const unsigned*)((const char*)(gbase) + (voff)[_i]), (PG8_LAS unsigned*)(lds + (bufoff) + ldsw + _i * 8192), 16, 0, 0); } while (0)
; #define PG8_LDA(dst, b, h) do { _Pragma("unroll") for (int m = 0; m < 4; ++m) _Pragma("unroll") for (int k = 0; k < 2; ++k) dst[m][k] = *(const PG8_LAS bf16x8*)(lds + PG8_SA(b, h) + aoff + m * 2048 + k * 1024); } while (0)
; #define PG8_LDB(dst, b, h) do { _Pragma("unroll") for (int n = 0; n < 2; ++n) _Pragma("unroll") for (int k = 0; k < 2; ++k) dst[n][k] = *(const PG8_LAS bf16x8*)(lds + PG8_SB(b, h) + boff + n * 2048 + k * 1024); } while (0)
; #define PG8_SCHED __builtin_amdgcn_sched_barrier(0)
; template <class Epi, class Sched, bool ALIGN_EPI = false, bool SP2 = false>
; __device__ __forceinline__ void gemm_phase(PG8_LAS unsigned char* lds, const Gemm g, const Sched& S, const Epi& E) {
;     ...
;             PG8_LDB(B0, 1, 0); PG8_LDB(B1, 1, 1); PG8_SCHED; PG8_LDA(At, 1, 0); PG8_STAGE(PG8_SA(0, 1), a2 + hstep, voffA);
	s_add_i32 s75, 0, 0x18000
	s_add_i32 s76, 0, 0x1c000
	v_add_u32_e32 v164, s75, v131
	v_add_u32_e32 v182, s76, v131
	ds_read_b128 v[148:151], v164
	ds_read_b128 v[152:155], v164 offset:1024
	ds_read_b128 v[160:163], v164 offset:2048
	ds_read_b128 v[164:167], v164 offset:3072
	ds_read_b128 v[168:171], v182
	ds_read_b128 v[174:177], v182 offset:1024
	ds_read_b128 v[178:181], v182 offset:2048
	ds_read_b128 v[182:185], v182 offset:3072

; #define PG8_STAGE(bufoff, gbase, voff) do { _Pragma("unroll") for (int _i = 0; _i < 2; ++_i) \
;         __builtin_amdgcn_global_load_lds((const unsigned*)((const char*)(gbase) + (voff)[_i]), (PG8_LAS unsigned*)(lds + (bufoff) + ldsw + _i * 8192), 16, 0, 0); } while (0)
; #define PG8_LDA(dst, b, h) do { _Pragma("unroll") for (int m = 0; m < 4; ++m) _Pragma("unroll") for (int k = 0; k < 2; ++k) dst[m][k] = *(const PG8_LAS bf16x8*)(lds + PG8_SA(b, h) + aoff + m * 2048 + k * 1024); } while (0)
; #define PG8_LDB(dst, b, h) do { _Pragma("unroll") for (int n = 0; n < 2; ++n) _Pragma("unroll") for (int k = 0; k < 2; ++k) dst[n][k] = *(const PG8_LAS bf16x8*)(lds + PG8_SB(b, h) + boff + n * 2048 + k * 1024); } while (0)
; #define PG8_MMA(ai, bj, At, Bt) do { __builtin_amdgcn_s_setprio(1); _Pragma("unroll") for (int m = 0; m < 4; ++m) _Pragma("unroll") for (int n = 0; n < 2; ++n) _Pragma("unroll") for (int k = 0; k < 2; ++k) \
;         acc[ai][bj][m][n] = __builtin_amdgcn_mfma_f32_16x16x32_bf16(Bt[n][k], At[m][k], acc[ai][bj][m][n], 0, 0, 0); __builtin_amdgcn_s_setprio(0); } while (0)
; #define PG8_WAIT_V(n) asm volatile("s_waitcnt vmcnt(" #n ")" ::: "memory")
; #define PG8_WAIT_L(n) asm volatile("s_waitcnt lgkmcnt(" #n ")" ::: "memory")
; #define PG8_BAR __builtin_amdgcn_s_barrier()
; #define PG8_SCHED __builtin_amdgcn_sched_barrier(0)
; template <class Epi, class Sched, bool ALIGN_EPI = false, bool SP2 = false>
; __device__ __forceinline__ void gemm_phase(PG8_LAS unsigned char* lds, const Gemm g, const Sched& S, const Epi& E) {
;     ...
;             PG8_LDB(B0, 1, 0); PG8_LDB(B1, 1, 1); PG8_SCHED; PG8_LDA(At, 1, 0); PG8_STAGE(PG8_SA(0, 1), a2 + hstep, voffA);
;             PG8_WAIT_V(8); PG8_WAIT_L(0); PG8_BAR; PG8_MMA(0, 0, At, B0); PG8_MMA(0, 1, At, B1); PG8_BAR; PG8_SCHED;
	s_add_u32 s34, s34, 0x40000
	s_addc_u32 s35, s35, 0
	s_mov_b32 m0, s52
	v_lshl_add_u64 v[226:227], s[34:35], 0, v[138:139]
	ds_read_b128 v[186:189], v159 offset:32768
	ds_read_b128 v[190:193], v159 offset:33792
	ds_read_b128 v[194:197], v159 offset:34816
	ds_read_b128 v[198:201], v159 offset:35840
	ds_read_b128 v[202:205], v159 offset:36864
	ds_read_b128 v[206:209], v159 offset:37888
	ds_read_b128 v[210:213], v159 offset:38912
	ds_read_b128 v[214:217], v159 offset:39936
	global_load_lds_dwordx4 v[226:227], off
	v_lshl_add_u64 v[226:227], s[34:35], 0, v[134:135]
	s_mov_b32 m0, s53
	s_nop 0
	global_load_lds_dwordx4 v[226:227], off
	s_waitcnt vmcnt(8)
	s_waitcnt lgkmcnt(0)
	s_barrier
	s_setprio 1
	s_waitcnt lgkmcnt(0)
	v_mfma_f32_16x16x32_bf16 v[126:129], v[148:151], v[186:189], v[126:129]
	v_mfma_f32_16x16x32_bf16 v[122:125], v[160:163], v[186:189], v[122:125]
	v_mfma_f32_16x16x32_bf16 v[114:117], v[148:151], v[194:197], v[114:117]
	v_mfma_f32_16x16x32_bf16 v[106:109], v[160:163], v[194:197], v[106:109]
	v_mfma_f32_16x16x32_bf16 v[98:101], v[148:151], v[202:205], v[98:101]
	v_mfma_f32_16x16x32_bf16 v[90:93], v[160:163], v[202:205], v[90:93]
	v_mfma_f32_16x16x32_bf16 v[82:85], v[148:151], v[210:213], v[82:85]
	v_mfma_f32_16x16x32_bf16 v[74:77], v[160:163], v[210:213], v[74:77]
	v_mfma_f32_16x16x32_bf16 v[126:129], v[152:155], v[190:193], v[126:129]
	v_mfma_f32_16x16x32_bf16 v[122:125], v[164:167], v[190:193], v[122:125]
	v_mfma_f32_16x16x32_bf16 v[114:117], v[152:155], v[198:201], v[114:117]
	v_mfma_f32_16x16x32_bf16 v[106:109], v[164:167], v[198:201], v[106:109]
	v_mfma_f32_16x16x32_bf16 v[98:101], v[152:155], v[206:209], v[98:101]
	v_mfma_f32_16x16x32_bf16 v[90:93], v[164:167], v[206:209], v[90:93]
	v_mfma_f32_16x16x32_bf16 v[82:85], v[152:155], v[214:217], v[82:85]
	v_mfma_f32_16x16x32_bf16 v[74:77], v[164:167], v[214:217], v[74:77]
	v_mfma_f32_16x16x32_bf16 v[118:121], v[168:171], v[186:189], v[118:121]
	v_mfma_f32_16x16x32_bf16 v[110:113], v[178:181], v[186:189], v[110:113]
	v_mfma_f32_16x16x32_bf16 v[102:105], v[168:171], v[194:197], v[102:105]
	v_mfma_f32_16x16x32_bf16 v[94:97], v[178:181], v[194:197], v[94:97]
	v_mfma_f32_16x16x32_bf16 v[86:89], v[168:171], v[202:205], v[86:89]
	v_mfma_f32_16x16x32_bf16 v[78:81], v[178:181], v[202:205], v[78:81]
	v_mfma_f32_16x16x32_bf16 v[70:73], v[168:171], v[210:213], v[70:73]
	v_mfma_f32_16x16x32_bf16 v[66:69], v[178:181], v[210:213], v[66:69]
	v_mfma_f32_16x16x32_bf16 v[118:121], v[174:177], v[190:193], v[118:121]
	v_mfma_f32_16x16x32_bf16 v[110:113], v[182:185], v[190:193], v[110:113]
	v_mfma_f32_16x16x32_bf16 v[102:105], v[174:177], v[198:201], v[102:105]
	v_mfma_f32_16x16x32_bf16 v[94:97], v[182:185], v[198:201], v[94:97]
	v_mfma_f32_16x16x32_bf16 v[86:89], v[174:177], v[206:209], v[86:89]
	v_mfma_f32_16x16x32_bf16 v[78:81], v[182:185], v[206:209], v[78:81]
	v_mfma_f32_16x16x32_bf16 v[70:73], v[174:177], v[214:217], v[70:73]
	v_mfma_f32_16x16x32_bf16 v[66:69], v[182:185], v[214:217], v[66:69]
	s_setprio 0
	s_barrier

; #define PG8_STAGE(bufoff, gbase, voff) do { _Pragma("unroll") for (int _i = 0; _i < 2; ++_i) \
;         __builtin_amdgcn_global_load_lds((const unsigned*)((const char*)(gbase) + (voff)[_i]), (PG8_LAS unsigned*)(lds + (bufoff) + ldsw + _i * 8192), 16, 0, 0); } while (0)
; #define PG8_LDA(dst, b, h) do { _Pragma("unroll") for (int m = 0; m < 4; ++m) _Pragma("unroll") for (int k = 0; k < 2; ++k) dst[m][k] = *(const PG8_LAS bf16x8*)(lds + PG8_SA(b, h) + aoff + m * 2048 + k * 1024); } while (0)
; #define PG8_MMA(ai, bj, At, Bt) do { __builtin_amdgcn_s_setprio(1); _Pragma("unroll") for (int m = 0; m < 4; ++m) _Pragma("unroll") for (int n = 0; n < 2; ++n) _Pragma("unroll") for (int k = 0; k < 2; ++k) \
;         acc[ai][bj][m][n] = __builtin_amdgcn_mfma_f32_16x16x32_bf16(Bt[n][k], At[m][k], acc[ai][bj][m][n], 0, 0, 0); __builtin_amdgcn_s_setprio(0); } while (0)
; #define PG8_WAIT_V(n) asm volatile("s_waitcnt vmcnt(" #n ")" ::: "memory")
; #define PG8_WAIT_L(n) asm volatile("s_waitcnt lgkmcnt(" #n ")" ::: "memory")
; #define PG8_BAR __builtin_amdgcn_s_barrier()
; #define PG8_SCHED __builtin_amdgcn_sched_barrier(0)
; template <class Epi, class Sched, bool ALIGN_EPI = false, bool SP2 = false>
; __device__ __forceinline__ void gemm_phase(PG8_LAS unsigned char* lds, const Gemm g, const Sched& S, const Epi& E) {
;     ...
;             PG8_LDA(At, 1, 1); PG8_STAGE(PG8_SB(1, 0), b3, voffB); PG8_STAGE(PG8_SB(1, 1), b3 + hstep, voffB); PG8_STAGE(PG8_SA(1, 0), a3, voffA);
;             PG8_WAIT_V(8); PG8_WAIT_L(0); PG8_BAR; PG8_MMA(1, 0, At, B0); PG8_MMA(1, 1, At, B1); PG8_BAR; PG8_SCHED;
	s_add_i32 s34, s75, s41
	v_lshl_add_u64 v[218:219], v[218:219], 0, s[10:11]
	s_mov_b32 m0, s34
	ds_read_b128 v[186:189], v159 offset:49152
	ds_read_b128 v[190:193], v159 offset:50176
	ds_read_b128 v[194:197], v159 offset:51200
	ds_read_b128 v[198:201], v159 offset:52224
	ds_read_b128 v[202:205], v159 offset:53248
	ds_read_b128 v[206:209], v159 offset:54272
	ds_read_b128 v[210:213], v159 offset:55296
	ds_read_b128 v[214:217], v159 offset:56320
	global_load_lds_dwordx4 v[218:219], off
	s_add_i32 m0, s34, 0x2000
	s_add_u32 s30, s30, 0x40080
	v_lshl_add_u64 v[218:219], v[220:221], 0, s[10:11]
	s_addc_u32 s31, s31, 0
	s_add_i32 s34, s76, s41
	global_load_lds_dwordx4 v[218:219], off
	v_lshl_add_u64 v[218:219], s[30:31], 0, v[136:137]
	s_mov_b32 m0, s34
	s_nop 0
	global_load_lds_dwordx4 v[218:219], off
	v_lshl_add_u64 v[218:219], s[30:31], 0, v[132:133]
	s_add_i32 m0, s34, 0x2000
	s_nop 0
	global_load_lds_dwordx4 v[218:219], off
	v_lshl_add_u64 v[218:219], v[222:223], 0, s[10:11]
	s_mov_b32 m0, s57
	s_nop 0
	global_load_lds_dwordx4 v[218:219], off
	v_lshl_add_u64 v[218:219], v[224:225], 0, s[10:11]
	s_mov_b32 m0, s60
	s_nop 0
	global_load_lds_dwordx4 v[218:219], off
	s_waitcnt vmcnt(8)
	s_waitcnt lgkmcnt(0)
	s_barrier
	s_setprio 1
	s_waitcnt lgkmcnt(0)
	v_mfma_f32_16x16x32_bf16 v[62:65], v[148:151], v[186:189], v[62:65]
	v_mfma_f32_16x16x32_bf16 v[58:61], v[160:163], v[186:189], v[58:61]
	v_mfma_f32_16x16x32_bf16 v[50:53], v[148:151], v[194:197], v[50:53]
	v_mfma_f32_16x16x32_bf16 v[42:45], v[160:163], v[194:197], v[42:45]
	v_mfma_f32_16x16x32_bf16 v[34:37], v[148:151], v[202:205], v[34:37]
	v_mfma_f32_16x16x32_bf16 v[26:29], v[160:163], v[202:205], v[26:29]
	v_mfma_f32_16x16x32_bf16 v[18:21], v[148:151], v[210:213], v[18:21]
	v_mfma_f32_16x16x32_bf16 v[10:13], v[160:163], v[210:213], v[10:13]
	v_mfma_f32_16x16x32_bf16 v[62:65], v[152:155], v[190:193], v[62:65]
	v_mfma_f32_16x16x32_bf16 v[58:61], v[164:167], v[190:193], v[58:61]
	v_mfma_f32_16x16x32_bf16 v[50:53], v[152:155], v[198:201], v[50:53]
	v_mfma_f32_16x16x32_bf16 v[42:45], v[164:167], v[198:201], v[42:45]
	v_mfma_f32_16x16x32_bf16 v[34:37], v[152:155], v[206:209], v[34:37]
	v_mfma_f32_16x16x32_bf16 v[26:29], v[164:167], v[206:209], v[26:29]
	v_mfma_f32_16x16x32_bf16 v[18:21], v[152:155], v[214:217], v[18:21]
	v_mfma_f32_16x16x32_bf16 v[10:13], v[164:167], v[214:217], v[10:13]
	v_mfma_f32_16x16x32_bf16 v[54:57], v[168:171], v[186:189], v[54:57]
	v_mfma_f32_16x16x32_bf16 v[46:49], v[178:181], v[186:189], v[46:49]
	v_mfma_f32_16x16x32_bf16 v[38:41], v[168:171], v[194:197], v[38:41]
	v_mfma_f32_16x16x32_bf16 v[30:33], v[178:181], v[194:197], v[30:33]
	v_mfma_f32_16x16x32_bf16 v[22:25], v[168:171], v[202:205], v[22:25]
	v_mfma_f32_16x16x32_bf16 v[14:17], v[178:181], v[202:205], v[14:17]
	v_mfma_f32_16x16x32_bf16 v[6:9], v[168:171], v[210:213], v[6:9]
	v_mfma_f32_16x16x32_bf16 v[2:5], v[178:181], v[210:213], v[2:5]
	v_mfma_f32_16x16x32_bf16 v[54:57], v[174:177], v[190:193], v[54:57]
	v_mfma_f32_16x16x32_bf16 v[46:49], v[182:185], v[190:193], v[46:49]
	v_mfma_f32_16x16x32_bf16 v[38:41], v[174:177], v[198:201], v[38:41]
	v_mfma_f32_16x16x32_bf16 v[30:33], v[182:185], v[198:201], v[30:33]
	v_mfma_f32_16x16x32_bf16 v[22:25], v[174:177], v[206:209], v[22:25]
	v_mfma_f32_16x16x32_bf16 v[14:17], v[182:185], v[206:209], v[14:17]
	v_mfma_f32_16x16x32_bf16 v[6:9], v[174:177], v[214:217], v[6:9]
	v_mfma_f32_16x16x32_bf16 v[2:5], v[182:185], v[214:217], v[2:5]
	s_setprio 0
	s_barrier

; #define PG8_STAGE(bufoff, gbase, voff) do { _Pragma("unroll") for (int _i = 0; _i < 2; ++_i) \
;         __builtin_amdgcn_global_load_lds((const unsigned*)((const char*)(gbase) + (voff)[_i]), (PG8_LAS unsigned*)(lds + (bufoff) + ldsw + _i * 8192), 16, 0, 0); } while (0)
; #define PG8_LDA(dst, b, h) do { _Pragma("unroll") for (int m = 0; m < 4; ++m) _Pragma("unroll") for (int k = 0; k < 2; ++k) dst[m][k] = *(const PG8_LAS bf16x8*)(lds + PG8_SA(b, h) + aoff + m * 2048 + k * 1024); } while (0)
; #define PG8_LDB(dst, b, h) do { _Pragma("unroll") for (int n = 0; n < 2; ++n) _Pragma("unroll") for (int k = 0; k < 2; ++k) dst[n][k] = *(const PG8_LAS bf16x8*)(lds + PG8_SB(b, h) + boff + n * 2048 + k * 1024); } while (0)
; #define PG8_MMA(ai, bj, At, Bt) do { __builtin_amdgcn_s_setprio(1); _Pragma("unroll") for (int m = 0; m < 4; ++m) _Pragma("unroll") for (int n = 0; n < 2; ++n) _Pragma("unroll") for (int k = 0; k < 2; ++k) \
;         acc[ai][bj][m][n] = __builtin_amdgcn_mfma_f32_16x16x32_bf16(Bt[n][k], At[m][k], acc[ai][bj][m][n], 0, 0, 0); __builtin_amdgcn_s_setprio(0); } while (0)
; #define PG8_WAIT_V(n) asm volatile("s_waitcnt vmcnt(" #n ")" ::: "memory")
; #define PG8_BAR __builtin_amdgcn_s_barrier()
; template <class Epi, class Sched, bool ALIGN_EPI = false, bool SP2 = false>
; __device__ __forceinline__ void gemm_phase(PG8_LAS unsigned char* lds, const Gemm g, const Sched& S, const Epi& E) {
;     ...
;         for (int t = 0; t < nt; t += 2) {
;             const bool last = (t == nt - 2);
;             const char* a1 = cA + (size_t)(t + 1) * kstep;
;             const char* a2 = last ? nA : cA + (size_t)(t + 2) * kstep; const char* b2 = last ? nB : cB + (size_t)(t + 2) * kstep;
;             const char* a3 = a2 + kstep; const char* b3 = b2 + kstep;
;             if (last && has_next) S.a_ready(nxt);
;             if constexpr (SP2) {
;             PG8_LDB(B0, 0, 0); PG8_LDB(B1, 0, 1); PG8_SCHED; PG8_LDA(At, 0, 0); PG8_STAGE(PG8_SA(1, 1), a1 + hstep, voffA);
;             PG8_WAIT_V(8); PG8_WAIT_L(0); PG8_BAR; PG8_MMA(0, 0, At, B0); PG8_MMA(0, 1, At, B1); PG8_BAR; PG8_SCHED;
;             PG8_LDA(At, 0, 1); PG8_STAGE(PG8_SB(0, 0), b2, voffB); PG8_STAGE(PG8_SB(0, 1), b2 + hstep, voffB); PG8_STAGE(PG8_SA(0, 0), a2, voffA);
;             PG8_WAIT_V(8); PG8_WAIT_L(0); PG8_BAR; PG8_MMA(1, 0, At, B0); PG8_MMA(1, 1, At, B1); PG8_BAR; PG8_SCHED;
	s_add_i32 s74, s74, 2
	s_add_u32 s28, s28, 0x100
	s_addc_u32 s29, s29, 0
	s_add_u32 s72, s72, 0x100
	s_addc_u32 s73, s73, 0
.LBB0_689:
	ds_read_b128 v[148:151], v157
	ds_read_b128 v[152:155], v157 offset:1024
	ds_read_b128 v[160:163], v157 offset:2048
	ds_read_b128 v[164:167], v157 offset:3072
	ds_read_b128 v[168:171], v158
	ds_read_b128 v[174:177], v158 offset:1024
	ds_read_b128 v[178:181], v158 offset:2048
	ds_read_b128 v[182:185], v158 offset:3072
	s_add_u32 s30, s28, 0xfffc0080
	s_addc_u32 s31, s29, -1
	s_cmp_eq_u32 s74, 12
	s_cselect_b32 s35, s23, s31
	s_cselect_b32 s34, s70, s30
	s_cselect_b32 s31, s21, s73
	s_cselect_b32 s30, s71, s72
	v_lshl_add_u64 v[218:219], s[28:29], 0, v[140:141]
	s_add_i32 m0, s44, 0xc000
	ds_read_b128 v[186:189], v159
	ds_read_b128 v[190:193], v159 offset:1024
	ds_read_b128 v[194:197], v159 offset:2048
	ds_read_b128 v[198:201], v159 offset:3072
	ds_read_b128 v[202:205], v159 offset:4096
	ds_read_b128 v[206:209], v159 offset:5120
	ds_read_b128 v[210:213], v159 offset:6144
	ds_read_b128 v[214:217], v159 offset:7168
	global_load_lds_dwordx4 v[218:219], off
	v_lshl_add_u64 v[218:219], s[28:29], 0, v[142:143]
	s_add_i32 m0, s44, 0xe000
	s_nop 0
	global_load_lds_dwordx4 v[218:219], off
	s_waitcnt vmcnt(8)
	s_waitcnt lgkmcnt(0)
	s_barrier
	s_setprio 1
	s_waitcnt lgkmcnt(0)
	v_mfma_f32_16x16x32_bf16 v[126:129], v[148:151], v[186:189], v[126:129]
	v_mfma_f32_16x16x32_bf16 v[122:125], v[160:163], v[186:189], v[122:125]
	v_mfma_f32_16x16x32_bf16 v[114:117], v[148:151], v[194:197], v[114:117]
	v_mfma_f32_16x16x32_bf16 v[106:109], v[160:163], v[194:197], v[106:109]
	v_mfma_f32_16x16x32_bf16 v[98:101], v[148:151], v[202:205], v[98:101]
	v_mfma_f32_16x16x32_bf16 v[90:93], v[160:163], v[202:205], v[90:93]
	v_mfma_f32_16x16x32_bf16 v[82:85], v[148:151], v[210:213], v[82:85]
	v_mfma_f32_16x16x32_bf16 v[74:77], v[160:163], v[210:213], v[74:77]
	v_mfma_f32_16x16x32_bf16 v[126:129], v[152:155], v[190:193], v[126:129]
	v_mfma_f32_16x16x32_bf16 v[122:125], v[164:167], v[190:193], v[122:125]
	v_mfma_f32_16x16x32_bf16 v[114:117], v[152:155], v[198:201], v[114:117]
	v_mfma_f32_16x16x32_bf16 v[106:109], v[164:167], v[198:201], v[106:109]
	v_mfma_f32_16x16x32_bf16 v[98:101], v[152:155], v[206:209], v[98:101]
	v_mfma_f32_16x16x32_bf16 v[90:93], v[164:167], v[206:209], v[90:93]
	v_mfma_f32_16x16x32_bf16 v[82:85], v[152:155], v[214:217], v[82:85]
	v_mfma_f32_16x16x32_bf16 v[74:77], v[164:167], v[214:217], v[74:77]
	v_mfma_f32_16x16x32_bf16 v[118:121], v[168:171], v[186:189], v[118:121]
	v_mfma_f32_16x16x32_bf16 v[110:113], v[178:181], v[186:189], v[110:113]
	v_mfma_f32_16x16x32_bf16 v[102:105], v[168:171], v[194:197], v[102:105]
	v_mfma_f32_16x16x32_bf16 v[94:97], v[178:181], v[194:197], v[94:97]
	v_mfma_f32_16x16x32_bf16 v[86:89], v[168:171], v[202:205], v[86:89]
	v_mfma_f32_16x16x32_bf16 v[78:81], v[178:181], v[202:205], v[78:81]
	v_mfma_f32_16x16x32_bf16 v[70:73], v[168:171], v[210:213], v[70:73]
	v_mfma_f32_16x16x32_bf16 v[66:69], v[178:181], v[210:213], v[66:69]
	v_mfma_f32_16x16x32_bf16 v[118:121], v[174:177], v[190:193], v[118:121]
	v_mfma_f32_16x16x32_bf16 v[110:113], v[182:185], v[190:193], v[110:113]
	v_mfma_f32_16x16x32_bf16 v[102:105], v[174:177], v[198:201], v[102:105]
	v_mfma_f32_16x16x32_bf16 v[94:97], v[182:185], v[198:201], v[94:97]
	v_mfma_f32_16x16x32_bf16 v[86:89], v[174:177], v[206:209], v[86:89]
	v_mfma_f32_16x16x32_bf16 v[78:81], v[182:185], v[206:209], v[78:81]
	v_mfma_f32_16x16x32_bf16 v[70:73], v[174:177], v[214:217], v[70:73]
	v_mfma_f32_16x16x32_bf16 v[66:69], v[182:185], v[214:217], v[66:69]
	s_setprio 0
	s_barrier
	s_add_i32 s75, s63, s41
	v_lshl_add_u64 v[218:219], s[30:31], 0, v[136:137]
	s_mov_b32 m0, s75
	ds_read_b128 v[186:189], v159 offset:16384
	ds_read_b128 v[190:193], v159 offset:17408
	ds_read_b128 v[194:197], v159 offset:18432
	ds_read_b128 v[198:201], v159 offset:19456
	ds_read_b128 v[202:205], v159 offset:20480
	ds_read_b128 v[206:209], v159 offset:21504
	ds_read_b128 v[210:213], v159 offset:22528
	ds_read_b128 v[214:217], v159 offset:23552
	global_load_lds_dwordx4 v[218:219], off
	s_add_i32 m0, s75, 0x2000
	s_add_u32 s76, s30, 0x40000
	v_lshl_add_u64 v[220:221], s[30:31], 0, v[132:133]
	s_addc_u32 s77, s31, 0
	s_add_i32 s75, s66, s41
	global_load_lds_dwordx4 v[220:221], off
	v_lshl_add_u64 v[222:223], s[76:77], 0, v[136:137]
	s_mov_b32 m0, s75
	v_lshl_add_u64 v[224:225], s[34:35], 0, v[134:135]
	global_load_lds_dwordx4 v[222:223], off
	v_lshl_add_u64 v[222:223], s[76:77], 0, v[132:133]
	s_add_i32 m0, s75, 0x2000
	s_nop 0
	global_load_lds_dwordx4 v[222:223], off
	v_lshl_add_u64 v[222:223], s[34:35], 0, v[138:139]
	s_mov_b32 m0, s44
	s_nop 0
	global_load_lds_dwordx4 v[222:223], off
	s_mov_b32 m0, s45
	s_nop 0
	global_load_lds_dwordx4 v[224:225], off
	s_waitcnt vmcnt(8)
	s_waitcnt lgkmcnt(0)
	s_barrier
; #define PG8_STAGE(bufoff, gbase, voff) do { _Pragma("unroll") for (int _i = 0; _i < 2; ++_i) \
;         __builtin_amdgcn_global_load_lds((const unsigned*)((const char*)(gbase) + (voff)[_i]), (PG8_LAS unsigned*)(lds + (bufoff) + ldsw + _i * 8192), 16, 0, 0); } while (0)
; #define PG8_LDA(dst, b, h) do { _Pragma("unroll") for (int m = 0; m < 4; ++m) _Pragma("unroll") for (int k = 0; k < 2; ++k) dst[m][k] = *(const PG8_LAS bf16x8*)(lds + PG8_SA(b, h) + aoff + m * 2048 + k * 1024); } while (0)
; #define PG8_LDB(dst, b, h) do { _Pragma("unroll") for (int n = 0; n < 2; ++n) _Pragma("unroll") for (int k = 0; k < 2; ++k) dst[n][k] = *(const PG8_LAS bf16x8*)(lds + PG8_SB(b, h) + boff + n * 2048 + k * 1024); } while (0)
; #define PG8_MMA(ai, bj, At, Bt) do { __builtin_amdgcn_s_setprio(1); _Pragma("unroll") for (int m = 0; m < 4; ++m) _Pragma("unroll") for (int n = 0; n < 2; ++n) _Pragma("unroll") for (int k = 0; k < 2; ++k) \
;         acc[ai][bj][m][n] = __builtin_amdgcn_mfma_f32_16x16x32_bf16(Bt[n][k], At[m][k], acc[ai][bj][m][n], 0, 0, 0); __builtin_amdgcn_s_setprio(0); } while (0)
; #define PG8_WAIT_V(n) asm volatile("s_waitcnt vmcnt(" #n ")" ::: "memory")
; #define PG8_WAIT_L(n) asm volatile("s_waitcnt lgkmcnt(" #n ")" ::: "memory")
; #define PG8_BAR __builtin_amdgcn_s_barrier()
; #define PG8_SCHED __builtin_amdgcn_sched_barrier(0)
; template <class Epi, class Sched, bool ALIGN_EPI = false, bool SP2 = false>
; __device__ __forceinline__ void gemm_phase(PG8_LAS unsigned char* lds, const Gemm g, const Sched& S, const Epi& E) {
;     ...
;             PG8_WAIT_V(8); PG8_WAIT_L(0); PG8_BAR; PG8_MMA(1, 0, At, B0); PG8_MMA(1, 1, At, B1); PG8_BAR; PG8_SCHED;
;             PG8_LDB(B0, 1, 0); PG8_LDB(B1, 1, 1); PG8_SCHED; PG8_LDA(At, 1, 0); PG8_STAGE(PG8_SA(0, 1), a2 + hstep, voffA);
;             PG8_WAIT_V(8); PG8_WAIT_L(0); PG8_BAR; PG8_MMA(0, 0, At, B0); PG8_MMA(0, 1, At, B1); PG8_BAR; PG8_SCHED;
	s_setprio 1
	s_waitcnt lgkmcnt(0)
	v_mfma_f32_16x16x32_bf16 v[62:65], v[148:151], v[186:189], v[62:65]
	v_mfma_f32_16x16x32_bf16 v[58:61], v[160:163], v[186:189], v[58:61]
	v_mfma_f32_16x16x32_bf16 v[50:53], v[148:151], v[194:197], v[50:53]
	v_mfma_f32_16x16x32_bf16 v[42:45], v[160:163], v[194:197], v[42:45]
	v_mfma_f32_16x16x32_bf16 v[34:37], v[148:151], v[202:205], v[34:37]
	v_mfma_f32_16x16x32_bf16 v[26:29], v[160:163], v[202:205], v[26:29]
	v_mfma_f32_16x16x32_bf16 v[18:21], v[148:151], v[210:213], v[18:21]
	v_mfma_f32_16x16x32_bf16 v[10:13], v[160:163], v[210:213], v[10:13]
	v_mfma_f32_16x16x32_bf16 v[62:65], v[152:155], v[190:193], v[62:65]
	v_mfma_f32_16x16x32_bf16 v[58:61], v[164:167], v[190:193], v[58:61]
	v_mfma_f32_16x16x32_bf16 v[50:53], v[152:155], v[198:201], v[50:53]
	v_mfma_f32_16x16x32_bf16 v[42:45], v[164:167], v[198:201], v[42:45]
	v_mfma_f32_16x16x32_bf16 v[34:37], v[152:155], v[206:209], v[34:37]
	v_mfma_f32_16x16x32_bf16 v[26:29], v[164:167], v[206:209], v[26:29]
	v_mfma_f32_16x16x32_bf16 v[18:21], v[152:155], v[214:217], v[18:21]
	v_mfma_f32_16x16x32_bf16 v[10:13], v[164:167], v[214:217], v[10:13]
	v_mfma_f32_16x16x32_bf16 v[54:57], v[168:171], v[186:189], v[54:57]
	v_mfma_f32_16x16x32_bf16 v[46:49], v[178:181], v[186:189], v[46:49]
	v_mfma_f32_16x16x32_bf16 v[38:41], v[168:171], v[194:197], v[38:41]
	v_mfma_f32_16x16x32_bf16 v[30:33], v[178:181], v[194:197], v[30:33]
	v_mfma_f32_16x16x32_bf16 v[22:25], v[168:171], v[202:205], v[22:25]
	v_mfma_f32_16x16x32_bf16 v[14:17], v[178:181], v[202:205], v[14:17]
	v_mfma_f32_16x16x32_bf16 v[6:9], v[168:171], v[210:213], v[6:9]
	v_mfma_f32_16x16x32_bf16 v[2:5], v[178:181], v[210:213], v[2:5]
	v_mfma_f32_16x16x32_bf16 v[54:57], v[174:177], v[190:193], v[54:57]
	v_mfma_f32_16x16x32_bf16 v[46:49], v[182:185], v[190:193], v[46:49]
	v_mfma_f32_16x16x32_bf16 v[38:41], v[174:177], v[198:201], v[38:41]
	v_mfma_f32_16x16x32_bf16 v[30:33], v[182:185], v[198:201], v[30:33]
	v_mfma_f32_16x16x32_bf16 v[22:25], v[174:177], v[206:209], v[22:25]
	v_mfma_f32_16x16x32_bf16 v[14:17], v[182:185], v[206:209], v[14:17]
	v_mfma_f32_16x16x32_bf16 v[6:9], v[174:177], v[214:217], v[6:9]
	v_mfma_f32_16x16x32_bf16 v[2:5], v[182:185], v[214:217], v[2:5]
	s_setprio 0
	s_barrier
	s_add_i32 s75, 0, 0x18000
	s_add_i32 s76, 0, 0x1c000
	v_add_u32_e32 v164, s75, v131
	v_add_u32_e32 v182, s76, v131
	ds_read_b128 v[148:151], v164
	ds_read_b128 v[152:155], v164 offset:1024
	ds_read_b128 v[160:163], v164 offset:2048
	ds_read_b128 v[164:167], v164 offset:3072
	ds_read_b128 v[168:171], v182
	ds_read_b128 v[174:177], v182 offset:1024
	ds_read_b128 v[178:181], v182 offset:2048
	ds_read_b128 v[182:185], v182 offset:3072
	s_add_u32 s34, s34, 0x40000
	s_addc_u32 s35, s35, 0
	s_mov_b32 m0, s52
	v_lshl_add_u64 v[226:227], s[34:35], 0, v[138:139]
	ds_read_b128 v[186:189], v159 offset:32768
	ds_read_b128 v[190:193], v159 offset:33792
	ds_read_b128 v[194:197], v159 offset:34816
	ds_read_b128 v[198:201], v159 offset:35840
	ds_read_b128 v[202:205], v159 offset:36864
	ds_read_b128 v[206:209], v159 offset:37888
	ds_read_b128 v[210:213], v159 offset:38912
	ds_read_b128 v[214:217], v159 offset:39936
	global_load_lds_dwordx4 v[226:227], off
	v_lshl_add_u64 v[226:227], s[34:35], 0, v[134:135]
	s_mov_b32 m0, s53
	s_nop 0
	global_load_lds_dwordx4 v[226:227], off
	s_waitcnt vmcnt(8)
	s_waitcnt lgkmcnt(0)
	s_barrier
	s_setprio 1
	s_waitcnt lgkmcnt(0)
	v_mfma_f32_16x16x32_bf16 v[126:129], v[148:151], v[186:189], v[126:129]
	v_mfma_f32_16x16x32_bf16 v[122:125], v[160:163], v[186:189], v[122:125]
	v_mfma_f32_16x16x32_bf16 v[114:117], v[148:151], v[194:197], v[114:117]
	v_mfma_f32_16x16x32_bf16 v[106:109], v[160:163], v[194:197], v[106:109]
	v_mfma_f32_16x16x32_bf16 v[98:101], v[148:151], v[202:205], v[98:101]
	v_mfma_f32_16x16x32_bf16 v[90:93], v[160:163], v[202:205], v[90:93]
	v_mfma_f32_16x16x32_bf16 v[82:85], v[148:151], v[210:213], v[82:85]
	v_mfma_f32_16x16x32_bf16 v[74:77], v[160:163], v[210:213], v[74:77]
	v_mfma_f32_16x16x32_bf16 v[126:129], v[152:155], v[190:193], v[126:129]
	v_mfma_f32_16x16x32_bf16 v[122:125], v[164:167], v[190:193], v[122:125]
	v_mfma_f32_16x16x32_bf16 v[114:117], v[152:155], v[198:201], v[114:117]
	v_mfma_f32_16x16x32_bf16 v[106:109], v[164:167], v[198:201], v[106:109]
	v_mfma_f32_16x16x32_bf16 v[98:101], v[152:155], v[206:209], v[98:101]
	v_mfma_f32_16x16x32_bf16 v[90:93], v[164:167], v[206:209], v[90:93]
	v_mfma_f32_16x16x32_bf16 v[82:85], v[152:155], v[214:217], v[82:85]
	v_mfma_f32_16x16x32_bf16 v[74:77], v[164:167], v[214:217], v[74:77]
	v_mfma_f32_16x16x32_bf16 v[118:121], v[168:171], v[186:189], v[118:121]
	v_mfma_f32_16x16x32_bf16 v[110:113], v[178:181], v[186:189], v[110:113]
	v_mfma_f32_16x16x32_bf16 v[102:105], v[168:171], v[194:197], v[102:105]
	v_mfma_f32_16x16x32_bf16 v[94:97], v[178:181], v[194:197], v[94:97]
	v_mfma_f32_16x16x32_bf16 v[86:89], v[168:171], v[202:205], v[86:89]
	v_mfma_f32_16x16x32_bf16 v[78:81], v[178:181], v[202:205], v[78:81]
	v_mfma_f32_16x16x32_bf16 v[70:73], v[168:171], v[210:213], v[70:73]
	v_mfma_f32_16x16x32_bf16 v[66:69], v[178:181], v[210:213], v[66:69]
	v_mfma_f32_16x16x32_bf16 v[118:121], v[174:177], v[190:193], v[118:121]
	v_mfma_f32_16x16x32_bf16 v[110:113], v[182:185], v[190:193], v[110:113]
	v_mfma_f32_16x16x32_bf16 v[102:105], v[174:177], v[198:201], v[102:105]
	v_mfma_f32_16x16x32_bf16 v[94:97], v[182:185], v[198:201], v[94:97]
	v_mfma_f32_16x16x32_bf16 v[86:89], v[174:177], v[206:209], v[86:89]
	v_mfma_f32_16x16x32_bf16 v[78:81], v[182:185], v[206:209], v[78:81]
	v_mfma_f32_16x16x32_bf16 v[70:73], v[174:177], v[214:217], v[70:73]
	v_mfma_f32_16x16x32_bf16 v[66:69], v[182:185], v[214:217], v[66:69]
	s_setprio 0
	s_barrier
; #define PG8_STAGE(bufoff, gbase, voff) do { _Pragma("unroll") for (int _i = 0; _i < 2; ++_i) \
;         __builtin_amdgcn_global_load_lds((const unsigned*)((const char*)(gbase) + (voff)[_i]), (PG8_LAS unsigned*)(lds + (bufoff) + ldsw + _i * 8192), 16, 0, 0); } while (0)
; #define PG8_LDA(dst, b, h) do { _Pragma("unroll") for (int m = 0; m < 4; ++m) _Pragma("unroll") for (int k = 0; k < 2; ++k) dst[m][k] = *(const PG8_LAS bf16x8*)(lds + PG8_SA(b, h) + aoff + m * 2048 + k * 1024); } while (0)
; #define PG8_MMA(ai, bj, At, Bt) do { __builtin_amdgcn_s_setprio(1); _Pragma("unroll") for (int m = 0; m < 4; ++m) _Pragma("unroll") for (int n = 0; n < 2; ++n) _Pragma("unroll") for (int k = 0; k < 2; ++k) \
;         acc[ai][bj][m][n] = __builtin_amdgcn_mfma_f32_16x16x32_bf16(Bt[n][k], At[m][k], acc[ai][bj][m][n], 0, 0, 0); __builtin_amdgcn_s_setprio(0); } while (0)
; #define PG8_WAIT_V(n) asm volatile("s_waitcnt vmcnt(" #n ")" ::: "memory")
; #define PG8_WAIT_L(n) asm volatile("s_waitcnt lgkmcnt(" #n ")" ::: "memory")
; #define PG8_BAR __builtin_amdgcn_s_barrier()
; #define PG8_SCHED __builtin_amdgcn_sched_barrier(0)
; template <class Epi, class Sched, bool ALIGN_EPI = false, bool SP2 = false>
; __device__ __forceinline__ void gemm_phase(PG8_LAS unsigned char* lds, const Gemm g, const Sched& S, const Epi& E) {
;     ...
;             PG8_LDA(At, 1, 1); PG8_STAGE(PG8_SB(1, 0), b3, voffB); PG8_STAGE(PG8_SB(1, 1), b3 + hstep, voffB); PG8_STAGE(PG8_SA(1, 0), a3, voffA);
;             PG8_WAIT_V(8); PG8_WAIT_L(0); PG8_BAR; PG8_MMA(1, 0, At, B0); PG8_MMA(1, 1, At, B1); PG8_BAR; PG8_SCHED;
;     ...
;         if constexpr (ALIGN_EPI) { if (wr == 0) PG8_BAR; }
	s_add_i32 s34, s75, s41
	v_lshl_add_u64 v[218:219], v[218:219], 0, s[10:11]
	s_mov_b32 m0, s34
	ds_read_b128 v[186:189], v159 offset:49152
	ds_read_b128 v[190:193], v159 offset:50176
	ds_read_b128 v[194:197], v159 offset:51200
	ds_read_b128 v[198:201], v159 offset:52224
	ds_read_b128 v[202:205], v159 offset:53248
	ds_read_b128 v[206:209], v159 offset:54272
	ds_read_b128 v[210:213], v159 offset:55296
	ds_read_b128 v[214:217], v159 offset:56320
	global_load_lds_dwordx4 v[218:219], off
	s_add_i32 m0, s34, 0x2000
	s_add_u32 s30, s30, 0x40080
	v_lshl_add_u64 v[218:219], v[220:221], 0, s[10:11]
	s_addc_u32 s31, s31, 0
	s_add_i32 s34, s76, s41
	global_load_lds_dwordx4 v[218:219], off
	v_lshl_add_u64 v[218:219], s[30:31], 0, v[136:137]
	s_mov_b32 m0, s34
	s_nop 0
	global_load_lds_dwordx4 v[218:219], off
	v_lshl_add_u64 v[218:219], s[30:31], 0, v[132:133]
	s_add_i32 m0, s34, 0x2000
	s_nop 0
	global_load_lds_dwordx4 v[218:219], off
	v_lshl_add_u64 v[218:219], v[222:223], 0, s[10:11]
	s_mov_b32 m0, s57
	s_nop 0
	global_load_lds_dwordx4 v[218:219], off
	v_lshl_add_u64 v[218:219], v[224:225], 0, s[10:11]
	s_mov_b32 m0, s60
	s_nop 0
	global_load_lds_dwordx4 v[218:219], off
	s_waitcnt vmcnt(8)
	s_waitcnt lgkmcnt(0)
	s_barrier
	s_setprio 1
	s_waitcnt lgkmcnt(0)
	v_mfma_f32_16x16x32_bf16 v[62:65], v[148:151], v[186:189], v[62:65]
	v_mfma_f32_16x16x32_bf16 v[58:61], v[160:163], v[186:189], v[58:61]
	v_mfma_f32_16x16x32_bf16 v[50:53], v[148:151], v[194:197], v[50:53]
	v_mfma_f32_16x16x32_bf16 v[42:45], v[160:163], v[194:197], v[42:45]
	v_mfma_f32_16x16x32_bf16 v[34:37], v[148:151], v[202:205], v[34:37]
	v_mfma_f32_16x16x32_bf16 v[26:29], v[160:163], v[202:205], v[26:29]
	v_mfma_f32_16x16x32_bf16 v[18:21], v[148:151], v[210:213], v[18:21]
	v_mfma_f32_16x16x32_bf16 v[10:13], v[160:163], v[210:213], v[10:13]
	v_mfma_f32_16x16x32_bf16 v[62:65], v[152:155], v[190:193], v[62:65]
	v_mfma_f32_16x16x32_bf16 v[58:61], v[164:167], v[190:193], v[58:61]
	v_mfma_f32_16x16x32_bf16 v[50:53], v[152:155], v[198:201], v[50:53]
	v_mfma_f32_16x16x32_bf16 v[42:45], v[164:167], v[198:201], v[42:45]
	v_mfma_f32_16x16x32_bf16 v[34:37], v[152:155], v[206:209], v[34:37]
	v_mfma_f32_16x16x32_bf16 v[26:29], v[164:167], v[206:209], v[26:29]
	v_mfma_f32_16x16x32_bf16 v[18:21], v[152:155], v[214:217], v[18:21]
	v_mfma_f32_16x16x32_bf16 v[10:13], v[164:167], v[214:217], v[10:13]
	v_mfma_f32_16x16x32_bf16 v[54:57], v[168:171], v[186:189], v[54:57]
	v_mfma_f32_16x16x32_bf16 v[46:49], v[178:181], v[186:189], v[46:49]
	v_mfma_f32_16x16x32_bf16 v[38:41], v[168:171], v[194:197], v[38:41]
	v_mfma_f32_16x16x32_bf16 v[30:33], v[178:181], v[194:197], v[30:33]
	v_mfma_f32_16x16x32_bf16 v[22:25], v[168:171], v[202:205], v[22:25]
	v_mfma_f32_16x16x32_bf16 v[14:17], v[178:181], v[202:205], v[14:17]
	v_mfma_f32_16x16x32_bf16 v[6:9], v[168:171], v[210:213], v[6:9]
	v_mfma_f32_16x16x32_bf16 v[2:5], v[178:181], v[210:213], v[2:5]
	v_mfma_f32_16x16x32_bf16 v[54:57], v[174:177], v[190:193], v[54:57]
	v_mfma_f32_16x16x32_bf16 v[46:49], v[182:185], v[190:193], v[46:49]
	v_mfma_f32_16x16x32_bf16 v[38:41], v[174:177], v[198:201], v[38:41]
	v_mfma_f32_16x16x32_bf16 v[30:33], v[182:185], v[198:201], v[30:33]
	v_mfma_f32_16x16x32_bf16 v[22:25], v[174:177], v[206:209], v[22:25]
	v_mfma_f32_16x16x32_bf16 v[14:17], v[182:185], v[206:209], v[14:17]
	v_mfma_f32_16x16x32_bf16 v[6:9], v[174:177], v[214:217], v[6:9]
	v_mfma_f32_16x16x32_bf16 v[2:5], v[182:185], v[214:217], v[2:5]
	s_setprio 0
	s_barrier
	s_add_i32 s74, s74, 2
	s_add_u32 s28, s28, 0x100
	s_addc_u32 s29, s29, 0
	s_add_u32 s72, s72, 0x100
	s_addc_u32 s73, s73, 0
	s_cmp_gt_u32 s74, 13
	s_cbranch_scc0 .LBB0_689
	s_and_b64 vcc, exec, s[12:13]
	s_cbranch_vccz .LBB0_692
	s_barrier

; #define PG8_STAGE(bufoff, gbase, voff) do { _Pragma("unroll") for (int _i = 0; _i < 2; ++_i) \
;         __builtin_amdgcn_global_load_lds((const unsigned*)((const char*)(gbase) + (voff)[_i]), (PG8_LAS unsigned*)(lds + (bufoff) + ldsw + _i * 8192), 16, 0, 0); } while (0)
; #define PG8_LDA(dst, b, h) do { _Pragma("unroll") for (int m = 0; m < 4; ++m) _Pragma("unroll") for (int k = 0; k < 2; ++k) dst[m][k] = *(const PG8_LAS bf16x8*)(lds + PG8_SA(b, h) + aoff + m * 2048 + k * 1024); } while (0)
; #define PG8_LDB(dst, b, h) do { _Pragma("unroll") for (int n = 0; n < 2; ++n) _Pragma("unroll") for (int k = 0; k < 2; ++k) dst[n][k] = *(const PG8_LAS bf16x8*)(lds + PG8_SB(b, h) + boff + n * 2048 + k * 1024); } while (0)
; #define PG8_MMA(ai, bj, At, Bt) do { __builtin_amdgcn_s_setprio(1); _Pragma("unroll") for (int m = 0; m < 4; ++m) _Pragma("unroll") for (int n = 0; n < 2; ++n) _Pragma("unroll") for (int k = 0; k < 2; ++k) \
;         acc[ai][bj][m][n] = __builtin_amdgcn_mfma_f32_16x16x32_bf16(Bt[n][k], At[m][k], acc[ai][bj][m][n], 0, 0, 0); __builtin_amdgcn_s_setprio(0); } while (0)
; #define PG8_WAIT_V(n) asm volatile("s_waitcnt vmcnt(" #n ")" ::: "memory")
; #define PG8_WAIT_L(n) asm volatile("s_waitcnt lgkmcnt(" #n ")" ::: "memory")
; #define PG8_BAR __builtin_amdgcn_s_barrier()
; #define PG8_SCHED __builtin_amdgcn_sched_barrier(0)
; template <class Epi, class Sched, bool ALIGN_EPI = false, bool SP2 = false>
; __device__ __forceinline__ void gemm_phase(PG8_LAS unsigned char* lds, const Gemm g, const Sched& S, const Epi& E) {
;     ...
;             const bool last = (t == nt - 2);
;             const char* a1 = cA + (size_t)(t + 1) * kstep;
;             const char* a2 = last ? nA : cA + (size_t)(t + 2) * kstep; const char* b2 = last ? nB : cB + (size_t)(t + 2) * kstep;
;             const char* a3 = a2 + kstep; const char* b3 = b2 + kstep;
;             if (last && has_next) S.a_ready(nxt);
;             if constexpr (SP2) {
;             PG8_LDB(B0, 0, 0); PG8_LDB(B1, 0, 1); PG8_SCHED; PG8_LDA(At, 0, 0); PG8_STAGE(PG8_SA(1, 1), a1 + hstep, voffA);
;             PG8_WAIT_V(8); PG8_WAIT_L(0); PG8_BAR; PG8_MMA(0, 0, At, B0); PG8_MMA(0, 1, At, B1); PG8_BAR; PG8_SCHED;
;             PG8_LDA(At, 0, 1); PG8_STAGE(PG8_SB(0, 0), b2, voffB); PG8_STAGE(PG8_SB(0, 1), b2 + hstep, voffB); PG8_STAGE(PG8_SA(0, 0), a2, voffA);
.LBB0_865:
	ds_read_b128 v[148:151], v170
	ds_read_b128 v[152:155], v170 offset:1024
	ds_read_b128 v[156:159], v170 offset:2048
	ds_read_b128 v[160:163], v170 offset:3072
	ds_read_b128 v[164:167], v171
	ds_read_b128 v[176:179], v171 offset:1024
	ds_read_b128 v[180:183], v171 offset:2048
	ds_read_b128 v[184:187], v171 offset:3072
	s_add_u32 s6, s4, 0xfffe8080
	s_addc_u32 s7, s5, -1
	s_cmp_eq_u32 s71, s101
	s_cselect_b32 s9, s29, s7
	s_cselect_b32 s8, s28, s6
	s_cselect_b32 s7, s31, s70
	s_cselect_b32 s6, s30, s35
	v_lshl_add_u64 v[220:221], s[4:5], 0, v[140:141]
	s_add_i32 m0, s43, 0xc000
	ds_read_b128 v[188:191], v174
	ds_read_b128 v[192:195], v174 offset:1024
	ds_read_b128 v[196:199], v174 offset:2048
	ds_read_b128 v[200:203], v174 offset:3072
	ds_read_b128 v[204:207], v174 offset:4096
	ds_read_b128 v[208:211], v174 offset:5120
	ds_read_b128 v[212:215], v174 offset:6144
	ds_read_b128 v[216:219], v174 offset:7168
	global_load_lds_dwordx4 v[220:221], off
	v_lshl_add_u64 v[220:221], s[4:5], 0, v[142:143]
	s_add_i32 m0, s43, 0xe000
	s_nop 0
	global_load_lds_dwordx4 v[220:221], off
	s_waitcnt vmcnt(8)
	s_waitcnt lgkmcnt(0)
	s_barrier
	s_setprio 1
	s_waitcnt lgkmcnt(0)
	v_mfma_f32_16x16x32_bf16 v[126:129], v[148:151], v[188:191], v[126:129]
	v_mfma_f32_16x16x32_bf16 v[122:125], v[156:159], v[188:191], v[122:125]
	v_mfma_f32_16x16x32_bf16 v[110:113], v[148:151], v[196:199], v[110:113]
	v_mfma_f32_16x16x32_bf16 v[106:109], v[156:159], v[196:199], v[106:109]
	v_mfma_f32_16x16x32_bf16 v[94:97], v[148:151], v[204:207], v[94:97]
	v_mfma_f32_16x16x32_bf16 v[90:93], v[156:159], v[204:207], v[90:93]
	v_mfma_f32_16x16x32_bf16 v[78:81], v[148:151], v[212:215], v[78:81]
	v_mfma_f32_16x16x32_bf16 v[74:77], v[156:159], v[212:215], v[74:77]
	v_mfma_f32_16x16x32_bf16 v[126:129], v[152:155], v[192:195], v[126:129]
	v_mfma_f32_16x16x32_bf16 v[122:125], v[160:163], v[192:195], v[122:125]
	v_mfma_f32_16x16x32_bf16 v[110:113], v[152:155], v[200:203], v[110:113]
	v_mfma_f32_16x16x32_bf16 v[106:109], v[160:163], v[200:203], v[106:109]
	v_mfma_f32_16x16x32_bf16 v[94:97], v[152:155], v[208:211], v[94:97]
	v_mfma_f32_16x16x32_bf16 v[90:93], v[160:163], v[208:211], v[90:93]
	v_mfma_f32_16x16x32_bf16 v[78:81], v[152:155], v[216:219], v[78:81]
	v_mfma_f32_16x16x32_bf16 v[74:77], v[160:163], v[216:219], v[74:77]
	v_mfma_f32_16x16x32_bf16 v[118:121], v[164:167], v[188:191], v[118:121]
	v_mfma_f32_16x16x32_bf16 v[114:117], v[180:183], v[188:191], v[114:117]
	v_mfma_f32_16x16x32_bf16 v[102:105], v[164:167], v[196:199], v[102:105]
	v_mfma_f32_16x16x32_bf16 v[98:101], v[180:183], v[196:199], v[98:101]
	v_mfma_f32_16x16x32_bf16 v[86:89], v[164:167], v[204:207], v[86:89]
	v_mfma_f32_16x16x32_bf16 v[82:85], v[180:183], v[204:207], v[82:85]
	v_mfma_f32_16x16x32_bf16 v[70:73], v[164:167], v[212:215], v[70:73]
	v_mfma_f32_16x16x32_bf16 v[66:69], v[180:183], v[212:215], v[66:69]
	v_mfma_f32_16x16x32_bf16 v[118:121], v[176:179], v[192:195], v[118:121]
	v_mfma_f32_16x16x32_bf16 v[114:117], v[184:187], v[192:195], v[114:117]
	v_mfma_f32_16x16x32_bf16 v[102:105], v[176:179], v[200:203], v[102:105]
	v_mfma_f32_16x16x32_bf16 v[98:101], v[184:187], v[200:203], v[98:101]
	v_mfma_f32_16x16x32_bf16 v[86:89], v[176:179], v[208:211], v[86:89]
	v_mfma_f32_16x16x32_bf16 v[82:85], v[184:187], v[208:211], v[82:85]
	v_mfma_f32_16x16x32_bf16 v[70:73], v[176:179], v[216:219], v[70:73]
	v_mfma_f32_16x16x32_bf16 v[66:69], v[184:187], v[216:219], v[66:69]
	s_setprio 0
	s_barrier
	s_add_i32 s72, s66, s42
	v_lshl_add_u64 v[220:221], s[6:7], 0, v[132:133]
	s_mov_b32 m0, s72
	ds_read_b128 v[188:191], v174 offset:16384
	ds_read_b128 v[192:195], v174 offset:17408
	ds_read_b128 v[196:199], v174 offset:18432
	ds_read_b128 v[200:203], v174 offset:19456
	ds_read_b128 v[204:207], v174 offset:20480
	ds_read_b128 v[208:211], v174 offset:21504
	ds_read_b128 v[212:215], v174 offset:22528
	ds_read_b128 v[216:219], v174 offset:23552
	global_load_lds_dwordx4 v[220:221], off
	s_add_i32 m0, s72, 0x2000
	s_add_u32 s72, s6, 0x18000
	v_lshl_add_u64 v[222:223], s[6:7], 0, v[136:137]
	s_addc_u32 s73, s7, 0
	s_add_i32 s74, s67, s42
	global_load_lds_dwordx4 v[222:223], off
	v_lshl_add_u64 v[224:225], s[72:73], 0, v[132:133]
	s_mov_b32 m0, s74
	v_lshl_add_u64 v[226:227], s[8:9], 0, v[134:135]
	global_load_lds_dwordx4 v[224:225], off
	v_lshl_add_u64 v[224:225], s[72:73], 0, v[136:137]
	s_add_i32 m0, s74, 0x2000
	s_nop 0
	global_load_lds_dwordx4 v[224:225], off
	v_lshl_add_u64 v[224:225], s[8:9], 0, v[130:131]
	s_mov_b32 m0, s43
	s_nop 0
	global_load_lds_dwordx4 v[224:225], off
	s_mov_b32 m0, s44
	s_nop 0
	global_load_lds_dwordx4 v[226:227], off
	s_waitcnt vmcnt(8)
	s_waitcnt lgkmcnt(0)
	s_barrier
; #define PG8_STAGE(bufoff, gbase, voff) do { _Pragma("unroll") for (int _i = 0; _i < 2; ++_i) \
;         __builtin_amdgcn_global_load_lds((const unsigned*)((const char*)(gbase) + (voff)[_i]), (PG8_LAS unsigned*)(lds + (bufoff) + ldsw + _i * 8192), 16, 0, 0); } while (0)
; #define PG8_LDA(dst, b, h) do { _Pragma("unroll") for (int m = 0; m < 4; ++m) _Pragma("unroll") for (int k = 0; k < 2; ++k) dst[m][k] = *(const PG8_LAS bf16x8*)(lds + PG8_SA(b, h) + aoff + m * 2048 + k * 1024); } while (0)
; #define PG8_LDB(dst, b, h) do { _Pragma("unroll") for (int n = 0; n < 2; ++n) _Pragma("unroll") for (int k = 0; k < 2; ++k) dst[n][k] = *(const PG8_LAS bf16x8*)(lds + PG8_SB(b, h) + boff + n * 2048 + k * 1024); } while (0)
; #define PG8_MMA(ai, bj, At, Bt) do { __builtin_amdgcn_s_setprio(1); _Pragma("unroll") for (int m = 0; m < 4; ++m) _Pragma("unroll") for (int n = 0; n < 2; ++n) _Pragma("unroll") for (int k = 0; k < 2; ++k) \
;         acc[ai][bj][m][n] = __builtin_amdgcn_mfma_f32_16x16x32_bf16(Bt[n][k], At[m][k], acc[ai][bj][m][n], 0, 0, 0); __builtin_amdgcn_s_setprio(0); } while (0)
; #define PG8_WAIT_V(n) asm volatile("s_waitcnt vmcnt(" #n ")" ::: "memory")
; #define PG8_WAIT_L(n) asm volatile("s_waitcnt lgkmcnt(" #n ")" ::: "memory")
; #define PG8_BAR __builtin_amdgcn_s_barrier()
; #define PG8_SCHED __builtin_amdgcn_sched_barrier(0)
; template <class Epi, class Sched, bool ALIGN_EPI = false, bool SP2 = false>
; __device__ __forceinline__ void gemm_phase(PG8_LAS unsigned char* lds, const Gemm g, const Sched& S, const Epi& E) {
;     ...
;             PG8_WAIT_V(8); PG8_WAIT_L(0); PG8_BAR; PG8_MMA(1, 0, At, B0); PG8_MMA(1, 1, At, B1); PG8_BAR; PG8_SCHED;
;             PG8_LDB(B0, 1, 0); PG8_LDB(B1, 1, 1); PG8_SCHED; PG8_LDA(At, 1, 0); PG8_STAGE(PG8_SA(0, 1), a2 + hstep, voffA);
;             PG8_WAIT_V(8); PG8_WAIT_L(0); PG8_BAR; PG8_MMA(0, 0, At, B0); PG8_MMA(0, 1, At, B1); PG8_BAR; PG8_SCHED;
	s_setprio 1
	s_waitcnt lgkmcnt(0)
	v_mfma_f32_16x16x32_bf16 v[62:65], v[148:151], v[188:191], v[62:65]
	v_mfma_f32_16x16x32_bf16 v[58:61], v[156:159], v[188:191], v[58:61]
	v_mfma_f32_16x16x32_bf16 v[46:49], v[148:151], v[196:199], v[46:49]
	v_mfma_f32_16x16x32_bf16 v[42:45], v[156:159], v[196:199], v[42:45]
	v_mfma_f32_16x16x32_bf16 v[30:33], v[148:151], v[204:207], v[30:33]
	v_mfma_f32_16x16x32_bf16 v[26:29], v[156:159], v[204:207], v[26:29]
	v_mfma_f32_16x16x32_bf16 v[14:17], v[148:151], v[212:215], v[14:17]
	v_mfma_f32_16x16x32_bf16 v[10:13], v[156:159], v[212:215], v[10:13]
	v_mfma_f32_16x16x32_bf16 v[62:65], v[152:155], v[192:195], v[62:65]
	v_mfma_f32_16x16x32_bf16 v[58:61], v[160:163], v[192:195], v[58:61]
	v_mfma_f32_16x16x32_bf16 v[46:49], v[152:155], v[200:203], v[46:49]
	v_mfma_f32_16x16x32_bf16 v[42:45], v[160:163], v[200:203], v[42:45]
	v_mfma_f32_16x16x32_bf16 v[30:33], v[152:155], v[208:211], v[30:33]
	v_mfma_f32_16x16x32_bf16 v[26:29], v[160:163], v[208:211], v[26:29]
	v_mfma_f32_16x16x32_bf16 v[14:17], v[152:155], v[216:219], v[14:17]
	v_mfma_f32_16x16x32_bf16 v[10:13], v[160:163], v[216:219], v[10:13]
	v_mfma_f32_16x16x32_bf16 v[54:57], v[164:167], v[188:191], v[54:57]
	v_mfma_f32_16x16x32_bf16 v[50:53], v[180:183], v[188:191], v[50:53]
	v_mfma_f32_16x16x32_bf16 v[38:41], v[164:167], v[196:199], v[38:41]
	v_mfma_f32_16x16x32_bf16 v[34:37], v[180:183], v[196:199], v[34:37]
	v_mfma_f32_16x16x32_bf16 v[22:25], v[164:167], v[204:207], v[22:25]
	v_mfma_f32_16x16x32_bf16 v[18:21], v[180:183], v[204:207], v[18:21]
	v_mfma_f32_16x16x32_bf16 v[6:9], v[164:167], v[212:215], v[6:9]
	v_mfma_f32_16x16x32_bf16 v[2:5], v[180:183], v[212:215], v[2:5]
	v_mfma_f32_16x16x32_bf16 v[54:57], v[176:179], v[192:195], v[54:57]
	v_mfma_f32_16x16x32_bf16 v[50:53], v[184:187], v[192:195], v[50:53]
	v_mfma_f32_16x16x32_bf16 v[38:41], v[176:179], v[200:203], v[38:41]
	v_mfma_f32_16x16x32_bf16 v[34:37], v[184:187], v[200:203], v[34:37]
	v_mfma_f32_16x16x32_bf16 v[22:25], v[176:179], v[208:211], v[22:25]
	v_mfma_f32_16x16x32_bf16 v[18:21], v[184:187], v[208:211], v[18:21]
	v_mfma_f32_16x16x32_bf16 v[6:9], v[176:179], v[216:219], v[6:9]
	v_mfma_f32_16x16x32_bf16 v[2:5], v[184:187], v[216:219], v[2:5]
	s_setprio 0
	s_barrier
	s_add_i32 s72, 0, 0x18000
	v_add_u32_e32 v138, s72, v168
	s_add_i32 s73, 0, 0x1c000
	ds_read_b128 v[148:151], v138
	ds_read_b128 v[152:155], v138 offset:1024
	ds_read_b128 v[156:159], v138 offset:2048
	ds_read_b128 v[160:163], v138 offset:3072
	v_add_u32_e32 v138, s73, v168
	ds_read_b128 v[164:167], v138
	ds_read_b128 v[176:179], v138 offset:1024
	ds_read_b128 v[180:183], v138 offset:2048
	ds_read_b128 v[184:187], v138 offset:3072
	s_add_u32 s8, s8, 0x18000
	s_addc_u32 s9, s9, 0
	s_mov_b32 m0, s45
	v_lshl_add_u64 v[228:229], s[8:9], 0, v[130:131]
	ds_read_b128 v[188:191], v174 offset:32768
	ds_read_b128 v[192:195], v174 offset:33792
	ds_read_b128 v[196:199], v174 offset:34816
	ds_read_b128 v[200:203], v174 offset:35840
	ds_read_b128 v[204:207], v174 offset:36864
	ds_read_b128 v[208:211], v174 offset:37888
	ds_read_b128 v[212:215], v174 offset:38912
	ds_read_b128 v[216:219], v174 offset:39936
	global_load_lds_dwordx4 v[228:229], off
	v_lshl_add_u64 v[228:229], s[8:9], 0, v[134:135]
	s_mov_b32 m0, s52
	s_nop 0
	global_load_lds_dwordx4 v[228:229], off
	s_waitcnt vmcnt(8)
	s_waitcnt lgkmcnt(0)
	s_barrier
	s_setprio 1
	s_waitcnt lgkmcnt(0)
	v_mfma_f32_16x16x32_bf16 v[126:129], v[148:151], v[188:191], v[126:129]
	v_mfma_f32_16x16x32_bf16 v[122:125], v[156:159], v[188:191], v[122:125]
	v_mfma_f32_16x16x32_bf16 v[110:113], v[148:151], v[196:199], v[110:113]
	v_mfma_f32_16x16x32_bf16 v[106:109], v[156:159], v[196:199], v[106:109]
	v_mfma_f32_16x16x32_bf16 v[94:97], v[148:151], v[204:207], v[94:97]
	v_mfma_f32_16x16x32_bf16 v[90:93], v[156:159], v[204:207], v[90:93]
	v_mfma_f32_16x16x32_bf16 v[78:81], v[148:151], v[212:215], v[78:81]
	v_mfma_f32_16x16x32_bf16 v[74:77], v[156:159], v[212:215], v[74:77]
	v_mfma_f32_16x16x32_bf16 v[126:129], v[152:155], v[192:195], v[126:129]
	v_mfma_f32_16x16x32_bf16 v[122:125], v[160:163], v[192:195], v[122:125]
	v_mfma_f32_16x16x32_bf16 v[110:113], v[152:155], v[200:203], v[110:113]
	v_mfma_f32_16x16x32_bf16 v[106:109], v[160:163], v[200:203], v[106:109]
	v_mfma_f32_16x16x32_bf16 v[94:97], v[152:155], v[208:211], v[94:97]
	v_mfma_f32_16x16x32_bf16 v[90:93], v[160:163], v[208:211], v[90:93]
	v_mfma_f32_16x16x32_bf16 v[78:81], v[152:155], v[216:219], v[78:81]
	v_mfma_f32_16x16x32_bf16 v[74:77], v[160:163], v[216:219], v[74:77]
	v_mfma_f32_16x16x32_bf16 v[118:121], v[164:167], v[188:191], v[118:121]
	v_mfma_f32_16x16x32_bf16 v[114:117], v[180:183], v[188:191], v[114:117]
	v_mfma_f32_16x16x32_bf16 v[102:105], v[164:167], v[196:199], v[102:105]
	v_mfma_f32_16x16x32_bf16 v[98:101], v[180:183], v[196:199], v[98:101]
	v_mfma_f32_16x16x32_bf16 v[86:89], v[164:167], v[204:207], v[86:89]
	v_mfma_f32_16x16x32_bf16 v[82:85], v[180:183], v[204:207], v[82:85]
	v_mfma_f32_16x16x32_bf16 v[70:73], v[164:167], v[212:215], v[70:73]
	v_mfma_f32_16x16x32_bf16 v[66:69], v[180:183], v[212:215], v[66:69]
	v_mfma_f32_16x16x32_bf16 v[118:121], v[176:179], v[192:195], v[118:121]
	v_mfma_f32_16x16x32_bf16 v[114:117], v[184:187], v[192:195], v[114:117]
	v_mfma_f32_16x16x32_bf16 v[102:105], v[176:179], v[200:203], v[102:105]
	v_mfma_f32_16x16x32_bf16 v[98:101], v[184:187], v[200:203], v[98:101]
	v_mfma_f32_16x16x32_bf16 v[86:89], v[176:179], v[208:211], v[86:89]
	v_mfma_f32_16x16x32_bf16 v[82:85], v[184:187], v[208:211], v[82:85]
	v_mfma_f32_16x16x32_bf16 v[70:73], v[176:179], v[216:219], v[70:73]
	v_mfma_f32_16x16x32_bf16 v[66:69], v[184:187], v[216:219], v[66:69]
	s_setprio 0
	s_barrier
; #define PG8_STAGE(bufoff, gbase, voff) do { _Pragma("unroll") for (int _i = 0; _i < 2; ++_i) \
;         __builtin_amdgcn_global_load_lds((const unsigned*)((const char*)(gbase) + (voff)[_i]), (PG8_LAS unsigned*)(lds + (bufoff) + ldsw + _i * 8192), 16, 0, 0); } while (0)
; #define PG8_LDA(dst, b, h) do { _Pragma("unroll") for (int m = 0; m < 4; ++m) _Pragma("unroll") for (int k = 0; k < 2; ++k) dst[m][k] = *(const PG8_LAS bf16x8*)(lds + PG8_SA(b, h) + aoff + m * 2048 + k * 1024); } while (0)
; #define PG8_MMA(ai, bj, At, Bt) do { __builtin_amdgcn_s_setprio(1); _Pragma("unroll") for (int m = 0; m < 4; ++m) _Pragma("unroll") for (int n = 0; n < 2; ++n) _Pragma("unroll") for (int k = 0; k < 2; ++k) \
;         acc[ai][bj][m][n] = __builtin_amdgcn_mfma_f32_16x16x32_bf16(Bt[n][k], At[m][k], acc[ai][bj][m][n], 0, 0, 0); __builtin_amdgcn_s_setprio(0); } while (0)
; #define PG8_WAIT_V(n) asm volatile("s_waitcnt vmcnt(" #n ")" ::: "memory")
; #define PG8_WAIT_L(n) asm volatile("s_waitcnt lgkmcnt(" #n ")" ::: "memory")
; #define PG8_BAR __builtin_amdgcn_s_barrier()
; #define PG8_SCHED __builtin_amdgcn_sched_barrier(0)
; template <class Epi, class Sched, bool ALIGN_EPI = false, bool SP2 = false>
; __device__ __forceinline__ void gemm_phase(PG8_LAS unsigned char* lds, const Gemm g, const Sched& S, const Epi& E) {
;     ...
;             PG8_LDA(At, 1, 1); PG8_STAGE(PG8_SB(1, 0), b3, voffB); PG8_STAGE(PG8_SB(1, 1), b3 + hstep, voffB); PG8_STAGE(PG8_SA(1, 0), a3, voffA);
;             PG8_WAIT_V(8); PG8_WAIT_L(0); PG8_BAR; PG8_MMA(1, 0, At, B0); PG8_MMA(1, 1, At, B1); PG8_BAR; PG8_SCHED;
;     ...
;         if constexpr (ALIGN_EPI) { if (wr == 0) PG8_BAR; }
	s_add_i32 s8, s72, s42
	v_lshl_add_u64 v[220:221], v[220:221], 0, s[14:15]
	s_mov_b32 m0, s8
	ds_read_b128 v[188:191], v174 offset:49152
	ds_read_b128 v[192:195], v174 offset:50176
	ds_read_b128 v[196:199], v174 offset:51200
	ds_read_b128 v[200:203], v174 offset:52224
	ds_read_b128 v[204:207], v174 offset:53248
	ds_read_b128 v[208:211], v174 offset:54272
	ds_read_b128 v[212:215], v174 offset:55296
	ds_read_b128 v[216:219], v174 offset:56320
	global_load_lds_dwordx4 v[220:221], off
	s_add_i32 m0, s8, 0x2000
	s_add_u32 s6, s6, 0x18080
	v_lshl_add_u64 v[220:221], v[222:223], 0, s[14:15]
	s_addc_u32 s7, s7, 0
	s_add_i32 s8, s73, s42
	global_load_lds_dwordx4 v[220:221], off
	v_lshl_add_u64 v[220:221], s[6:7], 0, v[132:133]
	s_mov_b32 m0, s8
	s_nop 0
	global_load_lds_dwordx4 v[220:221], off
	v_lshl_add_u64 v[220:221], s[6:7], 0, v[136:137]
	s_add_i32 m0, s8, 0x2000
	s_nop 0
	global_load_lds_dwordx4 v[220:221], off
	v_lshl_add_u64 v[220:221], v[224:225], 0, s[14:15]
	s_mov_b32 m0, s56
	s_nop 0
	global_load_lds_dwordx4 v[220:221], off
	v_lshl_add_u64 v[220:221], v[226:227], 0, s[14:15]
	s_mov_b32 m0, s57
	s_nop 0
	global_load_lds_dwordx4 v[220:221], off
	s_waitcnt vmcnt(8)
	s_waitcnt lgkmcnt(0)
	s_barrier
	s_setprio 1
	s_waitcnt lgkmcnt(0)
	v_mfma_f32_16x16x32_bf16 v[62:65], v[148:151], v[188:191], v[62:65]
	v_mfma_f32_16x16x32_bf16 v[58:61], v[156:159], v[188:191], v[58:61]
	v_mfma_f32_16x16x32_bf16 v[46:49], v[148:151], v[196:199], v[46:49]
	v_mfma_f32_16x16x32_bf16 v[42:45], v[156:159], v[196:199], v[42:45]
	v_mfma_f32_16x16x32_bf16 v[30:33], v[148:151], v[204:207], v[30:33]
	v_mfma_f32_16x16x32_bf16 v[26:29], v[156:159], v[204:207], v[26:29]
	v_mfma_f32_16x16x32_bf16 v[14:17], v[148:151], v[212:215], v[14:17]
	v_mfma_f32_16x16x32_bf16 v[10:13], v[156:159], v[212:215], v[10:13]
	v_mfma_f32_16x16x32_bf16 v[62:65], v[152:155], v[192:195], v[62:65]
	v_mfma_f32_16x16x32_bf16 v[58:61], v[160:163], v[192:195], v[58:61]
	v_mfma_f32_16x16x32_bf16 v[46:49], v[152:155], v[200:203], v[46:49]
	v_mfma_f32_16x16x32_bf16 v[42:45], v[160:163], v[200:203], v[42:45]
	v_mfma_f32_16x16x32_bf16 v[30:33], v[152:155], v[208:211], v[30:33]
	v_mfma_f32_16x16x32_bf16 v[26:29], v[160:163], v[208:211], v[26:29]
	v_mfma_f32_16x16x32_bf16 v[14:17], v[152:155], v[216:219], v[14:17]
	v_mfma_f32_16x16x32_bf16 v[10:13], v[160:163], v[216:219], v[10:13]
	v_mfma_f32_16x16x32_bf16 v[54:57], v[164:167], v[188:191], v[54:57]
	v_mfma_f32_16x16x32_bf16 v[50:53], v[180:183], v[188:191], v[50:53]
	v_mfma_f32_16x16x32_bf16 v[38:41], v[164:167], v[196:199], v[38:41]
	v_mfma_f32_16x16x32_bf16 v[34:37], v[180:183], v[196:199], v[34:37]
	v_mfma_f32_16x16x32_bf16 v[22:25], v[164:167], v[204:207], v[22:25]
	v_mfma_f32_16x16x32_bf16 v[18:21], v[180:183], v[204:207], v[18:21]
	v_mfma_f32_16x16x32_bf16 v[6:9], v[164:167], v[212:215], v[6:9]
	v_mfma_f32_16x16x32_bf16 v[2:5], v[180:183], v[212:215], v[2:5]
	v_mfma_f32_16x16x32_bf16 v[54:57], v[176:179], v[192:195], v[54:57]
	v_mfma_f32_16x16x32_bf16 v[50:53], v[184:187], v[192:195], v[50:53]
	v_mfma_f32_16x16x32_bf16 v[38:41], v[176:179], v[200:203], v[38:41]
	v_mfma_f32_16x16x32_bf16 v[34:37], v[184:187], v[200:203], v[34:37]
	v_mfma_f32_16x16x32_bf16 v[22:25], v[176:179], v[208:211], v[22:25]
	v_mfma_f32_16x16x32_bf16 v[18:21], v[184:187], v[208:211], v[18:21]
	v_mfma_f32_16x16x32_bf16 v[6:9], v[176:179], v[216:219], v[6:9]
	v_mfma_f32_16x16x32_bf16 v[2:5], v[184:187], v[216:219], v[2:5]
	s_setprio 0
	s_barrier
	s_add_i32 s71, s71, 2
	s_add_u32 s4, s4, 0x100
	s_addc_u32 s5, s5, 0
	s_add_u32 s35, s35, 0x100
	s_addc_u32 s70, s70, 0
	s_cmp_ge_i32 s71, s98
	s_cbranch_scc0 .LBB0_865
	s_and_b64 vcc, exec, s[16:17]
	s_cbranch_vccz .LBB0_868
	s_barrier

; #define PG8_STAGE(bufoff, gbase, voff) do { _Pragma("unroll") for (int _i = 0; _i < 2; ++_i) \
;         __builtin_amdgcn_global_load_lds((const unsigned*)((const char*)(gbase) + (voff)[_i]), (PG8_LAS unsigned*)(lds + (bufoff) + ldsw + _i * 8192), 16, 0, 0); } while (0)
; #define PG8_LDA(dst, b, h) do { _Pragma("unroll") for (int m = 0; m < 4; ++m) _Pragma("unroll") for (int k = 0; k < 2; ++k) dst[m][k] = *(const PG8_LAS bf16x8*)(lds + PG8_SA(b, h) + aoff + m * 2048 + k * 1024); } while (0)
; #define PG8_LDB(dst, b, h) do { _Pragma("unroll") for (int n = 0; n < 2; ++n) _Pragma("unroll") for (int k = 0; k < 2; ++k) dst[n][k] = *(const PG8_LAS bf16x8*)(lds + PG8_SB(b, h) + boff + n * 2048 + k * 1024); } while (0)
; #define PG8_SCHED __builtin_amdgcn_sched_barrier(0)
; template <class Epi, class Sched, bool ALIGN_EPI = false, bool SP2 = false>
; __device__ __forceinline__ void gemm_phase(PG8_LAS unsigned char* lds, const Gemm g, const Sched& S, const Epi& E) {
;     ...
;         const bool has_next = S.next(ui + 1, nxt);
;         const char* nA = has_next ? (const char*)g.A + (size_t)nxt.pm * tstep : cA; const char* nB = has_next ? (const char*)g.Bt + (size_t)nxt.pn * tstep : cB;
; #pragma nounroll
;         for (int t = 0; t < nt; t += 2) {
;             const bool last = (t == nt - 2);
;             const char* a1 = cA + (size_t)(t + 1) * kstep;
;             const char* a2 = last ? nA : cA + (size_t)(t + 2) * kstep; const char* b2 = last ? nB : cB + (size_t)(t + 2) * kstep;
;             const char* a3 = a2 + kstep; const char* b3 = b2 + kstep;
;             if (last && has_next) S.a_ready(nxt);
;             if constexpr (SP2) {
;             PG8_LDB(B0, 0, 0); PG8_LDB(B1, 0, 1); PG8_SCHED; PG8_LDA(At, 0, 0); PG8_STAGE(PG8_SA(1, 1), a1 + hstep, voffA);
.LBB0_1220:
	s_ashr_i32 s29, s28, 31
	s_lshl_b64 s[30:31], s[28:29], 19
	s_add_u32 s30, s44, s30
	s_addc_u32 s31, s45, s31
	s_and_b64 s[34:35], s[2:3], exec
	s_cselect_b32 s29, s31, s39
	s_cselect_b32 s67, s30, s38
	s_ashr_i32 s27, s26, 31
	s_lshl_b64 s[34:35], s[26:27], 19
	s_add_u32 s34, s52, s34
	s_addc_u32 s35, s53, s35
	s_and_b64 s[42:43], s[2:3], exec
	s_cselect_b32 s27, s35, s41
	s_cselect_b32 s68, s34, s40
	s_add_u32 s38, s38, 0x40080
	s_addc_u32 s39, s39, 0
	s_add_u32 s69, s40, 0x100
	s_addc_u32 s70, s41, 0
	s_mov_b32 s71, -2
	ds_read_b128 v[154:157], v150
	ds_read_b128 v[158:161], v150 offset:1024
	ds_read_b128 v[162:165], v150 offset:2048
	ds_read_b128 v[166:169], v150 offset:3072
	ds_read_b128 v[174:177], v151
	ds_read_b128 v[178:181], v151 offset:1024
	ds_read_b128 v[182:185], v151 offset:2048
	ds_read_b128 v[186:189], v151 offset:3072
	s_add_u32 s40, s38, 0xfffc0080
	s_addc_u32 s41, s39, -1
	s_cmp_eq_u32 s71, 12
	s_cselect_b32 s43, s29, s41
	s_cselect_b32 s42, s67, s40
	s_cselect_b32 s41, s27, s70
	s_cselect_b32 s40, s68, s69

; #define PG8_STAGE(bufoff, gbase, voff) do { _Pragma("unroll") for (int _i = 0; _i < 2; ++_i) \
;         __builtin_amdgcn_global_load_lds((const unsigned*)((const char*)(gbase) + (voff)[_i]), (PG8_LAS unsigned*)(lds + (bufoff) + ldsw + _i * 8192), 16, 0, 0); } while (0)
; #define PG8_LDA(dst, b, h) do { _Pragma("unroll") for (int m = 0; m < 4; ++m) _Pragma("unroll") for (int k = 0; k < 2; ++k) dst[m][k] = *(const PG8_LAS bf16x8*)(lds + PG8_SA(b, h) + aoff + m * 2048 + k * 1024); } while (0)
; #define PG8_LDB(dst, b, h) do { _Pragma("unroll") for (int n = 0; n < 2; ++n) _Pragma("unroll") for (int k = 0; k < 2; ++k) dst[n][k] = *(const PG8_LAS bf16x8*)(lds + PG8_SB(b, h) + boff + n * 2048 + k * 1024); } while (0)
; #define PG8_MMA(ai, bj, At, Bt) do { __builtin_amdgcn_s_setprio(1); _Pragma("unroll") for (int m = 0; m < 4; ++m) _Pragma("unroll") for (int n = 0; n < 2; ++n) _Pragma("unroll") for (int k = 0; k < 2; ++k) \
;         acc[ai][bj][m][n] = __builtin_amdgcn_mfma_f32_16x16x32_bf16(Bt[n][k], At[m][k], acc[ai][bj][m][n], 0, 0, 0); __builtin_amdgcn_s_setprio(0); } while (0)
; #define PG8_WAIT_V(n) asm volatile("s_waitcnt vmcnt(" #n ")" ::: "memory")
; #define PG8_WAIT_L(n) asm volatile("s_waitcnt lgkmcnt(" #n ")" ::: "memory")
; #define PG8_BAR __builtin_amdgcn_s_barrier()
; #define PG8_SCHED __builtin_amdgcn_sched_barrier(0)
; template <class Epi, class Sched, bool ALIGN_EPI = false, bool SP2 = false>
; __device__ __forceinline__ void gemm_phase(PG8_LAS unsigned char* lds, const Gemm g, const Sched& S, const Epi& E) {
;     ...
;             PG8_LDB(B0, 0, 0); PG8_LDB(B1, 0, 1); PG8_SCHED; PG8_LDA(At, 0, 0); PG8_STAGE(PG8_SA(1, 1), a1 + hstep, voffA);
;             PG8_WAIT_V(8); PG8_WAIT_L(0); PG8_BAR; PG8_MMA(0, 0, At, B0); PG8_MMA(0, 1, At, B1); PG8_BAR; PG8_SCHED;
;     ...
;                     for (int n = 0; n < 2; ++n) acc[a][b][m][n] = (f32x4){0.f, 0.f, 0.f, 0.f};
	v_lshl_add_u64 v[146:147], s[38:39], 0, v[138:139]
	s_add_i32 m0, s55, 0xc000
	ds_read_b128 v[190:193], v152
	ds_read_b128 v[194:197], v152 offset:1024
	ds_read_b128 v[198:201], v152 offset:2048
	ds_read_b128 v[202:205], v152 offset:3072
	ds_read_b128 v[206:209], v152 offset:4096
	ds_read_b128 v[210:213], v152 offset:5120
	ds_read_b128 v[214:217], v152 offset:6144
	ds_read_b128 v[218:221], v152 offset:7168
	global_load_lds_dwordx4 v[146:147], off
	v_lshl_add_u64 v[146:147], s[38:39], 0, v[140:141]
	s_add_i32 m0, s55, 0xe000
	s_nop 0
	global_load_lds_dwordx4 v[146:147], off
	s_waitcnt vmcnt(24)
	s_waitcnt lgkmcnt(0)
	s_barrier
	s_setprio 1
	s_waitcnt lgkmcnt(0)
	v_mfma_f32_16x16x32_bf16 v[126:129], v[154:157], v[190:193], 0
	v_mfma_f32_16x16x32_bf16 v[122:125], v[162:165], v[190:193], 0
	v_mfma_f32_16x16x32_bf16 v[110:113], v[154:157], v[198:201], 0
	v_mfma_f32_16x16x32_bf16 v[106:109], v[162:165], v[198:201], 0
	v_mfma_f32_16x16x32_bf16 v[94:97], v[154:157], v[206:209], 0
	v_mfma_f32_16x16x32_bf16 v[90:93], v[162:165], v[206:209], 0
	v_mfma_f32_16x16x32_bf16 v[78:81], v[154:157], v[214:217], 0
	v_mfma_f32_16x16x32_bf16 v[74:77], v[162:165], v[214:217], 0
	v_mfma_f32_16x16x32_bf16 v[126:129], v[158:161], v[194:197], v[126:129]
	v_mfma_f32_16x16x32_bf16 v[122:125], v[166:169], v[194:197], v[122:125]
	v_mfma_f32_16x16x32_bf16 v[110:113], v[158:161], v[202:205], v[110:113]
	v_mfma_f32_16x16x32_bf16 v[106:109], v[166:169], v[202:205], v[106:109]
	v_mfma_f32_16x16x32_bf16 v[94:97], v[158:161], v[210:213], v[94:97]
	v_mfma_f32_16x16x32_bf16 v[90:93], v[166:169], v[210:213], v[90:93]
	v_mfma_f32_16x16x32_bf16 v[78:81], v[158:161], v[218:221], v[78:81]
	v_mfma_f32_16x16x32_bf16 v[74:77], v[166:169], v[218:221], v[74:77]
	v_mfma_f32_16x16x32_bf16 v[118:121], v[174:177], v[190:193], 0
	v_mfma_f32_16x16x32_bf16 v[114:117], v[182:185], v[190:193], 0
	v_mfma_f32_16x16x32_bf16 v[102:105], v[174:177], v[198:201], 0
	v_mfma_f32_16x16x32_bf16 v[98:101], v[182:185], v[198:201], 0
	v_mfma_f32_16x16x32_bf16 v[86:89], v[174:177], v[206:209], 0
	v_mfma_f32_16x16x32_bf16 v[82:85], v[182:185], v[206:209], 0
	v_mfma_f32_16x16x32_bf16 v[70:73], v[174:177], v[214:217], 0
	v_mfma_f32_16x16x32_bf16 v[66:69], v[182:185], v[214:217], 0
	v_mfma_f32_16x16x32_bf16 v[118:121], v[178:181], v[194:197], v[118:121]
	v_mfma_f32_16x16x32_bf16 v[114:117], v[186:189], v[194:197], v[114:117]
	v_mfma_f32_16x16x32_bf16 v[102:105], v[178:181], v[202:205], v[102:105]
	v_mfma_f32_16x16x32_bf16 v[98:101], v[186:189], v[202:205], v[98:101]
	v_mfma_f32_16x16x32_bf16 v[86:89], v[178:181], v[210:213], v[86:89]
	v_mfma_f32_16x16x32_bf16 v[82:85], v[186:189], v[210:213], v[82:85]
	v_mfma_f32_16x16x32_bf16 v[70:73], v[178:181], v[218:221], v[70:73]
	v_mfma_f32_16x16x32_bf16 v[66:69], v[186:189], v[218:221], v[66:69]
	s_setprio 0
	s_barrier

; #define PG8_STAGE(bufoff, gbase, voff) do { _Pragma("unroll") for (int _i = 0; _i < 2; ++_i) \
;         __builtin_amdgcn_global_load_lds((const unsigned*)((const char*)(gbase) + (voff)[_i]), (PG8_LAS unsigned*)(lds + (bufoff) + ldsw + _i * 8192), 16, 0, 0); } while (0)
; #define PG8_LDA(dst, b, h) do { _Pragma("unroll") for (int m = 0; m < 4; ++m) _Pragma("unroll") for (int k = 0; k < 2; ++k) dst[m][k] = *(const PG8_LAS bf16x8*)(lds + PG8_SA(b, h) + aoff + m * 2048 + k * 1024); } while (0)
; #define PG8_MMA(ai, bj, At, Bt) do { __builtin_amdgcn_s_setprio(1); _Pragma("unroll") for (int m = 0; m < 4; ++m) _Pragma("unroll") for (int n = 0; n < 2; ++n) _Pragma("unroll") for (int k = 0; k < 2; ++k) \
;         acc[ai][bj][m][n] = __builtin_amdgcn_mfma_f32_16x16x32_bf16(Bt[n][k], At[m][k], acc[ai][bj][m][n], 0, 0, 0); __builtin_amdgcn_s_setprio(0); } while (0)
; #define PG8_WAIT_V(n) asm volatile("s_waitcnt vmcnt(" #n ")" ::: "memory")
; #define PG8_WAIT_L(n) asm volatile("s_waitcnt lgkmcnt(" #n ")" ::: "memory")
; #define PG8_BAR __builtin_amdgcn_s_barrier()
; #define PG8_SCHED __builtin_amdgcn_sched_barrier(0)
; template <class Epi, class Sched, bool ALIGN_EPI = false, bool SP2 = false>
; __device__ __forceinline__ void gemm_phase(PG8_LAS unsigned char* lds, const Gemm g, const Sched& S, const Epi& E) {
;     ...
;             PG8_LDA(At, 0, 1); PG8_STAGE(PG8_SB(0, 0), b2, voffB); PG8_STAGE(PG8_SB(0, 1), b2 + hstep, voffB); PG8_STAGE(PG8_SA(0, 0), a2, voffA);
;             PG8_WAIT_V(8); PG8_WAIT_L(0); PG8_BAR; PG8_MMA(1, 0, At, B0); PG8_MMA(1, 1, At, B1); PG8_BAR; PG8_SCHED;
;     ...
;                     for (int n = 0; n < 2; ++n) acc[a][b][m][n] = (f32x4){0.f, 0.f, 0.f, 0.f};
	s_add_i32 s72, s64, s54
	v_lshl_add_u64 v[146:147], s[40:41], 0, v[132:133]
	s_mov_b32 m0, s72
	ds_read_b128 v[190:193], v152 offset:16384
	ds_read_b128 v[194:197], v152 offset:17408
	ds_read_b128 v[198:201], v152 offset:18432
	ds_read_b128 v[202:205], v152 offset:19456
	ds_read_b128 v[206:209], v152 offset:20480
	ds_read_b128 v[210:213], v152 offset:21504
	ds_read_b128 v[214:217], v152 offset:22528
	ds_read_b128 v[218:221], v152 offset:23552
	global_load_lds_dwordx4 v[146:147], off
	s_add_i32 m0, s72, 0x2000
	s_add_u32 s72, s40, 0x40000
	v_lshl_add_u64 v[170:171], s[40:41], 0, v[136:137]
	s_addc_u32 s73, s41, 0
	s_add_i32 s74, s65, s54
	global_load_lds_dwordx4 v[170:171], off
	v_lshl_add_u64 v[222:223], s[72:73], 0, v[132:133]
	s_mov_b32 m0, s74
	v_lshl_add_u64 v[224:225], s[42:43], 0, v[134:135]
	global_load_lds_dwordx4 v[222:223], off
	v_lshl_add_u64 v[222:223], s[72:73], 0, v[136:137]
	s_add_i32 m0, s74, 0x2000
	s_nop 0
	global_load_lds_dwordx4 v[222:223], off
	v_lshl_add_u64 v[222:223], s[42:43], 0, v[130:131]
	s_mov_b32 m0, s55
	s_nop 0
	global_load_lds_dwordx4 v[222:223], off
	s_mov_b32 m0, s56
	s_nop 0
	global_load_lds_dwordx4 v[224:225], off
	s_waitcnt vmcnt(24)
	s_waitcnt lgkmcnt(0)
	s_barrier
	s_setprio 1
	s_waitcnt lgkmcnt(0)
	v_mfma_f32_16x16x32_bf16 v[62:65], v[154:157], v[190:193], 0
	v_mfma_f32_16x16x32_bf16 v[58:61], v[162:165], v[190:193], 0
	v_mfma_f32_16x16x32_bf16 v[46:49], v[154:157], v[198:201], 0
	v_mfma_f32_16x16x32_bf16 v[42:45], v[162:165], v[198:201], 0
	v_mfma_f32_16x16x32_bf16 v[30:33], v[154:157], v[206:209], 0
	v_mfma_f32_16x16x32_bf16 v[26:29], v[162:165], v[206:209], 0
	v_mfma_f32_16x16x32_bf16 v[14:17], v[154:157], v[214:217], 0
	v_mfma_f32_16x16x32_bf16 v[10:13], v[162:165], v[214:217], 0
	v_mfma_f32_16x16x32_bf16 v[62:65], v[158:161], v[194:197], v[62:65]
	v_mfma_f32_16x16x32_bf16 v[58:61], v[166:169], v[194:197], v[58:61]
	v_mfma_f32_16x16x32_bf16 v[46:49], v[158:161], v[202:205], v[46:49]
	v_mfma_f32_16x16x32_bf16 v[42:45], v[166:169], v[202:205], v[42:45]
	v_mfma_f32_16x16x32_bf16 v[30:33], v[158:161], v[210:213], v[30:33]
	v_mfma_f32_16x16x32_bf16 v[26:29], v[166:169], v[210:213], v[26:29]
	v_mfma_f32_16x16x32_bf16 v[14:17], v[158:161], v[218:221], v[14:17]
	v_mfma_f32_16x16x32_bf16 v[10:13], v[166:169], v[218:221], v[10:13]
	v_mfma_f32_16x16x32_bf16 v[54:57], v[174:177], v[190:193], 0
	v_mfma_f32_16x16x32_bf16 v[50:53], v[182:185], v[190:193], 0
	v_mfma_f32_16x16x32_bf16 v[38:41], v[174:177], v[198:201], 0
	v_mfma_f32_16x16x32_bf16 v[34:37], v[182:185], v[198:201], 0
	v_mfma_f32_16x16x32_bf16 v[22:25], v[174:177], v[206:209], 0
	v_mfma_f32_16x16x32_bf16 v[18:21], v[182:185], v[206:209], 0
	v_mfma_f32_16x16x32_bf16 v[6:9], v[174:177], v[214:217], 0
	v_mfma_f32_16x16x32_bf16 v[2:5], v[182:185], v[214:217], 0
	v_mfma_f32_16x16x32_bf16 v[54:57], v[178:181], v[194:197], v[54:57]
	v_mfma_f32_16x16x32_bf16 v[50:53], v[186:189], v[194:197], v[50:53]
	v_mfma_f32_16x16x32_bf16 v[38:41], v[178:181], v[202:205], v[38:41]
	v_mfma_f32_16x16x32_bf16 v[34:37], v[186:189], v[202:205], v[34:37]
	v_mfma_f32_16x16x32_bf16 v[22:25], v[178:181], v[210:213], v[22:25]
	v_mfma_f32_16x16x32_bf16 v[18:21], v[186:189], v[210:213], v[18:21]
	v_mfma_f32_16x16x32_bf16 v[6:9], v[178:181], v[218:221], v[6:9]
	v_mfma_f32_16x16x32_bf16 v[2:5], v[186:189], v[218:221], v[2:5]
	s_setprio 0
	s_barrier

; #define PG8_STAGE(bufoff, gbase, voff) do { _Pragma("unroll") for (int _i = 0; _i < 2; ++_i) \
;         __builtin_amdgcn_global_load_lds((const unsigned*)((const char*)(gbase) + (voff)[_i]), (PG8_LAS unsigned*)(lds + (bufoff) + ldsw + _i * 8192), 16, 0, 0); } while (0)
; #define PG8_LDA(dst, b, h) do { _Pragma("unroll") for (int m = 0; m < 4; ++m) _Pragma("unroll") for (int k = 0; k < 2; ++k) dst[m][k] = *(const PG8_LAS bf16x8*)(lds + PG8_SA(b, h) + aoff + m * 2048 + k * 1024); } while (0)
; #define PG8_LDB(dst, b, h) do { _Pragma("unroll") for (int n = 0; n < 2; ++n) _Pragma("unroll") for (int k = 0; k < 2; ++k) dst[n][k] = *(const PG8_LAS bf16x8*)(lds + PG8_SB(b, h) + boff + n * 2048 + k * 1024); } while (0)
; #define PG8_SCHED __builtin_amdgcn_sched_barrier(0)
; template <class Epi, class Sched, bool ALIGN_EPI = false, bool SP2 = false>
; __device__ __forceinline__ void gemm_phase(PG8_LAS unsigned char* lds, const Gemm g, const Sched& S, const Epi& E) {
;     ...
;             PG8_LDB(B0, 1, 0); PG8_LDB(B1, 1, 1); PG8_SCHED; PG8_LDA(At, 1, 0); PG8_STAGE(PG8_SA(0, 1), a2 + hstep, voffA);
	s_add_i32 s72, 0, 0x18000
	v_add_u32_e32 v153, s72, v148
	s_add_i32 s73, 0, 0x1c000
	ds_read_b128 v[154:157], v153
	ds_read_b128 v[158:161], v153 offset:1024
	ds_read_b128 v[162:165], v153 offset:2048
	ds_read_b128 v[166:169], v153 offset:3072
	v_add_u32_e32 v153, s73, v148
	ds_read_b128 v[174:177], v153
	ds_read_b128 v[178:181], v153 offset:1024
	ds_read_b128 v[182:185], v153 offset:2048
	ds_read_b128 v[186:189], v153 offset:3072

; #define PG8_STAGE(bufoff, gbase, voff) do { _Pragma("unroll") for (int _i = 0; _i < 2; ++_i) \
;         __builtin_amdgcn_global_load_lds((const unsigned*)((const char*)(gbase) + (voff)[_i]), (PG8_LAS unsigned*)(lds + (bufoff) + ldsw + _i * 8192), 16, 0, 0); } while (0)
; #define PG8_LDA(dst, b, h) do { _Pragma("unroll") for (int m = 0; m < 4; ++m) _Pragma("unroll") for (int k = 0; k < 2; ++k) dst[m][k] = *(const PG8_LAS bf16x8*)(lds + PG8_SA(b, h) + aoff + m * 2048 + k * 1024); } while (0)
; #define PG8_LDB(dst, b, h) do { _Pragma("unroll") for (int n = 0; n < 2; ++n) _Pragma("unroll") for (int k = 0; k < 2; ++k) dst[n][k] = *(const PG8_LAS bf16x8*)(lds + PG8_SB(b, h) + boff + n * 2048 + k * 1024); } while (0)
; #define PG8_MMA(ai, bj, At, Bt) do { __builtin_amdgcn_s_setprio(1); _Pragma("unroll") for (int m = 0; m < 4; ++m) _Pragma("unroll") for (int n = 0; n < 2; ++n) _Pragma("unroll") for (int k = 0; k < 2; ++k) \
;         acc[ai][bj][m][n] = __builtin_amdgcn_mfma_f32_16x16x32_bf16(Bt[n][k], At[m][k], acc[ai][bj][m][n], 0, 0, 0); __builtin_amdgcn_s_setprio(0); } while (0)
; #define PG8_WAIT_V(n) asm volatile("s_waitcnt vmcnt(" #n ")" ::: "memory")
; #define PG8_WAIT_L(n) asm volatile("s_waitcnt lgkmcnt(" #n ")" ::: "memory")
; #define PG8_BAR __builtin_amdgcn_s_barrier()
; #define PG8_SCHED __builtin_amdgcn_sched_barrier(0)
; template <class Epi, class Sched, bool ALIGN_EPI = false, bool SP2 = false>
; __device__ __forceinline__ void gemm_phase(PG8_LAS unsigned char* lds, const Gemm g, const Sched& S, const Epi& E) {
;     ...
;             PG8_LDB(B0, 1, 0); PG8_LDB(B1, 1, 1); PG8_SCHED; PG8_LDA(At, 1, 0); PG8_STAGE(PG8_SA(0, 1), a2 + hstep, voffA);
;             PG8_WAIT_V(8); PG8_WAIT_L(0); PG8_BAR; PG8_MMA(0, 0, At, B0); PG8_MMA(0, 1, At, B1); PG8_BAR; PG8_SCHED;
	s_add_u32 s42, s42, 0x40000
	s_addc_u32 s43, s43, 0
	s_mov_b32 m0, s57
	v_lshl_add_u64 v[226:227], s[42:43], 0, v[130:131]
	ds_read_b128 v[190:193], v152 offset:32768
	ds_read_b128 v[194:197], v152 offset:33792
	ds_read_b128 v[198:201], v152 offset:34816
	ds_read_b128 v[202:205], v152 offset:35840
	ds_read_b128 v[206:209], v152 offset:36864
	ds_read_b128 v[210:213], v152 offset:37888
	ds_read_b128 v[214:217], v152 offset:38912
	ds_read_b128 v[218:221], v152 offset:39936
	global_load_lds_dwordx4 v[226:227], off
	v_lshl_add_u64 v[226:227], s[42:43], 0, v[134:135]
	s_mov_b32 m0, s58
	s_nop 0
	global_load_lds_dwordx4 v[226:227], off
	s_waitcnt vmcnt(8)
	s_waitcnt lgkmcnt(0)
	s_barrier
	s_setprio 1
	s_waitcnt lgkmcnt(0)
	v_mfma_f32_16x16x32_bf16 v[126:129], v[154:157], v[190:193], v[126:129]
	v_mfma_f32_16x16x32_bf16 v[122:125], v[162:165], v[190:193], v[122:125]
	v_mfma_f32_16x16x32_bf16 v[110:113], v[154:157], v[198:201], v[110:113]
	v_mfma_f32_16x16x32_bf16 v[106:109], v[162:165], v[198:201], v[106:109]
	v_mfma_f32_16x16x32_bf16 v[94:97], v[154:157], v[206:209], v[94:97]
	v_mfma_f32_16x16x32_bf16 v[90:93], v[162:165], v[206:209], v[90:93]
	v_mfma_f32_16x16x32_bf16 v[78:81], v[154:157], v[214:217], v[78:81]
	v_mfma_f32_16x16x32_bf16 v[74:77], v[162:165], v[214:217], v[74:77]
	v_mfma_f32_16x16x32_bf16 v[126:129], v[158:161], v[194:197], v[126:129]
	v_mfma_f32_16x16x32_bf16 v[122:125], v[166:169], v[194:197], v[122:125]
	v_mfma_f32_16x16x32_bf16 v[110:113], v[158:161], v[202:205], v[110:113]
	v_mfma_f32_16x16x32_bf16 v[106:109], v[166:169], v[202:205], v[106:109]
	v_mfma_f32_16x16x32_bf16 v[94:97], v[158:161], v[210:213], v[94:97]
	v_mfma_f32_16x16x32_bf16 v[90:93], v[166:169], v[210:213], v[90:93]
	v_mfma_f32_16x16x32_bf16 v[78:81], v[158:161], v[218:221], v[78:81]
	v_mfma_f32_16x16x32_bf16 v[74:77], v[166:169], v[218:221], v[74:77]
	v_mfma_f32_16x16x32_bf16 v[118:121], v[174:177], v[190:193], v[118:121]
	v_mfma_f32_16x16x32_bf16 v[114:117], v[182:185], v[190:193], v[114:117]
	v_mfma_f32_16x16x32_bf16 v[102:105], v[174:177], v[198:201], v[102:105]
	v_mfma_f32_16x16x32_bf16 v[98:101], v[182:185], v[198:201], v[98:101]
	v_mfma_f32_16x16x32_bf16 v[86:89], v[174:177], v[206:209], v[86:89]
	v_mfma_f32_16x16x32_bf16 v[82:85], v[182:185], v[206:209], v[82:85]
	v_mfma_f32_16x16x32_bf16 v[70:73], v[174:177], v[214:217], v[70:73]
	v_mfma_f32_16x16x32_bf16 v[66:69], v[182:185], v[214:217], v[66:69]
	v_mfma_f32_16x16x32_bf16 v[118:121], v[178:181], v[194:197], v[118:121]
	v_mfma_f32_16x16x32_bf16 v[114:117], v[186:189], v[194:197], v[114:117]
	v_mfma_f32_16x16x32_bf16 v[102:105], v[178:181], v[202:205], v[102:105]
	v_mfma_f32_16x16x32_bf16 v[98:101], v[186:189], v[202:205], v[98:101]
	v_mfma_f32_16x16x32_bf16 v[86:89], v[178:181], v[210:213], v[86:89]
	v_mfma_f32_16x16x32_bf16 v[82:85], v[186:189], v[210:213], v[82:85]
	v_mfma_f32_16x16x32_bf16 v[70:73], v[178:181], v[218:221], v[70:73]
	v_mfma_f32_16x16x32_bf16 v[66:69], v[186:189], v[218:221], v[66:69]
	s_setprio 0
	s_barrier

; #define PG8_STAGE(bufoff, gbase, voff) do { _Pragma("unroll") for (int _i = 0; _i < 2; ++_i) \
;         __builtin_amdgcn_global_load_lds((const unsigned*)((const char*)(gbase) + (voff)[_i]), (PG8_LAS unsigned*)(lds + (bufoff) + ldsw + _i * 8192), 16, 0, 0); } while (0)
; #define PG8_LDA(dst, b, h) do { _Pragma("unroll") for (int m = 0; m < 4; ++m) _Pragma("unroll") for (int k = 0; k < 2; ++k) dst[m][k] = *(const PG8_LAS bf16x8*)(lds + PG8_SA(b, h) + aoff + m * 2048 + k * 1024); } while (0)
; #define PG8_MMA(ai, bj, At, Bt) do { __builtin_amdgcn_s_setprio(1); _Pragma("unroll") for (int m = 0; m < 4; ++m) _Pragma("unroll") for (int n = 0; n < 2; ++n) _Pragma("unroll") for (int k = 0; k < 2; ++k) \
;         acc[ai][bj][m][n] = __builtin_amdgcn_mfma_f32_16x16x32_bf16(Bt[n][k], At[m][k], acc[ai][bj][m][n], 0, 0, 0); __builtin_amdgcn_s_setprio(0); } while (0)
; #define PG8_WAIT_V(n) asm volatile("s_waitcnt vmcnt(" #n ")" ::: "memory")
; #define PG8_WAIT_L(n) asm volatile("s_waitcnt lgkmcnt(" #n ")" ::: "memory")
; #define PG8_BAR __builtin_amdgcn_s_barrier()
; #define PG8_SCHED __builtin_amdgcn_sched_barrier(0)
; template <class Epi, class Sched, bool ALIGN_EPI = false, bool SP2 = false>
; __device__ __forceinline__ void gemm_phase(PG8_LAS unsigned char* lds, const Gemm g, const Sched& S, const Epi& E) {
;     ...
;             PG8_LDA(At, 1, 1); PG8_STAGE(PG8_SB(1, 0), b3, voffB); PG8_STAGE(PG8_SB(1, 1), b3 + hstep, voffB); PG8_STAGE(PG8_SA(1, 0), a3, voffA);
;             PG8_WAIT_V(8); PG8_WAIT_L(0); PG8_BAR; PG8_MMA(1, 0, At, B0); PG8_MMA(1, 1, At, B1); PG8_BAR; PG8_SCHED;
	s_add_i32 s42, s72, s54
	v_lshl_add_u64 v[146:147], v[146:147], 0, s[10:11]
	s_mov_b32 m0, s42
	ds_read_b128 v[190:193], v152 offset:49152
	ds_read_b128 v[194:197], v152 offset:50176
	ds_read_b128 v[198:201], v152 offset:51200
	ds_read_b128 v[202:205], v152 offset:52224
	ds_read_b128 v[206:209], v152 offset:53248
	ds_read_b128 v[210:213], v152 offset:54272
	ds_read_b128 v[214:217], v152 offset:55296
	ds_read_b128 v[218:221], v152 offset:56320
	global_load_lds_dwordx4 v[146:147], off
	s_add_i32 m0, s42, 0x2000
	s_add_u32 s40, s40, 0x40080
	v_lshl_add_u64 v[146:147], v[170:171], 0, s[10:11]
	s_addc_u32 s41, s41, 0
	s_add_i32 s42, s73, s54
	global_load_lds_dwordx4 v[146:147], off
	v_lshl_add_u64 v[146:147], s[40:41], 0, v[132:133]
	s_mov_b32 m0, s42
	s_nop 0
	global_load_lds_dwordx4 v[146:147], off
	v_lshl_add_u64 v[146:147], s[40:41], 0, v[136:137]
	s_add_i32 m0, s42, 0x2000
	s_nop 0
	global_load_lds_dwordx4 v[146:147], off
	v_lshl_add_u64 v[146:147], v[222:223], 0, s[10:11]
	s_mov_b32 m0, s60
	s_nop 0
	global_load_lds_dwordx4 v[146:147], off
	v_lshl_add_u64 v[146:147], v[224:225], 0, s[10:11]
	s_mov_b32 m0, s61
	s_nop 0
	global_load_lds_dwordx4 v[146:147], off
	s_waitcnt vmcnt(8)
	s_waitcnt lgkmcnt(0)
	s_barrier
	s_setprio 1
	s_waitcnt lgkmcnt(0)
	v_mfma_f32_16x16x32_bf16 v[62:65], v[154:157], v[190:193], v[62:65]
	v_mfma_f32_16x16x32_bf16 v[58:61], v[162:165], v[190:193], v[58:61]
	v_mfma_f32_16x16x32_bf16 v[46:49], v[154:157], v[198:201], v[46:49]
	v_mfma_f32_16x16x32_bf16 v[42:45], v[162:165], v[198:201], v[42:45]
	v_mfma_f32_16x16x32_bf16 v[30:33], v[154:157], v[206:209], v[30:33]
	v_mfma_f32_16x16x32_bf16 v[26:29], v[162:165], v[206:209], v[26:29]
	v_mfma_f32_16x16x32_bf16 v[14:17], v[154:157], v[214:217], v[14:17]
	v_mfma_f32_16x16x32_bf16 v[10:13], v[162:165], v[214:217], v[10:13]
	v_mfma_f32_16x16x32_bf16 v[62:65], v[158:161], v[194:197], v[62:65]
	v_mfma_f32_16x16x32_bf16 v[58:61], v[166:169], v[194:197], v[58:61]
	v_mfma_f32_16x16x32_bf16 v[46:49], v[158:161], v[202:205], v[46:49]
	v_mfma_f32_16x16x32_bf16 v[42:45], v[166:169], v[202:205], v[42:45]
	v_mfma_f32_16x16x32_bf16 v[30:33], v[158:161], v[210:213], v[30:33]
	v_mfma_f32_16x16x32_bf16 v[26:29], v[166:169], v[210:213], v[26:29]
	v_mfma_f32_16x16x32_bf16 v[14:17], v[158:161], v[218:221], v[14:17]
	v_mfma_f32_16x16x32_bf16 v[10:13], v[166:169], v[218:221], v[10:13]
	v_mfma_f32_16x16x32_bf16 v[54:57], v[174:177], v[190:193], v[54:57]
	v_mfma_f32_16x16x32_bf16 v[50:53], v[182:185], v[190:193], v[50:53]
	v_mfma_f32_16x16x32_bf16 v[38:41], v[174:177], v[198:201], v[38:41]
	v_mfma_f32_16x16x32_bf16 v[34:37], v[182:185], v[198:201], v[34:37]
	v_mfma_f32_16x16x32_bf16 v[22:25], v[174:177], v[206:209], v[22:25]
	v_mfma_f32_16x16x32_bf16 v[18:21], v[182:185], v[206:209], v[18:21]
	v_mfma_f32_16x16x32_bf16 v[6:9], v[174:177], v[214:217], v[6:9]
	v_mfma_f32_16x16x32_bf16 v[2:5], v[182:185], v[214:217], v[2:5]
	v_mfma_f32_16x16x32_bf16 v[54:57], v[178:181], v[194:197], v[54:57]
	v_mfma_f32_16x16x32_bf16 v[50:53], v[186:189], v[194:197], v[50:53]
	v_mfma_f32_16x16x32_bf16 v[38:41], v[178:181], v[202:205], v[38:41]
	v_mfma_f32_16x16x32_bf16 v[34:37], v[186:189], v[202:205], v[34:37]
	v_mfma_f32_16x16x32_bf16 v[22:25], v[178:181], v[210:213], v[22:25]
	v_mfma_f32_16x16x32_bf16 v[18:21], v[186:189], v[210:213], v[18:21]
	v_mfma_f32_16x16x32_bf16 v[6:9], v[178:181], v[218:221], v[6:9]
	v_mfma_f32_16x16x32_bf16 v[2:5], v[186:189], v[218:221], v[2:5]
	s_setprio 0
	s_barrier

; #define PG8_STAGE(bufoff, gbase, voff) do { _Pragma("unroll") for (int _i = 0; _i < 2; ++_i) \
;         __builtin_amdgcn_global_load_lds((const unsigned*)((const char*)(gbase) + (voff)[_i]), (PG8_LAS unsigned*)(lds + (bufoff) + ldsw + _i * 8192), 16, 0, 0); } while (0)
; #define PG8_LDA(dst, b, h) do { _Pragma("unroll") for (int m = 0; m < 4; ++m) _Pragma("unroll") for (int k = 0; k < 2; ++k) dst[m][k] = *(const PG8_LAS bf16x8*)(lds + PG8_SA(b, h) + aoff + m * 2048 + k * 1024); } while (0)
; #define PG8_LDB(dst, b, h) do { _Pragma("unroll") for (int n = 0; n < 2; ++n) _Pragma("unroll") for (int k = 0; k < 2; ++k) dst[n][k] = *(const PG8_LAS bf16x8*)(lds + PG8_SB(b, h) + boff + n * 2048 + k * 1024); } while (0)
; #define PG8_MMA(ai, bj, At, Bt) do { __builtin_amdgcn_s_setprio(1); _Pragma("unroll") for (int m = 0; m < 4; ++m) _Pragma("unroll") for (int n = 0; n < 2; ++n) _Pragma("unroll") for (int k = 0; k < 2; ++k) \
;         acc[ai][bj][m][n] = __builtin_amdgcn_mfma_f32_16x16x32_bf16(Bt[n][k], At[m][k], acc[ai][bj][m][n], 0, 0, 0); __builtin_amdgcn_s_setprio(0); } while (0)
; #define PG8_WAIT_V(n) asm volatile("s_waitcnt vmcnt(" #n ")" ::: "memory")
; #define PG8_WAIT_L(n) asm volatile("s_waitcnt lgkmcnt(" #n ")" ::: "memory")
; #define PG8_BAR __builtin_amdgcn_s_barrier()
; #define PG8_SCHED __builtin_amdgcn_sched_barrier(0)
; template <class Epi, class Sched, bool ALIGN_EPI = false, bool SP2 = false>
; __device__ __forceinline__ void gemm_phase(PG8_LAS unsigned char* lds, const Gemm g, const Sched& S, const Epi& E) {
;     ...
;             const bool last = (t == nt - 2);
;             const char* a1 = cA + (size_t)(t + 1) * kstep;
;             const char* a2 = last ? nA : cA + (size_t)(t + 2) * kstep; const char* b2 = last ? nB : cB + (size_t)(t + 2) * kstep;
;             const char* a3 = a2 + kstep; const char* b3 = b2 + kstep;
;             if (last && has_next) S.a_ready(nxt);
;             if constexpr (SP2) {
;             PG8_LDB(B0, 0, 0); PG8_LDB(B1, 0, 1); PG8_SCHED; PG8_LDA(At, 0, 0); PG8_STAGE(PG8_SA(1, 1), a1 + hstep, voffA);
;             PG8_WAIT_V(8); PG8_WAIT_L(0); PG8_BAR; PG8_MMA(0, 0, At, B0); PG8_MMA(0, 1, At, B1); PG8_BAR; PG8_SCHED;
;             PG8_LDA(At, 0, 1); PG8_STAGE(PG8_SB(0, 0), b2, voffB); PG8_STAGE(PG8_SB(0, 1), b2 + hstep, voffB); PG8_STAGE(PG8_SA(0, 0), a2, voffA);
	s_add_i32 s71, s71, 2
	s_add_u32 s38, s38, 0x100
	s_addc_u32 s39, s39, 0
	s_add_u32 s69, s69, 0x100
	s_addc_u32 s70, s70, 0
.LBB0_1221:
	ds_read_b128 v[154:157], v150
	ds_read_b128 v[158:161], v150 offset:1024
	ds_read_b128 v[162:165], v150 offset:2048
	ds_read_b128 v[166:169], v150 offset:3072
	ds_read_b128 v[174:177], v151
	ds_read_b128 v[178:181], v151 offset:1024
	ds_read_b128 v[182:185], v151 offset:2048
	ds_read_b128 v[186:189], v151 offset:3072
	s_add_u32 s40, s38, 0xfffc0080
	s_addc_u32 s41, s39, -1
	s_cmp_eq_u32 s71, 12
	s_cselect_b32 s43, s29, s41
	s_cselect_b32 s42, s67, s40
	s_cselect_b32 s41, s27, s70
	s_cselect_b32 s40, s68, s69
	v_lshl_add_u64 v[146:147], s[38:39], 0, v[138:139]
	s_add_i32 m0, s55, 0xc000
	ds_read_b128 v[190:193], v152
	ds_read_b128 v[194:197], v152 offset:1024
	ds_read_b128 v[198:201], v152 offset:2048
	ds_read_b128 v[202:205], v152 offset:3072
	ds_read_b128 v[206:209], v152 offset:4096
	ds_read_b128 v[210:213], v152 offset:5120
	ds_read_b128 v[214:217], v152 offset:6144
	ds_read_b128 v[218:221], v152 offset:7168
	global_load_lds_dwordx4 v[146:147], off
	v_lshl_add_u64 v[146:147], s[38:39], 0, v[140:141]
	s_add_i32 m0, s55, 0xe000
	s_nop 0
	global_load_lds_dwordx4 v[146:147], off
	s_waitcnt vmcnt(8)
	s_waitcnt lgkmcnt(0)
	s_barrier
	s_setprio 1
	s_waitcnt lgkmcnt(0)
	v_mfma_f32_16x16x32_bf16 v[126:129], v[154:157], v[190:193], v[126:129]
	v_mfma_f32_16x16x32_bf16 v[122:125], v[162:165], v[190:193], v[122:125]
	v_mfma_f32_16x16x32_bf16 v[110:113], v[154:157], v[198:201], v[110:113]
	v_mfma_f32_16x16x32_bf16 v[106:109], v[162:165], v[198:201], v[106:109]
	v_mfma_f32_16x16x32_bf16 v[94:97], v[154:157], v[206:209], v[94:97]
	v_mfma_f32_16x16x32_bf16 v[90:93], v[162:165], v[206:209], v[90:93]
	v_mfma_f32_16x16x32_bf16 v[78:81], v[154:157], v[214:217], v[78:81]
	v_mfma_f32_16x16x32_bf16 v[74:77], v[162:165], v[214:217], v[74:77]
	v_mfma_f32_16x16x32_bf16 v[126:129], v[158:161], v[194:197], v[126:129]
	v_mfma_f32_16x16x32_bf16 v[122:125], v[166:169], v[194:197], v[122:125]
	v_mfma_f32_16x16x32_bf16 v[110:113], v[158:161], v[202:205], v[110:113]
	v_mfma_f32_16x16x32_bf16 v[106:109], v[166:169], v[202:205], v[106:109]
	v_mfma_f32_16x16x32_bf16 v[94:97], v[158:161], v[210:213], v[94:97]
	v_mfma_f32_16x16x32_bf16 v[90:93], v[166:169], v[210:213], v[90:93]
	v_mfma_f32_16x16x32_bf16 v[78:81], v[158:161], v[218:221], v[78:81]
	v_mfma_f32_16x16x32_bf16 v[74:77], v[166:169], v[218:221], v[74:77]
	v_mfma_f32_16x16x32_bf16 v[118:121], v[174:177], v[190:193], v[118:121]
	v_mfma_f32_16x16x32_bf16 v[114:117], v[182:185], v[190:193], v[114:117]
	v_mfma_f32_16x16x32_bf16 v[102:105], v[174:177], v[198:201], v[102:105]
	v_mfma_f32_16x16x32_bf16 v[98:101], v[182:185], v[198:201], v[98:101]
	v_mfma_f32_16x16x32_bf16 v[86:89], v[174:177], v[206:209], v[86:89]
	v_mfma_f32_16x16x32_bf16 v[82:85], v[182:185], v[206:209], v[82:85]
	v_mfma_f32_16x16x32_bf16 v[70:73], v[174:177], v[214:217], v[70:73]
	v_mfma_f32_16x16x32_bf16 v[66:69], v[182:185], v[214:217], v[66:69]
	v_mfma_f32_16x16x32_bf16 v[118:121], v[178:181], v[194:197], v[118:121]
	v_mfma_f32_16x16x32_bf16 v[114:117], v[186:189], v[194:197], v[114:117]
	v_mfma_f32_16x16x32_bf16 v[102:105], v[178:181], v[202:205], v[102:105]
	v_mfma_f32_16x16x32_bf16 v[98:101], v[186:189], v[202:205], v[98:101]
	v_mfma_f32_16x16x32_bf16 v[86:89], v[178:181], v[210:213], v[86:89]
	v_mfma_f32_16x16x32_bf16 v[82:85], v[186:189], v[210:213], v[82:85]
	v_mfma_f32_16x16x32_bf16 v[70:73], v[178:181], v[218:221], v[70:73]
	v_mfma_f32_16x16x32_bf16 v[66:69], v[186:189], v[218:221], v[66:69]
	s_setprio 0
	s_barrier
	s_add_i32 s72, s64, s54
	v_lshl_add_u64 v[146:147], s[40:41], 0, v[132:133]
	s_mov_b32 m0, s72
	ds_read_b128 v[190:193], v152 offset:16384
	ds_read_b128 v[194:197], v152 offset:17408
	ds_read_b128 v[198:201], v152 offset:18432
	ds_read_b128 v[202:205], v152 offset:19456
	ds_read_b128 v[206:209], v152 offset:20480
	ds_read_b128 v[210:213], v152 offset:21504
	ds_read_b128 v[214:217], v152 offset:22528
	ds_read_b128 v[218:221], v152 offset:23552
	global_load_lds_dwordx4 v[146:147], off
	s_add_i32 m0, s72, 0x2000
	s_add_u32 s72, s40, 0x40000
	v_lshl_add_u64 v[170:171], s[40:41], 0, v[136:137]
	s_addc_u32 s73, s41, 0
	s_add_i32 s74, s65, s54
	global_load_lds_dwordx4 v[170:171], off
	v_lshl_add_u64 v[222:223], s[72:73], 0, v[132:133]
	s_mov_b32 m0, s74
	v_lshl_add_u64 v[224:225], s[42:43], 0, v[134:135]
	global_load_lds_dwordx4 v[222:223], off
	v_lshl_add_u64 v[222:223], s[72:73], 0, v[136:137]
	s_add_i32 m0, s74, 0x2000
	s_nop 0
	global_load_lds_dwordx4 v[222:223], off
	v_lshl_add_u64 v[222:223], s[42:43], 0, v[130:131]
	s_mov_b32 m0, s55
	s_nop 0
	global_load_lds_dwordx4 v[222:223], off
	s_mov_b32 m0, s56
	s_nop 0
	global_load_lds_dwordx4 v[224:225], off
	s_waitcnt vmcnt(8)
	s_waitcnt lgkmcnt(0)
	s_barrier
; #define PG8_STAGE(bufoff, gbase, voff) do { _Pragma("unroll") for (int _i = 0; _i < 2; ++_i) \
;         __builtin_amdgcn_global_load_lds((const unsigned*)((const char*)(gbase) + (voff)[_i]), (PG8_LAS unsigned*)(lds + (bufoff) + ldsw + _i * 8192), 16, 0, 0); } while (0)
; #define PG8_LDA(dst, b, h) do { _Pragma("unroll") for (int m = 0; m < 4; ++m) _Pragma("unroll") for (int k = 0; k < 2; ++k) dst[m][k] = *(const PG8_LAS bf16x8*)(lds + PG8_SA(b, h) + aoff + m * 2048 + k * 1024); } while (0)
; #define PG8_LDB(dst, b, h) do { _Pragma("unroll") for (int n = 0; n < 2; ++n) _Pragma("unroll") for (int k = 0; k < 2; ++k) dst[n][k] = *(const PG8_LAS bf16x8*)(lds + PG8_SB(b, h) + boff + n * 2048 + k * 1024); } while (0)
; #define PG8_MMA(ai, bj, At, Bt) do { __builtin_amdgcn_s_setprio(1); _Pragma("unroll") for (int m = 0; m < 4; ++m) _Pragma("unroll") for (int n = 0; n < 2; ++n) _Pragma("unroll") for (int k = 0; k < 2; ++k) \
;         acc[ai][bj][m][n] = __builtin_amdgcn_mfma_f32_16x16x32_bf16(Bt[n][k], At[m][k], acc[ai][bj][m][n], 0, 0, 0); __builtin_amdgcn_s_setprio(0); } while (0)
; #define PG8_WAIT_V(n) asm volatile("s_waitcnt vmcnt(" #n ")" ::: "memory")
; #define PG8_WAIT_L(n) asm volatile("s_waitcnt lgkmcnt(" #n ")" ::: "memory")
; #define PG8_BAR __builtin_amdgcn_s_barrier()
; #define PG8_SCHED __builtin_amdgcn_sched_barrier(0)
; template <class Epi, class Sched, bool ALIGN_EPI = false, bool SP2 = false>
; __device__ __forceinline__ void gemm_phase(PG8_LAS unsigned char* lds, const Gemm g, const Sched& S, const Epi& E) {
;     ...
;             PG8_WAIT_V(8); PG8_WAIT_L(0); PG8_BAR; PG8_MMA(1, 0, At, B0); PG8_MMA(1, 1, At, B1); PG8_BAR; PG8_SCHED;
;             PG8_LDB(B0, 1, 0); PG8_LDB(B1, 1, 1); PG8_SCHED; PG8_LDA(At, 1, 0); PG8_STAGE(PG8_SA(0, 1), a2 + hstep, voffA);
;             PG8_WAIT_V(8); PG8_WAIT_L(0); PG8_BAR; PG8_MMA(0, 0, At, B0); PG8_MMA(0, 1, At, B1); PG8_BAR; PG8_SCHED;
	s_setprio 1
	s_waitcnt lgkmcnt(0)
	v_mfma_f32_16x16x32_bf16 v[62:65], v[154:157], v[190:193], v[62:65]
	v_mfma_f32_16x16x32_bf16 v[58:61], v[162:165], v[190:193], v[58:61]
	v_mfma_f32_16x16x32_bf16 v[46:49], v[154:157], v[198:201], v[46:49]
	v_mfma_f32_16x16x32_bf16 v[42:45], v[162:165], v[198:201], v[42:45]
	v_mfma_f32_16x16x32_bf16 v[30:33], v[154:157], v[206:209], v[30:33]
	v_mfma_f32_16x16x32_bf16 v[26:29], v[162:165], v[206:209], v[26:29]
	v_mfma_f32_16x16x32_bf16 v[14:17], v[154:157], v[214:217], v[14:17]
	v_mfma_f32_16x16x32_bf16 v[10:13], v[162:165], v[214:217], v[10:13]
	v_mfma_f32_16x16x32_bf16 v[62:65], v[158:161], v[194:197], v[62:65]
	v_mfma_f32_16x16x32_bf16 v[58:61], v[166:169], v[194:197], v[58:61]
	v_mfma_f32_16x16x32_bf16 v[46:49], v[158:161], v[202:205], v[46:49]
	v_mfma_f32_16x16x32_bf16 v[42:45], v[166:169], v[202:205], v[42:45]
	v_mfma_f32_16x16x32_bf16 v[30:33], v[158:161], v[210:213], v[30:33]
	v_mfma_f32_16x16x32_bf16 v[26:29], v[166:169], v[210:213], v[26:29]
	v_mfma_f32_16x16x32_bf16 v[14:17], v[158:161], v[218:221], v[14:17]
	v_mfma_f32_16x16x32_bf16 v[10:13], v[166:169], v[218:221], v[10:13]
	v_mfma_f32_16x16x32_bf16 v[54:57], v[174:177], v[190:193], v[54:57]
	v_mfma_f32_16x16x32_bf16 v[50:53], v[182:185], v[190:193], v[50:53]
	v_mfma_f32_16x16x32_bf16 v[38:41], v[174:177], v[198:201], v[38:41]
	v_mfma_f32_16x16x32_bf16 v[34:37], v[182:185], v[198:201], v[34:37]
	v_mfma_f32_16x16x32_bf16 v[22:25], v[174:177], v[206:209], v[22:25]
	v_mfma_f32_16x16x32_bf16 v[18:21], v[182:185], v[206:209], v[18:21]
	v_mfma_f32_16x16x32_bf16 v[6:9], v[174:177], v[214:217], v[6:9]
	v_mfma_f32_16x16x32_bf16 v[2:5], v[182:185], v[214:217], v[2:5]
	v_mfma_f32_16x16x32_bf16 v[54:57], v[178:181], v[194:197], v[54:57]
	v_mfma_f32_16x16x32_bf16 v[50:53], v[186:189], v[194:197], v[50:53]
	v_mfma_f32_16x16x32_bf16 v[38:41], v[178:181], v[202:205], v[38:41]
	v_mfma_f32_16x16x32_bf16 v[34:37], v[186:189], v[202:205], v[34:37]
	v_mfma_f32_16x16x32_bf16 v[22:25], v[178:181], v[210:213], v[22:25]
	v_mfma_f32_16x16x32_bf16 v[18:21], v[186:189], v[210:213], v[18:21]
	v_mfma_f32_16x16x32_bf16 v[6:9], v[178:181], v[218:221], v[6:9]
	v_mfma_f32_16x16x32_bf16 v[2:5], v[186:189], v[218:221], v[2:5]
	s_setprio 0
	s_barrier
	s_add_i32 s72, 0, 0x18000
	v_add_u32_e32 v153, s72, v148
	s_add_i32 s73, 0, 0x1c000
	ds_read_b128 v[154:157], v153
	ds_read_b128 v[158:161], v153 offset:1024
	ds_read_b128 v[162:165], v153 offset:2048
	ds_read_b128 v[166:169], v153 offset:3072
	v_add_u32_e32 v153, s73, v148
	ds_read_b128 v[174:177], v153
	ds_read_b128 v[178:181], v153 offset:1024
	ds_read_b128 v[182:185], v153 offset:2048
	ds_read_b128 v[186:189], v153 offset:3072
	s_add_u32 s42, s42, 0x40000
	s_addc_u32 s43, s43, 0
	s_mov_b32 m0, s57
	v_lshl_add_u64 v[226:227], s[42:43], 0, v[130:131]
	ds_read_b128 v[190:193], v152 offset:32768
	ds_read_b128 v[194:197], v152 offset:33792
	ds_read_b128 v[198:201], v152 offset:34816
	ds_read_b128 v[202:205], v152 offset:35840
	ds_read_b128 v[206:209], v152 offset:36864
	ds_read_b128 v[210:213], v152 offset:37888
	ds_read_b128 v[214:217], v152 offset:38912
	ds_read_b128 v[218:221], v152 offset:39936
	global_load_lds_dwordx4 v[226:227], off
	v_lshl_add_u64 v[226:227], s[42:43], 0, v[134:135]
	s_mov_b32 m0, s58
	s_nop 0
	global_load_lds_dwordx4 v[226:227], off
	s_waitcnt vmcnt(8)
	s_waitcnt lgkmcnt(0)
	s_barrier
	s_setprio 1
	s_waitcnt lgkmcnt(0)
	v_mfma_f32_16x16x32_bf16 v[126:129], v[154:157], v[190:193], v[126:129]
	v_mfma_f32_16x16x32_bf16 v[122:125], v[162:165], v[190:193], v[122:125]
	v_mfma_f32_16x16x32_bf16 v[110:113], v[154:157], v[198:201], v[110:113]
	v_mfma_f32_16x16x32_bf16 v[106:109], v[162:165], v[198:201], v[106:109]
	v_mfma_f32_16x16x32_bf16 v[94:97], v[154:157], v[206:209], v[94:97]
	v_mfma_f32_16x16x32_bf16 v[90:93], v[162:165], v[206:209], v[90:93]
	v_mfma_f32_16x16x32_bf16 v[78:81], v[154:157], v[214:217], v[78:81]
	v_mfma_f32_16x16x32_bf16 v[74:77], v[162:165], v[214:217], v[74:77]
	v_mfma_f32_16x16x32_bf16 v[126:129], v[158:161], v[194:197], v[126:129]
	v_mfma_f32_16x16x32_bf16 v[122:125], v[166:169], v[194:197], v[122:125]
	v_mfma_f32_16x16x32_bf16 v[110:113], v[158:161], v[202:205], v[110:113]
	v_mfma_f32_16x16x32_bf16 v[106:109], v[166:169], v[202:205], v[106:109]
	v_mfma_f32_16x16x32_bf16 v[94:97], v[158:161], v[210:213], v[94:97]
	v_mfma_f32_16x16x32_bf16 v[90:93], v[166:169], v[210:213], v[90:93]
	v_mfma_f32_16x16x32_bf16 v[78:81], v[158:161], v[218:221], v[78:81]
	v_mfma_f32_16x16x32_bf16 v[74:77], v[166:169], v[218:221], v[74:77]
	v_mfma_f32_16x16x32_bf16 v[118:121], v[174:177], v[190:193], v[118:121]
	v_mfma_f32_16x16x32_bf16 v[114:117], v[182:185], v[190:193], v[114:117]
	v_mfma_f32_16x16x32_bf16 v[102:105], v[174:177], v[198:201], v[102:105]
	v_mfma_f32_16x16x32_bf16 v[98:101], v[182:185], v[198:201], v[98:101]
	v_mfma_f32_16x16x32_bf16 v[86:89], v[174:177], v[206:209], v[86:89]
	v_mfma_f32_16x16x32_bf16 v[82:85], v[182:185], v[206:209], v[82:85]
	v_mfma_f32_16x16x32_bf16 v[70:73], v[174:177], v[214:217], v[70:73]
	v_mfma_f32_16x16x32_bf16 v[66:69], v[182:185], v[214:217], v[66:69]
	v_mfma_f32_16x16x32_bf16 v[118:121], v[178:181], v[194:197], v[118:121]
	v_mfma_f32_16x16x32_bf16 v[114:117], v[186:189], v[194:197], v[114:117]
	v_mfma_f32_16x16x32_bf16 v[102:105], v[178:181], v[202:205], v[102:105]
	v_mfma_f32_16x16x32_bf16 v[98:101], v[186:189], v[202:205], v[98:101]
	v_mfma_f32_16x16x32_bf16 v[86:89], v[178:181], v[210:213], v[86:89]
	v_mfma_f32_16x16x32_bf16 v[82:85], v[186:189], v[210:213], v[82:85]
	v_mfma_f32_16x16x32_bf16 v[70:73], v[178:181], v[218:221], v[70:73]
	v_mfma_f32_16x16x32_bf16 v[66:69], v[186:189], v[218:221], v[66:69]
	s_setprio 0
	s_barrier
; #define PG8_STAGE(bufoff, gbase, voff) do { _Pragma("unroll") for (int _i = 0; _i < 2; ++_i) \
;         __builtin_amdgcn_global_load_lds((const unsigned*)((const char*)(gbase) + (voff)[_i]), (PG8_LAS unsigned*)(lds + (bufoff) + ldsw + _i * 8192), 16, 0, 0); } while (0)
; #define PG8_LDA(dst, b, h) do { _Pragma("unroll") for (int m = 0; m < 4; ++m) _Pragma("unroll") for (int k = 0; k < 2; ++k) dst[m][k] = *(const PG8_LAS bf16x8*)(lds + PG8_SA(b, h) + aoff + m * 2048 + k * 1024); } while (0)
; #define PG8_MMA(ai, bj, At, Bt) do { __builtin_amdgcn_s_setprio(1); _Pragma("unroll") for (int m = 0; m < 4; ++m) _Pragma("unroll") for (int n = 0; n < 2; ++n) _Pragma("unroll") for (int k = 0; k < 2; ++k) \
;         acc[ai][bj][m][n] = __builtin_amdgcn_mfma_f32_16x16x32_bf16(Bt[n][k], At[m][k], acc[ai][bj][m][n], 0, 0, 0); __builtin_amdgcn_s_setprio(0); } while (0)
; #define PG8_WAIT_V(n) asm volatile("s_waitcnt vmcnt(" #n ")" ::: "memory")
; #define PG8_WAIT_L(n) asm volatile("s_waitcnt lgkmcnt(" #n ")" ::: "memory")
; #define PG8_BAR __builtin_amdgcn_s_barrier()
; #define PG8_SCHED __builtin_amdgcn_sched_barrier(0)
; template <class Epi, class Sched, bool ALIGN_EPI = false, bool SP2 = false>
; __device__ __forceinline__ void gemm_phase(PG8_LAS unsigned char* lds, const Gemm g, const Sched& S, const Epi& E) {
;     ...
;             PG8_LDA(At, 1, 1); PG8_STAGE(PG8_SB(1, 0), b3, voffB); PG8_STAGE(PG8_SB(1, 1), b3 + hstep, voffB); PG8_STAGE(PG8_SA(1, 0), a3, voffA);
;             PG8_WAIT_V(8); PG8_WAIT_L(0); PG8_BAR; PG8_MMA(1, 0, At, B0); PG8_MMA(1, 1, At, B1); PG8_BAR; PG8_SCHED;
;     ...
;         if constexpr (ALIGN_EPI) { if (wr == 0) PG8_BAR; }
	s_add_i32 s42, s72, s54
	v_lshl_add_u64 v[146:147], v[146:147], 0, s[10:11]
	s_mov_b32 m0, s42
	ds_read_b128 v[190:193], v152 offset:49152
	ds_read_b128 v[194:197], v152 offset:50176
	ds_read_b128 v[198:201], v152 offset:51200
	ds_read_b128 v[202:205], v152 offset:52224
	ds_read_b128 v[206:209], v152 offset:53248
	ds_read_b128 v[210:213], v152 offset:54272
	ds_read_b128 v[214:217], v152 offset:55296
	ds_read_b128 v[218:221], v152 offset:56320
	global_load_lds_dwordx4 v[146:147], off
	s_add_i32 m0, s42, 0x2000
	s_add_u32 s40, s40, 0x40080
	v_lshl_add_u64 v[146:147], v[170:171], 0, s[10:11]
	s_addc_u32 s41, s41, 0
	s_add_i32 s42, s73, s54
	global_load_lds_dwordx4 v[146:147], off
	v_lshl_add_u64 v[146:147], s[40:41], 0, v[132:133]
	s_mov_b32 m0, s42
	s_nop 0
	global_load_lds_dwordx4 v[146:147], off
	v_lshl_add_u64 v[146:147], s[40:41], 0, v[136:137]
	s_add_i32 m0, s42, 0x2000
	s_nop 0
	global_load_lds_dwordx4 v[146:147], off
	v_lshl_add_u64 v[146:147], v[222:223], 0, s[10:11]
	s_mov_b32 m0, s60
	s_nop 0
	global_load_lds_dwordx4 v[146:147], off
	v_lshl_add_u64 v[146:147], v[224:225], 0, s[10:11]
	s_mov_b32 m0, s61
	s_nop 0
	global_load_lds_dwordx4 v[146:147], off
	s_waitcnt vmcnt(8)
	s_waitcnt lgkmcnt(0)
	s_barrier
	s_setprio 1
	s_waitcnt lgkmcnt(0)
	v_mfma_f32_16x16x32_bf16 v[62:65], v[154:157], v[190:193], v[62:65]
	v_mfma_f32_16x16x32_bf16 v[58:61], v[162:165], v[190:193], v[58:61]
	v_mfma_f32_16x16x32_bf16 v[46:49], v[154:157], v[198:201], v[46:49]
	v_mfma_f32_16x16x32_bf16 v[42:45], v[162:165], v[198:201], v[42:45]
	v_mfma_f32_16x16x32_bf16 v[30:33], v[154:157], v[206:209], v[30:33]
	v_mfma_f32_16x16x32_bf16 v[26:29], v[162:165], v[206:209], v[26:29]
	v_mfma_f32_16x16x32_bf16 v[14:17], v[154:157], v[214:217], v[14:17]
	v_mfma_f32_16x16x32_bf16 v[10:13], v[162:165], v[214:217], v[10:13]
	v_mfma_f32_16x16x32_bf16 v[62:65], v[158:161], v[194:197], v[62:65]
	v_mfma_f32_16x16x32_bf16 v[58:61], v[166:169], v[194:197], v[58:61]
	v_mfma_f32_16x16x32_bf16 v[46:49], v[158:161], v[202:205], v[46:49]
	v_mfma_f32_16x16x32_bf16 v[42:45], v[166:169], v[202:205], v[42:45]
	v_mfma_f32_16x16x32_bf16 v[30:33], v[158:161], v[210:213], v[30:33]
	v_mfma_f32_16x16x32_bf16 v[26:29], v[166:169], v[210:213], v[26:29]
	v_mfma_f32_16x16x32_bf16 v[14:17], v[158:161], v[218:221], v[14:17]
	v_mfma_f32_16x16x32_bf16 v[10:13], v[166:169], v[218:221], v[10:13]
	v_mfma_f32_16x16x32_bf16 v[54:57], v[174:177], v[190:193], v[54:57]
	v_mfma_f32_16x16x32_bf16 v[50:53], v[182:185], v[190:193], v[50:53]
	v_mfma_f32_16x16x32_bf16 v[38:41], v[174:177], v[198:201], v[38:41]
	v_mfma_f32_16x16x32_bf16 v[34:37], v[182:185], v[198:201], v[34:37]
	v_mfma_f32_16x16x32_bf16 v[22:25], v[174:177], v[206:209], v[22:25]
	v_mfma_f32_16x16x32_bf16 v[18:21], v[182:185], v[206:209], v[18:21]
	v_mfma_f32_16x16x32_bf16 v[6:9], v[174:177], v[214:217], v[6:9]
	v_mfma_f32_16x16x32_bf16 v[2:5], v[182:185], v[214:217], v[2:5]
	v_mfma_f32_16x16x32_bf16 v[54:57], v[178:181], v[194:197], v[54:57]
	v_mfma_f32_16x16x32_bf16 v[50:53], v[186:189], v[194:197], v[50:53]
	v_mfma_f32_16x16x32_bf16 v[38:41], v[178:181], v[202:205], v[38:41]
	v_mfma_f32_16x16x32_bf16 v[34:37], v[186:189], v[202:205], v[34:37]
	v_mfma_f32_16x16x32_bf16 v[22:25], v[178:181], v[210:213], v[22:25]
	v_mfma_f32_16x16x32_bf16 v[18:21], v[186:189], v[210:213], v[18:21]
	v_mfma_f32_16x16x32_bf16 v[6:9], v[178:181], v[218:221], v[6:9]
	v_mfma_f32_16x16x32_bf16 v[2:5], v[186:189], v[218:221], v[2:5]
	s_setprio 0
	s_barrier
	s_add_i32 s71, s71, 2
	s_add_u32 s38, s38, 0x100
	s_addc_u32 s39, s39, 0
	s_add_u32 s69, s69, 0x100
	s_addc_u32 s70, s70, 0
	s_cmp_gt_u32 s71, 13
	s_cbranch_scc0 .LBB0_1221
	s_and_b64 vcc, exec, s[12:13]
	s_cbranch_vccz .LBB0_1224
	s_barrier

; #define PG8_STAGE(bufoff, gbase, voff) do { _Pragma("unroll") for (int _i = 0; _i < 2; ++_i) \
;         __builtin_amdgcn_global_load_lds((const unsigned*)((const char*)(gbase) + (voff)[_i]), (PG8_LAS unsigned*)(lds + (bufoff) + ldsw + _i * 8192), 16, 0, 0); } while (0)
; #define PG8_LDA(dst, b, h) do { _Pragma("unroll") for (int m = 0; m < 4; ++m) _Pragma("unroll") for (int k = 0; k < 2; ++k) dst[m][k] = *(const PG8_LAS bf16x8*)(lds + PG8_SA(b, h) + aoff + m * 2048 + k * 1024); } while (0)
; #define PG8_LDB(dst, b, h) do { _Pragma("unroll") for (int n = 0; n < 2; ++n) _Pragma("unroll") for (int k = 0; k < 2; ++k) dst[n][k] = *(const PG8_LAS bf16x8*)(lds + PG8_SB(b, h) + boff + n * 2048 + k * 1024); } while (0)
; #define PG8_SCHED __builtin_amdgcn_sched_barrier(0)
; template <class Epi, class Sched, bool ALIGN_EPI = false, bool SP2 = false>
; __device__ __forceinline__ void gemm_phase(PG8_LAS unsigned char* lds, const Gemm g, const Sched& S, const Epi& E) {
;     ...
;         const bool has_next = S.next(ui + 1, nxt);
;         const char* nA = has_next ? (const char*)g.A + (size_t)nxt.pm * tstep : cA; const char* nB = has_next ? (const char*)g.Bt + (size_t)nxt.pn * tstep : cB;
; #pragma nounroll
;         for (int t = 0; t < nt; t += 2) {
;             const bool last = (t == nt - 2);
;             const char* a1 = cA + (size_t)(t + 1) * kstep;
;             const char* a2 = last ? nA : cA + (size_t)(t + 2) * kstep; const char* b2 = last ? nB : cB + (size_t)(t + 2) * kstep;
;             const char* a3 = a2 + kstep; const char* b3 = b2 + kstep;
;             if (last && has_next) S.a_ready(nxt);
;             if constexpr (SP2) {
;             PG8_LDB(B0, 0, 0); PG8_LDB(B1, 0, 1); PG8_SCHED; PG8_LDA(At, 0, 0); PG8_STAGE(PG8_SA(1, 1), a1 + hstep, voffA);
.LBB0_1313:
	s_ashr_i32 s21, s20, 31
	s_lshl_b64 s[22:23], s[20:21], 19
	s_add_u32 s22, s38, s22
	s_addc_u32 s23, s39, s23
	s_and_b64 s[24:25], s[2:3], exec
	s_cselect_b32 s21, s23, s29
	s_cselect_b32 s60, s22, s28
	s_ashr_i32 s19, s18, 31
	s_lshl_b64 s[24:25], s[18:19], 19
	s_add_u32 s24, s40, s24
	s_addc_u32 s25, s41, s25
	s_and_b64 s[34:35], s[2:3], exec
	s_cselect_b32 s19, s25, s31
	s_cselect_b32 s61, s24, s30
	s_add_u32 s28, s28, 0x40080
	s_addc_u32 s29, s29, 0
	s_add_u32 s62, s30, 0x100
	s_addc_u32 s63, s31, 0
	s_mov_b32 s64, -2
	ds_read_b128 v[146:149], v154
	ds_read_b128 v[158:161], v154 offset:1024
	ds_read_b128 v[162:165], v154 offset:2048
	ds_read_b128 v[166:169], v154 offset:3072
	ds_read_b128 v[174:177], v155
	ds_read_b128 v[178:181], v155 offset:1024
	ds_read_b128 v[182:185], v155 offset:2048
	ds_read_b128 v[186:189], v155 offset:3072
	s_add_u32 s30, s28, 0xfffc0080
	s_addc_u32 s31, s29, -1
	s_cmp_eq_u32 s64, 12
	s_cselect_b32 s35, s21, s31
	s_cselect_b32 s34, s60, s30
	s_cselect_b32 s31, s19, s63
	s_cselect_b32 s30, s61, s62

; #define PG8_STAGE(bufoff, gbase, voff) do { _Pragma("unroll") for (int _i = 0; _i < 2; ++_i) \
;         __builtin_amdgcn_global_load_lds((const unsigned*)((const char*)(gbase) + (voff)[_i]), (PG8_LAS unsigned*)(lds + (bufoff) + ldsw + _i * 8192), 16, 0, 0); } while (0)
; #define PG8_LDA(dst, b, h) do { _Pragma("unroll") for (int m = 0; m < 4; ++m) _Pragma("unroll") for (int k = 0; k < 2; ++k) dst[m][k] = *(const PG8_LAS bf16x8*)(lds + PG8_SA(b, h) + aoff + m * 2048 + k * 1024); } while (0)
; #define PG8_LDB(dst, b, h) do { _Pragma("unroll") for (int n = 0; n < 2; ++n) _Pragma("unroll") for (int k = 0; k < 2; ++k) dst[n][k] = *(const PG8_LAS bf16x8*)(lds + PG8_SB(b, h) + boff + n * 2048 + k * 1024); } while (0)
; #define PG8_MMA(ai, bj, At, Bt) do { __builtin_amdgcn_s_setprio(1); _Pragma("unroll") for (int m = 0; m < 4; ++m) _Pragma("unroll") for (int n = 0; n < 2; ++n) _Pragma("unroll") for (int k = 0; k < 2; ++k) \
;         acc[ai][bj][m][n] = __builtin_amdgcn_mfma_f32_16x16x32_bf16(Bt[n][k], At[m][k], acc[ai][bj][m][n], 0, 0, 0); __builtin_amdgcn_s_setprio(0); } while (0)
; #define PG8_WAIT_V(n) asm volatile("s_waitcnt vmcnt(" #n ")" ::: "memory")
; #define PG8_WAIT_L(n) asm volatile("s_waitcnt lgkmcnt(" #n ")" ::: "memory")
; #define PG8_BAR __builtin_amdgcn_s_barrier()
; #define PG8_SCHED __builtin_amdgcn_sched_barrier(0)
; template <class Epi, class Sched, bool ALIGN_EPI = false, bool SP2 = false>
; __device__ __forceinline__ void gemm_phase(PG8_LAS unsigned char* lds, const Gemm g, const Sched& S, const Epi& E) {
;     ...
;             PG8_LDB(B0, 0, 0); PG8_LDB(B1, 0, 1); PG8_SCHED; PG8_LDA(At, 0, 0); PG8_STAGE(PG8_SA(1, 1), a1 + hstep, voffA);
;             PG8_WAIT_V(8); PG8_WAIT_L(0); PG8_BAR; PG8_MMA(0, 0, At, B0); PG8_MMA(0, 1, At, B1); PG8_BAR; PG8_SCHED;
;     ...
;                     for (int n = 0; n < 2; ++n) acc[a][b][m][n] = (f32x4){0.f, 0.f, 0.f, 0.f};
	v_lshl_add_u64 v[150:151], s[28:29], 0, v[138:139]
	s_add_i32 m0, s27, 0xc000
	ds_read_b128 v[190:193], v156
	ds_read_b128 v[194:197], v156 offset:1024
	ds_read_b128 v[198:201], v156 offset:2048
	ds_read_b128 v[202:205], v156 offset:3072
	ds_read_b128 v[206:209], v156 offset:4096
	ds_read_b128 v[210:213], v156 offset:5120
	ds_read_b128 v[214:217], v156 offset:6144
	ds_read_b128 v[218:221], v156 offset:7168
	global_load_lds_dwordx4 v[150:151], off
	v_lshl_add_u64 v[150:151], s[28:29], 0, v[140:141]
	s_add_i32 m0, s27, 0xe000
	s_nop 0
	global_load_lds_dwordx4 v[150:151], off
	s_waitcnt vmcnt(40)
	s_waitcnt lgkmcnt(0)
	s_barrier
	s_setprio 1
	s_waitcnt lgkmcnt(0)
	v_mfma_f32_16x16x32_bf16 v[126:129], v[146:149], v[190:193], 0
	v_mfma_f32_16x16x32_bf16 v[122:125], v[162:165], v[190:193], 0
	v_mfma_f32_16x16x32_bf16 v[114:117], v[146:149], v[198:201], 0
	v_mfma_f32_16x16x32_bf16 v[106:109], v[162:165], v[198:201], 0
	v_mfma_f32_16x16x32_bf16 v[98:101], v[146:149], v[206:209], 0
	v_mfma_f32_16x16x32_bf16 v[90:93], v[162:165], v[206:209], 0
	v_mfma_f32_16x16x32_bf16 v[82:85], v[146:149], v[214:217], 0
	v_mfma_f32_16x16x32_bf16 v[74:77], v[162:165], v[214:217], 0
	v_mfma_f32_16x16x32_bf16 v[126:129], v[158:161], v[194:197], v[126:129]
	v_mfma_f32_16x16x32_bf16 v[122:125], v[166:169], v[194:197], v[122:125]
	v_mfma_f32_16x16x32_bf16 v[114:117], v[158:161], v[202:205], v[114:117]
	v_mfma_f32_16x16x32_bf16 v[106:109], v[166:169], v[202:205], v[106:109]
	v_mfma_f32_16x16x32_bf16 v[98:101], v[158:161], v[210:213], v[98:101]
	v_mfma_f32_16x16x32_bf16 v[90:93], v[166:169], v[210:213], v[90:93]
	v_mfma_f32_16x16x32_bf16 v[82:85], v[158:161], v[218:221], v[82:85]
	v_mfma_f32_16x16x32_bf16 v[74:77], v[166:169], v[218:221], v[74:77]
	v_mfma_f32_16x16x32_bf16 v[118:121], v[174:177], v[190:193], 0
	v_mfma_f32_16x16x32_bf16 v[110:113], v[182:185], v[190:193], 0
	v_mfma_f32_16x16x32_bf16 v[102:105], v[174:177], v[198:201], 0
	v_mfma_f32_16x16x32_bf16 v[94:97], v[182:185], v[198:201], 0
	v_mfma_f32_16x16x32_bf16 v[86:89], v[174:177], v[206:209], 0
	v_mfma_f32_16x16x32_bf16 v[78:81], v[182:185], v[206:209], 0
	v_mfma_f32_16x16x32_bf16 v[70:73], v[174:177], v[214:217], 0
	v_mfma_f32_16x16x32_bf16 v[66:69], v[182:185], v[214:217], 0
	v_mfma_f32_16x16x32_bf16 v[118:121], v[178:181], v[194:197], v[118:121]
	v_mfma_f32_16x16x32_bf16 v[110:113], v[186:189], v[194:197], v[110:113]
	v_mfma_f32_16x16x32_bf16 v[102:105], v[178:181], v[202:205], v[102:105]
	v_mfma_f32_16x16x32_bf16 v[94:97], v[186:189], v[202:205], v[94:97]
	v_mfma_f32_16x16x32_bf16 v[86:89], v[178:181], v[210:213], v[86:89]
	v_mfma_f32_16x16x32_bf16 v[78:81], v[186:189], v[210:213], v[78:81]
	v_mfma_f32_16x16x32_bf16 v[70:73], v[178:181], v[218:221], v[70:73]
	v_mfma_f32_16x16x32_bf16 v[66:69], v[186:189], v[218:221], v[66:69]
	s_setprio 0
	s_barrier

; #define PG8_STAGE(bufoff, gbase, voff) do { _Pragma("unroll") for (int _i = 0; _i < 2; ++_i) \
;         __builtin_amdgcn_global_load_lds((const unsigned*)((const char*)(gbase) + (voff)[_i]), (PG8_LAS unsigned*)(lds + (bufoff) + ldsw + _i * 8192), 16, 0, 0); } while (0)
; #define PG8_LDA(dst, b, h) do { _Pragma("unroll") for (int m = 0; m < 4; ++m) _Pragma("unroll") for (int k = 0; k < 2; ++k) dst[m][k] = *(const PG8_LAS bf16x8*)(lds + PG8_SA(b, h) + aoff + m * 2048 + k * 1024); } while (0)
; #define PG8_MMA(ai, bj, At, Bt) do { __builtin_amdgcn_s_setprio(1); _Pragma("unroll") for (int m = 0; m < 4; ++m) _Pragma("unroll") for (int n = 0; n < 2; ++n) _Pragma("unroll") for (int k = 0; k < 2; ++k) \
;         acc[ai][bj][m][n] = __builtin_amdgcn_mfma_f32_16x16x32_bf16(Bt[n][k], At[m][k], acc[ai][bj][m][n], 0, 0, 0); __builtin_amdgcn_s_setprio(0); } while (0)
; #define PG8_WAIT_V(n) asm volatile("s_waitcnt vmcnt(" #n ")" ::: "memory")
; #define PG8_WAIT_L(n) asm volatile("s_waitcnt lgkmcnt(" #n ")" ::: "memory")
; #define PG8_BAR __builtin_amdgcn_s_barrier()
; #define PG8_SCHED __builtin_amdgcn_sched_barrier(0)
; template <class Epi, class Sched, bool ALIGN_EPI = false, bool SP2 = false>
; __device__ __forceinline__ void gemm_phase(PG8_LAS unsigned char* lds, const Gemm g, const Sched& S, const Epi& E) {
;     ...
;             PG8_LDA(At, 0, 1); PG8_STAGE(PG8_SB(0, 0), b2, voffB); PG8_STAGE(PG8_SB(0, 1), b2 + hstep, voffB); PG8_STAGE(PG8_SA(0, 0), a2, voffA);
;             PG8_WAIT_V(8); PG8_WAIT_L(0); PG8_BAR; PG8_MMA(1, 0, At, B0); PG8_MMA(1, 1, At, B1); PG8_BAR; PG8_SCHED;
;     ...
;                     for (int n = 0; n < 2; ++n) acc[a][b][m][n] = (f32x4){0.f, 0.f, 0.f, 0.f};
	s_add_i32 s65, s57, s42
	v_lshl_add_u64 v[150:151], s[30:31], 0, v[132:133]
	s_mov_b32 m0, s65
	ds_read_b128 v[190:193], v156 offset:16384
	ds_read_b128 v[194:197], v156 offset:17408
	ds_read_b128 v[198:201], v156 offset:18432
	ds_read_b128 v[202:205], v156 offset:19456
	ds_read_b128 v[206:209], v156 offset:20480
	ds_read_b128 v[210:213], v156 offset:21504
	ds_read_b128 v[214:217], v156 offset:22528
	ds_read_b128 v[218:221], v156 offset:23552
	global_load_lds_dwordx4 v[150:151], off
	s_add_i32 m0, s65, 0x2000
	s_add_u32 s66, s30, 0x40000
	v_lshl_add_u64 v[170:171], s[30:31], 0, v[136:137]
	s_addc_u32 s67, s31, 0
	s_add_i32 s65, s58, s42
	global_load_lds_dwordx4 v[170:171], off
	v_lshl_add_u64 v[222:223], s[66:67], 0, v[132:133]
	s_mov_b32 m0, s65
	v_lshl_add_u64 v[224:225], s[34:35], 0, v[134:135]
	global_load_lds_dwordx4 v[222:223], off
	v_lshl_add_u64 v[222:223], s[66:67], 0, v[136:137]
	s_add_i32 m0, s65, 0x2000
	s_nop 0
	global_load_lds_dwordx4 v[222:223], off
	v_lshl_add_u64 v[222:223], s[34:35], 0, v[130:131]
	s_mov_b32 m0, s27
	s_nop 0
	global_load_lds_dwordx4 v[222:223], off
	s_mov_b32 m0, s43
	s_nop 0
	global_load_lds_dwordx4 v[224:225], off
	s_waitcnt vmcnt(40)
	s_waitcnt lgkmcnt(0)
	s_barrier
	s_setprio 1
	s_waitcnt lgkmcnt(0)
	v_mfma_f32_16x16x32_bf16 v[62:65], v[146:149], v[190:193], 0
	v_mfma_f32_16x16x32_bf16 v[58:61], v[162:165], v[190:193], 0
	v_mfma_f32_16x16x32_bf16 v[50:53], v[146:149], v[198:201], 0
	v_mfma_f32_16x16x32_bf16 v[42:45], v[162:165], v[198:201], 0
	v_mfma_f32_16x16x32_bf16 v[34:37], v[146:149], v[206:209], 0
	v_mfma_f32_16x16x32_bf16 v[26:29], v[162:165], v[206:209], 0
	v_mfma_f32_16x16x32_bf16 v[18:21], v[146:149], v[214:217], 0
	v_mfma_f32_16x16x32_bf16 v[10:13], v[162:165], v[214:217], 0
	v_mfma_f32_16x16x32_bf16 v[62:65], v[158:161], v[194:197], v[62:65]
	v_mfma_f32_16x16x32_bf16 v[58:61], v[166:169], v[194:197], v[58:61]
	v_mfma_f32_16x16x32_bf16 v[50:53], v[158:161], v[202:205], v[50:53]
	v_mfma_f32_16x16x32_bf16 v[42:45], v[166:169], v[202:205], v[42:45]
	v_mfma_f32_16x16x32_bf16 v[34:37], v[158:161], v[210:213], v[34:37]
	v_mfma_f32_16x16x32_bf16 v[26:29], v[166:169], v[210:213], v[26:29]
	v_mfma_f32_16x16x32_bf16 v[18:21], v[158:161], v[218:221], v[18:21]
	v_mfma_f32_16x16x32_bf16 v[10:13], v[166:169], v[218:221], v[10:13]
	v_mfma_f32_16x16x32_bf16 v[54:57], v[174:177], v[190:193], 0
	v_mfma_f32_16x16x32_bf16 v[46:49], v[182:185], v[190:193], 0
	v_mfma_f32_16x16x32_bf16 v[38:41], v[174:177], v[198:201], 0
	v_mfma_f32_16x16x32_bf16 v[30:33], v[182:185], v[198:201], 0
	v_mfma_f32_16x16x32_bf16 v[22:25], v[174:177], v[206:209], 0
	v_mfma_f32_16x16x32_bf16 v[14:17], v[182:185], v[206:209], 0
	v_mfma_f32_16x16x32_bf16 v[6:9], v[174:177], v[214:217], 0
	v_mfma_f32_16x16x32_bf16 v[2:5], v[182:185], v[214:217], 0
	v_mfma_f32_16x16x32_bf16 v[54:57], v[178:181], v[194:197], v[54:57]
	v_mfma_f32_16x16x32_bf16 v[46:49], v[186:189], v[194:197], v[46:49]
	v_mfma_f32_16x16x32_bf16 v[38:41], v[178:181], v[202:205], v[38:41]
	v_mfma_f32_16x16x32_bf16 v[30:33], v[186:189], v[202:205], v[30:33]
	v_mfma_f32_16x16x32_bf16 v[22:25], v[178:181], v[210:213], v[22:25]
	v_mfma_f32_16x16x32_bf16 v[14:17], v[186:189], v[210:213], v[14:17]
	v_mfma_f32_16x16x32_bf16 v[6:9], v[178:181], v[218:221], v[6:9]
	v_mfma_f32_16x16x32_bf16 v[2:5], v[186:189], v[218:221], v[2:5]
	s_setprio 0
	s_barrier

; #define PG8_STAGE(bufoff, gbase, voff) do { _Pragma("unroll") for (int _i = 0; _i < 2; ++_i) \
;         __builtin_amdgcn_global_load_lds((const unsigned*)((const char*)(gbase) + (voff)[_i]), (PG8_LAS unsigned*)(lds + (bufoff) + ldsw + _i * 8192), 16, 0, 0); } while (0)
; #define PG8_LDA(dst, b, h) do { _Pragma("unroll") for (int m = 0; m < 4; ++m) _Pragma("unroll") for (int k = 0; k < 2; ++k) dst[m][k] = *(const PG8_LAS bf16x8*)(lds + PG8_SA(b, h) + aoff + m * 2048 + k * 1024); } while (0)
; #define PG8_LDB(dst, b, h) do { _Pragma("unroll") for (int n = 0; n < 2; ++n) _Pragma("unroll") for (int k = 0; k < 2; ++k) dst[n][k] = *(const PG8_LAS bf16x8*)(lds + PG8_SB(b, h) + boff + n * 2048 + k * 1024); } while (0)
; #define PG8_SCHED __builtin_amdgcn_sched_barrier(0)
; template <class Epi, class Sched, bool ALIGN_EPI = false, bool SP2 = false>
; __device__ __forceinline__ void gemm_phase(PG8_LAS unsigned char* lds, const Gemm g, const Sched& S, const Epi& E) {
;     ...
;             PG8_LDB(B0, 1, 0); PG8_LDB(B1, 1, 1); PG8_SCHED; PG8_LDA(At, 1, 0); PG8_STAGE(PG8_SA(0, 1), a2 + hstep, voffA);
	s_add_i32 s65, 0, 0x18000
	v_add_u32_e32 v157, s65, v152
	s_add_i32 s66, 0, 0x1c000
	ds_read_b128 v[146:149], v157
	ds_read_b128 v[158:161], v157 offset:1024
	ds_read_b128 v[162:165], v157 offset:2048
	ds_read_b128 v[166:169], v157 offset:3072
	v_add_u32_e32 v157, s66, v152
	ds_read_b128 v[174:177], v157
	ds_read_b128 v[178:181], v157 offset:1024
	ds_read_b128 v[182:185], v157 offset:2048
	ds_read_b128 v[186:189], v157 offset:3072

; #define PG8_STAGE(bufoff, gbase, voff) do { _Pragma("unroll") for (int _i = 0; _i < 2; ++_i) \
;         __builtin_amdgcn_global_load_lds((const unsigned*)((const char*)(gbase) + (voff)[_i]), (PG8_LAS unsigned*)(lds + (bufoff) + ldsw + _i * 8192), 16, 0, 0); } while (0)
; #define PG8_LDA(dst, b, h) do { _Pragma("unroll") for (int m = 0; m < 4; ++m) _Pragma("unroll") for (int k = 0; k < 2; ++k) dst[m][k] = *(const PG8_LAS bf16x8*)(lds + PG8_SA(b, h) + aoff + m * 2048 + k * 1024); } while (0)
; #define PG8_LDB(dst, b, h) do { _Pragma("unroll") for (int n = 0; n < 2; ++n) _Pragma("unroll") for (int k = 0; k < 2; ++k) dst[n][k] = *(const PG8_LAS bf16x8*)(lds + PG8_SB(b, h) + boff + n * 2048 + k * 1024); } while (0)
; #define PG8_MMA(ai, bj, At, Bt) do { __builtin_amdgcn_s_setprio(1); _Pragma("unroll") for (int m = 0; m < 4; ++m) _Pragma("unroll") for (int n = 0; n < 2; ++n) _Pragma("unroll") for (int k = 0; k < 2; ++k) \
;         acc[ai][bj][m][n] = __builtin_amdgcn_mfma_f32_16x16x32_bf16(Bt[n][k], At[m][k], acc[ai][bj][m][n], 0, 0, 0); __builtin_amdgcn_s_setprio(0); } while (0)
; #define PG8_WAIT_V(n) asm volatile("s_waitcnt vmcnt(" #n ")" ::: "memory")
; #define PG8_WAIT_L(n) asm volatile("s_waitcnt lgkmcnt(" #n ")" ::: "memory")
; #define PG8_BAR __builtin_amdgcn_s_barrier()
; #define PG8_SCHED __builtin_amdgcn_sched_barrier(0)
; template <class Epi, class Sched, bool ALIGN_EPI = false, bool SP2 = false>
; __device__ __forceinline__ void gemm_phase(PG8_LAS unsigned char* lds, const Gemm g, const Sched& S, const Epi& E) {
;     ...
;             PG8_LDB(B0, 1, 0); PG8_LDB(B1, 1, 1); PG8_SCHED; PG8_LDA(At, 1, 0); PG8_STAGE(PG8_SA(0, 1), a2 + hstep, voffA);
;             PG8_WAIT_V(8); PG8_WAIT_L(0); PG8_BAR; PG8_MMA(0, 0, At, B0); PG8_MMA(0, 1, At, B1); PG8_BAR; PG8_SCHED;
	s_add_u32 s34, s34, 0x40000
	s_addc_u32 s35, s35, 0
	s_mov_b32 m0, s44
	v_lshl_add_u64 v[226:227], s[34:35], 0, v[130:131]
	ds_read_b128 v[190:193], v156 offset:32768
	ds_read_b128 v[194:197], v156 offset:33792
	ds_read_b128 v[198:201], v156 offset:34816
	ds_read_b128 v[202:205], v156 offset:35840
	ds_read_b128 v[206:209], v156 offset:36864
	ds_read_b128 v[210:213], v156 offset:37888
	ds_read_b128 v[214:217], v156 offset:38912
	ds_read_b128 v[218:221], v156 offset:39936
	global_load_lds_dwordx4 v[226:227], off
	v_lshl_add_u64 v[226:227], s[34:35], 0, v[134:135]
	s_mov_b32 m0, s45
	s_nop 0
	global_load_lds_dwordx4 v[226:227], off
	s_waitcnt vmcnt(8)
	s_waitcnt lgkmcnt(0)
	s_barrier
	s_setprio 1
	s_waitcnt lgkmcnt(0)
	v_mfma_f32_16x16x32_bf16 v[126:129], v[146:149], v[190:193], v[126:129]
	v_mfma_f32_16x16x32_bf16 v[122:125], v[162:165], v[190:193], v[122:125]
	v_mfma_f32_16x16x32_bf16 v[114:117], v[146:149], v[198:201], v[114:117]
	v_mfma_f32_16x16x32_bf16 v[106:109], v[162:165], v[198:201], v[106:109]
	v_mfma_f32_16x16x32_bf16 v[98:101], v[146:149], v[206:209], v[98:101]
	v_mfma_f32_16x16x32_bf16 v[90:93], v[162:165], v[206:209], v[90:93]
	v_mfma_f32_16x16x32_bf16 v[82:85], v[146:149], v[214:217], v[82:85]
	v_mfma_f32_16x16x32_bf16 v[74:77], v[162:165], v[214:217], v[74:77]
	v_mfma_f32_16x16x32_bf16 v[126:129], v[158:161], v[194:197], v[126:129]
	v_mfma_f32_16x16x32_bf16 v[122:125], v[166:169], v[194:197], v[122:125]
	v_mfma_f32_16x16x32_bf16 v[114:117], v[158:161], v[202:205], v[114:117]
	v_mfma_f32_16x16x32_bf16 v[106:109], v[166:169], v[202:205], v[106:109]
	v_mfma_f32_16x16x32_bf16 v[98:101], v[158:161], v[210:213], v[98:101]
	v_mfma_f32_16x16x32_bf16 v[90:93], v[166:169], v[210:213], v[90:93]
	v_mfma_f32_16x16x32_bf16 v[82:85], v[158:161], v[218:221], v[82:85]
	v_mfma_f32_16x16x32_bf16 v[74:77], v[166:169], v[218:221], v[74:77]
	v_mfma_f32_16x16x32_bf16 v[118:121], v[174:177], v[190:193], v[118:121]
	v_mfma_f32_16x16x32_bf16 v[110:113], v[182:185], v[190:193], v[110:113]
	v_mfma_f32_16x16x32_bf16 v[102:105], v[174:177], v[198:201], v[102:105]
	v_mfma_f32_16x16x32_bf16 v[94:97], v[182:185], v[198:201], v[94:97]
	v_mfma_f32_16x16x32_bf16 v[86:89], v[174:177], v[206:209], v[86:89]
	v_mfma_f32_16x16x32_bf16 v[78:81], v[182:185], v[206:209], v[78:81]
	v_mfma_f32_16x16x32_bf16 v[70:73], v[174:177], v[214:217], v[70:73]
	v_mfma_f32_16x16x32_bf16 v[66:69], v[182:185], v[214:217], v[66:69]
	v_mfma_f32_16x16x32_bf16 v[118:121], v[178:181], v[194:197], v[118:121]
	v_mfma_f32_16x16x32_bf16 v[110:113], v[186:189], v[194:197], v[110:113]
	v_mfma_f32_16x16x32_bf16 v[102:105], v[178:181], v[202:205], v[102:105]
	v_mfma_f32_16x16x32_bf16 v[94:97], v[186:189], v[202:205], v[94:97]
	v_mfma_f32_16x16x32_bf16 v[86:89], v[178:181], v[210:213], v[86:89]
	v_mfma_f32_16x16x32_bf16 v[78:81], v[186:189], v[210:213], v[78:81]
	v_mfma_f32_16x16x32_bf16 v[70:73], v[178:181], v[218:221], v[70:73]
	v_mfma_f32_16x16x32_bf16 v[66:69], v[186:189], v[218:221], v[66:69]
	s_setprio 0
	s_barrier

; #define PG8_STAGE(bufoff, gbase, voff) do { _Pragma("unroll") for (int _i = 0; _i < 2; ++_i) \
;         __builtin_amdgcn_global_load_lds((const unsigned*)((const char*)(gbase) + (voff)[_i]), (PG8_LAS unsigned*)(lds + (bufoff) + ldsw + _i * 8192), 16, 0, 0); } while (0)
; #define PG8_LDA(dst, b, h) do { _Pragma("unroll") for (int m = 0; m < 4; ++m) _Pragma("unroll") for (int k = 0; k < 2; ++k) dst[m][k] = *(const PG8_LAS bf16x8*)(lds + PG8_SA(b, h) + aoff + m * 2048 + k * 1024); } while (0)
; #define PG8_MMA(ai, bj, At, Bt) do { __builtin_amdgcn_s_setprio(1); _Pragma("unroll") for (int m = 0; m < 4; ++m) _Pragma("unroll") for (int n = 0; n < 2; ++n) _Pragma("unroll") for (int k = 0; k < 2; ++k) \
;         acc[ai][bj][m][n] = __builtin_amdgcn_mfma_f32_16x16x32_bf16(Bt[n][k], At[m][k], acc[ai][bj][m][n], 0, 0, 0); __builtin_amdgcn_s_setprio(0); } while (0)
; #define PG8_WAIT_V(n) asm volatile("s_waitcnt vmcnt(" #n ")" ::: "memory")
; #define PG8_WAIT_L(n) asm volatile("s_waitcnt lgkmcnt(" #n ")" ::: "memory")
; #define PG8_BAR __builtin_amdgcn_s_barrier()
; #define PG8_SCHED __builtin_amdgcn_sched_barrier(0)
; template <class Epi, class Sched, bool ALIGN_EPI = false, bool SP2 = false>
; __device__ __forceinline__ void gemm_phase(PG8_LAS unsigned char* lds, const Gemm g, const Sched& S, const Epi& E) {
;     ...
;             PG8_LDA(At, 1, 1); PG8_STAGE(PG8_SB(1, 0), b3, voffB); PG8_STAGE(PG8_SB(1, 1), b3 + hstep, voffB); PG8_STAGE(PG8_SA(1, 0), a3, voffA);
;             PG8_WAIT_V(8); PG8_WAIT_L(0); PG8_BAR; PG8_MMA(1, 0, At, B0); PG8_MMA(1, 1, At, B1); PG8_BAR; PG8_SCHED;
	s_add_i32 s34, s65, s42
	v_lshl_add_u64 v[150:151], v[150:151], 0, s[8:9]
	s_mov_b32 m0, s34
	ds_read_b128 v[190:193], v156 offset:49152
	ds_read_b128 v[194:197], v156 offset:50176
	ds_read_b128 v[198:201], v156 offset:51200
	ds_read_b128 v[202:205], v156 offset:52224
	ds_read_b128 v[206:209], v156 offset:53248
	ds_read_b128 v[210:213], v156 offset:54272
	ds_read_b128 v[214:217], v156 offset:55296
	ds_read_b128 v[218:221], v156 offset:56320
	global_load_lds_dwordx4 v[150:151], off
	s_add_i32 m0, s34, 0x2000
	s_add_u32 s30, s30, 0x40080
	v_lshl_add_u64 v[150:151], v[170:171], 0, s[8:9]
	s_addc_u32 s31, s31, 0
	s_add_i32 s34, s66, s42
	global_load_lds_dwordx4 v[150:151], off
	v_lshl_add_u64 v[150:151], s[30:31], 0, v[132:133]
	s_mov_b32 m0, s34
	s_nop 0
	global_load_lds_dwordx4 v[150:151], off
	v_lshl_add_u64 v[150:151], s[30:31], 0, v[136:137]
	s_add_i32 m0, s34, 0x2000
	s_nop 0
	global_load_lds_dwordx4 v[150:151], off
	v_lshl_add_u64 v[150:151], v[222:223], 0, s[8:9]
	s_mov_b32 m0, s53
	s_nop 0
	global_load_lds_dwordx4 v[150:151], off
	v_lshl_add_u64 v[150:151], v[224:225], 0, s[8:9]
	s_mov_b32 m0, s54
	s_nop 0
	global_load_lds_dwordx4 v[150:151], off
	s_waitcnt vmcnt(8)
	s_waitcnt lgkmcnt(0)
	s_barrier
	s_setprio 1
	s_waitcnt lgkmcnt(0)
	v_mfma_f32_16x16x32_bf16 v[62:65], v[146:149], v[190:193], v[62:65]
	v_mfma_f32_16x16x32_bf16 v[58:61], v[162:165], v[190:193], v[58:61]
	v_mfma_f32_16x16x32_bf16 v[50:53], v[146:149], v[198:201], v[50:53]
	v_mfma_f32_16x16x32_bf16 v[42:45], v[162:165], v[198:201], v[42:45]
	v_mfma_f32_16x16x32_bf16 v[34:37], v[146:149], v[206:209], v[34:37]
	v_mfma_f32_16x16x32_bf16 v[26:29], v[162:165], v[206:209], v[26:29]
	v_mfma_f32_16x16x32_bf16 v[18:21], v[146:149], v[214:217], v[18:21]
	v_mfma_f32_16x16x32_bf16 v[10:13], v[162:165], v[214:217], v[10:13]
	v_mfma_f32_16x16x32_bf16 v[62:65], v[158:161], v[194:197], v[62:65]
	v_mfma_f32_16x16x32_bf16 v[58:61], v[166:169], v[194:197], v[58:61]
	v_mfma_f32_16x16x32_bf16 v[50:53], v[158:161], v[202:205], v[50:53]
	v_mfma_f32_16x16x32_bf16 v[42:45], v[166:169], v[202:205], v[42:45]
	v_mfma_f32_16x16x32_bf16 v[34:37], v[158:161], v[210:213], v[34:37]
	v_mfma_f32_16x16x32_bf16 v[26:29], v[166:169], v[210:213], v[26:29]
	v_mfma_f32_16x16x32_bf16 v[18:21], v[158:161], v[218:221], v[18:21]
	v_mfma_f32_16x16x32_bf16 v[10:13], v[166:169], v[218:221], v[10:13]
	v_mfma_f32_16x16x32_bf16 v[54:57], v[174:177], v[190:193], v[54:57]
	v_mfma_f32_16x16x32_bf16 v[46:49], v[182:185], v[190:193], v[46:49]
	v_mfma_f32_16x16x32_bf16 v[38:41], v[174:177], v[198:201], v[38:41]
	v_mfma_f32_16x16x32_bf16 v[30:33], v[182:185], v[198:201], v[30:33]
	v_mfma_f32_16x16x32_bf16 v[22:25], v[174:177], v[206:209], v[22:25]
	v_mfma_f32_16x16x32_bf16 v[14:17], v[182:185], v[206:209], v[14:17]
	v_mfma_f32_16x16x32_bf16 v[6:9], v[174:177], v[214:217], v[6:9]
	v_mfma_f32_16x16x32_bf16 v[2:5], v[182:185], v[214:217], v[2:5]
	v_mfma_f32_16x16x32_bf16 v[54:57], v[178:181], v[194:197], v[54:57]
	v_mfma_f32_16x16x32_bf16 v[46:49], v[186:189], v[194:197], v[46:49]
	v_mfma_f32_16x16x32_bf16 v[38:41], v[178:181], v[202:205], v[38:41]
	v_mfma_f32_16x16x32_bf16 v[30:33], v[186:189], v[202:205], v[30:33]
	v_mfma_f32_16x16x32_bf16 v[22:25], v[178:181], v[210:213], v[22:25]
	v_mfma_f32_16x16x32_bf16 v[14:17], v[186:189], v[210:213], v[14:17]
	v_mfma_f32_16x16x32_bf16 v[6:9], v[178:181], v[218:221], v[6:9]
	v_mfma_f32_16x16x32_bf16 v[2:5], v[186:189], v[218:221], v[2:5]
	s_setprio 0
	s_barrier

; #define PG8_STAGE(bufoff, gbase, voff) do { _Pragma("unroll") for (int _i = 0; _i < 2; ++_i) \
;         __builtin_amdgcn_global_load_lds((const unsigned*)((const char*)(gbase) + (voff)[_i]), (PG8_LAS unsigned*)(lds + (bufoff) + ldsw + _i * 8192), 16, 0, 0); } while (0)
; #define PG8_LDA(dst, b, h) do { _Pragma("unroll") for (int m = 0; m < 4; ++m) _Pragma("unroll") for (int k = 0; k < 2; ++k) dst[m][k] = *(const PG8_LAS bf16x8*)(lds + PG8_SA(b, h) + aoff + m * 2048 + k * 1024); } while (0)
; #define PG8_LDB(dst, b, h) do { _Pragma("unroll") for (int n = 0; n < 2; ++n) _Pragma("unroll") for (int k = 0; k < 2; ++k) dst[n][k] = *(const PG8_LAS bf16x8*)(lds + PG8_SB(b, h) + boff + n * 2048 + k * 1024); } while (0)
; #define PG8_MMA(ai, bj, At, Bt) do { __builtin_amdgcn_s_setprio(1); _Pragma("unroll") for (int m = 0; m < 4; ++m) _Pragma("unroll") for (int n = 0; n < 2; ++n) _Pragma("unroll") for (int k = 0; k < 2; ++k) \
;         acc[ai][bj][m][n] = __builtin_amdgcn_mfma_f32_16x16x32_bf16(Bt[n][k], At[m][k], acc[ai][bj][m][n], 0, 0, 0); __builtin_amdgcn_s_setprio(0); } while (0)
; #define PG8_WAIT_V(n) asm volatile("s_waitcnt vmcnt(" #n ")" ::: "memory")
; #define PG8_WAIT_L(n) asm volatile("s_waitcnt lgkmcnt(" #n ")" ::: "memory")
; #define PG8_BAR __builtin_amdgcn_s_barrier()
; #define PG8_SCHED __builtin_amdgcn_sched_barrier(0)
; template <class Epi, class Sched, bool ALIGN_EPI = false, bool SP2 = false>
; __device__ __forceinline__ void gemm_phase(PG8_LAS unsigned char* lds, const Gemm g, const Sched& S, const Epi& E) {
;     ...
;             const bool last = (t == nt - 2);
;             const char* a1 = cA + (size_t)(t + 1) * kstep;
;             const char* a2 = last ? nA : cA + (size_t)(t + 2) * kstep; const char* b2 = last ? nB : cB + (size_t)(t + 2) * kstep;
;             const char* a3 = a2 + kstep; const char* b3 = b2 + kstep;
;             if (last && has_next) S.a_ready(nxt);
;             if constexpr (SP2) {
;             PG8_LDB(B0, 0, 0); PG8_LDB(B1, 0, 1); PG8_SCHED; PG8_LDA(At, 0, 0); PG8_STAGE(PG8_SA(1, 1), a1 + hstep, voffA);
;             PG8_WAIT_V(8); PG8_WAIT_L(0); PG8_BAR; PG8_MMA(0, 0, At, B0); PG8_MMA(0, 1, At, B1); PG8_BAR; PG8_SCHED;
;             PG8_LDA(At, 0, 1); PG8_STAGE(PG8_SB(0, 0), b2, voffB); PG8_STAGE(PG8_SB(0, 1), b2 + hstep, voffB); PG8_STAGE(PG8_SA(0, 0), a2, voffA);
	s_add_i32 s64, s64, 2
	s_add_u32 s28, s28, 0x100
	s_addc_u32 s29, s29, 0
	s_add_u32 s62, s62, 0x100
	s_addc_u32 s63, s63, 0
.LBB0_1314:
	ds_read_b128 v[146:149], v154
	ds_read_b128 v[158:161], v154 offset:1024
	ds_read_b128 v[162:165], v154 offset:2048
	ds_read_b128 v[166:169], v154 offset:3072
	ds_read_b128 v[174:177], v155
	ds_read_b128 v[178:181], v155 offset:1024
	ds_read_b128 v[182:185], v155 offset:2048
	ds_read_b128 v[186:189], v155 offset:3072
	s_add_u32 s30, s28, 0xfffc0080
	s_addc_u32 s31, s29, -1
	s_cmp_eq_u32 s64, 12
	s_cselect_b32 s35, s21, s31
	s_cselect_b32 s34, s60, s30
	s_cselect_b32 s31, s19, s63
	s_cselect_b32 s30, s61, s62
	v_lshl_add_u64 v[150:151], s[28:29], 0, v[138:139]
	s_add_i32 m0, s27, 0xc000
	ds_read_b128 v[190:193], v156
	ds_read_b128 v[194:197], v156 offset:1024
	ds_read_b128 v[198:201], v156 offset:2048
	ds_read_b128 v[202:205], v156 offset:3072
	ds_read_b128 v[206:209], v156 offset:4096
	ds_read_b128 v[210:213], v156 offset:5120
	ds_read_b128 v[214:217], v156 offset:6144
	ds_read_b128 v[218:221], v156 offset:7168
	global_load_lds_dwordx4 v[150:151], off
	v_lshl_add_u64 v[150:151], s[28:29], 0, v[140:141]
	s_add_i32 m0, s27, 0xe000
	s_nop 0
	global_load_lds_dwordx4 v[150:151], off
	s_waitcnt vmcnt(8)
	s_waitcnt lgkmcnt(0)
	s_barrier
	s_setprio 1
	s_waitcnt lgkmcnt(0)
	v_mfma_f32_16x16x32_bf16 v[126:129], v[146:149], v[190:193], v[126:129]
	v_mfma_f32_16x16x32_bf16 v[122:125], v[162:165], v[190:193], v[122:125]
	v_mfma_f32_16x16x32_bf16 v[114:117], v[146:149], v[198:201], v[114:117]
	v_mfma_f32_16x16x32_bf16 v[106:109], v[162:165], v[198:201], v[106:109]
	v_mfma_f32_16x16x32_bf16 v[98:101], v[146:149], v[206:209], v[98:101]
	v_mfma_f32_16x16x32_bf16 v[90:93], v[162:165], v[206:209], v[90:93]
	v_mfma_f32_16x16x32_bf16 v[82:85], v[146:149], v[214:217], v[82:85]
	v_mfma_f32_16x16x32_bf16 v[74:77], v[162:165], v[214:217], v[74:77]
	v_mfma_f32_16x16x32_bf16 v[126:129], v[158:161], v[194:197], v[126:129]
	v_mfma_f32_16x16x32_bf16 v[122:125], v[166:169], v[194:197], v[122:125]
	v_mfma_f32_16x16x32_bf16 v[114:117], v[158:161], v[202:205], v[114:117]
	v_mfma_f32_16x16x32_bf16 v[106:109], v[166:169], v[202:205], v[106:109]
	v_mfma_f32_16x16x32_bf16 v[98:101], v[158:161], v[210:213], v[98:101]
	v_mfma_f32_16x16x32_bf16 v[90:93], v[166:169], v[210:213], v[90:93]
	v_mfma_f32_16x16x32_bf16 v[82:85], v[158:161], v[218:221], v[82:85]
	v_mfma_f32_16x16x32_bf16 v[74:77], v[166:169], v[218:221], v[74:77]
	v_mfma_f32_16x16x32_bf16 v[118:121], v[174:177], v[190:193], v[118:121]
	v_mfma_f32_16x16x32_bf16 v[110:113], v[182:185], v[190:193], v[110:113]
	v_mfma_f32_16x16x32_bf16 v[102:105], v[174:177], v[198:201], v[102:105]
	v_mfma_f32_16x16x32_bf16 v[94:97], v[182:185], v[198:201], v[94:97]
	v_mfma_f32_16x16x32_bf16 v[86:89], v[174:177], v[206:209], v[86:89]
	v_mfma_f32_16x16x32_bf16 v[78:81], v[182:185], v[206:209], v[78:81]
	v_mfma_f32_16x16x32_bf16 v[70:73], v[174:177], v[214:217], v[70:73]
	v_mfma_f32_16x16x32_bf16 v[66:69], v[182:185], v[214:217], v[66:69]
	v_mfma_f32_16x16x32_bf16 v[118:121], v[178:181], v[194:197], v[118:121]
	v_mfma_f32_16x16x32_bf16 v[110:113], v[186:189], v[194:197], v[110:113]
	v_mfma_f32_16x16x32_bf16 v[102:105], v[178:181], v[202:205], v[102:105]
	v_mfma_f32_16x16x32_bf16 v[94:97], v[186:189], v[202:205], v[94:97]
	v_mfma_f32_16x16x32_bf16 v[86:89], v[178:181], v[210:213], v[86:89]
	v_mfma_f32_16x16x32_bf16 v[78:81], v[186:189], v[210:213], v[78:81]
	v_mfma_f32_16x16x32_bf16 v[70:73], v[178:181], v[218:221], v[70:73]
	v_mfma_f32_16x16x32_bf16 v[66:69], v[186:189], v[218:221], v[66:69]
	s_setprio 0
	s_barrier
	s_add_i32 s65, s57, s42
	v_lshl_add_u64 v[150:151], s[30:31], 0, v[132:133]
	s_mov_b32 m0, s65
	ds_read_b128 v[190:193], v156 offset:16384
	ds_read_b128 v[194:197], v156 offset:17408
	ds_read_b128 v[198:201], v156 offset:18432
	ds_read_b128 v[202:205], v156 offset:19456
	ds_read_b128 v[206:209], v156 offset:20480
	ds_read_b128 v[210:213], v156 offset:21504
	ds_read_b128 v[214:217], v156 offset:22528
	ds_read_b128 v[218:221], v156 offset:23552
	global_load_lds_dwordx4 v[150:151], off
	s_add_i32 m0, s65, 0x2000
	s_add_u32 s66, s30, 0x40000
	v_lshl_add_u64 v[170:171], s[30:31], 0, v[136:137]
	s_addc_u32 s67, s31, 0
	s_add_i32 s65, s58, s42
	global_load_lds_dwordx4 v[170:171], off
	v_lshl_add_u64 v[222:223], s[66:67], 0, v[132:133]
	s_mov_b32 m0, s65
	v_lshl_add_u64 v[224:225], s[34:35], 0, v[134:135]
	global_load_lds_dwordx4 v[222:223], off
	v_lshl_add_u64 v[222:223], s[66:67], 0, v[136:137]
	s_add_i32 m0, s65, 0x2000
	s_nop 0
	global_load_lds_dwordx4 v[222:223], off
	v_lshl_add_u64 v[222:223], s[34:35], 0, v[130:131]
	s_mov_b32 m0, s27
	s_nop 0
	global_load_lds_dwordx4 v[222:223], off
	s_mov_b32 m0, s43
	s_nop 0
	global_load_lds_dwordx4 v[224:225], off
	s_waitcnt vmcnt(8)
	s_waitcnt lgkmcnt(0)
	s_barrier
; #define PG8_STAGE(bufoff, gbase, voff) do { _Pragma("unroll") for (int _i = 0; _i < 2; ++_i) \
;         __builtin_amdgcn_global_load_lds((const unsigned*)((const char*)(gbase) + (voff)[_i]), (PG8_LAS unsigned*)(lds + (bufoff) + ldsw + _i * 8192), 16, 0, 0); } while (0)
; #define PG8_LDA(dst, b, h) do { _Pragma("unroll") for (int m = 0; m < 4; ++m) _Pragma("unroll") for (int k = 0; k < 2; ++k) dst[m][k] = *(const PG8_LAS bf16x8*)(lds + PG8_SA(b, h) + aoff + m * 2048 + k * 1024); } while (0)
; #define PG8_LDB(dst, b, h) do { _Pragma("unroll") for (int n = 0; n < 2; ++n) _Pragma("unroll") for (int k = 0; k < 2; ++k) dst[n][k] = *(const PG8_LAS bf16x8*)(lds + PG8_SB(b, h) + boff + n * 2048 + k * 1024); } while (0)
; #define PG8_MMA(ai, bj, At, Bt) do { __builtin_amdgcn_s_setprio(1); _Pragma("unroll") for (int m = 0; m < 4; ++m) _Pragma("unroll") for (int n = 0; n < 2; ++n) _Pragma("unroll") for (int k = 0; k < 2; ++k) \
;         acc[ai][bj][m][n] = __builtin_amdgcn_mfma_f32_16x16x32_bf16(Bt[n][k], At[m][k], acc[ai][bj][m][n], 0, 0, 0); __builtin_amdgcn_s_setprio(0); } while (0)
; #define PG8_WAIT_V(n) asm volatile("s_waitcnt vmcnt(" #n ")" ::: "memory")
; #define PG8_WAIT_L(n) asm volatile("s_waitcnt lgkmcnt(" #n ")" ::: "memory")
; #define PG8_BAR __builtin_amdgcn_s_barrier()
; #define PG8_SCHED __builtin_amdgcn_sched_barrier(0)
; template <class Epi, class Sched, bool ALIGN_EPI = false, bool SP2 = false>
; __device__ __forceinline__ void gemm_phase(PG8_LAS unsigned char* lds, const Gemm g, const Sched& S, const Epi& E) {
;     ...
;             PG8_WAIT_V(8); PG8_WAIT_L(0); PG8_BAR; PG8_MMA(1, 0, At, B0); PG8_MMA(1, 1, At, B1); PG8_BAR; PG8_SCHED;
;             PG8_LDB(B0, 1, 0); PG8_LDB(B1, 1, 1); PG8_SCHED; PG8_LDA(At, 1, 0); PG8_STAGE(PG8_SA(0, 1), a2 + hstep, voffA);
;             PG8_WAIT_V(8); PG8_WAIT_L(0); PG8_BAR; PG8_MMA(0, 0, At, B0); PG8_MMA(0, 1, At, B1); PG8_BAR; PG8_SCHED;
	s_setprio 1
	s_waitcnt lgkmcnt(0)
	v_mfma_f32_16x16x32_bf16 v[62:65], v[146:149], v[190:193], v[62:65]
	v_mfma_f32_16x16x32_bf16 v[58:61], v[162:165], v[190:193], v[58:61]
	v_mfma_f32_16x16x32_bf16 v[50:53], v[146:149], v[198:201], v[50:53]
	v_mfma_f32_16x16x32_bf16 v[42:45], v[162:165], v[198:201], v[42:45]
	v_mfma_f32_16x16x32_bf16 v[34:37], v[146:149], v[206:209], v[34:37]
	v_mfma_f32_16x16x32_bf16 v[26:29], v[162:165], v[206:209], v[26:29]
	v_mfma_f32_16x16x32_bf16 v[18:21], v[146:149], v[214:217], v[18:21]
	v_mfma_f32_16x16x32_bf16 v[10:13], v[162:165], v[214:217], v[10:13]
	v_mfma_f32_16x16x32_bf16 v[62:65], v[158:161], v[194:197], v[62:65]
	v_mfma_f32_16x16x32_bf16 v[58:61], v[166:169], v[194:197], v[58:61]
	v_mfma_f32_16x16x32_bf16 v[50:53], v[158:161], v[202:205], v[50:53]
	v_mfma_f32_16x16x32_bf16 v[42:45], v[166:169], v[202:205], v[42:45]
	v_mfma_f32_16x16x32_bf16 v[34:37], v[158:161], v[210:213], v[34:37]
	v_mfma_f32_16x16x32_bf16 v[26:29], v[166:169], v[210:213], v[26:29]
	v_mfma_f32_16x16x32_bf16 v[18:21], v[158:161], v[218:221], v[18:21]
	v_mfma_f32_16x16x32_bf16 v[10:13], v[166:169], v[218:221], v[10:13]
	v_mfma_f32_16x16x32_bf16 v[54:57], v[174:177], v[190:193], v[54:57]
	v_mfma_f32_16x16x32_bf16 v[46:49], v[182:185], v[190:193], v[46:49]
	v_mfma_f32_16x16x32_bf16 v[38:41], v[174:177], v[198:201], v[38:41]
	v_mfma_f32_16x16x32_bf16 v[30:33], v[182:185], v[198:201], v[30:33]
	v_mfma_f32_16x16x32_bf16 v[22:25], v[174:177], v[206:209], v[22:25]
	v_mfma_f32_16x16x32_bf16 v[14:17], v[182:185], v[206:209], v[14:17]
	v_mfma_f32_16x16x32_bf16 v[6:9], v[174:177], v[214:217], v[6:9]
	v_mfma_f32_16x16x32_bf16 v[2:5], v[182:185], v[214:217], v[2:5]
	v_mfma_f32_16x16x32_bf16 v[54:57], v[178:181], v[194:197], v[54:57]
	v_mfma_f32_16x16x32_bf16 v[46:49], v[186:189], v[194:197], v[46:49]
	v_mfma_f32_16x16x32_bf16 v[38:41], v[178:181], v[202:205], v[38:41]
	v_mfma_f32_16x16x32_bf16 v[30:33], v[186:189], v[202:205], v[30:33]
	v_mfma_f32_16x16x32_bf16 v[22:25], v[178:181], v[210:213], v[22:25]
	v_mfma_f32_16x16x32_bf16 v[14:17], v[186:189], v[210:213], v[14:17]
	v_mfma_f32_16x16x32_bf16 v[6:9], v[178:181], v[218:221], v[6:9]
	v_mfma_f32_16x16x32_bf16 v[2:5], v[186:189], v[218:221], v[2:5]
	s_setprio 0
	s_barrier
	s_add_i32 s65, 0, 0x18000
	v_add_u32_e32 v157, s65, v152
	s_add_i32 s66, 0, 0x1c000
	ds_read_b128 v[146:149], v157
	ds_read_b128 v[158:161], v157 offset:1024
	ds_read_b128 v[162:165], v157 offset:2048
	ds_read_b128 v[166:169], v157 offset:3072
	v_add_u32_e32 v157, s66, v152
	ds_read_b128 v[174:177], v157
	ds_read_b128 v[178:181], v157 offset:1024
	ds_read_b128 v[182:185], v157 offset:2048
	ds_read_b128 v[186:189], v157 offset:3072
	s_add_u32 s34, s34, 0x40000
	s_addc_u32 s35, s35, 0
	s_mov_b32 m0, s44
	v_lshl_add_u64 v[226:227], s[34:35], 0, v[130:131]
	ds_read_b128 v[190:193], v156 offset:32768
	ds_read_b128 v[194:197], v156 offset:33792
	ds_read_b128 v[198:201], v156 offset:34816
	ds_read_b128 v[202:205], v156 offset:35840
	ds_read_b128 v[206:209], v156 offset:36864
	ds_read_b128 v[210:213], v156 offset:37888
	ds_read_b128 v[214:217], v156 offset:38912
	ds_read_b128 v[218:221], v156 offset:39936
	global_load_lds_dwordx4 v[226:227], off
	v_lshl_add_u64 v[226:227], s[34:35], 0, v[134:135]
	s_mov_b32 m0, s45
	s_nop 0
	global_load_lds_dwordx4 v[226:227], off
	s_waitcnt vmcnt(8)
	s_waitcnt lgkmcnt(0)
	s_barrier
	s_setprio 1
	s_waitcnt lgkmcnt(0)
	v_mfma_f32_16x16x32_bf16 v[126:129], v[146:149], v[190:193], v[126:129]
	v_mfma_f32_16x16x32_bf16 v[122:125], v[162:165], v[190:193], v[122:125]
	v_mfma_f32_16x16x32_bf16 v[114:117], v[146:149], v[198:201], v[114:117]
	v_mfma_f32_16x16x32_bf16 v[106:109], v[162:165], v[198:201], v[106:109]
	v_mfma_f32_16x16x32_bf16 v[98:101], v[146:149], v[206:209], v[98:101]
	v_mfma_f32_16x16x32_bf16 v[90:93], v[162:165], v[206:209], v[90:93]
	v_mfma_f32_16x16x32_bf16 v[82:85], v[146:149], v[214:217], v[82:85]
	v_mfma_f32_16x16x32_bf16 v[74:77], v[162:165], v[214:217], v[74:77]
	v_mfma_f32_16x16x32_bf16 v[126:129], v[158:161], v[194:197], v[126:129]
	v_mfma_f32_16x16x32_bf16 v[122:125], v[166:169], v[194:197], v[122:125]
	v_mfma_f32_16x16x32_bf16 v[114:117], v[158:161], v[202:205], v[114:117]
	v_mfma_f32_16x16x32_bf16 v[106:109], v[166:169], v[202:205], v[106:109]
	v_mfma_f32_16x16x32_bf16 v[98:101], v[158:161], v[210:213], v[98:101]
	v_mfma_f32_16x16x32_bf16 v[90:93], v[166:169], v[210:213], v[90:93]
	v_mfma_f32_16x16x32_bf16 v[82:85], v[158:161], v[218:221], v[82:85]
	v_mfma_f32_16x16x32_bf16 v[74:77], v[166:169], v[218:221], v[74:77]
	v_mfma_f32_16x16x32_bf16 v[118:121], v[174:177], v[190:193], v[118:121]
	v_mfma_f32_16x16x32_bf16 v[110:113], v[182:185], v[190:193], v[110:113]
	v_mfma_f32_16x16x32_bf16 v[102:105], v[174:177], v[198:201], v[102:105]
	v_mfma_f32_16x16x32_bf16 v[94:97], v[182:185], v[198:201], v[94:97]
	v_mfma_f32_16x16x32_bf16 v[86:89], v[174:177], v[206:209], v[86:89]
	v_mfma_f32_16x16x32_bf16 v[78:81], v[182:185], v[206:209], v[78:81]
	v_mfma_f32_16x16x32_bf16 v[70:73], v[174:177], v[214:217], v[70:73]
	v_mfma_f32_16x16x32_bf16 v[66:69], v[182:185], v[214:217], v[66:69]
	v_mfma_f32_16x16x32_bf16 v[118:121], v[178:181], v[194:197], v[118:121]
	v_mfma_f32_16x16x32_bf16 v[110:113], v[186:189], v[194:197], v[110:113]
	v_mfma_f32_16x16x32_bf16 v[102:105], v[178:181], v[202:205], v[102:105]
	v_mfma_f32_16x16x32_bf16 v[94:97], v[186:189], v[202:205], v[94:97]
	v_mfma_f32_16x16x32_bf16 v[86:89], v[178:181], v[210:213], v[86:89]
	v_mfma_f32_16x16x32_bf16 v[78:81], v[186:189], v[210:213], v[78:81]
	v_mfma_f32_16x16x32_bf16 v[70:73], v[178:181], v[218:221], v[70:73]
	v_mfma_f32_16x16x32_bf16 v[66:69], v[186:189], v[218:221], v[66:69]
	s_setprio 0
	s_barrier
; #define PG8_STAGE(bufoff, gbase, voff) do { _Pragma("unroll") for (int _i = 0; _i < 2; ++_i) \
;         __builtin_amdgcn_global_load_lds((const unsigned*)((const char*)(gbase) + (voff)[_i]), (PG8_LAS unsigned*)(lds + (bufoff) + ldsw + _i * 8192), 16, 0, 0); } while (0)
; #define PG8_LDA(dst, b, h) do { _Pragma("unroll") for (int m = 0; m < 4; ++m) _Pragma("unroll") for (int k = 0; k < 2; ++k) dst[m][k] = *(const PG8_LAS bf16x8*)(lds + PG8_SA(b, h) + aoff + m * 2048 + k * 1024); } while (0)
; #define PG8_MMA(ai, bj, At, Bt) do { __builtin_amdgcn_s_setprio(1); _Pragma("unroll") for (int m = 0; m < 4; ++m) _Pragma("unroll") for (int n = 0; n < 2; ++n) _Pragma("unroll") for (int k = 0; k < 2; ++k) \
;         acc[ai][bj][m][n] = __builtin_amdgcn_mfma_f32_16x16x32_bf16(Bt[n][k], At[m][k], acc[ai][bj][m][n], 0, 0, 0); __builtin_amdgcn_s_setprio(0); } while (0)
; #define PG8_WAIT_V(n) asm volatile("s_waitcnt vmcnt(" #n ")" ::: "memory")
; #define PG8_WAIT_L(n) asm volatile("s_waitcnt lgkmcnt(" #n ")" ::: "memory")
; #define PG8_BAR __builtin_amdgcn_s_barrier()
; #define PG8_SCHED __builtin_amdgcn_sched_barrier(0)
; template <class Epi, class Sched, bool ALIGN_EPI = false, bool SP2 = false>
; __device__ __forceinline__ void gemm_phase(PG8_LAS unsigned char* lds, const Gemm g, const Sched& S, const Epi& E) {
;     ...
;             PG8_LDA(At, 1, 1); PG8_STAGE(PG8_SB(1, 0), b3, voffB); PG8_STAGE(PG8_SB(1, 1), b3 + hstep, voffB); PG8_STAGE(PG8_SA(1, 0), a3, voffA);
;             PG8_WAIT_V(8); PG8_WAIT_L(0); PG8_BAR; PG8_MMA(1, 0, At, B0); PG8_MMA(1, 1, At, B1); PG8_BAR; PG8_SCHED;
;     ...
;         if constexpr (ALIGN_EPI) { if (wr == 0) PG8_BAR; }
	s_add_i32 s34, s65, s42
	v_lshl_add_u64 v[150:151], v[150:151], 0, s[8:9]
	s_mov_b32 m0, s34
	ds_read_b128 v[190:193], v156 offset:49152
	ds_read_b128 v[194:197], v156 offset:50176
	ds_read_b128 v[198:201], v156 offset:51200
	ds_read_b128 v[202:205], v156 offset:52224
	ds_read_b128 v[206:209], v156 offset:53248
	ds_read_b128 v[210:213], v156 offset:54272
	ds_read_b128 v[214:217], v156 offset:55296
	ds_read_b128 v[218:221], v156 offset:56320
	global_load_lds_dwordx4 v[150:151], off
	s_add_i32 m0, s34, 0x2000
	s_add_u32 s30, s30, 0x40080
	v_lshl_add_u64 v[150:151], v[170:171], 0, s[8:9]
	s_addc_u32 s31, s31, 0
	s_add_i32 s34, s66, s42
	global_load_lds_dwordx4 v[150:151], off
	v_lshl_add_u64 v[150:151], s[30:31], 0, v[132:133]
	s_mov_b32 m0, s34
	s_nop 0
	global_load_lds_dwordx4 v[150:151], off
	v_lshl_add_u64 v[150:151], s[30:31], 0, v[136:137]
	s_add_i32 m0, s34, 0x2000
	s_nop 0
	global_load_lds_dwordx4 v[150:151], off
	v_lshl_add_u64 v[150:151], v[222:223], 0, s[8:9]
	s_mov_b32 m0, s53
	s_nop 0
	global_load_lds_dwordx4 v[150:151], off
	v_lshl_add_u64 v[150:151], v[224:225], 0, s[8:9]
	s_mov_b32 m0, s54
	s_nop 0
	global_load_lds_dwordx4 v[150:151], off
	s_waitcnt vmcnt(8)
	s_waitcnt lgkmcnt(0)
	s_barrier
	s_setprio 1
	s_waitcnt lgkmcnt(0)
	v_mfma_f32_16x16x32_bf16 v[62:65], v[146:149], v[190:193], v[62:65]
	v_mfma_f32_16x16x32_bf16 v[58:61], v[162:165], v[190:193], v[58:61]
	v_mfma_f32_16x16x32_bf16 v[50:53], v[146:149], v[198:201], v[50:53]
	v_mfma_f32_16x16x32_bf16 v[42:45], v[162:165], v[198:201], v[42:45]
	v_mfma_f32_16x16x32_bf16 v[34:37], v[146:149], v[206:209], v[34:37]
	v_mfma_f32_16x16x32_bf16 v[26:29], v[162:165], v[206:209], v[26:29]
	v_mfma_f32_16x16x32_bf16 v[18:21], v[146:149], v[214:217], v[18:21]
	v_mfma_f32_16x16x32_bf16 v[10:13], v[162:165], v[214:217], v[10:13]
	v_mfma_f32_16x16x32_bf16 v[62:65], v[158:161], v[194:197], v[62:65]
	v_mfma_f32_16x16x32_bf16 v[58:61], v[166:169], v[194:197], v[58:61]
	v_mfma_f32_16x16x32_bf16 v[50:53], v[158:161], v[202:205], v[50:53]
	v_mfma_f32_16x16x32_bf16 v[42:45], v[166:169], v[202:205], v[42:45]
	v_mfma_f32_16x16x32_bf16 v[34:37], v[158:161], v[210:213], v[34:37]
	v_mfma_f32_16x16x32_bf16 v[26:29], v[166:169], v[210:213], v[26:29]
	v_mfma_f32_16x16x32_bf16 v[18:21], v[158:161], v[218:221], v[18:21]
	v_mfma_f32_16x16x32_bf16 v[10:13], v[166:169], v[218:221], v[10:13]
	v_mfma_f32_16x16x32_bf16 v[54:57], v[174:177], v[190:193], v[54:57]
	v_mfma_f32_16x16x32_bf16 v[46:49], v[182:185], v[190:193], v[46:49]
	v_mfma_f32_16x16x32_bf16 v[38:41], v[174:177], v[198:201], v[38:41]
	v_mfma_f32_16x16x32_bf16 v[30:33], v[182:185], v[198:201], v[30:33]
	v_mfma_f32_16x16x32_bf16 v[22:25], v[174:177], v[206:209], v[22:25]
	v_mfma_f32_16x16x32_bf16 v[14:17], v[182:185], v[206:209], v[14:17]
	v_mfma_f32_16x16x32_bf16 v[6:9], v[174:177], v[214:217], v[6:9]
	v_mfma_f32_16x16x32_bf16 v[2:5], v[182:185], v[214:217], v[2:5]
	v_mfma_f32_16x16x32_bf16 v[54:57], v[178:181], v[194:197], v[54:57]
	v_mfma_f32_16x16x32_bf16 v[46:49], v[186:189], v[194:197], v[46:49]
	v_mfma_f32_16x16x32_bf16 v[38:41], v[178:181], v[202:205], v[38:41]
	v_mfma_f32_16x16x32_bf16 v[30:33], v[186:189], v[202:205], v[30:33]
	v_mfma_f32_16x16x32_bf16 v[22:25], v[178:181], v[210:213], v[22:25]
	v_mfma_f32_16x16x32_bf16 v[14:17], v[186:189], v[210:213], v[14:17]
	v_mfma_f32_16x16x32_bf16 v[6:9], v[178:181], v[218:221], v[6:9]
	v_mfma_f32_16x16x32_bf16 v[2:5], v[186:189], v[218:221], v[2:5]
	s_setprio 0
	s_barrier
	s_add_i32 s64, s64, 2
	s_add_u32 s28, s28, 0x100
	s_addc_u32 s29, s29, 0
	s_add_u32 s62, s62, 0x100
	s_addc_u32 s63, s63, 0
	s_cmp_gt_u32 s64, 13
	s_cbranch_scc0 .LBB0_1314
	s_and_b64 vcc, exec, s[10:11]
	s_cbranch_vccz .LBB0_1317
	s_barrier

; #define PG8_STAGE(bufoff, gbase, voff) do { _Pragma("unroll") for (int _i = 0; _i < 2; ++_i) \
;         __builtin_amdgcn_global_load_lds((const unsigned*)((const char*)(gbase) + (voff)[_i]), (PG8_LAS unsigned*)(lds + (bufoff) + ldsw + _i * 8192), 16, 0, 0); } while (0)
; #define PG8_LDA(dst, b, h) do { _Pragma("unroll") for (int m = 0; m < 4; ++m) _Pragma("unroll") for (int k = 0; k < 2; ++k) dst[m][k] = *(const PG8_LAS bf16x8*)(lds + PG8_SA(b, h) + aoff + m * 2048 + k * 1024); } while (0)
; #define PG8_LDB(dst, b, h) do { _Pragma("unroll") for (int n = 0; n < 2; ++n) _Pragma("unroll") for (int k = 0; k < 2; ++k) dst[n][k] = *(const PG8_LAS bf16x8*)(lds + PG8_SB(b, h) + boff + n * 2048 + k * 1024); } while (0)
; #define PG8_SCHED __builtin_amdgcn_sched_barrier(0)
; template <class Epi, class Sched, bool ALIGN_EPI = false, bool SP2 = false>
; __device__ __forceinline__ void gemm_phase(PG8_LAS unsigned char* lds, const Gemm g, const Sched& S, const Epi& E) {
;     ...
;         const bool has_next = S.next(ui + 1, nxt);
;         const char* nA = has_next ? (const char*)g.A + (size_t)nxt.pm * tstep : cA; const char* nB = has_next ? (const char*)g.Bt + (size_t)nxt.pn * tstep : cB;
; #pragma nounroll
;         for (int t = 0; t < nt; t += 2) {
;             const bool last = (t == nt - 2);
;             const char* a1 = cA + (size_t)(t + 1) * kstep;
;             const char* a2 = last ? nA : cA + (size_t)(t + 2) * kstep; const char* b2 = last ? nB : cB + (size_t)(t + 2) * kstep;
;             const char* a3 = a2 + kstep; const char* b3 = b2 + kstep;
;             if (last && has_next) S.a_ready(nxt);
;             if constexpr (SP2) {
;             PG8_LDB(B0, 0, 0); PG8_LDB(B1, 0, 1); PG8_SCHED; PG8_LDA(At, 0, 0); PG8_STAGE(PG8_SA(1, 1), a1 + hstep, voffA);
.LBB0_1338:
	s_ashr_i32 s25, s24, 31
	s_lshl_b64 s[26:27], s[24:25], 18
	s_add_u32 s26, s42, s26
	s_addc_u32 s27, s43, s27
	s_and_b64 s[28:29], s[2:3], exec
	s_cselect_b32 s25, s27, s35
	s_cselect_b32 s64, s26, s34
	s_ashr_i32 s23, s22, 31
	s_lshl_b64 s[28:29], s[22:23], 18
	s_add_u32 s28, s44, s28
	s_addc_u32 s29, s45, s29
	s_and_b64 s[40:41], s[2:3], exec
	s_cselect_b32 s23, s29, s39
	s_cselect_b32 s65, s28, s38
	s_add_u32 s34, s34, 0x20080
	s_addc_u32 s35, s35, 0
	s_add_u32 s66, s38, 0x100
	s_addc_u32 s67, s39, 0
	s_mov_b32 s68, -2
	ds_read_b128 v[146:149], v154
	ds_read_b128 v[158:161], v154 offset:1024
	ds_read_b128 v[162:165], v154 offset:2048
	ds_read_b128 v[166:169], v154 offset:3072
	ds_read_b128 v[174:177], v155
	ds_read_b128 v[178:181], v155 offset:1024
	ds_read_b128 v[182:185], v155 offset:2048
	ds_read_b128 v[186:189], v155 offset:3072
	s_add_u32 s38, s34, 0xfffe0080
	s_addc_u32 s39, s35, -1
	s_cmp_eq_u32 s68, 4
	s_cselect_b32 s41, s25, s39
	s_cselect_b32 s40, s64, s38
	s_cselect_b32 s39, s23, s67
	s_cselect_b32 s38, s65, s66

; #define PG8_STAGE(bufoff, gbase, voff) do { _Pragma("unroll") for (int _i = 0; _i < 2; ++_i) \
;         __builtin_amdgcn_global_load_lds((const unsigned*)((const char*)(gbase) + (voff)[_i]), (PG8_LAS unsigned*)(lds + (bufoff) + ldsw + _i * 8192), 16, 0, 0); } while (0)
; #define PG8_LDA(dst, b, h) do { _Pragma("unroll") for (int m = 0; m < 4; ++m) _Pragma("unroll") for (int k = 0; k < 2; ++k) dst[m][k] = *(const PG8_LAS bf16x8*)(lds + PG8_SA(b, h) + aoff + m * 2048 + k * 1024); } while (0)
; #define PG8_LDB(dst, b, h) do { _Pragma("unroll") for (int n = 0; n < 2; ++n) _Pragma("unroll") for (int k = 0; k < 2; ++k) dst[n][k] = *(const PG8_LAS bf16x8*)(lds + PG8_SB(b, h) + boff + n * 2048 + k * 1024); } while (0)
; #define PG8_MMA(ai, bj, At, Bt) do { __builtin_amdgcn_s_setprio(1); _Pragma("unroll") for (int m = 0; m < 4; ++m) _Pragma("unroll") for (int n = 0; n < 2; ++n) _Pragma("unroll") for (int k = 0; k < 2; ++k) \
;         acc[ai][bj][m][n] = __builtin_amdgcn_mfma_f32_16x16x32_bf16(Bt[n][k], At[m][k], acc[ai][bj][m][n], 0, 0, 0); __builtin_amdgcn_s_setprio(0); } while (0)
; #define PG8_WAIT_V(n) asm volatile("s_waitcnt vmcnt(" #n ")" ::: "memory")
; #define PG8_WAIT_L(n) asm volatile("s_waitcnt lgkmcnt(" #n ")" ::: "memory")
; #define PG8_BAR __builtin_amdgcn_s_barrier()
; #define PG8_SCHED __builtin_amdgcn_sched_barrier(0)
; template <class Epi, class Sched, bool ALIGN_EPI = false, bool SP2 = false>
; __device__ __forceinline__ void gemm_phase(PG8_LAS unsigned char* lds, const Gemm g, const Sched& S, const Epi& E) {
;     ...
;             PG8_LDB(B0, 0, 0); PG8_LDB(B1, 0, 1); PG8_SCHED; PG8_LDA(At, 0, 0); PG8_STAGE(PG8_SA(1, 1), a1 + hstep, voffA);
;             PG8_WAIT_V(8); PG8_WAIT_L(0); PG8_BAR; PG8_MMA(0, 0, At, B0); PG8_MMA(0, 1, At, B1); PG8_BAR; PG8_SCHED;
;     ...
;                     for (int n = 0; n < 2; ++n) acc[a][b][m][n] = (f32x4){0.f, 0.f, 0.f, 0.f};
	v_lshl_add_u64 v[150:151], s[34:35], 0, v[138:139]
	s_add_i32 m0, s31, 0xc000
	ds_read_b128 v[190:193], v156
	ds_read_b128 v[194:197], v156 offset:1024
	ds_read_b128 v[198:201], v156 offset:2048
	ds_read_b128 v[202:205], v156 offset:3072
	ds_read_b128 v[206:209], v156 offset:4096
	ds_read_b128 v[210:213], v156 offset:5120
	ds_read_b128 v[214:217], v156 offset:6144
	ds_read_b128 v[218:221], v156 offset:7168
	global_load_lds_dwordx4 v[150:151], off
	v_lshl_add_u64 v[150:151], s[34:35], 0, v[140:141]
	s_add_i32 m0, s31, 0xe000
	s_nop 0
	global_load_lds_dwordx4 v[150:151], off
	s_waitcnt vmcnt(56)
	s_waitcnt lgkmcnt(0)
	s_barrier
	s_setprio 1
	s_waitcnt lgkmcnt(0)
	v_mfma_f32_16x16x32_bf16 v[126:129], v[146:149], v[190:193], 0
	v_mfma_f32_16x16x32_bf16 v[122:125], v[162:165], v[190:193], 0
	v_mfma_f32_16x16x32_bf16 v[110:113], v[146:149], v[198:201], 0
	v_mfma_f32_16x16x32_bf16 v[106:109], v[162:165], v[198:201], 0
	v_mfma_f32_16x16x32_bf16 v[94:97], v[146:149], v[206:209], 0
	v_mfma_f32_16x16x32_bf16 v[90:93], v[162:165], v[206:209], 0
	v_mfma_f32_16x16x32_bf16 v[78:81], v[146:149], v[214:217], 0
	v_mfma_f32_16x16x32_bf16 v[74:77], v[162:165], v[214:217], 0
	v_mfma_f32_16x16x32_bf16 v[126:129], v[158:161], v[194:197], v[126:129]
	v_mfma_f32_16x16x32_bf16 v[122:125], v[166:169], v[194:197], v[122:125]
	v_mfma_f32_16x16x32_bf16 v[110:113], v[158:161], v[202:205], v[110:113]
	v_mfma_f32_16x16x32_bf16 v[106:109], v[166:169], v[202:205], v[106:109]
	v_mfma_f32_16x16x32_bf16 v[94:97], v[158:161], v[210:213], v[94:97]
	v_mfma_f32_16x16x32_bf16 v[90:93], v[166:169], v[210:213], v[90:93]
	v_mfma_f32_16x16x32_bf16 v[78:81], v[158:161], v[218:221], v[78:81]
	v_mfma_f32_16x16x32_bf16 v[74:77], v[166:169], v[218:221], v[74:77]
	v_mfma_f32_16x16x32_bf16 v[118:121], v[174:177], v[190:193], 0
	v_mfma_f32_16x16x32_bf16 v[114:117], v[182:185], v[190:193], 0
	v_mfma_f32_16x16x32_bf16 v[102:105], v[174:177], v[198:201], 0
	v_mfma_f32_16x16x32_bf16 v[98:101], v[182:185], v[198:201], 0
	v_mfma_f32_16x16x32_bf16 v[86:89], v[174:177], v[206:209], 0
	v_mfma_f32_16x16x32_bf16 v[82:85], v[182:185], v[206:209], 0
	v_mfma_f32_16x16x32_bf16 v[70:73], v[174:177], v[214:217], 0
	v_mfma_f32_16x16x32_bf16 v[66:69], v[182:185], v[214:217], 0
	v_mfma_f32_16x16x32_bf16 v[118:121], v[178:181], v[194:197], v[118:121]
	v_mfma_f32_16x16x32_bf16 v[114:117], v[186:189], v[194:197], v[114:117]
	v_mfma_f32_16x16x32_bf16 v[102:105], v[178:181], v[202:205], v[102:105]
	v_mfma_f32_16x16x32_bf16 v[98:101], v[186:189], v[202:205], v[98:101]
	v_mfma_f32_16x16x32_bf16 v[86:89], v[178:181], v[210:213], v[86:89]
	v_mfma_f32_16x16x32_bf16 v[82:85], v[186:189], v[210:213], v[82:85]
	v_mfma_f32_16x16x32_bf16 v[70:73], v[178:181], v[218:221], v[70:73]
	v_mfma_f32_16x16x32_bf16 v[66:69], v[186:189], v[218:221], v[66:69]
	s_setprio 0
	s_barrier

; #define PG8_STAGE(bufoff, gbase, voff) do { _Pragma("unroll") for (int _i = 0; _i < 2; ++_i) \
;         __builtin_amdgcn_global_load_lds((const unsigned*)((const char*)(gbase) + (voff)[_i]), (PG8_LAS unsigned*)(lds + (bufoff) + ldsw + _i * 8192), 16, 0, 0); } while (0)
; #define PG8_LDA(dst, b, h) do { _Pragma("unroll") for (int m = 0; m < 4; ++m) _Pragma("unroll") for (int k = 0; k < 2; ++k) dst[m][k] = *(const PG8_LAS bf16x8*)(lds + PG8_SA(b, h) + aoff + m * 2048 + k * 1024); } while (0)
; #define PG8_MMA(ai, bj, At, Bt) do { __builtin_amdgcn_s_setprio(1); _Pragma("unroll") for (int m = 0; m < 4; ++m) _Pragma("unroll") for (int n = 0; n < 2; ++n) _Pragma("unroll") for (int k = 0; k < 2; ++k) \
;         acc[ai][bj][m][n] = __builtin_amdgcn_mfma_f32_16x16x32_bf16(Bt[n][k], At[m][k], acc[ai][bj][m][n], 0, 0, 0); __builtin_amdgcn_s_setprio(0); } while (0)
; #define PG8_WAIT_V(n) asm volatile("s_waitcnt vmcnt(" #n ")" ::: "memory")
; #define PG8_WAIT_L(n) asm volatile("s_waitcnt lgkmcnt(" #n ")" ::: "memory")
; #define PG8_BAR __builtin_amdgcn_s_barrier()
; #define PG8_SCHED __builtin_amdgcn_sched_barrier(0)
; template <class Epi, class Sched, bool ALIGN_EPI = false, bool SP2 = false>
; __device__ __forceinline__ void gemm_phase(PG8_LAS unsigned char* lds, const Gemm g, const Sched& S, const Epi& E) {
;     ...
;             PG8_LDA(At, 0, 1); PG8_STAGE(PG8_SB(0, 0), b2, voffB); PG8_STAGE(PG8_SB(0, 1), b2 + hstep, voffB); PG8_STAGE(PG8_SA(0, 0), a2, voffA);
;             PG8_WAIT_V(8); PG8_WAIT_L(0); PG8_BAR; PG8_MMA(1, 0, At, B0); PG8_MMA(1, 1, At, B1); PG8_BAR; PG8_SCHED;
;     ...
;                     for (int n = 0; n < 2; ++n) acc[a][b][m][n] = (f32x4){0.f, 0.f, 0.f, 0.f};
	s_add_i32 s69, s61, s52
	v_lshl_add_u64 v[150:151], s[38:39], 0, v[132:133]
	s_mov_b32 m0, s69
	ds_read_b128 v[190:193], v156 offset:16384
	ds_read_b128 v[194:197], v156 offset:17408
	ds_read_b128 v[198:201], v156 offset:18432
	ds_read_b128 v[202:205], v156 offset:19456
	ds_read_b128 v[206:209], v156 offset:20480
	ds_read_b128 v[210:213], v156 offset:21504
	ds_read_b128 v[214:217], v156 offset:22528
	ds_read_b128 v[218:221], v156 offset:23552
	global_load_lds_dwordx4 v[150:151], off
	s_add_i32 m0, s69, 0x2000
	s_add_u32 s70, s38, 0x20000
	v_lshl_add_u64 v[170:171], s[38:39], 0, v[136:137]
	s_addc_u32 s71, s39, 0
	s_add_i32 s69, s62, s52
	global_load_lds_dwordx4 v[170:171], off
	v_lshl_add_u64 v[222:223], s[70:71], 0, v[132:133]
	s_mov_b32 m0, s69
	v_lshl_add_u64 v[224:225], s[40:41], 0, v[134:135]
	global_load_lds_dwordx4 v[222:223], off
	v_lshl_add_u64 v[222:223], s[70:71], 0, v[136:137]
	s_add_i32 m0, s69, 0x2000
	s_nop 0
	global_load_lds_dwordx4 v[222:223], off
	v_lshl_add_u64 v[222:223], s[40:41], 0, v[130:131]
	s_mov_b32 m0, s31
	s_nop 0
	global_load_lds_dwordx4 v[222:223], off
	s_mov_b32 m0, s53
	s_nop 0
	global_load_lds_dwordx4 v[224:225], off
	s_waitcnt vmcnt(56)
	s_waitcnt lgkmcnt(0)
	s_barrier
	s_setprio 1
	s_waitcnt lgkmcnt(0)
	v_mfma_f32_16x16x32_bf16 v[62:65], v[146:149], v[190:193], 0
	v_mfma_f32_16x16x32_bf16 v[58:61], v[162:165], v[190:193], 0
	v_mfma_f32_16x16x32_bf16 v[46:49], v[146:149], v[198:201], 0
	v_mfma_f32_16x16x32_bf16 v[42:45], v[162:165], v[198:201], 0
	v_mfma_f32_16x16x32_bf16 v[30:33], v[146:149], v[206:209], 0
	v_mfma_f32_16x16x32_bf16 v[26:29], v[162:165], v[206:209], 0
	v_mfma_f32_16x16x32_bf16 v[14:17], v[146:149], v[214:217], 0
	v_mfma_f32_16x16x32_bf16 v[10:13], v[162:165], v[214:217], 0
	v_mfma_f32_16x16x32_bf16 v[62:65], v[158:161], v[194:197], v[62:65]
	v_mfma_f32_16x16x32_bf16 v[58:61], v[166:169], v[194:197], v[58:61]
	v_mfma_f32_16x16x32_bf16 v[46:49], v[158:161], v[202:205], v[46:49]
	v_mfma_f32_16x16x32_bf16 v[42:45], v[166:169], v[202:205], v[42:45]
	v_mfma_f32_16x16x32_bf16 v[30:33], v[158:161], v[210:213], v[30:33]
	v_mfma_f32_16x16x32_bf16 v[26:29], v[166:169], v[210:213], v[26:29]
	v_mfma_f32_16x16x32_bf16 v[14:17], v[158:161], v[218:221], v[14:17]
	v_mfma_f32_16x16x32_bf16 v[10:13], v[166:169], v[218:221], v[10:13]
	v_mfma_f32_16x16x32_bf16 v[54:57], v[174:177], v[190:193], 0
	v_mfma_f32_16x16x32_bf16 v[50:53], v[182:185], v[190:193], 0
	v_mfma_f32_16x16x32_bf16 v[38:41], v[174:177], v[198:201], 0
	v_mfma_f32_16x16x32_bf16 v[34:37], v[182:185], v[198:201], 0
	v_mfma_f32_16x16x32_bf16 v[22:25], v[174:177], v[206:209], 0
	v_mfma_f32_16x16x32_bf16 v[18:21], v[182:185], v[206:209], 0
	v_mfma_f32_16x16x32_bf16 v[6:9], v[174:177], v[214:217], 0
	v_mfma_f32_16x16x32_bf16 v[2:5], v[182:185], v[214:217], 0
	v_mfma_f32_16x16x32_bf16 v[54:57], v[178:181], v[194:197], v[54:57]
	v_mfma_f32_16x16x32_bf16 v[50:53], v[186:189], v[194:197], v[50:53]
	v_mfma_f32_16x16x32_bf16 v[38:41], v[178:181], v[202:205], v[38:41]
	v_mfma_f32_16x16x32_bf16 v[34:37], v[186:189], v[202:205], v[34:37]
	v_mfma_f32_16x16x32_bf16 v[22:25], v[178:181], v[210:213], v[22:25]
	v_mfma_f32_16x16x32_bf16 v[18:21], v[186:189], v[210:213], v[18:21]
	v_mfma_f32_16x16x32_bf16 v[6:9], v[178:181], v[218:221], v[6:9]
	v_mfma_f32_16x16x32_bf16 v[2:5], v[186:189], v[218:221], v[2:5]
	s_setprio 0
	s_barrier

; #define PG8_STAGE(bufoff, gbase, voff) do { _Pragma("unroll") for (int _i = 0; _i < 2; ++_i) \
;         __builtin_amdgcn_global_load_lds((const unsigned*)((const char*)(gbase) + (voff)[_i]), (PG8_LAS unsigned*)(lds + (bufoff) + ldsw + _i * 8192), 16, 0, 0); } while (0)
; #define PG8_LDA(dst, b, h) do { _Pragma("unroll") for (int m = 0; m < 4; ++m) _Pragma("unroll") for (int k = 0; k < 2; ++k) dst[m][k] = *(const PG8_LAS bf16x8*)(lds + PG8_SA(b, h) + aoff + m * 2048 + k * 1024); } while (0)
; #define PG8_LDB(dst, b, h) do { _Pragma("unroll") for (int n = 0; n < 2; ++n) _Pragma("unroll") for (int k = 0; k < 2; ++k) dst[n][k] = *(const PG8_LAS bf16x8*)(lds + PG8_SB(b, h) + boff + n * 2048 + k * 1024); } while (0)
; #define PG8_SCHED __builtin_amdgcn_sched_barrier(0)
; template <class Epi, class Sched, bool ALIGN_EPI = false, bool SP2 = false>
; __device__ __forceinline__ void gemm_phase(PG8_LAS unsigned char* lds, const Gemm g, const Sched& S, const Epi& E) {
;     ...
;             PG8_LDB(B0, 1, 0); PG8_LDB(B1, 1, 1); PG8_SCHED; PG8_LDA(At, 1, 0); PG8_STAGE(PG8_SA(0, 1), a2 + hstep, voffA);
	s_add_i32 s69, 0, 0x18000
	v_add_u32_e32 v157, s69, v152
	s_add_i32 s70, 0, 0x1c000
	ds_read_b128 v[146:149], v157
	ds_read_b128 v[158:161], v157 offset:1024
	ds_read_b128 v[162:165], v157 offset:2048
	ds_read_b128 v[166:169], v157 offset:3072
	v_add_u32_e32 v157, s70, v152
	ds_read_b128 v[174:177], v157
	ds_read_b128 v[178:181], v157 offset:1024
	ds_read_b128 v[182:185], v157 offset:2048
	ds_read_b128 v[186:189], v157 offset:3072

; #define PG8_STAGE(bufoff, gbase, voff) do { _Pragma("unroll") for (int _i = 0; _i < 2; ++_i) \
;         __builtin_amdgcn_global_load_lds((const unsigned*)((const char*)(gbase) + (voff)[_i]), (PG8_LAS unsigned*)(lds + (bufoff) + ldsw + _i * 8192), 16, 0, 0); } while (0)
; #define PG8_LDA(dst, b, h) do { _Pragma("unroll") for (int m = 0; m < 4; ++m) _Pragma("unroll") for (int k = 0; k < 2; ++k) dst[m][k] = *(const PG8_LAS bf16x8*)(lds + PG8_SA(b, h) + aoff + m * 2048 + k * 1024); } while (0)
; #define PG8_LDB(dst, b, h) do { _Pragma("unroll") for (int n = 0; n < 2; ++n) _Pragma("unroll") for (int k = 0; k < 2; ++k) dst[n][k] = *(const PG8_LAS bf16x8*)(lds + PG8_SB(b, h) + boff + n * 2048 + k * 1024); } while (0)
; #define PG8_MMA(ai, bj, At, Bt) do { __builtin_amdgcn_s_setprio(1); _Pragma("unroll") for (int m = 0; m < 4; ++m) _Pragma("unroll") for (int n = 0; n < 2; ++n) _Pragma("unroll") for (int k = 0; k < 2; ++k) \
;         acc[ai][bj][m][n] = __builtin_amdgcn_mfma_f32_16x16x32_bf16(Bt[n][k], At[m][k], acc[ai][bj][m][n], 0, 0, 0); __builtin_amdgcn_s_setprio(0); } while (0)
; #define PG8_WAIT_V(n) asm volatile("s_waitcnt vmcnt(" #n ")" ::: "memory")
; #define PG8_WAIT_L(n) asm volatile("s_waitcnt lgkmcnt(" #n ")" ::: "memory")
; #define PG8_BAR __builtin_amdgcn_s_barrier()
; #define PG8_SCHED __builtin_amdgcn_sched_barrier(0)
; template <class Epi, class Sched, bool ALIGN_EPI = false, bool SP2 = false>
; __device__ __forceinline__ void gemm_phase(PG8_LAS unsigned char* lds, const Gemm g, const Sched& S, const Epi& E) {
;     ...
;             PG8_LDB(B0, 1, 0); PG8_LDB(B1, 1, 1); PG8_SCHED; PG8_LDA(At, 1, 0); PG8_STAGE(PG8_SA(0, 1), a2 + hstep, voffA);
;             PG8_WAIT_V(8); PG8_WAIT_L(0); PG8_BAR; PG8_MMA(0, 0, At, B0); PG8_MMA(0, 1, At, B1); PG8_BAR; PG8_SCHED;
	s_add_u32 s40, s40, 0x20000
	s_addc_u32 s41, s41, 0
	s_mov_b32 m0, s54
	v_lshl_add_u64 v[226:227], s[40:41], 0, v[130:131]
	ds_read_b128 v[190:193], v156 offset:32768
	ds_read_b128 v[194:197], v156 offset:33792
	ds_read_b128 v[198:201], v156 offset:34816
	ds_read_b128 v[202:205], v156 offset:35840
	ds_read_b128 v[206:209], v156 offset:36864
	ds_read_b128 v[210:213], v156 offset:37888
	ds_read_b128 v[214:217], v156 offset:38912
	ds_read_b128 v[218:221], v156 offset:39936
	global_load_lds_dwordx4 v[226:227], off
	v_lshl_add_u64 v[226:227], s[40:41], 0, v[134:135]
	s_mov_b32 m0, s55
	s_nop 0
	global_load_lds_dwordx4 v[226:227], off
	s_waitcnt vmcnt(8)
	s_waitcnt lgkmcnt(0)
	s_barrier
	s_setprio 1
	s_waitcnt lgkmcnt(0)
	v_mfma_f32_16x16x32_bf16 v[126:129], v[146:149], v[190:193], v[126:129]
	v_mfma_f32_16x16x32_bf16 v[122:125], v[162:165], v[190:193], v[122:125]
	v_mfma_f32_16x16x32_bf16 v[110:113], v[146:149], v[198:201], v[110:113]
	v_mfma_f32_16x16x32_bf16 v[106:109], v[162:165], v[198:201], v[106:109]
	v_mfma_f32_16x16x32_bf16 v[94:97], v[146:149], v[206:209], v[94:97]
	v_mfma_f32_16x16x32_bf16 v[90:93], v[162:165], v[206:209], v[90:93]
	v_mfma_f32_16x16x32_bf16 v[78:81], v[146:149], v[214:217], v[78:81]
	v_mfma_f32_16x16x32_bf16 v[74:77], v[162:165], v[214:217], v[74:77]
	v_mfma_f32_16x16x32_bf16 v[126:129], v[158:161], v[194:197], v[126:129]
	v_mfma_f32_16x16x32_bf16 v[122:125], v[166:169], v[194:197], v[122:125]
	v_mfma_f32_16x16x32_bf16 v[110:113], v[158:161], v[202:205], v[110:113]
	v_mfma_f32_16x16x32_bf16 v[106:109], v[166:169], v[202:205], v[106:109]
	v_mfma_f32_16x16x32_bf16 v[94:97], v[158:161], v[210:213], v[94:97]
	v_mfma_f32_16x16x32_bf16 v[90:93], v[166:169], v[210:213], v[90:93]
	v_mfma_f32_16x16x32_bf16 v[78:81], v[158:161], v[218:221], v[78:81]
	v_mfma_f32_16x16x32_bf16 v[74:77], v[166:169], v[218:221], v[74:77]
	v_mfma_f32_16x16x32_bf16 v[118:121], v[174:177], v[190:193], v[118:121]
	v_mfma_f32_16x16x32_bf16 v[114:117], v[182:185], v[190:193], v[114:117]
	v_mfma_f32_16x16x32_bf16 v[102:105], v[174:177], v[198:201], v[102:105]
	v_mfma_f32_16x16x32_bf16 v[98:101], v[182:185], v[198:201], v[98:101]
	v_mfma_f32_16x16x32_bf16 v[86:89], v[174:177], v[206:209], v[86:89]
	v_mfma_f32_16x16x32_bf16 v[82:85], v[182:185], v[206:209], v[82:85]
	v_mfma_f32_16x16x32_bf16 v[70:73], v[174:177], v[214:217], v[70:73]
	v_mfma_f32_16x16x32_bf16 v[66:69], v[182:185], v[214:217], v[66:69]
	v_mfma_f32_16x16x32_bf16 v[118:121], v[178:181], v[194:197], v[118:121]
	v_mfma_f32_16x16x32_bf16 v[114:117], v[186:189], v[194:197], v[114:117]
	v_mfma_f32_16x16x32_bf16 v[102:105], v[178:181], v[202:205], v[102:105]
	v_mfma_f32_16x16x32_bf16 v[98:101], v[186:189], v[202:205], v[98:101]
	v_mfma_f32_16x16x32_bf16 v[86:89], v[178:181], v[210:213], v[86:89]
	v_mfma_f32_16x16x32_bf16 v[82:85], v[186:189], v[210:213], v[82:85]
	v_mfma_f32_16x16x32_bf16 v[70:73], v[178:181], v[218:221], v[70:73]
	v_mfma_f32_16x16x32_bf16 v[66:69], v[186:189], v[218:221], v[66:69]
	s_setprio 0
	s_barrier

; #define PG8_STAGE(bufoff, gbase, voff) do { _Pragma("unroll") for (int _i = 0; _i < 2; ++_i) \
;         __builtin_amdgcn_global_load_lds((const unsigned*)((const char*)(gbase) + (voff)[_i]), (PG8_LAS unsigned*)(lds + (bufoff) + ldsw + _i * 8192), 16, 0, 0); } while (0)
; #define PG8_LDA(dst, b, h) do { _Pragma("unroll") for (int m = 0; m < 4; ++m) _Pragma("unroll") for (int k = 0; k < 2; ++k) dst[m][k] = *(const PG8_LAS bf16x8*)(lds + PG8_SA(b, h) + aoff + m * 2048 + k * 1024); } while (0)
; #define PG8_MMA(ai, bj, At, Bt) do { __builtin_amdgcn_s_setprio(1); _Pragma("unroll") for (int m = 0; m < 4; ++m) _Pragma("unroll") for (int n = 0; n < 2; ++n) _Pragma("unroll") for (int k = 0; k < 2; ++k) \
;         acc[ai][bj][m][n] = __builtin_amdgcn_mfma_f32_16x16x32_bf16(Bt[n][k], At[m][k], acc[ai][bj][m][n], 0, 0, 0); __builtin_amdgcn_s_setprio(0); } while (0)
; #define PG8_WAIT_V(n) asm volatile("s_waitcnt vmcnt(" #n ")" ::: "memory")
; #define PG8_WAIT_L(n) asm volatile("s_waitcnt lgkmcnt(" #n ")" ::: "memory")
; #define PG8_BAR __builtin_amdgcn_s_barrier()
; #define PG8_SCHED __builtin_amdgcn_sched_barrier(0)
; template <class Epi, class Sched, bool ALIGN_EPI = false, bool SP2 = false>
; __device__ __forceinline__ void gemm_phase(PG8_LAS unsigned char* lds, const Gemm g, const Sched& S, const Epi& E) {
;     ...
;             PG8_LDA(At, 1, 1); PG8_STAGE(PG8_SB(1, 0), b3, voffB); PG8_STAGE(PG8_SB(1, 1), b3 + hstep, voffB); PG8_STAGE(PG8_SA(1, 0), a3, voffA);
;             PG8_WAIT_V(8); PG8_WAIT_L(0); PG8_BAR; PG8_MMA(1, 0, At, B0); PG8_MMA(1, 1, At, B1); PG8_BAR; PG8_SCHED;
	s_add_i32 s40, s69, s52
	v_lshl_add_u64 v[150:151], v[150:151], 0, s[10:11]
	s_mov_b32 m0, s40
	ds_read_b128 v[190:193], v156 offset:49152
	ds_read_b128 v[194:197], v156 offset:50176
	ds_read_b128 v[198:201], v156 offset:51200
	ds_read_b128 v[202:205], v156 offset:52224
	ds_read_b128 v[206:209], v156 offset:53248
	ds_read_b128 v[210:213], v156 offset:54272
	ds_read_b128 v[214:217], v156 offset:55296
	ds_read_b128 v[218:221], v156 offset:56320
	global_load_lds_dwordx4 v[150:151], off
	s_add_i32 m0, s40, 0x2000
	s_add_u32 s38, s38, 0x20080
	v_lshl_add_u64 v[150:151], v[170:171], 0, s[10:11]
	s_addc_u32 s39, s39, 0
	s_add_i32 s40, s70, s52
	global_load_lds_dwordx4 v[150:151], off
	v_lshl_add_u64 v[150:151], s[38:39], 0, v[132:133]
	s_mov_b32 m0, s40
	s_nop 0
	global_load_lds_dwordx4 v[150:151], off
	v_lshl_add_u64 v[150:151], s[38:39], 0, v[136:137]
	s_add_i32 m0, s40, 0x2000
	s_nop 0
	global_load_lds_dwordx4 v[150:151], off
	v_lshl_add_u64 v[150:151], v[222:223], 0, s[10:11]
	s_mov_b32 m0, s57
	s_nop 0
	global_load_lds_dwordx4 v[150:151], off
	v_lshl_add_u64 v[150:151], v[224:225], 0, s[10:11]
	s_mov_b32 m0, s58
	s_nop 0
	global_load_lds_dwordx4 v[150:151], off
	s_waitcnt vmcnt(8)
	s_waitcnt lgkmcnt(0)
	s_barrier
	s_setprio 1
	s_waitcnt lgkmcnt(0)
	v_mfma_f32_16x16x32_bf16 v[62:65], v[146:149], v[190:193], v[62:65]
	v_mfma_f32_16x16x32_bf16 v[58:61], v[162:165], v[190:193], v[58:61]
	v_mfma_f32_16x16x32_bf16 v[46:49], v[146:149], v[198:201], v[46:49]
	v_mfma_f32_16x16x32_bf16 v[42:45], v[162:165], v[198:201], v[42:45]
	v_mfma_f32_16x16x32_bf16 v[30:33], v[146:149], v[206:209], v[30:33]
	v_mfma_f32_16x16x32_bf16 v[26:29], v[162:165], v[206:209], v[26:29]
	v_mfma_f32_16x16x32_bf16 v[14:17], v[146:149], v[214:217], v[14:17]
	v_mfma_f32_16x16x32_bf16 v[10:13], v[162:165], v[214:217], v[10:13]
	v_mfma_f32_16x16x32_bf16 v[62:65], v[158:161], v[194:197], v[62:65]
	v_mfma_f32_16x16x32_bf16 v[58:61], v[166:169], v[194:197], v[58:61]
	v_mfma_f32_16x16x32_bf16 v[46:49], v[158:161], v[202:205], v[46:49]
	v_mfma_f32_16x16x32_bf16 v[42:45], v[166:169], v[202:205], v[42:45]
	v_mfma_f32_16x16x32_bf16 v[30:33], v[158:161], v[210:213], v[30:33]
	v_mfma_f32_16x16x32_bf16 v[26:29], v[166:169], v[210:213], v[26:29]
	v_mfma_f32_16x16x32_bf16 v[14:17], v[158:161], v[218:221], v[14:17]
	v_mfma_f32_16x16x32_bf16 v[10:13], v[166:169], v[218:221], v[10:13]
	v_mfma_f32_16x16x32_bf16 v[54:57], v[174:177], v[190:193], v[54:57]
	v_mfma_f32_16x16x32_bf16 v[50:53], v[182:185], v[190:193], v[50:53]
	v_mfma_f32_16x16x32_bf16 v[38:41], v[174:177], v[198:201], v[38:41]
	v_mfma_f32_16x16x32_bf16 v[34:37], v[182:185], v[198:201], v[34:37]
	v_mfma_f32_16x16x32_bf16 v[22:25], v[174:177], v[206:209], v[22:25]
	v_mfma_f32_16x16x32_bf16 v[18:21], v[182:185], v[206:209], v[18:21]
	v_mfma_f32_16x16x32_bf16 v[6:9], v[174:177], v[214:217], v[6:9]
	v_mfma_f32_16x16x32_bf16 v[2:5], v[182:185], v[214:217], v[2:5]
	v_mfma_f32_16x16x32_bf16 v[54:57], v[178:181], v[194:197], v[54:57]
	v_mfma_f32_16x16x32_bf16 v[50:53], v[186:189], v[194:197], v[50:53]
	v_mfma_f32_16x16x32_bf16 v[38:41], v[178:181], v[202:205], v[38:41]
	v_mfma_f32_16x16x32_bf16 v[34:37], v[186:189], v[202:205], v[34:37]
	v_mfma_f32_16x16x32_bf16 v[22:25], v[178:181], v[210:213], v[22:25]
	v_mfma_f32_16x16x32_bf16 v[18:21], v[186:189], v[210:213], v[18:21]
	v_mfma_f32_16x16x32_bf16 v[6:9], v[178:181], v[218:221], v[6:9]
	v_mfma_f32_16x16x32_bf16 v[2:5], v[186:189], v[218:221], v[2:5]
	s_setprio 0
	s_barrier

; #define PG8_STAGE(bufoff, gbase, voff) do { _Pragma("unroll") for (int _i = 0; _i < 2; ++_i) \
;         __builtin_amdgcn_global_load_lds((const unsigned*)((const char*)(gbase) + (voff)[_i]), (PG8_LAS unsigned*)(lds + (bufoff) + ldsw + _i * 8192), 16, 0, 0); } while (0)
; #define PG8_LDA(dst, b, h) do { _Pragma("unroll") for (int m = 0; m < 4; ++m) _Pragma("unroll") for (int k = 0; k < 2; ++k) dst[m][k] = *(const PG8_LAS bf16x8*)(lds + PG8_SA(b, h) + aoff + m * 2048 + k * 1024); } while (0)
; #define PG8_LDB(dst, b, h) do { _Pragma("unroll") for (int n = 0; n < 2; ++n) _Pragma("unroll") for (int k = 0; k < 2; ++k) dst[n][k] = *(const PG8_LAS bf16x8*)(lds + PG8_SB(b, h) + boff + n * 2048 + k * 1024); } while (0)
; #define PG8_MMA(ai, bj, At, Bt) do { __builtin_amdgcn_s_setprio(1); _Pragma("unroll") for (int m = 0; m < 4; ++m) _Pragma("unroll") for (int n = 0; n < 2; ++n) _Pragma("unroll") for (int k = 0; k < 2; ++k) \
;         acc[ai][bj][m][n] = __builtin_amdgcn_mfma_f32_16x16x32_bf16(Bt[n][k], At[m][k], acc[ai][bj][m][n], 0, 0, 0); __builtin_amdgcn_s_setprio(0); } while (0)
; #define PG8_WAIT_V(n) asm volatile("s_waitcnt vmcnt(" #n ")" ::: "memory")
; #define PG8_WAIT_L(n) asm volatile("s_waitcnt lgkmcnt(" #n ")" ::: "memory")
; #define PG8_BAR __builtin_amdgcn_s_barrier()
; #define PG8_SCHED __builtin_amdgcn_sched_barrier(0)
; template <class Epi, class Sched, bool ALIGN_EPI = false, bool SP2 = false>
; __device__ __forceinline__ void gemm_phase(PG8_LAS unsigned char* lds, const Gemm g, const Sched& S, const Epi& E) {
;     ...
;             const bool last = (t == nt - 2);
;             const char* a1 = cA + (size_t)(t + 1) * kstep;
;             const char* a2 = last ? nA : cA + (size_t)(t + 2) * kstep; const char* b2 = last ? nB : cB + (size_t)(t + 2) * kstep;
;             const char* a3 = a2 + kstep; const char* b3 = b2 + kstep;
;             if (last && has_next) S.a_ready(nxt);
;             if constexpr (SP2) {
;             PG8_LDB(B0, 0, 0); PG8_LDB(B1, 0, 1); PG8_SCHED; PG8_LDA(At, 0, 0); PG8_STAGE(PG8_SA(1, 1), a1 + hstep, voffA);
;             PG8_WAIT_V(8); PG8_WAIT_L(0); PG8_BAR; PG8_MMA(0, 0, At, B0); PG8_MMA(0, 1, At, B1); PG8_BAR; PG8_SCHED;
;             PG8_LDA(At, 0, 1); PG8_STAGE(PG8_SB(0, 0), b2, voffB); PG8_STAGE(PG8_SB(0, 1), b2 + hstep, voffB); PG8_STAGE(PG8_SA(0, 0), a2, voffA);
	s_add_i32 s68, s68, 2
	s_add_u32 s34, s34, 0x100
	s_addc_u32 s35, s35, 0
	s_add_u32 s66, s66, 0x100
	s_addc_u32 s67, s67, 0
.LBB0_1339:
	ds_read_b128 v[146:149], v154
	ds_read_b128 v[158:161], v154 offset:1024
	ds_read_b128 v[162:165], v154 offset:2048
	ds_read_b128 v[166:169], v154 offset:3072
	ds_read_b128 v[174:177], v155
	ds_read_b128 v[178:181], v155 offset:1024
	ds_read_b128 v[182:185], v155 offset:2048
	ds_read_b128 v[186:189], v155 offset:3072
	s_add_u32 s38, s34, 0xfffe0080
	s_addc_u32 s39, s35, -1
	s_cmp_eq_u32 s68, 4
	s_cselect_b32 s41, s25, s39
	s_cselect_b32 s40, s64, s38
	s_cselect_b32 s39, s23, s67
	s_cselect_b32 s38, s65, s66
	v_lshl_add_u64 v[150:151], s[34:35], 0, v[138:139]
	s_add_i32 m0, s31, 0xc000
	ds_read_b128 v[190:193], v156
	ds_read_b128 v[194:197], v156 offset:1024
	ds_read_b128 v[198:201], v156 offset:2048
	ds_read_b128 v[202:205], v156 offset:3072
	ds_read_b128 v[206:209], v156 offset:4096
	ds_read_b128 v[210:213], v156 offset:5120
	ds_read_b128 v[214:217], v156 offset:6144
	ds_read_b128 v[218:221], v156 offset:7168
	global_load_lds_dwordx4 v[150:151], off
	v_lshl_add_u64 v[150:151], s[34:35], 0, v[140:141]
	s_add_i32 m0, s31, 0xe000
	s_nop 0
	global_load_lds_dwordx4 v[150:151], off
	s_waitcnt vmcnt(8)
	s_waitcnt lgkmcnt(0)
	s_barrier
	s_setprio 1
	s_waitcnt lgkmcnt(0)
	v_mfma_f32_16x16x32_bf16 v[126:129], v[146:149], v[190:193], v[126:129]
	v_mfma_f32_16x16x32_bf16 v[122:125], v[162:165], v[190:193], v[122:125]
	v_mfma_f32_16x16x32_bf16 v[110:113], v[146:149], v[198:201], v[110:113]
	v_mfma_f32_16x16x32_bf16 v[106:109], v[162:165], v[198:201], v[106:109]
	v_mfma_f32_16x16x32_bf16 v[94:97], v[146:149], v[206:209], v[94:97]
	v_mfma_f32_16x16x32_bf16 v[90:93], v[162:165], v[206:209], v[90:93]
	v_mfma_f32_16x16x32_bf16 v[78:81], v[146:149], v[214:217], v[78:81]
	v_mfma_f32_16x16x32_bf16 v[74:77], v[162:165], v[214:217], v[74:77]
	v_mfma_f32_16x16x32_bf16 v[126:129], v[158:161], v[194:197], v[126:129]
	v_mfma_f32_16x16x32_bf16 v[122:125], v[166:169], v[194:197], v[122:125]
	v_mfma_f32_16x16x32_bf16 v[110:113], v[158:161], v[202:205], v[110:113]
	v_mfma_f32_16x16x32_bf16 v[106:109], v[166:169], v[202:205], v[106:109]
	v_mfma_f32_16x16x32_bf16 v[94:97], v[158:161], v[210:213], v[94:97]
	v_mfma_f32_16x16x32_bf16 v[90:93], v[166:169], v[210:213], v[90:93]
	v_mfma_f32_16x16x32_bf16 v[78:81], v[158:161], v[218:221], v[78:81]
	v_mfma_f32_16x16x32_bf16 v[74:77], v[166:169], v[218:221], v[74:77]
	v_mfma_f32_16x16x32_bf16 v[118:121], v[174:177], v[190:193], v[118:121]
	v_mfma_f32_16x16x32_bf16 v[114:117], v[182:185], v[190:193], v[114:117]
	v_mfma_f32_16x16x32_bf16 v[102:105], v[174:177], v[198:201], v[102:105]
	v_mfma_f32_16x16x32_bf16 v[98:101], v[182:185], v[198:201], v[98:101]
	v_mfma_f32_16x16x32_bf16 v[86:89], v[174:177], v[206:209], v[86:89]
	v_mfma_f32_16x16x32_bf16 v[82:85], v[182:185], v[206:209], v[82:85]
	v_mfma_f32_16x16x32_bf16 v[70:73], v[174:177], v[214:217], v[70:73]
	v_mfma_f32_16x16x32_bf16 v[66:69], v[182:185], v[214:217], v[66:69]
	v_mfma_f32_16x16x32_bf16 v[118:121], v[178:181], v[194:197], v[118:121]
	v_mfma_f32_16x16x32_bf16 v[114:117], v[186:189], v[194:197], v[114:117]
	v_mfma_f32_16x16x32_bf16 v[102:105], v[178:181], v[202:205], v[102:105]
	v_mfma_f32_16x16x32_bf16 v[98:101], v[186:189], v[202:205], v[98:101]
	v_mfma_f32_16x16x32_bf16 v[86:89], v[178:181], v[210:213], v[86:89]
	v_mfma_f32_16x16x32_bf16 v[82:85], v[186:189], v[210:213], v[82:85]
	v_mfma_f32_16x16x32_bf16 v[70:73], v[178:181], v[218:221], v[70:73]
	v_mfma_f32_16x16x32_bf16 v[66:69], v[186:189], v[218:221], v[66:69]
	s_setprio 0
	s_barrier
	s_add_i32 s69, s61, s52
	v_lshl_add_u64 v[150:151], s[38:39], 0, v[132:133]
	s_mov_b32 m0, s69
	ds_read_b128 v[190:193], v156 offset:16384
	ds_read_b128 v[194:197], v156 offset:17408
	ds_read_b128 v[198:201], v156 offset:18432
	ds_read_b128 v[202:205], v156 offset:19456
	ds_read_b128 v[206:209], v156 offset:20480
	ds_read_b128 v[210:213], v156 offset:21504
	ds_read_b128 v[214:217], v156 offset:22528
	ds_read_b128 v[218:221], v156 offset:23552
	global_load_lds_dwordx4 v[150:151], off
	s_add_i32 m0, s69, 0x2000
	s_add_u32 s70, s38, 0x20000
	v_lshl_add_u64 v[170:171], s[38:39], 0, v[136:137]
	s_addc_u32 s71, s39, 0
	s_add_i32 s69, s62, s52
	global_load_lds_dwordx4 v[170:171], off
	v_lshl_add_u64 v[222:223], s[70:71], 0, v[132:133]
	s_mov_b32 m0, s69
	v_lshl_add_u64 v[224:225], s[40:41], 0, v[134:135]
	global_load_lds_dwordx4 v[222:223], off
	v_lshl_add_u64 v[222:223], s[70:71], 0, v[136:137]
	s_add_i32 m0, s69, 0x2000
	s_nop 0
	global_load_lds_dwordx4 v[222:223], off
	v_lshl_add_u64 v[222:223], s[40:41], 0, v[130:131]
	s_mov_b32 m0, s31
	s_nop 0
	global_load_lds_dwordx4 v[222:223], off
	s_mov_b32 m0, s53
	s_nop 0
	global_load_lds_dwordx4 v[224:225], off
	s_waitcnt vmcnt(8)
	s_waitcnt lgkmcnt(0)
	s_barrier
; #define PG8_STAGE(bufoff, gbase, voff) do { _Pragma("unroll") for (int _i = 0; _i < 2; ++_i) \
;         __builtin_amdgcn_global_load_lds((const unsigned*)((const char*)(gbase) + (voff)[_i]), (PG8_LAS unsigned*)(lds + (bufoff) + ldsw + _i * 8192), 16, 0, 0); } while (0)
; #define PG8_LDA(dst, b, h) do { _Pragma("unroll") for (int m = 0; m < 4; ++m) _Pragma("unroll") for (int k = 0; k < 2; ++k) dst[m][k] = *(const PG8_LAS bf16x8*)(lds + PG8_SA(b, h) + aoff + m * 2048 + k * 1024); } while (0)
; #define PG8_LDB(dst, b, h) do { _Pragma("unroll") for (int n = 0; n < 2; ++n) _Pragma("unroll") for (int k = 0; k < 2; ++k) dst[n][k] = *(const PG8_LAS bf16x8*)(lds + PG8_SB(b, h) + boff + n * 2048 + k * 1024); } while (0)
; #define PG8_MMA(ai, bj, At, Bt) do { __builtin_amdgcn_s_setprio(1); _Pragma("unroll") for (int m = 0; m < 4; ++m) _Pragma("unroll") for (int n = 0; n < 2; ++n) _Pragma("unroll") for (int k = 0; k < 2; ++k) \
;         acc[ai][bj][m][n] = __builtin_amdgcn_mfma_f32_16x16x32_bf16(Bt[n][k], At[m][k], acc[ai][bj][m][n], 0, 0, 0); __builtin_amdgcn_s_setprio(0); } while (0)
; #define PG8_WAIT_V(n) asm volatile("s_waitcnt vmcnt(" #n ")" ::: "memory")
; #define PG8_WAIT_L(n) asm volatile("s_waitcnt lgkmcnt(" #n ")" ::: "memory")
; #define PG8_BAR __builtin_amdgcn_s_barrier()
; #define PG8_SCHED __builtin_amdgcn_sched_barrier(0)
; template <class Epi, class Sched, bool ALIGN_EPI = false, bool SP2 = false>
; __device__ __forceinline__ void gemm_phase(PG8_LAS unsigned char* lds, const Gemm g, const Sched& S, const Epi& E) {
;     ...
;             PG8_WAIT_V(8); PG8_WAIT_L(0); PG8_BAR; PG8_MMA(1, 0, At, B0); PG8_MMA(1, 1, At, B1); PG8_BAR; PG8_SCHED;
;             PG8_LDB(B0, 1, 0); PG8_LDB(B1, 1, 1); PG8_SCHED; PG8_LDA(At, 1, 0); PG8_STAGE(PG8_SA(0, 1), a2 + hstep, voffA);
;             PG8_WAIT_V(8); PG8_WAIT_L(0); PG8_BAR; PG8_MMA(0, 0, At, B0); PG8_MMA(0, 1, At, B1); PG8_BAR; PG8_SCHED;
	s_setprio 1
	s_waitcnt lgkmcnt(0)
	v_mfma_f32_16x16x32_bf16 v[62:65], v[146:149], v[190:193], v[62:65]
	v_mfma_f32_16x16x32_bf16 v[58:61], v[162:165], v[190:193], v[58:61]
	v_mfma_f32_16x16x32_bf16 v[46:49], v[146:149], v[198:201], v[46:49]
	v_mfma_f32_16x16x32_bf16 v[42:45], v[162:165], v[198:201], v[42:45]
	v_mfma_f32_16x16x32_bf16 v[30:33], v[146:149], v[206:209], v[30:33]
	v_mfma_f32_16x16x32_bf16 v[26:29], v[162:165], v[206:209], v[26:29]
	v_mfma_f32_16x16x32_bf16 v[14:17], v[146:149], v[214:217], v[14:17]
	v_mfma_f32_16x16x32_bf16 v[10:13], v[162:165], v[214:217], v[10:13]
	v_mfma_f32_16x16x32_bf16 v[62:65], v[158:161], v[194:197], v[62:65]
	v_mfma_f32_16x16x32_bf16 v[58:61], v[166:169], v[194:197], v[58:61]
	v_mfma_f32_16x16x32_bf16 v[46:49], v[158:161], v[202:205], v[46:49]
	v_mfma_f32_16x16x32_bf16 v[42:45], v[166:169], v[202:205], v[42:45]
	v_mfma_f32_16x16x32_bf16 v[30:33], v[158:161], v[210:213], v[30:33]
	v_mfma_f32_16x16x32_bf16 v[26:29], v[166:169], v[210:213], v[26:29]
	v_mfma_f32_16x16x32_bf16 v[14:17], v[158:161], v[218:221], v[14:17]
	v_mfma_f32_16x16x32_bf16 v[10:13], v[166:169], v[218:221], v[10:13]
	v_mfma_f32_16x16x32_bf16 v[54:57], v[174:177], v[190:193], v[54:57]
	v_mfma_f32_16x16x32_bf16 v[50:53], v[182:185], v[190:193], v[50:53]
	v_mfma_f32_16x16x32_bf16 v[38:41], v[174:177], v[198:201], v[38:41]
	v_mfma_f32_16x16x32_bf16 v[34:37], v[182:185], v[198:201], v[34:37]
	v_mfma_f32_16x16x32_bf16 v[22:25], v[174:177], v[206:209], v[22:25]
	v_mfma_f32_16x16x32_bf16 v[18:21], v[182:185], v[206:209], v[18:21]
	v_mfma_f32_16x16x32_bf16 v[6:9], v[174:177], v[214:217], v[6:9]
	v_mfma_f32_16x16x32_bf16 v[2:5], v[182:185], v[214:217], v[2:5]
	v_mfma_f32_16x16x32_bf16 v[54:57], v[178:181], v[194:197], v[54:57]
	v_mfma_f32_16x16x32_bf16 v[50:53], v[186:189], v[194:197], v[50:53]
	v_mfma_f32_16x16x32_bf16 v[38:41], v[178:181], v[202:205], v[38:41]
	v_mfma_f32_16x16x32_bf16 v[34:37], v[186:189], v[202:205], v[34:37]
	v_mfma_f32_16x16x32_bf16 v[22:25], v[178:181], v[210:213], v[22:25]
	v_mfma_f32_16x16x32_bf16 v[18:21], v[186:189], v[210:213], v[18:21]
	v_mfma_f32_16x16x32_bf16 v[6:9], v[178:181], v[218:221], v[6:9]
	v_mfma_f32_16x16x32_bf16 v[2:5], v[186:189], v[218:221], v[2:5]
	s_setprio 0
	s_barrier
	s_add_i32 s69, 0, 0x18000
	v_add_u32_e32 v157, s69, v152
	s_add_i32 s70, 0, 0x1c000
	ds_read_b128 v[146:149], v157
	ds_read_b128 v[158:161], v157 offset:1024
	ds_read_b128 v[162:165], v157 offset:2048
	ds_read_b128 v[166:169], v157 offset:3072
	v_add_u32_e32 v157, s70, v152
	ds_read_b128 v[174:177], v157
	ds_read_b128 v[178:181], v157 offset:1024
	ds_read_b128 v[182:185], v157 offset:2048
	ds_read_b128 v[186:189], v157 offset:3072
	s_add_u32 s40, s40, 0x20000
	s_addc_u32 s41, s41, 0
	s_mov_b32 m0, s54
	v_lshl_add_u64 v[226:227], s[40:41], 0, v[130:131]
	ds_read_b128 v[190:193], v156 offset:32768
	ds_read_b128 v[194:197], v156 offset:33792
	ds_read_b128 v[198:201], v156 offset:34816
	ds_read_b128 v[202:205], v156 offset:35840
	ds_read_b128 v[206:209], v156 offset:36864
	ds_read_b128 v[210:213], v156 offset:37888
	ds_read_b128 v[214:217], v156 offset:38912
	ds_read_b128 v[218:221], v156 offset:39936
	global_load_lds_dwordx4 v[226:227], off
	v_lshl_add_u64 v[226:227], s[40:41], 0, v[134:135]
	s_mov_b32 m0, s55
	s_nop 0
	global_load_lds_dwordx4 v[226:227], off
	s_waitcnt vmcnt(8)
	s_waitcnt lgkmcnt(0)
	s_barrier
	s_setprio 1
	s_waitcnt lgkmcnt(0)
	v_mfma_f32_16x16x32_bf16 v[126:129], v[146:149], v[190:193], v[126:129]
	v_mfma_f32_16x16x32_bf16 v[122:125], v[162:165], v[190:193], v[122:125]
	v_mfma_f32_16x16x32_bf16 v[110:113], v[146:149], v[198:201], v[110:113]
	v_mfma_f32_16x16x32_bf16 v[106:109], v[162:165], v[198:201], v[106:109]
	v_mfma_f32_16x16x32_bf16 v[94:97], v[146:149], v[206:209], v[94:97]
	v_mfma_f32_16x16x32_bf16 v[90:93], v[162:165], v[206:209], v[90:93]
	v_mfma_f32_16x16x32_bf16 v[78:81], v[146:149], v[214:217], v[78:81]
	v_mfma_f32_16x16x32_bf16 v[74:77], v[162:165], v[214:217], v[74:77]
	v_mfma_f32_16x16x32_bf16 v[126:129], v[158:161], v[194:197], v[126:129]
	v_mfma_f32_16x16x32_bf16 v[122:125], v[166:169], v[194:197], v[122:125]
	v_mfma_f32_16x16x32_bf16 v[110:113], v[158:161], v[202:205], v[110:113]
	v_mfma_f32_16x16x32_bf16 v[106:109], v[166:169], v[202:205], v[106:109]
	v_mfma_f32_16x16x32_bf16 v[94:97], v[158:161], v[210:213], v[94:97]
	v_mfma_f32_16x16x32_bf16 v[90:93], v[166:169], v[210:213], v[90:93]
	v_mfma_f32_16x16x32_bf16 v[78:81], v[158:161], v[218:221], v[78:81]
	v_mfma_f32_16x16x32_bf16 v[74:77], v[166:169], v[218:221], v[74:77]
	v_mfma_f32_16x16x32_bf16 v[118:121], v[174:177], v[190:193], v[118:121]
	v_mfma_f32_16x16x32_bf16 v[114:117], v[182:185], v[190:193], v[114:117]
	v_mfma_f32_16x16x32_bf16 v[102:105], v[174:177], v[198:201], v[102:105]
	v_mfma_f32_16x16x32_bf16 v[98:101], v[182:185], v[198:201], v[98:101]
	v_mfma_f32_16x16x32_bf16 v[86:89], v[174:177], v[206:209], v[86:89]
	v_mfma_f32_16x16x32_bf16 v[82:85], v[182:185], v[206:209], v[82:85]
	v_mfma_f32_16x16x32_bf16 v[70:73], v[174:177], v[214:217], v[70:73]
	v_mfma_f32_16x16x32_bf16 v[66:69], v[182:185], v[214:217], v[66:69]
	v_mfma_f32_16x16x32_bf16 v[118:121], v[178:181], v[194:197], v[118:121]
	v_mfma_f32_16x16x32_bf16 v[114:117], v[186:189], v[194:197], v[114:117]
	v_mfma_f32_16x16x32_bf16 v[102:105], v[178:181], v[202:205], v[102:105]
	v_mfma_f32_16x16x32_bf16 v[98:101], v[186:189], v[202:205], v[98:101]
	v_mfma_f32_16x16x32_bf16 v[86:89], v[178:181], v[210:213], v[86:89]
	v_mfma_f32_16x16x32_bf16 v[82:85], v[186:189], v[210:213], v[82:85]
	v_mfma_f32_16x16x32_bf16 v[70:73], v[178:181], v[218:221], v[70:73]
	v_mfma_f32_16x16x32_bf16 v[66:69], v[186:189], v[218:221], v[66:69]
	s_setprio 0
	s_barrier
; #define PG8_STAGE(bufoff, gbase, voff) do { _Pragma("unroll") for (int _i = 0; _i < 2; ++_i) \
;         __builtin_amdgcn_global_load_lds((const unsigned*)((const char*)(gbase) + (voff)[_i]), (PG8_LAS unsigned*)(lds + (bufoff) + ldsw + _i * 8192), 16, 0, 0); } while (0)
; #define PG8_LDA(dst, b, h) do { _Pragma("unroll") for (int m = 0; m < 4; ++m) _Pragma("unroll") for (int k = 0; k < 2; ++k) dst[m][k] = *(const PG8_LAS bf16x8*)(lds + PG8_SA(b, h) + aoff + m * 2048 + k * 1024); } while (0)
; #define PG8_MMA(ai, bj, At, Bt) do { __builtin_amdgcn_s_setprio(1); _Pragma("unroll") for (int m = 0; m < 4; ++m) _Pragma("unroll") for (int n = 0; n < 2; ++n) _Pragma("unroll") for (int k = 0; k < 2; ++k) \
;         acc[ai][bj][m][n] = __builtin_amdgcn_mfma_f32_16x16x32_bf16(Bt[n][k], At[m][k], acc[ai][bj][m][n], 0, 0, 0); __builtin_amdgcn_s_setprio(0); } while (0)
; #define PG8_WAIT_V(n) asm volatile("s_waitcnt vmcnt(" #n ")" ::: "memory")
; #define PG8_WAIT_L(n) asm volatile("s_waitcnt lgkmcnt(" #n ")" ::: "memory")
; #define PG8_BAR __builtin_amdgcn_s_barrier()
; #define PG8_SCHED __builtin_amdgcn_sched_barrier(0)
; template <class Epi, class Sched, bool ALIGN_EPI = false, bool SP2 = false>
; __device__ __forceinline__ void gemm_phase(PG8_LAS unsigned char* lds, const Gemm g, const Sched& S, const Epi& E) {
;     ...
;             PG8_LDA(At, 1, 1); PG8_STAGE(PG8_SB(1, 0), b3, voffB); PG8_STAGE(PG8_SB(1, 1), b3 + hstep, voffB); PG8_STAGE(PG8_SA(1, 0), a3, voffA);
;             PG8_WAIT_V(8); PG8_WAIT_L(0); PG8_BAR; PG8_MMA(1, 0, At, B0); PG8_MMA(1, 1, At, B1); PG8_BAR; PG8_SCHED;
;     ...
;         if constexpr (ALIGN_EPI) { if (wr == 0) PG8_BAR; }
	s_add_i32 s40, s69, s52
	v_lshl_add_u64 v[150:151], v[150:151], 0, s[10:11]
	s_mov_b32 m0, s40
	ds_read_b128 v[190:193], v156 offset:49152
	ds_read_b128 v[194:197], v156 offset:50176
	ds_read_b128 v[198:201], v156 offset:51200
	ds_read_b128 v[202:205], v156 offset:52224
	ds_read_b128 v[206:209], v156 offset:53248
	ds_read_b128 v[210:213], v156 offset:54272
	ds_read_b128 v[214:217], v156 offset:55296
	ds_read_b128 v[218:221], v156 offset:56320
	global_load_lds_dwordx4 v[150:151], off
	s_add_i32 m0, s40, 0x2000
	s_add_u32 s38, s38, 0x20080
	v_lshl_add_u64 v[150:151], v[170:171], 0, s[10:11]
	s_addc_u32 s39, s39, 0
	s_add_i32 s40, s70, s52
	global_load_lds_dwordx4 v[150:151], off
	v_lshl_add_u64 v[150:151], s[38:39], 0, v[132:133]
	s_mov_b32 m0, s40
	s_nop 0
	global_load_lds_dwordx4 v[150:151], off
	v_lshl_add_u64 v[150:151], s[38:39], 0, v[136:137]
	s_add_i32 m0, s40, 0x2000
	s_nop 0
	global_load_lds_dwordx4 v[150:151], off
	v_lshl_add_u64 v[150:151], v[222:223], 0, s[10:11]
	s_mov_b32 m0, s57
	s_nop 0
	global_load_lds_dwordx4 v[150:151], off
	v_lshl_add_u64 v[150:151], v[224:225], 0, s[10:11]
	s_mov_b32 m0, s58
	s_nop 0
	global_load_lds_dwordx4 v[150:151], off
	s_waitcnt vmcnt(8)
	s_waitcnt lgkmcnt(0)
	s_barrier
	s_setprio 1
	s_waitcnt lgkmcnt(0)
	v_mfma_f32_16x16x32_bf16 v[62:65], v[146:149], v[190:193], v[62:65]
	v_mfma_f32_16x16x32_bf16 v[58:61], v[162:165], v[190:193], v[58:61]
	v_mfma_f32_16x16x32_bf16 v[46:49], v[146:149], v[198:201], v[46:49]
	v_mfma_f32_16x16x32_bf16 v[42:45], v[162:165], v[198:201], v[42:45]
	v_mfma_f32_16x16x32_bf16 v[30:33], v[146:149], v[206:209], v[30:33]
	v_mfma_f32_16x16x32_bf16 v[26:29], v[162:165], v[206:209], v[26:29]
	v_mfma_f32_16x16x32_bf16 v[14:17], v[146:149], v[214:217], v[14:17]
	v_mfma_f32_16x16x32_bf16 v[10:13], v[162:165], v[214:217], v[10:13]
	v_mfma_f32_16x16x32_bf16 v[62:65], v[158:161], v[194:197], v[62:65]
	v_mfma_f32_16x16x32_bf16 v[58:61], v[166:169], v[194:197], v[58:61]
	v_mfma_f32_16x16x32_bf16 v[46:49], v[158:161], v[202:205], v[46:49]
	v_mfma_f32_16x16x32_bf16 v[42:45], v[166:169], v[202:205], v[42:45]
	v_mfma_f32_16x16x32_bf16 v[30:33], v[158:161], v[210:213], v[30:33]
	v_mfma_f32_16x16x32_bf16 v[26:29], v[166:169], v[210:213], v[26:29]
	v_mfma_f32_16x16x32_bf16 v[14:17], v[158:161], v[218:221], v[14:17]
	v_mfma_f32_16x16x32_bf16 v[10:13], v[166:169], v[218:221], v[10:13]
	v_mfma_f32_16x16x32_bf16 v[54:57], v[174:177], v[190:193], v[54:57]
	v_mfma_f32_16x16x32_bf16 v[50:53], v[182:185], v[190:193], v[50:53]
	v_mfma_f32_16x16x32_bf16 v[38:41], v[174:177], v[198:201], v[38:41]
	v_mfma_f32_16x16x32_bf16 v[34:37], v[182:185], v[198:201], v[34:37]
	v_mfma_f32_16x16x32_bf16 v[22:25], v[174:177], v[206:209], v[22:25]
	v_mfma_f32_16x16x32_bf16 v[18:21], v[182:185], v[206:209], v[18:21]
	v_mfma_f32_16x16x32_bf16 v[6:9], v[174:177], v[214:217], v[6:9]
	v_mfma_f32_16x16x32_bf16 v[2:5], v[182:185], v[214:217], v[2:5]
	v_mfma_f32_16x16x32_bf16 v[54:57], v[178:181], v[194:197], v[54:57]
	v_mfma_f32_16x16x32_bf16 v[50:53], v[186:189], v[194:197], v[50:53]
	v_mfma_f32_16x16x32_bf16 v[38:41], v[178:181], v[202:205], v[38:41]
	v_mfma_f32_16x16x32_bf16 v[34:37], v[186:189], v[202:205], v[34:37]
	v_mfma_f32_16x16x32_bf16 v[22:25], v[178:181], v[210:213], v[22:25]
	v_mfma_f32_16x16x32_bf16 v[18:21], v[186:189], v[210:213], v[18:21]
	v_mfma_f32_16x16x32_bf16 v[6:9], v[178:181], v[218:221], v[6:9]
	v_mfma_f32_16x16x32_bf16 v[2:5], v[186:189], v[218:221], v[2:5]
	s_setprio 0
	s_barrier
	s_add_i32 s68, s68, 2
	s_add_u32 s34, s34, 0x100
	s_addc_u32 s35, s35, 0
	s_add_u32 s66, s66, 0x100
	s_addc_u32 s67, s67, 0
	s_cmp_gt_u32 s68, 5
	s_cbranch_scc0 .LBB0_1339
	s_and_b64 vcc, exec, s[12:13]
	s_cbranch_vccz .LBB0_1342
	s_barrier

; #define PG8_STAGE(bufoff, gbase, voff) do { _Pragma("unroll") for (int _i = 0; _i < 2; ++_i) \
;         __builtin_amdgcn_global_load_lds((const unsigned*)((const char*)(gbase) + (voff)[_i]), (PG8_LAS unsigned*)(lds + (bufoff) + ldsw + _i * 8192), 16, 0, 0); } while (0)
; #define PG8_LDA(dst, b, h) do { _Pragma("unroll") for (int m = 0; m < 4; ++m) _Pragma("unroll") for (int k = 0; k < 2; ++k) dst[m][k] = *(const PG8_LAS bf16x8*)(lds + PG8_SA(b, h) + aoff + m * 2048 + k * 1024); } while (0)
; #define PG8_LDB(dst, b, h) do { _Pragma("unroll") for (int n = 0; n < 2; ++n) _Pragma("unroll") for (int k = 0; k < 2; ++k) dst[n][k] = *(const PG8_LAS bf16x8*)(lds + PG8_SB(b, h) + boff + n * 2048 + k * 1024); } while (0)
; #define PG8_SCHED __builtin_amdgcn_sched_barrier(0)
; template <class Epi, class Sched, bool ALIGN_EPI = false, bool SP2 = false>
; __device__ __forceinline__ void gemm_phase(PG8_LAS unsigned char* lds, const Gemm g, const Sched& S, const Epi& E) {
;     ...
;         const bool has_next = S.next(ui + 1, nxt);
;         const char* nA = has_next ? (const char*)g.A + (size_t)nxt.pm * tstep : cA; const char* nB = has_next ? (const char*)g.Bt + (size_t)nxt.pn * tstep : cB;
; #pragma nounroll
;         for (int t = 0; t < nt; t += 2) {
;             const bool last = (t == nt - 2);
;             const char* a1 = cA + (size_t)(t + 1) * kstep;
;             const char* a2 = last ? nA : cA + (size_t)(t + 2) * kstep; const char* b2 = last ? nB : cB + (size_t)(t + 2) * kstep;
;             const char* a3 = a2 + kstep; const char* b3 = b2 + kstep;
;             if (last && has_next) S.a_ready(nxt);
;             if constexpr (SP2) {
;             PG8_LDB(B0, 0, 0); PG8_LDB(B1, 0, 1); PG8_SCHED; PG8_LDA(At, 0, 0); PG8_STAGE(PG8_SA(1, 1), a1 + hstep, voffA);
.LBB0_1431:
	s_ashr_i32 s21, s20, 31
	s_lshl_b64 s[22:23], s[20:21], 19
	s_add_u32 s22, s38, s22
	s_addc_u32 s23, s39, s23
	s_and_b64 s[24:25], s[2:3], exec
	s_cselect_b32 s21, s23, s29
	s_cselect_b32 s64, s22, s28
	s_ashr_i32 s19, s18, 31
	s_lshl_b64 s[24:25], s[18:19], 19
	s_add_u32 s24, s40, s24
	s_addc_u32 s25, s41, s25
	s_and_b64 s[34:35], s[2:3], exec
	s_cselect_b32 s19, s25, s31
	s_cselect_b32 s65, s24, s30
	s_add_u32 s28, s28, 0x40080
	s_addc_u32 s29, s29, 0
	s_add_u32 s66, s30, 0x100
	s_addc_u32 s67, s31, 0
	s_mov_b32 s68, -2
	ds_read_b128 v[154:157], v150
	ds_read_b128 v[158:161], v150 offset:1024
	ds_read_b128 v[162:165], v150 offset:2048
	ds_read_b128 v[166:169], v150 offset:3072
	ds_read_b128 v[174:177], v151
	ds_read_b128 v[178:181], v151 offset:1024
	ds_read_b128 v[182:185], v151 offset:2048
	ds_read_b128 v[186:189], v151 offset:3072
	s_add_u32 s30, s28, 0xfffc0080
	s_addc_u32 s31, s29, -1
	s_cmp_eq_u32 s68, 12
	s_cselect_b32 s35, s21, s31
	s_cselect_b32 s34, s64, s30
	s_cselect_b32 s31, s19, s67
	s_cselect_b32 s30, s65, s66

; #define PG8_STAGE(bufoff, gbase, voff) do { _Pragma("unroll") for (int _i = 0; _i < 2; ++_i) \
;         __builtin_amdgcn_global_load_lds((const unsigned*)((const char*)(gbase) + (voff)[_i]), (PG8_LAS unsigned*)(lds + (bufoff) + ldsw + _i * 8192), 16, 0, 0); } while (0)
; #define PG8_LDA(dst, b, h) do { _Pragma("unroll") for (int m = 0; m < 4; ++m) _Pragma("unroll") for (int k = 0; k < 2; ++k) dst[m][k] = *(const PG8_LAS bf16x8*)(lds + PG8_SA(b, h) + aoff + m * 2048 + k * 1024); } while (0)
; #define PG8_LDB(dst, b, h) do { _Pragma("unroll") for (int n = 0; n < 2; ++n) _Pragma("unroll") for (int k = 0; k < 2; ++k) dst[n][k] = *(const PG8_LAS bf16x8*)(lds + PG8_SB(b, h) + boff + n * 2048 + k * 1024); } while (0)
; #define PG8_MMA(ai, bj, At, Bt) do { __builtin_amdgcn_s_setprio(1); _Pragma("unroll") for (int m = 0; m < 4; ++m) _Pragma("unroll") for (int n = 0; n < 2; ++n) _Pragma("unroll") for (int k = 0; k < 2; ++k) \
;         acc[ai][bj][m][n] = __builtin_amdgcn_mfma_f32_16x16x32_bf16(Bt[n][k], At[m][k], acc[ai][bj][m][n], 0, 0, 0); __builtin_amdgcn_s_setprio(0); } while (0)
; #define PG8_WAIT_V(n) asm volatile("s_waitcnt vmcnt(" #n ")" ::: "memory")
; #define PG8_WAIT_L(n) asm volatile("s_waitcnt lgkmcnt(" #n ")" ::: "memory")
; #define PG8_BAR __builtin_amdgcn_s_barrier()
; #define PG8_SCHED __builtin_amdgcn_sched_barrier(0)
; template <class Epi, class Sched, bool ALIGN_EPI = false, bool SP2 = false>
; __device__ __forceinline__ void gemm_phase(PG8_LAS unsigned char* lds, const Gemm g, const Sched& S, const Epi& E) {
;     ...
;             PG8_LDB(B0, 0, 0); PG8_LDB(B1, 0, 1); PG8_SCHED; PG8_LDA(At, 0, 0); PG8_STAGE(PG8_SA(1, 1), a1 + hstep, voffA);
;             PG8_WAIT_V(8); PG8_WAIT_L(0); PG8_BAR; PG8_MMA(0, 0, At, B0); PG8_MMA(0, 1, At, B1); PG8_BAR; PG8_SCHED;
;     ...
;                     for (int n = 0; n < 2; ++n) acc[a][b][m][n] = (f32x4){0.f, 0.f, 0.f, 0.f};
	v_lshl_add_u64 v[146:147], s[28:29], 0, v[138:139]
	s_add_i32 m0, s27, 0xc000
	ds_read_b128 v[190:193], v152
	ds_read_b128 v[194:197], v152 offset:1024
	ds_read_b128 v[198:201], v152 offset:2048
	ds_read_b128 v[202:205], v152 offset:3072
	ds_read_b128 v[206:209], v152 offset:4096
	ds_read_b128 v[210:213], v152 offset:5120
	ds_read_b128 v[214:217], v152 offset:6144
	ds_read_b128 v[218:221], v152 offset:7168
	global_load_lds_dwordx4 v[146:147], off
	v_lshl_add_u64 v[146:147], s[28:29], 0, v[140:141]
	s_add_i32 m0, s27, 0xe000
	s_nop 0
	global_load_lds_dwordx4 v[146:147], off
	s_waitcnt vmcnt(24)
	s_waitcnt lgkmcnt(0)
	s_barrier
	s_setprio 1
	s_waitcnt lgkmcnt(0)
	v_mfma_f32_16x16x32_bf16 v[126:129], v[154:157], v[190:193], 0
	v_mfma_f32_16x16x32_bf16 v[122:125], v[162:165], v[190:193], 0
	v_mfma_f32_16x16x32_bf16 v[118:121], v[154:157], v[198:201], 0
	v_mfma_f32_16x16x32_bf16 v[110:113], v[162:165], v[198:201], 0
	v_mfma_f32_16x16x32_bf16 v[102:105], v[154:157], v[206:209], 0
	v_mfma_f32_16x16x32_bf16 v[94:97], v[162:165], v[206:209], 0
	v_mfma_f32_16x16x32_bf16 v[86:89], v[154:157], v[214:217], 0
	v_mfma_f32_16x16x32_bf16 v[78:81], v[162:165], v[214:217], 0
	v_mfma_f32_16x16x32_bf16 v[126:129], v[158:161], v[194:197], v[126:129]
	v_mfma_f32_16x16x32_bf16 v[122:125], v[166:169], v[194:197], v[122:125]
	v_mfma_f32_16x16x32_bf16 v[118:121], v[158:161], v[202:205], v[118:121]
	v_mfma_f32_16x16x32_bf16 v[110:113], v[166:169], v[202:205], v[110:113]
	v_mfma_f32_16x16x32_bf16 v[102:105], v[158:161], v[210:213], v[102:105]
	v_mfma_f32_16x16x32_bf16 v[94:97], v[166:169], v[210:213], v[94:97]
	v_mfma_f32_16x16x32_bf16 v[86:89], v[158:161], v[218:221], v[86:89]
	v_mfma_f32_16x16x32_bf16 v[78:81], v[166:169], v[218:221], v[78:81]
	v_mfma_f32_16x16x32_bf16 v[114:117], v[174:177], v[190:193], 0
	v_mfma_f32_16x16x32_bf16 v[106:109], v[182:185], v[190:193], 0
	v_mfma_f32_16x16x32_bf16 v[98:101], v[174:177], v[198:201], 0
	v_mfma_f32_16x16x32_bf16 v[90:93], v[182:185], v[198:201], 0
	v_mfma_f32_16x16x32_bf16 v[82:85], v[174:177], v[206:209], 0
	v_mfma_f32_16x16x32_bf16 v[74:77], v[182:185], v[206:209], 0
	v_mfma_f32_16x16x32_bf16 v[70:73], v[174:177], v[214:217], 0
	v_mfma_f32_16x16x32_bf16 v[66:69], v[182:185], v[214:217], 0
	v_mfma_f32_16x16x32_bf16 v[114:117], v[178:181], v[194:197], v[114:117]
	v_mfma_f32_16x16x32_bf16 v[106:109], v[186:189], v[194:197], v[106:109]
	v_mfma_f32_16x16x32_bf16 v[98:101], v[178:181], v[202:205], v[98:101]
	v_mfma_f32_16x16x32_bf16 v[90:93], v[186:189], v[202:205], v[90:93]
	v_mfma_f32_16x16x32_bf16 v[82:85], v[178:181], v[210:213], v[82:85]
	v_mfma_f32_16x16x32_bf16 v[74:77], v[186:189], v[210:213], v[74:77]
	v_mfma_f32_16x16x32_bf16 v[70:73], v[178:181], v[218:221], v[70:73]
	v_mfma_f32_16x16x32_bf16 v[66:69], v[186:189], v[218:221], v[66:69]
	s_setprio 0
	s_barrier

; #define PG8_STAGE(bufoff, gbase, voff) do { _Pragma("unroll") for (int _i = 0; _i < 2; ++_i) \
;         __builtin_amdgcn_global_load_lds((const unsigned*)((const char*)(gbase) + (voff)[_i]), (PG8_LAS unsigned*)(lds + (bufoff) + ldsw + _i * 8192), 16, 0, 0); } while (0)
; #define PG8_LDA(dst, b, h) do { _Pragma("unroll") for (int m = 0; m < 4; ++m) _Pragma("unroll") for (int k = 0; k < 2; ++k) dst[m][k] = *(const PG8_LAS bf16x8*)(lds + PG8_SA(b, h) + aoff + m * 2048 + k * 1024); } while (0)
; #define PG8_MMA(ai, bj, At, Bt) do { __builtin_amdgcn_s_setprio(1); _Pragma("unroll") for (int m = 0; m < 4; ++m) _Pragma("unroll") for (int n = 0; n < 2; ++n) _Pragma("unroll") for (int k = 0; k < 2; ++k) \
;         acc[ai][bj][m][n] = __builtin_amdgcn_mfma_f32_16x16x32_bf16(Bt[n][k], At[m][k], acc[ai][bj][m][n], 0, 0, 0); __builtin_amdgcn_s_setprio(0); } while (0)
; #define PG8_WAIT_V(n) asm volatile("s_waitcnt vmcnt(" #n ")" ::: "memory")
; #define PG8_WAIT_L(n) asm volatile("s_waitcnt lgkmcnt(" #n ")" ::: "memory")
; #define PG8_BAR __builtin_amdgcn_s_barrier()
; #define PG8_SCHED __builtin_amdgcn_sched_barrier(0)
; template <class Epi, class Sched, bool ALIGN_EPI = false, bool SP2 = false>
; __device__ __forceinline__ void gemm_phase(PG8_LAS unsigned char* lds, const Gemm g, const Sched& S, const Epi& E) {
;     ...
;             PG8_LDA(At, 0, 1); PG8_STAGE(PG8_SB(0, 0), b2, voffB); PG8_STAGE(PG8_SB(0, 1), b2 + hstep, voffB); PG8_STAGE(PG8_SA(0, 0), a2, voffA);
;             PG8_WAIT_V(8); PG8_WAIT_L(0); PG8_BAR; PG8_MMA(1, 0, At, B0); PG8_MMA(1, 1, At, B1); PG8_BAR; PG8_SCHED;
;     ...
;                     for (int n = 0; n < 2; ++n) acc[a][b][m][n] = (f32x4){0.f, 0.f, 0.f, 0.f};
	s_add_i32 s69, s57, s42
	v_lshl_add_u64 v[146:147], s[30:31], 0, v[132:133]
	s_mov_b32 m0, s69
	ds_read_b128 v[190:193], v152 offset:16384
	ds_read_b128 v[194:197], v152 offset:17408
	ds_read_b128 v[198:201], v152 offset:18432
	ds_read_b128 v[202:205], v152 offset:19456
	ds_read_b128 v[206:209], v152 offset:20480
	ds_read_b128 v[210:213], v152 offset:21504
	ds_read_b128 v[214:217], v152 offset:22528
	ds_read_b128 v[218:221], v152 offset:23552
	global_load_lds_dwordx4 v[146:147], off
	s_add_i32 m0, s69, 0x2000
	s_add_u32 s70, s30, 0x40000
	v_lshl_add_u64 v[170:171], s[30:31], 0, v[136:137]
	s_addc_u32 s71, s31, 0
	s_add_i32 s69, s58, s42
	global_load_lds_dwordx4 v[170:171], off
	v_lshl_add_u64 v[222:223], s[70:71], 0, v[132:133]
	s_mov_b32 m0, s69
	v_lshl_add_u64 v[224:225], s[34:35], 0, v[134:135]
	global_load_lds_dwordx4 v[222:223], off
	v_lshl_add_u64 v[222:223], s[70:71], 0, v[136:137]
	s_add_i32 m0, s69, 0x2000
	s_nop 0
	global_load_lds_dwordx4 v[222:223], off
	v_lshl_add_u64 v[222:223], s[34:35], 0, v[130:131]
	s_mov_b32 m0, s27
	s_nop 0
	global_load_lds_dwordx4 v[222:223], off
	s_mov_b32 m0, s43
	s_nop 0
	global_load_lds_dwordx4 v[224:225], off
	s_waitcnt vmcnt(24)
	s_waitcnt lgkmcnt(0)
	s_barrier
	s_setprio 1
	s_waitcnt lgkmcnt(0)
	v_mfma_f32_16x16x32_bf16 v[62:65], v[154:157], v[190:193], 0
	v_mfma_f32_16x16x32_bf16 v[58:61], v[162:165], v[190:193], 0
	v_mfma_f32_16x16x32_bf16 v[54:57], v[154:157], v[198:201], 0
	v_mfma_f32_16x16x32_bf16 v[46:49], v[162:165], v[198:201], 0
	v_mfma_f32_16x16x32_bf16 v[38:41], v[154:157], v[206:209], 0
	v_mfma_f32_16x16x32_bf16 v[30:33], v[162:165], v[206:209], 0
	v_mfma_f32_16x16x32_bf16 v[22:25], v[154:157], v[214:217], 0
	v_mfma_f32_16x16x32_bf16 v[14:17], v[162:165], v[214:217], 0
	v_mfma_f32_16x16x32_bf16 v[62:65], v[158:161], v[194:197], v[62:65]
	v_mfma_f32_16x16x32_bf16 v[58:61], v[166:169], v[194:197], v[58:61]
	v_mfma_f32_16x16x32_bf16 v[54:57], v[158:161], v[202:205], v[54:57]
	v_mfma_f32_16x16x32_bf16 v[46:49], v[166:169], v[202:205], v[46:49]
	v_mfma_f32_16x16x32_bf16 v[38:41], v[158:161], v[210:213], v[38:41]
	v_mfma_f32_16x16x32_bf16 v[30:33], v[166:169], v[210:213], v[30:33]
	v_mfma_f32_16x16x32_bf16 v[22:25], v[158:161], v[218:221], v[22:25]
	v_mfma_f32_16x16x32_bf16 v[14:17], v[166:169], v[218:221], v[14:17]
	v_mfma_f32_16x16x32_bf16 v[50:53], v[174:177], v[190:193], 0
	v_mfma_f32_16x16x32_bf16 v[42:45], v[182:185], v[190:193], 0
	v_mfma_f32_16x16x32_bf16 v[34:37], v[174:177], v[198:201], 0
	v_mfma_f32_16x16x32_bf16 v[26:29], v[182:185], v[198:201], 0
	v_mfma_f32_16x16x32_bf16 v[18:21], v[174:177], v[206:209], 0
	v_mfma_f32_16x16x32_bf16 v[10:13], v[182:185], v[206:209], 0
	v_mfma_f32_16x16x32_bf16 v[6:9], v[174:177], v[214:217], 0
	v_mfma_f32_16x16x32_bf16 v[2:5], v[182:185], v[214:217], 0
	v_mfma_f32_16x16x32_bf16 v[50:53], v[178:181], v[194:197], v[50:53]
	v_mfma_f32_16x16x32_bf16 v[42:45], v[186:189], v[194:197], v[42:45]
	v_mfma_f32_16x16x32_bf16 v[34:37], v[178:181], v[202:205], v[34:37]
	v_mfma_f32_16x16x32_bf16 v[26:29], v[186:189], v[202:205], v[26:29]
	v_mfma_f32_16x16x32_bf16 v[18:21], v[178:181], v[210:213], v[18:21]
	v_mfma_f32_16x16x32_bf16 v[10:13], v[186:189], v[210:213], v[10:13]
	v_mfma_f32_16x16x32_bf16 v[6:9], v[178:181], v[218:221], v[6:9]
	v_mfma_f32_16x16x32_bf16 v[2:5], v[186:189], v[218:221], v[2:5]
	s_setprio 0
	s_barrier

; #define PG8_STAGE(bufoff, gbase, voff) do { _Pragma("unroll") for (int _i = 0; _i < 2; ++_i) \
;         __builtin_amdgcn_global_load_lds((const unsigned*)((const char*)(gbase) + (voff)[_i]), (PG8_LAS unsigned*)(lds + (bufoff) + ldsw + _i * 8192), 16, 0, 0); } while (0)
; #define PG8_LDA(dst, b, h) do { _Pragma("unroll") for (int m = 0; m < 4; ++m) _Pragma("unroll") for (int k = 0; k < 2; ++k) dst[m][k] = *(const PG8_LAS bf16x8*)(lds + PG8_SA(b, h) + aoff + m * 2048 + k * 1024); } while (0)
; #define PG8_LDB(dst, b, h) do { _Pragma("unroll") for (int n = 0; n < 2; ++n) _Pragma("unroll") for (int k = 0; k < 2; ++k) dst[n][k] = *(const PG8_LAS bf16x8*)(lds + PG8_SB(b, h) + boff + n * 2048 + k * 1024); } while (0)
; #define PG8_SCHED __builtin_amdgcn_sched_barrier(0)
; template <class Epi, class Sched, bool ALIGN_EPI = false, bool SP2 = false>
; __device__ __forceinline__ void gemm_phase(PG8_LAS unsigned char* lds, const Gemm g, const Sched& S, const Epi& E) {
;     ...
;             PG8_LDB(B0, 1, 0); PG8_LDB(B1, 1, 1); PG8_SCHED; PG8_LDA(At, 1, 0); PG8_STAGE(PG8_SA(0, 1), a2 + hstep, voffA);
	s_add_i32 s69, 0, 0x18000
	v_add_u32_e32 v153, s69, v148
	s_add_i32 s70, 0, 0x1c000
	ds_read_b128 v[154:157], v153
	ds_read_b128 v[158:161], v153 offset:1024
	ds_read_b128 v[162:165], v153 offset:2048
	ds_read_b128 v[166:169], v153 offset:3072
	v_add_u32_e32 v153, s70, v148
	ds_read_b128 v[174:177], v153
	ds_read_b128 v[178:181], v153 offset:1024
	ds_read_b128 v[182:185], v153 offset:2048
	ds_read_b128 v[186:189], v153 offset:3072

; #define PG8_STAGE(bufoff, gbase, voff) do { _Pragma("unroll") for (int _i = 0; _i < 2; ++_i) \
;         __builtin_amdgcn_global_load_lds((const unsigned*)((const char*)(gbase) + (voff)[_i]), (PG8_LAS unsigned*)(lds + (bufoff) + ldsw + _i * 8192), 16, 0, 0); } while (0)
; #define PG8_LDA(dst, b, h) do { _Pragma("unroll") for (int m = 0; m < 4; ++m) _Pragma("unroll") for (int k = 0; k < 2; ++k) dst[m][k] = *(const PG8_LAS bf16x8*)(lds + PG8_SA(b, h) + aoff + m * 2048 + k * 1024); } while (0)
; #define PG8_LDB(dst, b, h) do { _Pragma("unroll") for (int n = 0; n < 2; ++n) _Pragma("unroll") for (int k = 0; k < 2; ++k) dst[n][k] = *(const PG8_LAS bf16x8*)(lds + PG8_SB(b, h) + boff + n * 2048 + k * 1024); } while (0)
; #define PG8_MMA(ai, bj, At, Bt) do { __builtin_amdgcn_s_setprio(1); _Pragma("unroll") for (int m = 0; m < 4; ++m) _Pragma("unroll") for (int n = 0; n < 2; ++n) _Pragma("unroll") for (int k = 0; k < 2; ++k) \
;         acc[ai][bj][m][n] = __builtin_amdgcn_mfma_f32_16x16x32_bf16(Bt[n][k], At[m][k], acc[ai][bj][m][n], 0, 0, 0); __builtin_amdgcn_s_setprio(0); } while (0)
; #define PG8_WAIT_V(n) asm volatile("s_waitcnt vmcnt(" #n ")" ::: "memory")
; #define PG8_WAIT_L(n) asm volatile("s_waitcnt lgkmcnt(" #n ")" ::: "memory")
; #define PG8_BAR __builtin_amdgcn_s_barrier()
; #define PG8_SCHED __builtin_amdgcn_sched_barrier(0)
; template <class Epi, class Sched, bool ALIGN_EPI = false, bool SP2 = false>
; __device__ __forceinline__ void gemm_phase(PG8_LAS unsigned char* lds, const Gemm g, const Sched& S, const Epi& E) {
;     ...
;             PG8_LDB(B0, 1, 0); PG8_LDB(B1, 1, 1); PG8_SCHED; PG8_LDA(At, 1, 0); PG8_STAGE(PG8_SA(0, 1), a2 + hstep, voffA);
;             PG8_WAIT_V(8); PG8_WAIT_L(0); PG8_BAR; PG8_MMA(0, 0, At, B0); PG8_MMA(0, 1, At, B1); PG8_BAR; PG8_SCHED;
	s_add_u32 s34, s34, 0x40000
	s_addc_u32 s35, s35, 0
	s_mov_b32 m0, s44
	v_lshl_add_u64 v[226:227], s[34:35], 0, v[130:131]
	ds_read_b128 v[190:193], v152 offset:32768
	ds_read_b128 v[194:197], v152 offset:33792
	ds_read_b128 v[198:201], v152 offset:34816
	ds_read_b128 v[202:205], v152 offset:35840
	ds_read_b128 v[206:209], v152 offset:36864
	ds_read_b128 v[210:213], v152 offset:37888
	ds_read_b128 v[214:217], v152 offset:38912
	ds_read_b128 v[218:221], v152 offset:39936
	global_load_lds_dwordx4 v[226:227], off
	v_lshl_add_u64 v[226:227], s[34:35], 0, v[134:135]
	s_mov_b32 m0, s45
	s_nop 0
	global_load_lds_dwordx4 v[226:227], off
	s_waitcnt vmcnt(8)
	s_waitcnt lgkmcnt(0)
	s_barrier
	s_setprio 1
	s_waitcnt lgkmcnt(0)
	v_mfma_f32_16x16x32_bf16 v[126:129], v[154:157], v[190:193], v[126:129]
	v_mfma_f32_16x16x32_bf16 v[122:125], v[162:165], v[190:193], v[122:125]
	v_mfma_f32_16x16x32_bf16 v[118:121], v[154:157], v[198:201], v[118:121]
	v_mfma_f32_16x16x32_bf16 v[110:113], v[162:165], v[198:201], v[110:113]
	v_mfma_f32_16x16x32_bf16 v[102:105], v[154:157], v[206:209], v[102:105]
	v_mfma_f32_16x16x32_bf16 v[94:97], v[162:165], v[206:209], v[94:97]
	v_mfma_f32_16x16x32_bf16 v[86:89], v[154:157], v[214:217], v[86:89]
	v_mfma_f32_16x16x32_bf16 v[78:81], v[162:165], v[214:217], v[78:81]
	v_mfma_f32_16x16x32_bf16 v[126:129], v[158:161], v[194:197], v[126:129]
	v_mfma_f32_16x16x32_bf16 v[122:125], v[166:169], v[194:197], v[122:125]
	v_mfma_f32_16x16x32_bf16 v[118:121], v[158:161], v[202:205], v[118:121]
	v_mfma_f32_16x16x32_bf16 v[110:113], v[166:169], v[202:205], v[110:113]
	v_mfma_f32_16x16x32_bf16 v[102:105], v[158:161], v[210:213], v[102:105]
	v_mfma_f32_16x16x32_bf16 v[94:97], v[166:169], v[210:213], v[94:97]
	v_mfma_f32_16x16x32_bf16 v[86:89], v[158:161], v[218:221], v[86:89]
	v_mfma_f32_16x16x32_bf16 v[78:81], v[166:169], v[218:221], v[78:81]
	v_mfma_f32_16x16x32_bf16 v[114:117], v[174:177], v[190:193], v[114:117]
	v_mfma_f32_16x16x32_bf16 v[106:109], v[182:185], v[190:193], v[106:109]
	v_mfma_f32_16x16x32_bf16 v[98:101], v[174:177], v[198:201], v[98:101]
	v_mfma_f32_16x16x32_bf16 v[90:93], v[182:185], v[198:201], v[90:93]
	v_mfma_f32_16x16x32_bf16 v[82:85], v[174:177], v[206:209], v[82:85]
	v_mfma_f32_16x16x32_bf16 v[74:77], v[182:185], v[206:209], v[74:77]
	v_mfma_f32_16x16x32_bf16 v[70:73], v[174:177], v[214:217], v[70:73]
	v_mfma_f32_16x16x32_bf16 v[66:69], v[182:185], v[214:217], v[66:69]
	v_mfma_f32_16x16x32_bf16 v[114:117], v[178:181], v[194:197], v[114:117]
	v_mfma_f32_16x16x32_bf16 v[106:109], v[186:189], v[194:197], v[106:109]
	v_mfma_f32_16x16x32_bf16 v[98:101], v[178:181], v[202:205], v[98:101]
	v_mfma_f32_16x16x32_bf16 v[90:93], v[186:189], v[202:205], v[90:93]
	v_mfma_f32_16x16x32_bf16 v[82:85], v[178:181], v[210:213], v[82:85]
	v_mfma_f32_16x16x32_bf16 v[74:77], v[186:189], v[210:213], v[74:77]
	v_mfma_f32_16x16x32_bf16 v[70:73], v[178:181], v[218:221], v[70:73]
	v_mfma_f32_16x16x32_bf16 v[66:69], v[186:189], v[218:221], v[66:69]
	s_setprio 0
	s_barrier

; #define PG8_STAGE(bufoff, gbase, voff) do { _Pragma("unroll") for (int _i = 0; _i < 2; ++_i) \
;         __builtin_amdgcn_global_load_lds((const unsigned*)((const char*)(gbase) + (voff)[_i]), (PG8_LAS unsigned*)(lds + (bufoff) + ldsw + _i * 8192), 16, 0, 0); } while (0)
; #define PG8_LDA(dst, b, h) do { _Pragma("unroll") for (int m = 0; m < 4; ++m) _Pragma("unroll") for (int k = 0; k < 2; ++k) dst[m][k] = *(const PG8_LAS bf16x8*)(lds + PG8_SA(b, h) + aoff + m * 2048 + k * 1024); } while (0)
; #define PG8_MMA(ai, bj, At, Bt) do { __builtin_amdgcn_s_setprio(1); _Pragma("unroll") for (int m = 0; m < 4; ++m) _Pragma("unroll") for (int n = 0; n < 2; ++n) _Pragma("unroll") for (int k = 0; k < 2; ++k) \
;         acc[ai][bj][m][n] = __builtin_amdgcn_mfma_f32_16x16x32_bf16(Bt[n][k], At[m][k], acc[ai][bj][m][n], 0, 0, 0); __builtin_amdgcn_s_setprio(0); } while (0)
; #define PG8_WAIT_V(n) asm volatile("s_waitcnt vmcnt(" #n ")" ::: "memory")
; #define PG8_WAIT_L(n) asm volatile("s_waitcnt lgkmcnt(" #n ")" ::: "memory")
; #define PG8_BAR __builtin_amdgcn_s_barrier()
; #define PG8_SCHED __builtin_amdgcn_sched_barrier(0)
; template <class Epi, class Sched, bool ALIGN_EPI = false, bool SP2 = false>
; __device__ __forceinline__ void gemm_phase(PG8_LAS unsigned char* lds, const Gemm g, const Sched& S, const Epi& E) {
;     ...
;             PG8_LDA(At, 1, 1); PG8_STAGE(PG8_SB(1, 0), b3, voffB); PG8_STAGE(PG8_SB(1, 1), b3 + hstep, voffB); PG8_STAGE(PG8_SA(1, 0), a3, voffA);
;             PG8_WAIT_V(8); PG8_WAIT_L(0); PG8_BAR; PG8_MMA(1, 0, At, B0); PG8_MMA(1, 1, At, B1); PG8_BAR; PG8_SCHED;
	s_add_i32 s34, s69, s42
	v_lshl_add_u64 v[146:147], v[146:147], 0, s[8:9]
	s_mov_b32 m0, s34
	ds_read_b128 v[190:193], v152 offset:49152
	ds_read_b128 v[194:197], v152 offset:50176
	ds_read_b128 v[198:201], v152 offset:51200
	ds_read_b128 v[202:205], v152 offset:52224
	ds_read_b128 v[206:209], v152 offset:53248
	ds_read_b128 v[210:213], v152 offset:54272
	ds_read_b128 v[214:217], v152 offset:55296
	ds_read_b128 v[218:221], v152 offset:56320
	global_load_lds_dwordx4 v[146:147], off
	s_add_i32 m0, s34, 0x2000
	s_add_u32 s30, s30, 0x40080
	v_lshl_add_u64 v[146:147], v[170:171], 0, s[8:9]
	s_addc_u32 s31, s31, 0
	s_add_i32 s34, s70, s42
	global_load_lds_dwordx4 v[146:147], off
	v_lshl_add_u64 v[146:147], s[30:31], 0, v[132:133]
	s_mov_b32 m0, s34
	s_nop 0
	global_load_lds_dwordx4 v[146:147], off
	v_lshl_add_u64 v[146:147], s[30:31], 0, v[136:137]
	s_add_i32 m0, s34, 0x2000
	s_nop 0
	global_load_lds_dwordx4 v[146:147], off
	v_lshl_add_u64 v[146:147], v[222:223], 0, s[8:9]
	s_mov_b32 m0, s53
	s_nop 0
	global_load_lds_dwordx4 v[146:147], off
	v_lshl_add_u64 v[146:147], v[224:225], 0, s[8:9]
	s_mov_b32 m0, s54
	s_nop 0
	global_load_lds_dwordx4 v[146:147], off
	s_waitcnt vmcnt(8)
	s_waitcnt lgkmcnt(0)
	s_barrier
	s_setprio 1
	s_waitcnt lgkmcnt(0)
	v_mfma_f32_16x16x32_bf16 v[62:65], v[154:157], v[190:193], v[62:65]
	v_mfma_f32_16x16x32_bf16 v[58:61], v[162:165], v[190:193], v[58:61]
	v_mfma_f32_16x16x32_bf16 v[54:57], v[154:157], v[198:201], v[54:57]
	v_mfma_f32_16x16x32_bf16 v[46:49], v[162:165], v[198:201], v[46:49]
	v_mfma_f32_16x16x32_bf16 v[38:41], v[154:157], v[206:209], v[38:41]
	v_mfma_f32_16x16x32_bf16 v[30:33], v[162:165], v[206:209], v[30:33]
	v_mfma_f32_16x16x32_bf16 v[22:25], v[154:157], v[214:217], v[22:25]
	v_mfma_f32_16x16x32_bf16 v[14:17], v[162:165], v[214:217], v[14:17]
	v_mfma_f32_16x16x32_bf16 v[62:65], v[158:161], v[194:197], v[62:65]
	v_mfma_f32_16x16x32_bf16 v[58:61], v[166:169], v[194:197], v[58:61]
	v_mfma_f32_16x16x32_bf16 v[54:57], v[158:161], v[202:205], v[54:57]
	v_mfma_f32_16x16x32_bf16 v[46:49], v[166:169], v[202:205], v[46:49]
	v_mfma_f32_16x16x32_bf16 v[38:41], v[158:161], v[210:213], v[38:41]
	v_mfma_f32_16x16x32_bf16 v[30:33], v[166:169], v[210:213], v[30:33]
	v_mfma_f32_16x16x32_bf16 v[22:25], v[158:161], v[218:221], v[22:25]
	v_mfma_f32_16x16x32_bf16 v[14:17], v[166:169], v[218:221], v[14:17]
	v_mfma_f32_16x16x32_bf16 v[50:53], v[174:177], v[190:193], v[50:53]
	v_mfma_f32_16x16x32_bf16 v[42:45], v[182:185], v[190:193], v[42:45]
	v_mfma_f32_16x16x32_bf16 v[34:37], v[174:177], v[198:201], v[34:37]
	v_mfma_f32_16x16x32_bf16 v[26:29], v[182:185], v[198:201], v[26:29]
	v_mfma_f32_16x16x32_bf16 v[18:21], v[174:177], v[206:209], v[18:21]
	v_mfma_f32_16x16x32_bf16 v[10:13], v[182:185], v[206:209], v[10:13]
	v_mfma_f32_16x16x32_bf16 v[6:9], v[174:177], v[214:217], v[6:9]
	v_mfma_f32_16x16x32_bf16 v[2:5], v[182:185], v[214:217], v[2:5]
	v_mfma_f32_16x16x32_bf16 v[50:53], v[178:181], v[194:197], v[50:53]
	v_mfma_f32_16x16x32_bf16 v[42:45], v[186:189], v[194:197], v[42:45]
	v_mfma_f32_16x16x32_bf16 v[34:37], v[178:181], v[202:205], v[34:37]
	v_mfma_f32_16x16x32_bf16 v[26:29], v[186:189], v[202:205], v[26:29]
	v_mfma_f32_16x16x32_bf16 v[18:21], v[178:181], v[210:213], v[18:21]
	v_mfma_f32_16x16x32_bf16 v[10:13], v[186:189], v[210:213], v[10:13]
	v_mfma_f32_16x16x32_bf16 v[6:9], v[178:181], v[218:221], v[6:9]
	v_mfma_f32_16x16x32_bf16 v[2:5], v[186:189], v[218:221], v[2:5]
	s_setprio 0
	s_barrier

; #define PG8_STAGE(bufoff, gbase, voff) do { _Pragma("unroll") for (int _i = 0; _i < 2; ++_i) \
;         __builtin_amdgcn_global_load_lds((const unsigned*)((const char*)(gbase) + (voff)[_i]), (PG8_LAS unsigned*)(lds + (bufoff) + ldsw + _i * 8192), 16, 0, 0); } while (0)
; #define PG8_LDA(dst, b, h) do { _Pragma("unroll") for (int m = 0; m < 4; ++m) _Pragma("unroll") for (int k = 0; k < 2; ++k) dst[m][k] = *(const PG8_LAS bf16x8*)(lds + PG8_SA(b, h) + aoff + m * 2048 + k * 1024); } while (0)
; #define PG8_LDB(dst, b, h) do { _Pragma("unroll") for (int n = 0; n < 2; ++n) _Pragma("unroll") for (int k = 0; k < 2; ++k) dst[n][k] = *(const PG8_LAS bf16x8*)(lds + PG8_SB(b, h) + boff + n * 2048 + k * 1024); } while (0)
; #define PG8_MMA(ai, bj, At, Bt) do { __builtin_amdgcn_s_setprio(1); _Pragma("unroll") for (int m = 0; m < 4; ++m) _Pragma("unroll") for (int n = 0; n < 2; ++n) _Pragma("unroll") for (int k = 0; k < 2; ++k) \
;         acc[ai][bj][m][n] = __builtin_amdgcn_mfma_f32_16x16x32_bf16(Bt[n][k], At[m][k], acc[ai][bj][m][n], 0, 0, 0); __builtin_amdgcn_s_setprio(0); } while (0)
; #define PG8_WAIT_V(n) asm volatile("s_waitcnt vmcnt(" #n ")" ::: "memory")
; #define PG8_BAR __builtin_amdgcn_s_barrier()
; template <class Epi, class Sched, bool ALIGN_EPI = false, bool SP2 = false>
; __device__ __forceinline__ void gemm_phase(PG8_LAS unsigned char* lds, const Gemm g, const Sched& S, const Epi& E) {
;     ...
;         for (int t = 0; t < nt; t += 2) {
;             const bool last = (t == nt - 2);
;             const char* a1 = cA + (size_t)(t + 1) * kstep;
;             const char* a2 = last ? nA : cA + (size_t)(t + 2) * kstep; const char* b2 = last ? nB : cB + (size_t)(t + 2) * kstep;
;             const char* a3 = a2 + kstep; const char* b3 = b2 + kstep;
;             if (last && has_next) S.a_ready(nxt);
;             if constexpr (SP2) {
;             PG8_LDB(B0, 0, 0); PG8_LDB(B1, 0, 1); PG8_SCHED; PG8_LDA(At, 0, 0); PG8_STAGE(PG8_SA(1, 1), a1 + hstep, voffA);
;             PG8_WAIT_V(8); PG8_WAIT_L(0); PG8_BAR; PG8_MMA(0, 0, At, B0); PG8_MMA(0, 1, At, B1); PG8_BAR; PG8_SCHED;
;             PG8_LDA(At, 0, 1); PG8_STAGE(PG8_SB(0, 0), b2, voffB); PG8_STAGE(PG8_SB(0, 1), b2 + hstep, voffB); PG8_STAGE(PG8_SA(0, 0), a2, voffA);
;             PG8_WAIT_V(8); PG8_WAIT_L(0); PG8_BAR; PG8_MMA(1, 0, At, B0); PG8_MMA(1, 1, At, B1); PG8_BAR; PG8_SCHED;
	s_add_i32 s68, s68, 2
	s_add_u32 s28, s28, 0x100
	s_addc_u32 s29, s29, 0
	s_add_u32 s66, s66, 0x100
	s_addc_u32 s67, s67, 0
.LBB0_1432:
	ds_read_b128 v[154:157], v150
	ds_read_b128 v[158:161], v150 offset:1024
	ds_read_b128 v[162:165], v150 offset:2048
	ds_read_b128 v[166:169], v150 offset:3072
	ds_read_b128 v[174:177], v151
	ds_read_b128 v[178:181], v151 offset:1024
	ds_read_b128 v[182:185], v151 offset:2048
	ds_read_b128 v[186:189], v151 offset:3072
	s_add_u32 s30, s28, 0xfffc0080
	s_addc_u32 s31, s29, -1
	s_cmp_eq_u32 s68, 12
	s_cselect_b32 s35, s21, s31
	s_cselect_b32 s34, s64, s30
	s_cselect_b32 s31, s19, s67
	s_cselect_b32 s30, s65, s66
	v_lshl_add_u64 v[146:147], s[28:29], 0, v[138:139]
	s_add_i32 m0, s27, 0xc000
	ds_read_b128 v[190:193], v152
	ds_read_b128 v[194:197], v152 offset:1024
	ds_read_b128 v[198:201], v152 offset:2048
	ds_read_b128 v[202:205], v152 offset:3072
	ds_read_b128 v[206:209], v152 offset:4096
	ds_read_b128 v[210:213], v152 offset:5120
	ds_read_b128 v[214:217], v152 offset:6144
	ds_read_b128 v[218:221], v152 offset:7168
	global_load_lds_dwordx4 v[146:147], off
	v_lshl_add_u64 v[146:147], s[28:29], 0, v[140:141]
	s_add_i32 m0, s27, 0xe000
	s_nop 0
	global_load_lds_dwordx4 v[146:147], off
	s_waitcnt vmcnt(8)
	s_waitcnt lgkmcnt(0)
	s_barrier
	s_setprio 1
	s_waitcnt lgkmcnt(0)
	v_mfma_f32_16x16x32_bf16 v[126:129], v[154:157], v[190:193], v[126:129]
	v_mfma_f32_16x16x32_bf16 v[122:125], v[162:165], v[190:193], v[122:125]
	v_mfma_f32_16x16x32_bf16 v[118:121], v[154:157], v[198:201], v[118:121]
	v_mfma_f32_16x16x32_bf16 v[110:113], v[162:165], v[198:201], v[110:113]
	v_mfma_f32_16x16x32_bf16 v[102:105], v[154:157], v[206:209], v[102:105]
	v_mfma_f32_16x16x32_bf16 v[94:97], v[162:165], v[206:209], v[94:97]
	v_mfma_f32_16x16x32_bf16 v[86:89], v[154:157], v[214:217], v[86:89]
	v_mfma_f32_16x16x32_bf16 v[78:81], v[162:165], v[214:217], v[78:81]
	v_mfma_f32_16x16x32_bf16 v[126:129], v[158:161], v[194:197], v[126:129]
	v_mfma_f32_16x16x32_bf16 v[122:125], v[166:169], v[194:197], v[122:125]
	v_mfma_f32_16x16x32_bf16 v[118:121], v[158:161], v[202:205], v[118:121]
	v_mfma_f32_16x16x32_bf16 v[110:113], v[166:169], v[202:205], v[110:113]
	v_mfma_f32_16x16x32_bf16 v[102:105], v[158:161], v[210:213], v[102:105]
	v_mfma_f32_16x16x32_bf16 v[94:97], v[166:169], v[210:213], v[94:97]
	v_mfma_f32_16x16x32_bf16 v[86:89], v[158:161], v[218:221], v[86:89]
	v_mfma_f32_16x16x32_bf16 v[78:81], v[166:169], v[218:221], v[78:81]
	v_mfma_f32_16x16x32_bf16 v[114:117], v[174:177], v[190:193], v[114:117]
	v_mfma_f32_16x16x32_bf16 v[106:109], v[182:185], v[190:193], v[106:109]
	v_mfma_f32_16x16x32_bf16 v[98:101], v[174:177], v[198:201], v[98:101]
	v_mfma_f32_16x16x32_bf16 v[90:93], v[182:185], v[198:201], v[90:93]
	v_mfma_f32_16x16x32_bf16 v[82:85], v[174:177], v[206:209], v[82:85]
	v_mfma_f32_16x16x32_bf16 v[74:77], v[182:185], v[206:209], v[74:77]
	v_mfma_f32_16x16x32_bf16 v[70:73], v[174:177], v[214:217], v[70:73]
	v_mfma_f32_16x16x32_bf16 v[66:69], v[182:185], v[214:217], v[66:69]
	v_mfma_f32_16x16x32_bf16 v[114:117], v[178:181], v[194:197], v[114:117]
	v_mfma_f32_16x16x32_bf16 v[106:109], v[186:189], v[194:197], v[106:109]
	v_mfma_f32_16x16x32_bf16 v[98:101], v[178:181], v[202:205], v[98:101]
	v_mfma_f32_16x16x32_bf16 v[90:93], v[186:189], v[202:205], v[90:93]
	v_mfma_f32_16x16x32_bf16 v[82:85], v[178:181], v[210:213], v[82:85]
	v_mfma_f32_16x16x32_bf16 v[74:77], v[186:189], v[210:213], v[74:77]
	v_mfma_f32_16x16x32_bf16 v[70:73], v[178:181], v[218:221], v[70:73]
	v_mfma_f32_16x16x32_bf16 v[66:69], v[186:189], v[218:221], v[66:69]
	s_setprio 0
	s_barrier
	s_add_i32 s69, s57, s42
	v_lshl_add_u64 v[146:147], s[30:31], 0, v[132:133]
	s_mov_b32 m0, s69
	ds_read_b128 v[190:193], v152 offset:16384
	ds_read_b128 v[194:197], v152 offset:17408
	ds_read_b128 v[198:201], v152 offset:18432
	ds_read_b128 v[202:205], v152 offset:19456
	ds_read_b128 v[206:209], v152 offset:20480
	ds_read_b128 v[210:213], v152 offset:21504
	ds_read_b128 v[214:217], v152 offset:22528
	ds_read_b128 v[218:221], v152 offset:23552
	global_load_lds_dwordx4 v[146:147], off
	s_add_i32 m0, s69, 0x2000
	s_add_u32 s70, s30, 0x40000
	v_lshl_add_u64 v[170:171], s[30:31], 0, v[136:137]
	s_addc_u32 s71, s31, 0
	s_add_i32 s69, s58, s42
	global_load_lds_dwordx4 v[170:171], off
	v_lshl_add_u64 v[222:223], s[70:71], 0, v[132:133]
	s_mov_b32 m0, s69
	v_lshl_add_u64 v[224:225], s[34:35], 0, v[134:135]
	global_load_lds_dwordx4 v[222:223], off
	v_lshl_add_u64 v[222:223], s[70:71], 0, v[136:137]
	s_add_i32 m0, s69, 0x2000
	s_nop 0
	global_load_lds_dwordx4 v[222:223], off
	v_lshl_add_u64 v[222:223], s[34:35], 0, v[130:131]
	s_mov_b32 m0, s27
	s_nop 0
	global_load_lds_dwordx4 v[222:223], off
	s_mov_b32 m0, s43
	s_nop 0
	global_load_lds_dwordx4 v[224:225], off
	s_waitcnt vmcnt(8)
	s_waitcnt lgkmcnt(0)
	s_barrier
; #define PG8_STAGE(bufoff, gbase, voff) do { _Pragma("unroll") for (int _i = 0; _i < 2; ++_i) \
;         __builtin_amdgcn_global_load_lds((const unsigned*)((const char*)(gbase) + (voff)[_i]), (PG8_LAS unsigned*)(lds + (bufoff) + ldsw + _i * 8192), 16, 0, 0); } while (0)
; #define PG8_LDA(dst, b, h) do { _Pragma("unroll") for (int m = 0; m < 4; ++m) _Pragma("unroll") for (int k = 0; k < 2; ++k) dst[m][k] = *(const PG8_LAS bf16x8*)(lds + PG8_SA(b, h) + aoff + m * 2048 + k * 1024); } while (0)
; #define PG8_LDB(dst, b, h) do { _Pragma("unroll") for (int n = 0; n < 2; ++n) _Pragma("unroll") for (int k = 0; k < 2; ++k) dst[n][k] = *(const PG8_LAS bf16x8*)(lds + PG8_SB(b, h) + boff + n * 2048 + k * 1024); } while (0)
; #define PG8_MMA(ai, bj, At, Bt) do { __builtin_amdgcn_s_setprio(1); _Pragma("unroll") for (int m = 0; m < 4; ++m) _Pragma("unroll") for (int n = 0; n < 2; ++n) _Pragma("unroll") for (int k = 0; k < 2; ++k) \
;         acc[ai][bj][m][n] = __builtin_amdgcn_mfma_f32_16x16x32_bf16(Bt[n][k], At[m][k], acc[ai][bj][m][n], 0, 0, 0); __builtin_amdgcn_s_setprio(0); } while (0)
; #define PG8_WAIT_V(n) asm volatile("s_waitcnt vmcnt(" #n ")" ::: "memory")
; #define PG8_WAIT_L(n) asm volatile("s_waitcnt lgkmcnt(" #n ")" ::: "memory")
; #define PG8_BAR __builtin_amdgcn_s_barrier()
; #define PG8_SCHED __builtin_amdgcn_sched_barrier(0)
; template <class Epi, class Sched, bool ALIGN_EPI = false, bool SP2 = false>
; __device__ __forceinline__ void gemm_phase(PG8_LAS unsigned char* lds, const Gemm g, const Sched& S, const Epi& E) {
;     ...
;             PG8_WAIT_V(8); PG8_WAIT_L(0); PG8_BAR; PG8_MMA(1, 0, At, B0); PG8_MMA(1, 1, At, B1); PG8_BAR; PG8_SCHED;
;             PG8_LDB(B0, 1, 0); PG8_LDB(B1, 1, 1); PG8_SCHED; PG8_LDA(At, 1, 0); PG8_STAGE(PG8_SA(0, 1), a2 + hstep, voffA);
;             PG8_WAIT_V(8); PG8_WAIT_L(0); PG8_BAR; PG8_MMA(0, 0, At, B0); PG8_MMA(0, 1, At, B1); PG8_BAR; PG8_SCHED;
	s_setprio 1
	s_waitcnt lgkmcnt(0)
	v_mfma_f32_16x16x32_bf16 v[62:65], v[154:157], v[190:193], v[62:65]
	v_mfma_f32_16x16x32_bf16 v[58:61], v[162:165], v[190:193], v[58:61]
	v_mfma_f32_16x16x32_bf16 v[54:57], v[154:157], v[198:201], v[54:57]
	v_mfma_f32_16x16x32_bf16 v[46:49], v[162:165], v[198:201], v[46:49]
	v_mfma_f32_16x16x32_bf16 v[38:41], v[154:157], v[206:209], v[38:41]
	v_mfma_f32_16x16x32_bf16 v[30:33], v[162:165], v[206:209], v[30:33]
	v_mfma_f32_16x16x32_bf16 v[22:25], v[154:157], v[214:217], v[22:25]
	v_mfma_f32_16x16x32_bf16 v[14:17], v[162:165], v[214:217], v[14:17]
	v_mfma_f32_16x16x32_bf16 v[62:65], v[158:161], v[194:197], v[62:65]
	v_mfma_f32_16x16x32_bf16 v[58:61], v[166:169], v[194:197], v[58:61]
	v_mfma_f32_16x16x32_bf16 v[54:57], v[158:161], v[202:205], v[54:57]
	v_mfma_f32_16x16x32_bf16 v[46:49], v[166:169], v[202:205], v[46:49]
	v_mfma_f32_16x16x32_bf16 v[38:41], v[158:161], v[210:213], v[38:41]
	v_mfma_f32_16x16x32_bf16 v[30:33], v[166:169], v[210:213], v[30:33]
	v_mfma_f32_16x16x32_bf16 v[22:25], v[158:161], v[218:221], v[22:25]
	v_mfma_f32_16x16x32_bf16 v[14:17], v[166:169], v[218:221], v[14:17]
	v_mfma_f32_16x16x32_bf16 v[50:53], v[174:177], v[190:193], v[50:53]
	v_mfma_f32_16x16x32_bf16 v[42:45], v[182:185], v[190:193], v[42:45]
	v_mfma_f32_16x16x32_bf16 v[34:37], v[174:177], v[198:201], v[34:37]
	v_mfma_f32_16x16x32_bf16 v[26:29], v[182:185], v[198:201], v[26:29]
	v_mfma_f32_16x16x32_bf16 v[18:21], v[174:177], v[206:209], v[18:21]
	v_mfma_f32_16x16x32_bf16 v[10:13], v[182:185], v[206:209], v[10:13]
	v_mfma_f32_16x16x32_bf16 v[6:9], v[174:177], v[214:217], v[6:9]
	v_mfma_f32_16x16x32_bf16 v[2:5], v[182:185], v[214:217], v[2:5]
	v_mfma_f32_16x16x32_bf16 v[50:53], v[178:181], v[194:197], v[50:53]
	v_mfma_f32_16x16x32_bf16 v[42:45], v[186:189], v[194:197], v[42:45]
	v_mfma_f32_16x16x32_bf16 v[34:37], v[178:181], v[202:205], v[34:37]
	v_mfma_f32_16x16x32_bf16 v[26:29], v[186:189], v[202:205], v[26:29]
	v_mfma_f32_16x16x32_bf16 v[18:21], v[178:181], v[210:213], v[18:21]
	v_mfma_f32_16x16x32_bf16 v[10:13], v[186:189], v[210:213], v[10:13]
	v_mfma_f32_16x16x32_bf16 v[6:9], v[178:181], v[218:221], v[6:9]
	v_mfma_f32_16x16x32_bf16 v[2:5], v[186:189], v[218:221], v[2:5]
	s_setprio 0
	s_barrier
	s_add_i32 s69, 0, 0x18000
	v_add_u32_e32 v153, s69, v148
	s_add_i32 s70, 0, 0x1c000
	ds_read_b128 v[154:157], v153
	ds_read_b128 v[158:161], v153 offset:1024
	ds_read_b128 v[162:165], v153 offset:2048
	ds_read_b128 v[166:169], v153 offset:3072
	v_add_u32_e32 v153, s70, v148
	ds_read_b128 v[174:177], v153
	ds_read_b128 v[178:181], v153 offset:1024
	ds_read_b128 v[182:185], v153 offset:2048
	ds_read_b128 v[186:189], v153 offset:3072
	s_add_u32 s34, s34, 0x40000
	s_addc_u32 s35, s35, 0
	s_mov_b32 m0, s44
	v_lshl_add_u64 v[226:227], s[34:35], 0, v[130:131]
	ds_read_b128 v[190:193], v152 offset:32768
	ds_read_b128 v[194:197], v152 offset:33792
	ds_read_b128 v[198:201], v152 offset:34816
	ds_read_b128 v[202:205], v152 offset:35840
	ds_read_b128 v[206:209], v152 offset:36864
	ds_read_b128 v[210:213], v152 offset:37888
	ds_read_b128 v[214:217], v152 offset:38912
	ds_read_b128 v[218:221], v152 offset:39936
	global_load_lds_dwordx4 v[226:227], off
	v_lshl_add_u64 v[226:227], s[34:35], 0, v[134:135]
	s_mov_b32 m0, s45
	s_nop 0
	global_load_lds_dwordx4 v[226:227], off
	s_waitcnt vmcnt(8)
	s_waitcnt lgkmcnt(0)
	s_barrier
	s_setprio 1
	s_waitcnt lgkmcnt(0)
	v_mfma_f32_16x16x32_bf16 v[126:129], v[154:157], v[190:193], v[126:129]
	v_mfma_f32_16x16x32_bf16 v[122:125], v[162:165], v[190:193], v[122:125]
	v_mfma_f32_16x16x32_bf16 v[118:121], v[154:157], v[198:201], v[118:121]
	v_mfma_f32_16x16x32_bf16 v[110:113], v[162:165], v[198:201], v[110:113]
	v_mfma_f32_16x16x32_bf16 v[102:105], v[154:157], v[206:209], v[102:105]
	v_mfma_f32_16x16x32_bf16 v[94:97], v[162:165], v[206:209], v[94:97]
	v_mfma_f32_16x16x32_bf16 v[86:89], v[154:157], v[214:217], v[86:89]
	v_mfma_f32_16x16x32_bf16 v[78:81], v[162:165], v[214:217], v[78:81]
	v_mfma_f32_16x16x32_bf16 v[126:129], v[158:161], v[194:197], v[126:129]
	v_mfma_f32_16x16x32_bf16 v[122:125], v[166:169], v[194:197], v[122:125]
	v_mfma_f32_16x16x32_bf16 v[118:121], v[158:161], v[202:205], v[118:121]
	v_mfma_f32_16x16x32_bf16 v[110:113], v[166:169], v[202:205], v[110:113]
	v_mfma_f32_16x16x32_bf16 v[102:105], v[158:161], v[210:213], v[102:105]
	v_mfma_f32_16x16x32_bf16 v[94:97], v[166:169], v[210:213], v[94:97]
	v_mfma_f32_16x16x32_bf16 v[86:89], v[158:161], v[218:221], v[86:89]
	v_mfma_f32_16x16x32_bf16 v[78:81], v[166:169], v[218:221], v[78:81]
	v_mfma_f32_16x16x32_bf16 v[114:117], v[174:177], v[190:193], v[114:117]
	v_mfma_f32_16x16x32_bf16 v[106:109], v[182:185], v[190:193], v[106:109]
	v_mfma_f32_16x16x32_bf16 v[98:101], v[174:177], v[198:201], v[98:101]
	v_mfma_f32_16x16x32_bf16 v[90:93], v[182:185], v[198:201], v[90:93]
	v_mfma_f32_16x16x32_bf16 v[82:85], v[174:177], v[206:209], v[82:85]
	v_mfma_f32_16x16x32_bf16 v[74:77], v[182:185], v[206:209], v[74:77]
	v_mfma_f32_16x16x32_bf16 v[70:73], v[174:177], v[214:217], v[70:73]
	v_mfma_f32_16x16x32_bf16 v[66:69], v[182:185], v[214:217], v[66:69]
	v_mfma_f32_16x16x32_bf16 v[114:117], v[178:181], v[194:197], v[114:117]
	v_mfma_f32_16x16x32_bf16 v[106:109], v[186:189], v[194:197], v[106:109]
	v_mfma_f32_16x16x32_bf16 v[98:101], v[178:181], v[202:205], v[98:101]
	v_mfma_f32_16x16x32_bf16 v[90:93], v[186:189], v[202:205], v[90:93]
	v_mfma_f32_16x16x32_bf16 v[82:85], v[178:181], v[210:213], v[82:85]
	v_mfma_f32_16x16x32_bf16 v[74:77], v[186:189], v[210:213], v[74:77]
	v_mfma_f32_16x16x32_bf16 v[70:73], v[178:181], v[218:221], v[70:73]
	v_mfma_f32_16x16x32_bf16 v[66:69], v[186:189], v[218:221], v[66:69]
	s_setprio 0
	s_barrier
; #define PG8_STAGE(bufoff, gbase, voff) do { _Pragma("unroll") for (int _i = 0; _i < 2; ++_i) \
;         __builtin_amdgcn_global_load_lds((const unsigned*)((const char*)(gbase) + (voff)[_i]), (PG8_LAS unsigned*)(lds + (bufoff) + ldsw + _i * 8192), 16, 0, 0); } while (0)
; #define PG8_LDA(dst, b, h) do { _Pragma("unroll") for (int m = 0; m < 4; ++m) _Pragma("unroll") for (int k = 0; k < 2; ++k) dst[m][k] = *(const PG8_LAS bf16x8*)(lds + PG8_SA(b, h) + aoff + m * 2048 + k * 1024); } while (0)
; #define PG8_MMA(ai, bj, At, Bt) do { __builtin_amdgcn_s_setprio(1); _Pragma("unroll") for (int m = 0; m < 4; ++m) _Pragma("unroll") for (int n = 0; n < 2; ++n) _Pragma("unroll") for (int k = 0; k < 2; ++k) \
;         acc[ai][bj][m][n] = __builtin_amdgcn_mfma_f32_16x16x32_bf16(Bt[n][k], At[m][k], acc[ai][bj][m][n], 0, 0, 0); __builtin_amdgcn_s_setprio(0); } while (0)
; #define PG8_WAIT_V(n) asm volatile("s_waitcnt vmcnt(" #n ")" ::: "memory")
; #define PG8_WAIT_L(n) asm volatile("s_waitcnt lgkmcnt(" #n ")" ::: "memory")
; #define PG8_BAR __builtin_amdgcn_s_barrier()
; #define PG8_SCHED __builtin_amdgcn_sched_barrier(0)
; template <class Epi, class Sched, bool ALIGN_EPI = false, bool SP2 = false>
; __device__ __forceinline__ void gemm_phase(PG8_LAS unsigned char* lds, const Gemm g, const Sched& S, const Epi& E) {
;     ...
;             PG8_WAIT_V(8); PG8_WAIT_L(0); PG8_BAR; PG8_MMA(0, 0, At, B0); PG8_MMA(0, 1, At, B1); PG8_BAR; PG8_SCHED;
;             PG8_LDA(At, 1, 1); PG8_STAGE(PG8_SB(1, 0), b3, voffB); PG8_STAGE(PG8_SB(1, 1), b3 + hstep, voffB); PG8_STAGE(PG8_SA(1, 0), a3, voffA);
;             PG8_WAIT_V(8); PG8_WAIT_L(0); PG8_BAR; PG8_MMA(1, 0, At, B0); PG8_MMA(1, 1, At, B1); PG8_BAR; PG8_SCHED;
	s_add_i32 s34, s69, s42
	v_lshl_add_u64 v[146:147], v[146:147], 0, s[8:9]
	s_mov_b32 m0, s34
	ds_read_b128 v[190:193], v152 offset:49152
	ds_read_b128 v[194:197], v152 offset:50176
	ds_read_b128 v[198:201], v152 offset:51200
	ds_read_b128 v[202:205], v152 offset:52224
	ds_read_b128 v[206:209], v152 offset:53248
	ds_read_b128 v[210:213], v152 offset:54272
	ds_read_b128 v[214:217], v152 offset:55296
	ds_read_b128 v[218:221], v152 offset:56320
	global_load_lds_dwordx4 v[146:147], off
	s_add_i32 m0, s34, 0x2000
	s_add_u32 s30, s30, 0x40080
	v_lshl_add_u64 v[146:147], v[170:171], 0, s[8:9]
	s_addc_u32 s31, s31, 0
	s_add_i32 s34, s70, s42
	global_load_lds_dwordx4 v[146:147], off
	v_lshl_add_u64 v[146:147], s[30:31], 0, v[132:133]
	s_mov_b32 m0, s34
	s_nop 0
	global_load_lds_dwordx4 v[146:147], off
	v_lshl_add_u64 v[146:147], s[30:31], 0, v[136:137]
	s_add_i32 m0, s34, 0x2000
	s_nop 0
	global_load_lds_dwordx4 v[146:147], off
	v_lshl_add_u64 v[146:147], v[222:223], 0, s[8:9]
	s_mov_b32 m0, s53
	s_nop 0
	global_load_lds_dwordx4 v[146:147], off
	v_lshl_add_u64 v[146:147], v[224:225], 0, s[8:9]
	s_mov_b32 m0, s54
	s_nop 0
	global_load_lds_dwordx4 v[146:147], off
	s_waitcnt vmcnt(8)
	s_waitcnt lgkmcnt(0)
	s_barrier
	s_setprio 1
	s_waitcnt lgkmcnt(0)
	v_mfma_f32_16x16x32_bf16 v[62:65], v[154:157], v[190:193], v[62:65]
	v_mfma_f32_16x16x32_bf16 v[58:61], v[162:165], v[190:193], v[58:61]
	v_mfma_f32_16x16x32_bf16 v[54:57], v[154:157], v[198:201], v[54:57]
	v_mfma_f32_16x16x32_bf16 v[46:49], v[162:165], v[198:201], v[46:49]
	v_mfma_f32_16x16x32_bf16 v[38:41], v[154:157], v[206:209], v[38:41]
	v_mfma_f32_16x16x32_bf16 v[30:33], v[162:165], v[206:209], v[30:33]
	v_mfma_f32_16x16x32_bf16 v[22:25], v[154:157], v[214:217], v[22:25]
	v_mfma_f32_16x16x32_bf16 v[14:17], v[162:165], v[214:217], v[14:17]
	v_mfma_f32_16x16x32_bf16 v[62:65], v[158:161], v[194:197], v[62:65]
	v_mfma_f32_16x16x32_bf16 v[58:61], v[166:169], v[194:197], v[58:61]
	v_mfma_f32_16x16x32_bf16 v[54:57], v[158:161], v[202:205], v[54:57]
	v_mfma_f32_16x16x32_bf16 v[46:49], v[166:169], v[202:205], v[46:49]
	v_mfma_f32_16x16x32_bf16 v[38:41], v[158:161], v[210:213], v[38:41]
	v_mfma_f32_16x16x32_bf16 v[30:33], v[166:169], v[210:213], v[30:33]
	v_mfma_f32_16x16x32_bf16 v[22:25], v[158:161], v[218:221], v[22:25]
	v_mfma_f32_16x16x32_bf16 v[14:17], v[166:169], v[218:221], v[14:17]
	v_mfma_f32_16x16x32_bf16 v[50:53], v[174:177], v[190:193], v[50:53]
	v_mfma_f32_16x16x32_bf16 v[42:45], v[182:185], v[190:193], v[42:45]
	v_mfma_f32_16x16x32_bf16 v[34:37], v[174:177], v[198:201], v[34:37]
	v_mfma_f32_16x16x32_bf16 v[26:29], v[182:185], v[198:201], v[26:29]
	v_mfma_f32_16x16x32_bf16 v[18:21], v[174:177], v[206:209], v[18:21]
	v_mfma_f32_16x16x32_bf16 v[10:13], v[182:185], v[206:209], v[10:13]
	v_mfma_f32_16x16x32_bf16 v[6:9], v[174:177], v[214:217], v[6:9]
	v_mfma_f32_16x16x32_bf16 v[2:5], v[182:185], v[214:217], v[2:5]
	v_mfma_f32_16x16x32_bf16 v[50:53], v[178:181], v[194:197], v[50:53]
	v_mfma_f32_16x16x32_bf16 v[42:45], v[186:189], v[194:197], v[42:45]
	v_mfma_f32_16x16x32_bf16 v[34:37], v[178:181], v[202:205], v[34:37]
	v_mfma_f32_16x16x32_bf16 v[26:29], v[186:189], v[202:205], v[26:29]
	v_mfma_f32_16x16x32_bf16 v[18:21], v[178:181], v[210:213], v[18:21]
	v_mfma_f32_16x16x32_bf16 v[10:13], v[186:189], v[210:213], v[10:13]
	v_mfma_f32_16x16x32_bf16 v[6:9], v[178:181], v[218:221], v[6:9]
	v_mfma_f32_16x16x32_bf16 v[2:5], v[186:189], v[218:221], v[2:5]
	s_setprio 0
	s_barrier
	s_add_i32 s68, s68, 2
	s_add_u32 s28, s28, 0x100
	s_addc_u32 s29, s29, 0
	s_add_u32 s66, s66, 0x100
	s_addc_u32 s67, s67, 0
	s_cmp_gt_u32 s68, 13
	s_cbranch_scc0 .LBB0_1432
	s_and_b64 vcc, exec, s[10:11]
	s_cbranch_vccz .LBB0_1435
	s_barrier

; #define PG8_STAGE(bufoff, gbase, voff) do { _Pragma("unroll") for (int _i = 0; _i < 2; ++_i) \
;         __builtin_amdgcn_global_load_lds((const unsigned*)((const char*)(gbase) + (voff)[_i]), (PG8_LAS unsigned*)(lds + (bufoff) + ldsw + _i * 8192), 16, 0, 0); } while (0)
; #define PG8_LDA(dst, b, h) do { _Pragma("unroll") for (int m = 0; m < 4; ++m) _Pragma("unroll") for (int k = 0; k < 2; ++k) dst[m][k] = *(const PG8_LAS bf16x8*)(lds + PG8_SA(b, h) + aoff + m * 2048 + k * 1024); } while (0)
; #define PG8_LDB(dst, b, h) do { _Pragma("unroll") for (int n = 0; n < 2; ++n) _Pragma("unroll") for (int k = 0; k < 2; ++k) dst[n][k] = *(const PG8_LAS bf16x8*)(lds + PG8_SB(b, h) + boff + n * 2048 + k * 1024); } while (0)
; #define PG8_SCHED __builtin_amdgcn_sched_barrier(0)
; template <class Epi, class Sched, bool ALIGN_EPI = false, bool SP2 = false>
; __device__ __forceinline__ void gemm_phase(PG8_LAS unsigned char* lds, const Gemm g, const Sched& S, const Epi& E) {
;     ...
;         const bool has_next = S.next(ui + 1, nxt);
;         const char* nA = has_next ? (const char*)g.A + (size_t)nxt.pm * tstep : cA; const char* nB = has_next ? (const char*)g.Bt + (size_t)nxt.pn * tstep : cB;
; #pragma nounroll
;         for (int t = 0; t < nt; t += 2) {
;             const bool last = (t == nt - 2);
;             const char* a1 = cA + (size_t)(t + 1) * kstep;
;             const char* a2 = last ? nA : cA + (size_t)(t + 2) * kstep; const char* b2 = last ? nB : cB + (size_t)(t + 2) * kstep;
;             const char* a3 = a2 + kstep; const char* b3 = b2 + kstep;
;             if (last && has_next) S.a_ready(nxt);
;             if constexpr (SP2) {
;             PG8_LDB(B0, 0, 0); PG8_LDB(B1, 0, 1); PG8_SCHED; PG8_LDA(At, 0, 0); PG8_STAGE(PG8_SA(1, 1), a1 + hstep, voffA);
.LBB0_1590:
	s_ashr_i32 s13, s12, 31
	s_lshl_b64 s[14:15], s[12:13], 19
	s_add_u32 s14, s26, s14
	s_addc_u32 s15, s27, s15
	s_and_b64 s[16:17], s[2:3], exec
	s_cselect_b32 s13, s15, s21
	s_cselect_b32 s52, s14, s20
	s_ashr_i32 s11, s10, 31
	s_lshl_b64 s[16:17], s[10:11], 19
	s_add_u32 s16, s28, s16
	s_addc_u32 s17, s29, s17
	s_and_b64 s[24:25], s[2:3], exec
	s_cselect_b32 s11, s17, s23
	s_cselect_b32 s53, s16, s22
	s_add_u32 s20, s20, 0x40080
	s_addc_u32 s21, s21, 0
	s_add_u32 s54, s22, 0x100
	s_addc_u32 s55, s23, 0
	s_mov_b32 s56, -2
	ds_read_b128 v[152:155], v149
	ds_read_b128 v[156:159], v149 offset:1024
	ds_read_b128 v[160:163], v149 offset:2048
	ds_read_b128 v[164:167], v149 offset:3072
	ds_read_b128 v[168:171], v150
	ds_read_b128 v[174:177], v150 offset:1024
	ds_read_b128 v[178:181], v150 offset:2048
	ds_read_b128 v[182:185], v150 offset:3072
	s_add_u32 s22, s20, 0xfffc0080
	s_addc_u32 s23, s21, -1
	s_cmp_eq_u32 s56, 12
	s_cselect_b32 s25, s13, s23
	s_cselect_b32 s24, s52, s22
	s_cselect_b32 s23, s11, s55
	s_cselect_b32 s22, s53, s54

; #define PG8_STAGE(bufoff, gbase, voff) do { _Pragma("unroll") for (int _i = 0; _i < 2; ++_i) \
;         __builtin_amdgcn_global_load_lds((const unsigned*)((const char*)(gbase) + (voff)[_i]), (PG8_LAS unsigned*)(lds + (bufoff) + ldsw + _i * 8192), 16, 0, 0); } while (0)
; #define PG8_LDA(dst, b, h) do { _Pragma("unroll") for (int m = 0; m < 4; ++m) _Pragma("unroll") for (int k = 0; k < 2; ++k) dst[m][k] = *(const PG8_LAS bf16x8*)(lds + PG8_SA(b, h) + aoff + m * 2048 + k * 1024); } while (0)
; #define PG8_LDB(dst, b, h) do { _Pragma("unroll") for (int n = 0; n < 2; ++n) _Pragma("unroll") for (int k = 0; k < 2; ++k) dst[n][k] = *(const PG8_LAS bf16x8*)(lds + PG8_SB(b, h) + boff + n * 2048 + k * 1024); } while (0)
; #define PG8_MMA(ai, bj, At, Bt) do { __builtin_amdgcn_s_setprio(1); _Pragma("unroll") for (int m = 0; m < 4; ++m) _Pragma("unroll") for (int n = 0; n < 2; ++n) _Pragma("unroll") for (int k = 0; k < 2; ++k) \
;         acc[ai][bj][m][n] = __builtin_amdgcn_mfma_f32_16x16x32_bf16(Bt[n][k], At[m][k], acc[ai][bj][m][n], 0, 0, 0); __builtin_amdgcn_s_setprio(0); } while (0)
; #define PG8_WAIT_V(n) asm volatile("s_waitcnt vmcnt(" #n ")" ::: "memory")
; #define PG8_WAIT_L(n) asm volatile("s_waitcnt lgkmcnt(" #n ")" ::: "memory")
; #define PG8_BAR __builtin_amdgcn_s_barrier()
; #define PG8_SCHED __builtin_amdgcn_sched_barrier(0)
; template <class Epi, class Sched, bool ALIGN_EPI = false, bool SP2 = false>
; __device__ __forceinline__ void gemm_phase(PG8_LAS unsigned char* lds, const Gemm g, const Sched& S, const Epi& E) {
;     ...
;             PG8_LDB(B0, 0, 0); PG8_LDB(B1, 0, 1); PG8_SCHED; PG8_LDA(At, 0, 0); PG8_STAGE(PG8_SA(1, 1), a1 + hstep, voffA);
;             PG8_WAIT_V(8); PG8_WAIT_L(0); PG8_BAR; PG8_MMA(0, 0, At, B0); PG8_MMA(0, 1, At, B1); PG8_BAR; PG8_SCHED;
	v_lshl_add_u64 v[218:219], s[20:21], 0, v[140:141]
	s_add_i32 m0, s34, 0xc000
	ds_read_b128 v[186:189], v151
	ds_read_b128 v[190:193], v151 offset:1024
	ds_read_b128 v[194:197], v151 offset:2048
	ds_read_b128 v[198:201], v151 offset:3072
	ds_read_b128 v[202:205], v151 offset:4096
	ds_read_b128 v[206:209], v151 offset:5120
	ds_read_b128 v[210:213], v151 offset:6144
	ds_read_b128 v[214:217], v151 offset:7168
	global_load_lds_dwordx4 v[218:219], off
	v_lshl_add_u64 v[218:219], s[20:21], 0, v[142:143]
	s_add_i32 m0, s34, 0xe000
	s_nop 0
	global_load_lds_dwordx4 v[218:219], off
	s_waitcnt vmcnt(16)
	s_waitcnt lgkmcnt(0)
	s_barrier
	s_setprio 1
	s_waitcnt lgkmcnt(0)
	v_mfma_f32_16x16x32_bf16 v[126:129], v[152:155], v[186:189], 0
	v_mfma_f32_16x16x32_bf16 v[122:125], v[160:163], v[186:189], 0
	v_mfma_f32_16x16x32_bf16 v[110:113], v[152:155], v[194:197], 0
	v_mfma_f32_16x16x32_bf16 v[106:109], v[160:163], v[194:197], 0
	v_mfma_f32_16x16x32_bf16 v[94:97], v[152:155], v[202:205], 0
	v_mfma_f32_16x16x32_bf16 v[90:93], v[160:163], v[202:205], 0
	v_mfma_f32_16x16x32_bf16 v[78:81], v[152:155], v[210:213], 0
	v_mfma_f32_16x16x32_bf16 v[74:77], v[160:163], v[210:213], 0
	v_mfma_f32_16x16x32_bf16 v[126:129], v[156:159], v[190:193], v[126:129]
	v_mfma_f32_16x16x32_bf16 v[122:125], v[164:167], v[190:193], v[122:125]
	v_mfma_f32_16x16x32_bf16 v[110:113], v[156:159], v[198:201], v[110:113]
	v_mfma_f32_16x16x32_bf16 v[106:109], v[164:167], v[198:201], v[106:109]
	v_mfma_f32_16x16x32_bf16 v[94:97], v[156:159], v[206:209], v[94:97]
	v_mfma_f32_16x16x32_bf16 v[90:93], v[164:167], v[206:209], v[90:93]
	v_mfma_f32_16x16x32_bf16 v[78:81], v[156:159], v[214:217], v[78:81]
	v_mfma_f32_16x16x32_bf16 v[74:77], v[164:167], v[214:217], v[74:77]
	v_mfma_f32_16x16x32_bf16 v[118:121], v[168:171], v[186:189], 0
	v_mfma_f32_16x16x32_bf16 v[114:117], v[178:181], v[186:189], 0
	v_mfma_f32_16x16x32_bf16 v[102:105], v[168:171], v[194:197], 0
	v_mfma_f32_16x16x32_bf16 v[98:101], v[178:181], v[194:197], 0
	v_mfma_f32_16x16x32_bf16 v[86:89], v[168:171], v[202:205], 0
	v_mfma_f32_16x16x32_bf16 v[82:85], v[178:181], v[202:205], 0
	v_mfma_f32_16x16x32_bf16 v[70:73], v[168:171], v[210:213], 0
	v_mfma_f32_16x16x32_bf16 v[66:69], v[178:181], v[210:213], 0
	v_mfma_f32_16x16x32_bf16 v[118:121], v[174:177], v[190:193], v[118:121]
	v_mfma_f32_16x16x32_bf16 v[114:117], v[182:185], v[190:193], v[114:117]
	v_mfma_f32_16x16x32_bf16 v[102:105], v[174:177], v[198:201], v[102:105]
	v_mfma_f32_16x16x32_bf16 v[98:101], v[182:185], v[198:201], v[98:101]
	v_mfma_f32_16x16x32_bf16 v[86:89], v[174:177], v[206:209], v[86:89]
	v_mfma_f32_16x16x32_bf16 v[82:85], v[182:185], v[206:209], v[82:85]
	v_mfma_f32_16x16x32_bf16 v[70:73], v[174:177], v[214:217], v[70:73]
	v_mfma_f32_16x16x32_bf16 v[66:69], v[182:185], v[214:217], v[66:69]
	s_setprio 0
	s_barrier

; #define PG8_STAGE(bufoff, gbase, voff) do { _Pragma("unroll") for (int _i = 0; _i < 2; ++_i) \
;         __builtin_amdgcn_global_load_lds((const unsigned*)((const char*)(gbase) + (voff)[_i]), (PG8_LAS unsigned*)(lds + (bufoff) + ldsw + _i * 8192), 16, 0, 0); } while (0)
; #define PG8_LDA(dst, b, h) do { _Pragma("unroll") for (int m = 0; m < 4; ++m) _Pragma("unroll") for (int k = 0; k < 2; ++k) dst[m][k] = *(const PG8_LAS bf16x8*)(lds + PG8_SA(b, h) + aoff + m * 2048 + k * 1024); } while (0)
; #define PG8_MMA(ai, bj, At, Bt) do { __builtin_amdgcn_s_setprio(1); _Pragma("unroll") for (int m = 0; m < 4; ++m) _Pragma("unroll") for (int n = 0; n < 2; ++n) _Pragma("unroll") for (int k = 0; k < 2; ++k) \
;         acc[ai][bj][m][n] = __builtin_amdgcn_mfma_f32_16x16x32_bf16(Bt[n][k], At[m][k], acc[ai][bj][m][n], 0, 0, 0); __builtin_amdgcn_s_setprio(0); } while (0)
; #define PG8_WAIT_V(n) asm volatile("s_waitcnt vmcnt(" #n ")" ::: "memory")
; #define PG8_WAIT_L(n) asm volatile("s_waitcnt lgkmcnt(" #n ")" ::: "memory")
; #define PG8_BAR __builtin_amdgcn_s_barrier()
; #define PG8_SCHED __builtin_amdgcn_sched_barrier(0)
; template <class Epi, class Sched, bool ALIGN_EPI = false, bool SP2 = false>
; __device__ __forceinline__ void gemm_phase(PG8_LAS unsigned char* lds, const Gemm g, const Sched& S, const Epi& E) {
;     ...
;             PG8_LDA(At, 0, 1); PG8_STAGE(PG8_SB(0, 0), b2, voffB); PG8_STAGE(PG8_SB(0, 1), b2 + hstep, voffB); PG8_STAGE(PG8_SA(0, 0), a2, voffA);
;             PG8_WAIT_V(8); PG8_WAIT_L(0); PG8_BAR; PG8_MMA(1, 0, At, B0); PG8_MMA(1, 1, At, B1); PG8_BAR; PG8_SCHED;
	s_add_i32 s57, s45, s30
	v_lshl_add_u64 v[218:219], s[22:23], 0, v[134:135]
	s_mov_b32 m0, s57
	ds_read_b128 v[186:189], v151 offset:16384
	ds_read_b128 v[190:193], v151 offset:17408
	ds_read_b128 v[194:197], v151 offset:18432
	ds_read_b128 v[198:201], v151 offset:19456
	ds_read_b128 v[202:205], v151 offset:20480
	ds_read_b128 v[206:209], v151 offset:21504
	ds_read_b128 v[210:213], v151 offset:22528
	ds_read_b128 v[214:217], v151 offset:23552
	global_load_lds_dwordx4 v[218:219], off
	s_add_i32 m0, s57, 0x2000
	s_add_u32 s58, s22, 0x40000
	v_lshl_add_u64 v[220:221], s[22:23], 0, v[130:131]
	s_addc_u32 s59, s23, 0
	s_add_i32 s57, s48, s30
	global_load_lds_dwordx4 v[220:221], off
	v_lshl_add_u64 v[222:223], s[58:59], 0, v[134:135]
	s_mov_b32 m0, s57
	v_lshl_add_u64 v[224:225], s[24:25], 0, v[132:133]
	global_load_lds_dwordx4 v[222:223], off
	v_lshl_add_u64 v[222:223], s[58:59], 0, v[130:131]
	s_add_i32 m0, s57, 0x2000
	s_nop 0
	global_load_lds_dwordx4 v[222:223], off
	v_lshl_add_u64 v[222:223], s[24:25], 0, v[136:137]
	s_mov_b32 m0, s34
	s_nop 0
	global_load_lds_dwordx4 v[222:223], off
	s_mov_b32 m0, s35
	s_nop 0
	global_load_lds_dwordx4 v[224:225], off
	s_waitcnt vmcnt(16)
	s_waitcnt lgkmcnt(0)
	s_barrier
	s_setprio 1
	s_waitcnt lgkmcnt(0)
	v_mfma_f32_16x16x32_bf16 v[62:65], v[152:155], v[186:189], 0
	v_mfma_f32_16x16x32_bf16 v[58:61], v[160:163], v[186:189], 0
	v_mfma_f32_16x16x32_bf16 v[46:49], v[152:155], v[194:197], 0
	v_mfma_f32_16x16x32_bf16 v[42:45], v[160:163], v[194:197], 0
	v_mfma_f32_16x16x32_bf16 v[30:33], v[152:155], v[202:205], 0
	v_mfma_f32_16x16x32_bf16 v[26:29], v[160:163], v[202:205], 0
	v_mfma_f32_16x16x32_bf16 v[14:17], v[152:155], v[210:213], 0
	v_mfma_f32_16x16x32_bf16 v[10:13], v[160:163], v[210:213], 0
	v_mfma_f32_16x16x32_bf16 v[62:65], v[156:159], v[190:193], v[62:65]
	v_mfma_f32_16x16x32_bf16 v[58:61], v[164:167], v[190:193], v[58:61]
	v_mfma_f32_16x16x32_bf16 v[46:49], v[156:159], v[198:201], v[46:49]
	v_mfma_f32_16x16x32_bf16 v[42:45], v[164:167], v[198:201], v[42:45]
	v_mfma_f32_16x16x32_bf16 v[30:33], v[156:159], v[206:209], v[30:33]
	v_mfma_f32_16x16x32_bf16 v[26:29], v[164:167], v[206:209], v[26:29]
	v_mfma_f32_16x16x32_bf16 v[14:17], v[156:159], v[214:217], v[14:17]
	v_mfma_f32_16x16x32_bf16 v[10:13], v[164:167], v[214:217], v[10:13]
	v_mfma_f32_16x16x32_bf16 v[54:57], v[168:171], v[186:189], 0
	v_mfma_f32_16x16x32_bf16 v[50:53], v[178:181], v[186:189], 0
	v_mfma_f32_16x16x32_bf16 v[38:41], v[168:171], v[194:197], 0
	v_mfma_f32_16x16x32_bf16 v[34:37], v[178:181], v[194:197], 0
	v_mfma_f32_16x16x32_bf16 v[22:25], v[168:171], v[202:205], 0
	v_mfma_f32_16x16x32_bf16 v[18:21], v[178:181], v[202:205], 0
	v_mfma_f32_16x16x32_bf16 v[6:9], v[168:171], v[210:213], 0
	v_mfma_f32_16x16x32_bf16 v[2:5], v[178:181], v[210:213], 0
	v_mfma_f32_16x16x32_bf16 v[54:57], v[174:177], v[190:193], v[54:57]
	v_mfma_f32_16x16x32_bf16 v[50:53], v[182:185], v[190:193], v[50:53]
	v_mfma_f32_16x16x32_bf16 v[38:41], v[174:177], v[198:201], v[38:41]
	v_mfma_f32_16x16x32_bf16 v[34:37], v[182:185], v[198:201], v[34:37]
	v_mfma_f32_16x16x32_bf16 v[22:25], v[174:177], v[206:209], v[22:25]
	v_mfma_f32_16x16x32_bf16 v[18:21], v[182:185], v[206:209], v[18:21]
	v_mfma_f32_16x16x32_bf16 v[6:9], v[174:177], v[214:217], v[6:9]
	v_mfma_f32_16x16x32_bf16 v[2:5], v[182:185], v[214:217], v[2:5]
	s_setprio 0
	s_barrier

; #define PG8_STAGE(bufoff, gbase, voff) do { _Pragma("unroll") for (int _i = 0; _i < 2; ++_i) \
;         __builtin_amdgcn_global_load_lds((const unsigned*)((const char*)(gbase) + (voff)[_i]), (PG8_LAS unsigned*)(lds + (bufoff) + ldsw + _i * 8192), 16, 0, 0); } while (0)
; #define PG8_LDA(dst, b, h) do { _Pragma("unroll") for (int m = 0; m < 4; ++m) _Pragma("unroll") for (int k = 0; k < 2; ++k) dst[m][k] = *(const PG8_LAS bf16x8*)(lds + PG8_SA(b, h) + aoff + m * 2048 + k * 1024); } while (0)
; #define PG8_LDB(dst, b, h) do { _Pragma("unroll") for (int n = 0; n < 2; ++n) _Pragma("unroll") for (int k = 0; k < 2; ++k) dst[n][k] = *(const PG8_LAS bf16x8*)(lds + PG8_SB(b, h) + boff + n * 2048 + k * 1024); } while (0)
; #define PG8_SCHED __builtin_amdgcn_sched_barrier(0)
; template <class Epi, class Sched, bool ALIGN_EPI = false, bool SP2 = false>
; __device__ __forceinline__ void gemm_phase(PG8_LAS unsigned char* lds, const Gemm g, const Sched& S, const Epi& E) {
;     ...
;             PG8_LDB(B0, 1, 0); PG8_LDB(B1, 1, 1); PG8_SCHED; PG8_LDA(At, 1, 0); PG8_STAGE(PG8_SA(0, 1), a2 + hstep, voffA);
	s_add_i32 s57, 0, 0x18000
	s_add_i32 s58, 0, 0x1c000
	v_add_u32_e32 v164, s57, v148
	v_add_u32_e32 v182, s58, v148
	ds_read_b128 v[152:155], v164
	ds_read_b128 v[156:159], v164 offset:1024
	ds_read_b128 v[160:163], v164 offset:2048
	ds_read_b128 v[164:167], v164 offset:3072
	ds_read_b128 v[168:171], v182
	ds_read_b128 v[174:177], v182 offset:1024
	ds_read_b128 v[178:181], v182 offset:2048
	ds_read_b128 v[182:185], v182 offset:3072

; #define PG8_STAGE(bufoff, gbase, voff) do { _Pragma("unroll") for (int _i = 0; _i < 2; ++_i) \
;         __builtin_amdgcn_global_load_lds((const unsigned*)((const char*)(gbase) + (voff)[_i]), (PG8_LAS unsigned*)(lds + (bufoff) + ldsw + _i * 8192), 16, 0, 0); } while (0)
; #define PG8_LDA(dst, b, h) do { _Pragma("unroll") for (int m = 0; m < 4; ++m) _Pragma("unroll") for (int k = 0; k < 2; ++k) dst[m][k] = *(const PG8_LAS bf16x8*)(lds + PG8_SA(b, h) + aoff + m * 2048 + k * 1024); } while (0)
; #define PG8_LDB(dst, b, h) do { _Pragma("unroll") for (int n = 0; n < 2; ++n) _Pragma("unroll") for (int k = 0; k < 2; ++k) dst[n][k] = *(const PG8_LAS bf16x8*)(lds + PG8_SB(b, h) + boff + n * 2048 + k * 1024); } while (0)
; #define PG8_MMA(ai, bj, At, Bt) do { __builtin_amdgcn_s_setprio(1); _Pragma("unroll") for (int m = 0; m < 4; ++m) _Pragma("unroll") for (int n = 0; n < 2; ++n) _Pragma("unroll") for (int k = 0; k < 2; ++k) \
;         acc[ai][bj][m][n] = __builtin_amdgcn_mfma_f32_16x16x32_bf16(Bt[n][k], At[m][k], acc[ai][bj][m][n], 0, 0, 0); __builtin_amdgcn_s_setprio(0); } while (0)
; #define PG8_WAIT_V(n) asm volatile("s_waitcnt vmcnt(" #n ")" ::: "memory")
; #define PG8_WAIT_L(n) asm volatile("s_waitcnt lgkmcnt(" #n ")" ::: "memory")
; #define PG8_BAR __builtin_amdgcn_s_barrier()
; #define PG8_SCHED __builtin_amdgcn_sched_barrier(0)
; template <class Epi, class Sched, bool ALIGN_EPI = false, bool SP2 = false>
; __device__ __forceinline__ void gemm_phase(PG8_LAS unsigned char* lds, const Gemm g, const Sched& S, const Epi& E) {
;     ...
;             PG8_LDB(B0, 1, 0); PG8_LDB(B1, 1, 1); PG8_SCHED; PG8_LDA(At, 1, 0); PG8_STAGE(PG8_SA(0, 1), a2 + hstep, voffA);
;             PG8_WAIT_V(8); PG8_WAIT_L(0); PG8_BAR; PG8_MMA(0, 0, At, B0); PG8_MMA(0, 1, At, B1); PG8_BAR; PG8_SCHED;
	s_add_u32 s24, s24, 0x40000
	s_addc_u32 s25, s25, 0
	s_mov_b32 m0, s38
	v_lshl_add_u64 v[226:227], s[24:25], 0, v[136:137]
	ds_read_b128 v[186:189], v151 offset:32768
	ds_read_b128 v[190:193], v151 offset:33792
	ds_read_b128 v[194:197], v151 offset:34816
	ds_read_b128 v[198:201], v151 offset:35840
	ds_read_b128 v[202:205], v151 offset:36864
	ds_read_b128 v[206:209], v151 offset:37888
	ds_read_b128 v[210:213], v151 offset:38912
	ds_read_b128 v[214:217], v151 offset:39936
	global_load_lds_dwordx4 v[226:227], off
	v_lshl_add_u64 v[226:227], s[24:25], 0, v[132:133]
	s_mov_b32 m0, s39
	s_nop 0
	global_load_lds_dwordx4 v[226:227], off
	s_waitcnt vmcnt(8)
	s_waitcnt lgkmcnt(0)
	s_barrier
	s_setprio 1
	s_waitcnt lgkmcnt(0)
	v_mfma_f32_16x16x32_bf16 v[126:129], v[152:155], v[186:189], v[126:129]
	v_mfma_f32_16x16x32_bf16 v[122:125], v[160:163], v[186:189], v[122:125]
	v_mfma_f32_16x16x32_bf16 v[110:113], v[152:155], v[194:197], v[110:113]
	v_mfma_f32_16x16x32_bf16 v[106:109], v[160:163], v[194:197], v[106:109]
	v_mfma_f32_16x16x32_bf16 v[94:97], v[152:155], v[202:205], v[94:97]
	v_mfma_f32_16x16x32_bf16 v[90:93], v[160:163], v[202:205], v[90:93]
	v_mfma_f32_16x16x32_bf16 v[78:81], v[152:155], v[210:213], v[78:81]
	v_mfma_f32_16x16x32_bf16 v[74:77], v[160:163], v[210:213], v[74:77]
	v_mfma_f32_16x16x32_bf16 v[126:129], v[156:159], v[190:193], v[126:129]
	v_mfma_f32_16x16x32_bf16 v[122:125], v[164:167], v[190:193], v[122:125]
	v_mfma_f32_16x16x32_bf16 v[110:113], v[156:159], v[198:201], v[110:113]
	v_mfma_f32_16x16x32_bf16 v[106:109], v[164:167], v[198:201], v[106:109]
	v_mfma_f32_16x16x32_bf16 v[94:97], v[156:159], v[206:209], v[94:97]
	v_mfma_f32_16x16x32_bf16 v[90:93], v[164:167], v[206:209], v[90:93]
	v_mfma_f32_16x16x32_bf16 v[78:81], v[156:159], v[214:217], v[78:81]
	v_mfma_f32_16x16x32_bf16 v[74:77], v[164:167], v[214:217], v[74:77]
	v_mfma_f32_16x16x32_bf16 v[118:121], v[168:171], v[186:189], v[118:121]
	v_mfma_f32_16x16x32_bf16 v[114:117], v[178:181], v[186:189], v[114:117]
	v_mfma_f32_16x16x32_bf16 v[102:105], v[168:171], v[194:197], v[102:105]
	v_mfma_f32_16x16x32_bf16 v[98:101], v[178:181], v[194:197], v[98:101]
	v_mfma_f32_16x16x32_bf16 v[86:89], v[168:171], v[202:205], v[86:89]
	v_mfma_f32_16x16x32_bf16 v[82:85], v[178:181], v[202:205], v[82:85]
	v_mfma_f32_16x16x32_bf16 v[70:73], v[168:171], v[210:213], v[70:73]
	v_mfma_f32_16x16x32_bf16 v[66:69], v[178:181], v[210:213], v[66:69]
	v_mfma_f32_16x16x32_bf16 v[118:121], v[174:177], v[190:193], v[118:121]
	v_mfma_f32_16x16x32_bf16 v[114:117], v[182:185], v[190:193], v[114:117]
	v_mfma_f32_16x16x32_bf16 v[102:105], v[174:177], v[198:201], v[102:105]
	v_mfma_f32_16x16x32_bf16 v[98:101], v[182:185], v[198:201], v[98:101]
	v_mfma_f32_16x16x32_bf16 v[86:89], v[174:177], v[206:209], v[86:89]
	v_mfma_f32_16x16x32_bf16 v[82:85], v[182:185], v[206:209], v[82:85]
	v_mfma_f32_16x16x32_bf16 v[70:73], v[174:177], v[214:217], v[70:73]
	v_mfma_f32_16x16x32_bf16 v[66:69], v[182:185], v[214:217], v[66:69]
	s_setprio 0
	s_barrier

; #define PG8_STAGE(bufoff, gbase, voff) do { _Pragma("unroll") for (int _i = 0; _i < 2; ++_i) \
;         __builtin_amdgcn_global_load_lds((const unsigned*)((const char*)(gbase) + (voff)[_i]), (PG8_LAS unsigned*)(lds + (bufoff) + ldsw + _i * 8192), 16, 0, 0); } while (0)
; #define PG8_LDA(dst, b, h) do { _Pragma("unroll") for (int m = 0; m < 4; ++m) _Pragma("unroll") for (int k = 0; k < 2; ++k) dst[m][k] = *(const PG8_LAS bf16x8*)(lds + PG8_SA(b, h) + aoff + m * 2048 + k * 1024); } while (0)
; #define PG8_MMA(ai, bj, At, Bt) do { __builtin_amdgcn_s_setprio(1); _Pragma("unroll") for (int m = 0; m < 4; ++m) _Pragma("unroll") for (int n = 0; n < 2; ++n) _Pragma("unroll") for (int k = 0; k < 2; ++k) \
;         acc[ai][bj][m][n] = __builtin_amdgcn_mfma_f32_16x16x32_bf16(Bt[n][k], At[m][k], acc[ai][bj][m][n], 0, 0, 0); __builtin_amdgcn_s_setprio(0); } while (0)
; #define PG8_WAIT_V(n) asm volatile("s_waitcnt vmcnt(" #n ")" ::: "memory")
; #define PG8_WAIT_L(n) asm volatile("s_waitcnt lgkmcnt(" #n ")" ::: "memory")
; #define PG8_BAR __builtin_amdgcn_s_barrier()
; #define PG8_SCHED __builtin_amdgcn_sched_barrier(0)
; template <class Epi, class Sched, bool ALIGN_EPI = false, bool SP2 = false>
; __device__ __forceinline__ void gemm_phase(PG8_LAS unsigned char* lds, const Gemm g, const Sched& S, const Epi& E) {
;     ...
;             PG8_LDA(At, 1, 1); PG8_STAGE(PG8_SB(1, 0), b3, voffB); PG8_STAGE(PG8_SB(1, 1), b3 + hstep, voffB); PG8_STAGE(PG8_SA(1, 0), a3, voffA);
;             PG8_WAIT_V(8); PG8_WAIT_L(0); PG8_BAR; PG8_MMA(1, 0, At, B0); PG8_MMA(1, 1, At, B1); PG8_BAR; PG8_SCHED;
	s_add_i32 s24, s57, s30
	v_lshl_add_u64 v[218:219], v[218:219], 0, s[6:7]
	s_mov_b32 m0, s24
	ds_read_b128 v[186:189], v151 offset:49152
	ds_read_b128 v[190:193], v151 offset:50176
	ds_read_b128 v[194:197], v151 offset:51200
	ds_read_b128 v[198:201], v151 offset:52224
	ds_read_b128 v[202:205], v151 offset:53248
	ds_read_b128 v[206:209], v151 offset:54272
	ds_read_b128 v[210:213], v151 offset:55296
	ds_read_b128 v[214:217], v151 offset:56320
	global_load_lds_dwordx4 v[218:219], off
	s_add_i32 m0, s24, 0x2000
	s_add_u32 s22, s22, 0x40080
	v_lshl_add_u64 v[218:219], v[220:221], 0, s[6:7]
	s_addc_u32 s23, s23, 0
	s_add_i32 s24, s58, s30
	global_load_lds_dwordx4 v[218:219], off
	v_lshl_add_u64 v[218:219], s[22:23], 0, v[134:135]
	s_mov_b32 m0, s24
	s_nop 0
	global_load_lds_dwordx4 v[218:219], off
	v_lshl_add_u64 v[218:219], s[22:23], 0, v[130:131]
	s_add_i32 m0, s24, 0x2000
	s_nop 0
	global_load_lds_dwordx4 v[218:219], off
	v_lshl_add_u64 v[218:219], v[222:223], 0, s[6:7]
	s_mov_b32 m0, s41
	s_nop 0
	global_load_lds_dwordx4 v[218:219], off
	v_lshl_add_u64 v[218:219], v[224:225], 0, s[6:7]
	s_mov_b32 m0, s42
	s_nop 0
	global_load_lds_dwordx4 v[218:219], off
	s_waitcnt vmcnt(8)
	s_waitcnt lgkmcnt(0)
	s_barrier
	s_setprio 1
	s_waitcnt lgkmcnt(0)
	v_mfma_f32_16x16x32_bf16 v[62:65], v[152:155], v[186:189], v[62:65]
	v_mfma_f32_16x16x32_bf16 v[58:61], v[160:163], v[186:189], v[58:61]
	v_mfma_f32_16x16x32_bf16 v[46:49], v[152:155], v[194:197], v[46:49]
	v_mfma_f32_16x16x32_bf16 v[42:45], v[160:163], v[194:197], v[42:45]
	v_mfma_f32_16x16x32_bf16 v[30:33], v[152:155], v[202:205], v[30:33]
	v_mfma_f32_16x16x32_bf16 v[26:29], v[160:163], v[202:205], v[26:29]
	v_mfma_f32_16x16x32_bf16 v[14:17], v[152:155], v[210:213], v[14:17]
	v_mfma_f32_16x16x32_bf16 v[10:13], v[160:163], v[210:213], v[10:13]
	v_mfma_f32_16x16x32_bf16 v[62:65], v[156:159], v[190:193], v[62:65]
	v_mfma_f32_16x16x32_bf16 v[58:61], v[164:167], v[190:193], v[58:61]
	v_mfma_f32_16x16x32_bf16 v[46:49], v[156:159], v[198:201], v[46:49]
	v_mfma_f32_16x16x32_bf16 v[42:45], v[164:167], v[198:201], v[42:45]
	v_mfma_f32_16x16x32_bf16 v[30:33], v[156:159], v[206:209], v[30:33]
	v_mfma_f32_16x16x32_bf16 v[26:29], v[164:167], v[206:209], v[26:29]
	v_mfma_f32_16x16x32_bf16 v[14:17], v[156:159], v[214:217], v[14:17]
	v_mfma_f32_16x16x32_bf16 v[10:13], v[164:167], v[214:217], v[10:13]
	v_mfma_f32_16x16x32_bf16 v[54:57], v[168:171], v[186:189], v[54:57]
	v_mfma_f32_16x16x32_bf16 v[50:53], v[178:181], v[186:189], v[50:53]
	v_mfma_f32_16x16x32_bf16 v[38:41], v[168:171], v[194:197], v[38:41]
	v_mfma_f32_16x16x32_bf16 v[34:37], v[178:181], v[194:197], v[34:37]
	v_mfma_f32_16x16x32_bf16 v[22:25], v[168:171], v[202:205], v[22:25]
	v_mfma_f32_16x16x32_bf16 v[18:21], v[178:181], v[202:205], v[18:21]
	v_mfma_f32_16x16x32_bf16 v[6:9], v[168:171], v[210:213], v[6:9]
	v_mfma_f32_16x16x32_bf16 v[2:5], v[178:181], v[210:213], v[2:5]
	v_mfma_f32_16x16x32_bf16 v[54:57], v[174:177], v[190:193], v[54:57]
	v_mfma_f32_16x16x32_bf16 v[50:53], v[182:185], v[190:193], v[50:53]
	v_mfma_f32_16x16x32_bf16 v[38:41], v[174:177], v[198:201], v[38:41]
	v_mfma_f32_16x16x32_bf16 v[34:37], v[182:185], v[198:201], v[34:37]
	v_mfma_f32_16x16x32_bf16 v[22:25], v[174:177], v[206:209], v[22:25]
	v_mfma_f32_16x16x32_bf16 v[18:21], v[182:185], v[206:209], v[18:21]
	v_mfma_f32_16x16x32_bf16 v[6:9], v[174:177], v[214:217], v[6:9]
	v_mfma_f32_16x16x32_bf16 v[2:5], v[182:185], v[214:217], v[2:5]
	s_setprio 0
	s_barrier

; #define PG8_STAGE(bufoff, gbase, voff) do { _Pragma("unroll") for (int _i = 0; _i < 2; ++_i) \
;         __builtin_amdgcn_global_load_lds((const unsigned*)((const char*)(gbase) + (voff)[_i]), (PG8_LAS unsigned*)(lds + (bufoff) + ldsw + _i * 8192), 16, 0, 0); } while (0)
; #define PG8_LDA(dst, b, h) do { _Pragma("unroll") for (int m = 0; m < 4; ++m) _Pragma("unroll") for (int k = 0; k < 2; ++k) dst[m][k] = *(const PG8_LAS bf16x8*)(lds + PG8_SA(b, h) + aoff + m * 2048 + k * 1024); } while (0)
; #define PG8_LDB(dst, b, h) do { _Pragma("unroll") for (int n = 0; n < 2; ++n) _Pragma("unroll") for (int k = 0; k < 2; ++k) dst[n][k] = *(const PG8_LAS bf16x8*)(lds + PG8_SB(b, h) + boff + n * 2048 + k * 1024); } while (0)
; #define PG8_MMA(ai, bj, At, Bt) do { __builtin_amdgcn_s_setprio(1); _Pragma("unroll") for (int m = 0; m < 4; ++m) _Pragma("unroll") for (int n = 0; n < 2; ++n) _Pragma("unroll") for (int k = 0; k < 2; ++k) \
;         acc[ai][bj][m][n] = __builtin_amdgcn_mfma_f32_16x16x32_bf16(Bt[n][k], At[m][k], acc[ai][bj][m][n], 0, 0, 0); __builtin_amdgcn_s_setprio(0); } while (0)
; #define PG8_WAIT_V(n) asm volatile("s_waitcnt vmcnt(" #n ")" ::: "memory")
; #define PG8_BAR __builtin_amdgcn_s_barrier()
; template <class Epi, class Sched, bool ALIGN_EPI = false, bool SP2 = false>
; __device__ __forceinline__ void gemm_phase(PG8_LAS unsigned char* lds, const Gemm g, const Sched& S, const Epi& E) {
;     ...
;         for (int t = 0; t < nt; t += 2) {
;             const bool last = (t == nt - 2);
;             const char* a1 = cA + (size_t)(t + 1) * kstep;
;             const char* a2 = last ? nA : cA + (size_t)(t + 2) * kstep; const char* b2 = last ? nB : cB + (size_t)(t + 2) * kstep;
;             const char* a3 = a2 + kstep; const char* b3 = b2 + kstep;
;             if (last && has_next) S.a_ready(nxt);
;             if constexpr (SP2) {
;             PG8_LDB(B0, 0, 0); PG8_LDB(B1, 0, 1); PG8_SCHED; PG8_LDA(At, 0, 0); PG8_STAGE(PG8_SA(1, 1), a1 + hstep, voffA);
;             PG8_WAIT_V(8); PG8_WAIT_L(0); PG8_BAR; PG8_MMA(0, 0, At, B0); PG8_MMA(0, 1, At, B1); PG8_BAR; PG8_SCHED;
;             PG8_LDA(At, 0, 1); PG8_STAGE(PG8_SB(0, 0), b2, voffB); PG8_STAGE(PG8_SB(0, 1), b2 + hstep, voffB); PG8_STAGE(PG8_SA(0, 0), a2, voffA);
;             PG8_WAIT_V(8); PG8_WAIT_L(0); PG8_BAR; PG8_MMA(1, 0, At, B0); PG8_MMA(1, 1, At, B1); PG8_BAR; PG8_SCHED;
	s_add_i32 s56, s56, 2
	s_add_u32 s20, s20, 0x100
	s_addc_u32 s21, s21, 0
	s_add_u32 s54, s54, 0x100
	s_addc_u32 s55, s55, 0
.LBB0_1591:
	ds_read_b128 v[152:155], v149
	ds_read_b128 v[156:159], v149 offset:1024
	ds_read_b128 v[160:163], v149 offset:2048
	ds_read_b128 v[164:167], v149 offset:3072
	ds_read_b128 v[168:171], v150
	ds_read_b128 v[174:177], v150 offset:1024
	ds_read_b128 v[178:181], v150 offset:2048
	ds_read_b128 v[182:185], v150 offset:3072
	s_add_u32 s22, s20, 0xfffc0080
	s_addc_u32 s23, s21, -1
	s_cmp_eq_u32 s56, 12
	s_cselect_b32 s25, s13, s23
	s_cselect_b32 s24, s52, s22
	s_cselect_b32 s23, s11, s55
	s_cselect_b32 s22, s53, s54
	v_lshl_add_u64 v[218:219], s[20:21], 0, v[140:141]
	s_add_i32 m0, s34, 0xc000
	ds_read_b128 v[186:189], v151
	ds_read_b128 v[190:193], v151 offset:1024
	ds_read_b128 v[194:197], v151 offset:2048
	ds_read_b128 v[198:201], v151 offset:3072
	ds_read_b128 v[202:205], v151 offset:4096
	ds_read_b128 v[206:209], v151 offset:5120
	ds_read_b128 v[210:213], v151 offset:6144
	ds_read_b128 v[214:217], v151 offset:7168
	global_load_lds_dwordx4 v[218:219], off
	v_lshl_add_u64 v[218:219], s[20:21], 0, v[142:143]
	s_add_i32 m0, s34, 0xe000
	s_nop 0
	global_load_lds_dwordx4 v[218:219], off
	s_waitcnt vmcnt(8)
	s_waitcnt lgkmcnt(0)
	s_barrier
	s_setprio 1
	s_waitcnt lgkmcnt(0)
	v_mfma_f32_16x16x32_bf16 v[126:129], v[152:155], v[186:189], v[126:129]
	v_mfma_f32_16x16x32_bf16 v[122:125], v[160:163], v[186:189], v[122:125]
	v_mfma_f32_16x16x32_bf16 v[110:113], v[152:155], v[194:197], v[110:113]
	v_mfma_f32_16x16x32_bf16 v[106:109], v[160:163], v[194:197], v[106:109]
	v_mfma_f32_16x16x32_bf16 v[94:97], v[152:155], v[202:205], v[94:97]
	v_mfma_f32_16x16x32_bf16 v[90:93], v[160:163], v[202:205], v[90:93]
	v_mfma_f32_16x16x32_bf16 v[78:81], v[152:155], v[210:213], v[78:81]
	v_mfma_f32_16x16x32_bf16 v[74:77], v[160:163], v[210:213], v[74:77]
	v_mfma_f32_16x16x32_bf16 v[126:129], v[156:159], v[190:193], v[126:129]
	v_mfma_f32_16x16x32_bf16 v[122:125], v[164:167], v[190:193], v[122:125]
	v_mfma_f32_16x16x32_bf16 v[110:113], v[156:159], v[198:201], v[110:113]
	v_mfma_f32_16x16x32_bf16 v[106:109], v[164:167], v[198:201], v[106:109]
	v_mfma_f32_16x16x32_bf16 v[94:97], v[156:159], v[206:209], v[94:97]
	v_mfma_f32_16x16x32_bf16 v[90:93], v[164:167], v[206:209], v[90:93]
	v_mfma_f32_16x16x32_bf16 v[78:81], v[156:159], v[214:217], v[78:81]
	v_mfma_f32_16x16x32_bf16 v[74:77], v[164:167], v[214:217], v[74:77]
	v_mfma_f32_16x16x32_bf16 v[118:121], v[168:171], v[186:189], v[118:121]
	v_mfma_f32_16x16x32_bf16 v[114:117], v[178:181], v[186:189], v[114:117]
	v_mfma_f32_16x16x32_bf16 v[102:105], v[168:171], v[194:197], v[102:105]
	v_mfma_f32_16x16x32_bf16 v[98:101], v[178:181], v[194:197], v[98:101]
	v_mfma_f32_16x16x32_bf16 v[86:89], v[168:171], v[202:205], v[86:89]
	v_mfma_f32_16x16x32_bf16 v[82:85], v[178:181], v[202:205], v[82:85]
	v_mfma_f32_16x16x32_bf16 v[70:73], v[168:171], v[210:213], v[70:73]
	v_mfma_f32_16x16x32_bf16 v[66:69], v[178:181], v[210:213], v[66:69]
	v_mfma_f32_16x16x32_bf16 v[118:121], v[174:177], v[190:193], v[118:121]
	v_mfma_f32_16x16x32_bf16 v[114:117], v[182:185], v[190:193], v[114:117]
	v_mfma_f32_16x16x32_bf16 v[102:105], v[174:177], v[198:201], v[102:105]
	v_mfma_f32_16x16x32_bf16 v[98:101], v[182:185], v[198:201], v[98:101]
	v_mfma_f32_16x16x32_bf16 v[86:89], v[174:177], v[206:209], v[86:89]
	v_mfma_f32_16x16x32_bf16 v[82:85], v[182:185], v[206:209], v[82:85]
	v_mfma_f32_16x16x32_bf16 v[70:73], v[174:177], v[214:217], v[70:73]
	v_mfma_f32_16x16x32_bf16 v[66:69], v[182:185], v[214:217], v[66:69]
	s_setprio 0
	s_barrier
	s_add_i32 s57, s45, s30
	v_lshl_add_u64 v[218:219], s[22:23], 0, v[134:135]
	s_mov_b32 m0, s57
	ds_read_b128 v[186:189], v151 offset:16384
	ds_read_b128 v[190:193], v151 offset:17408
	ds_read_b128 v[194:197], v151 offset:18432
	ds_read_b128 v[198:201], v151 offset:19456
	ds_read_b128 v[202:205], v151 offset:20480
	ds_read_b128 v[206:209], v151 offset:21504
	ds_read_b128 v[210:213], v151 offset:22528
	ds_read_b128 v[214:217], v151 offset:23552
	global_load_lds_dwordx4 v[218:219], off
	s_add_i32 m0, s57, 0x2000
	s_add_u32 s58, s22, 0x40000
	v_lshl_add_u64 v[220:221], s[22:23], 0, v[130:131]
	s_addc_u32 s59, s23, 0
	s_add_i32 s57, s48, s30
	global_load_lds_dwordx4 v[220:221], off
	v_lshl_add_u64 v[222:223], s[58:59], 0, v[134:135]
	s_mov_b32 m0, s57
	v_lshl_add_u64 v[224:225], s[24:25], 0, v[132:133]
	global_load_lds_dwordx4 v[222:223], off
	v_lshl_add_u64 v[222:223], s[58:59], 0, v[130:131]
	s_add_i32 m0, s57, 0x2000
	s_nop 0
	global_load_lds_dwordx4 v[222:223], off
	v_lshl_add_u64 v[222:223], s[24:25], 0, v[136:137]
	s_mov_b32 m0, s34
	s_nop 0
	global_load_lds_dwordx4 v[222:223], off
	s_mov_b32 m0, s35
	s_nop 0
	global_load_lds_dwordx4 v[224:225], off
	s_waitcnt vmcnt(8)
	s_waitcnt lgkmcnt(0)
	s_barrier
; #define PG8_STAGE(bufoff, gbase, voff) do { _Pragma("unroll") for (int _i = 0; _i < 2; ++_i) \
;         __builtin_amdgcn_global_load_lds((const unsigned*)((const char*)(gbase) + (voff)[_i]), (PG8_LAS unsigned*)(lds + (bufoff) + ldsw + _i * 8192), 16, 0, 0); } while (0)
; #define PG8_LDA(dst, b, h) do { _Pragma("unroll") for (int m = 0; m < 4; ++m) _Pragma("unroll") for (int k = 0; k < 2; ++k) dst[m][k] = *(const PG8_LAS bf16x8*)(lds + PG8_SA(b, h) + aoff + m * 2048 + k * 1024); } while (0)
; #define PG8_LDB(dst, b, h) do { _Pragma("unroll") for (int n = 0; n < 2; ++n) _Pragma("unroll") for (int k = 0; k < 2; ++k) dst[n][k] = *(const PG8_LAS bf16x8*)(lds + PG8_SB(b, h) + boff + n * 2048 + k * 1024); } while (0)
; #define PG8_MMA(ai, bj, At, Bt) do { __builtin_amdgcn_s_setprio(1); _Pragma("unroll") for (int m = 0; m < 4; ++m) _Pragma("unroll") for (int n = 0; n < 2; ++n) _Pragma("unroll") for (int k = 0; k < 2; ++k) \
;         acc[ai][bj][m][n] = __builtin_amdgcn_mfma_f32_16x16x32_bf16(Bt[n][k], At[m][k], acc[ai][bj][m][n], 0, 0, 0); __builtin_amdgcn_s_setprio(0); } while (0)
; #define PG8_WAIT_V(n) asm volatile("s_waitcnt vmcnt(" #n ")" ::: "memory")
; #define PG8_WAIT_L(n) asm volatile("s_waitcnt lgkmcnt(" #n ")" ::: "memory")
; #define PG8_BAR __builtin_amdgcn_s_barrier()
; #define PG8_SCHED __builtin_amdgcn_sched_barrier(0)
; template <class Epi, class Sched, bool ALIGN_EPI = false, bool SP2 = false>
; __device__ __forceinline__ void gemm_phase(PG8_LAS unsigned char* lds, const Gemm g, const Sched& S, const Epi& E) {
;     ...
;             PG8_WAIT_V(8); PG8_WAIT_L(0); PG8_BAR; PG8_MMA(1, 0, At, B0); PG8_MMA(1, 1, At, B1); PG8_BAR; PG8_SCHED;
;             PG8_LDB(B0, 1, 0); PG8_LDB(B1, 1, 1); PG8_SCHED; PG8_LDA(At, 1, 0); PG8_STAGE(PG8_SA(0, 1), a2 + hstep, voffA);
;             PG8_WAIT_V(8); PG8_WAIT_L(0); PG8_BAR; PG8_MMA(0, 0, At, B0); PG8_MMA(0, 1, At, B1); PG8_BAR; PG8_SCHED;
	s_setprio 1
	s_waitcnt lgkmcnt(0)
	v_mfma_f32_16x16x32_bf16 v[62:65], v[152:155], v[186:189], v[62:65]
	v_mfma_f32_16x16x32_bf16 v[58:61], v[160:163], v[186:189], v[58:61]
	v_mfma_f32_16x16x32_bf16 v[46:49], v[152:155], v[194:197], v[46:49]
	v_mfma_f32_16x16x32_bf16 v[42:45], v[160:163], v[194:197], v[42:45]
	v_mfma_f32_16x16x32_bf16 v[30:33], v[152:155], v[202:205], v[30:33]
	v_mfma_f32_16x16x32_bf16 v[26:29], v[160:163], v[202:205], v[26:29]
	v_mfma_f32_16x16x32_bf16 v[14:17], v[152:155], v[210:213], v[14:17]
	v_mfma_f32_16x16x32_bf16 v[10:13], v[160:163], v[210:213], v[10:13]
	v_mfma_f32_16x16x32_bf16 v[62:65], v[156:159], v[190:193], v[62:65]
	v_mfma_f32_16x16x32_bf16 v[58:61], v[164:167], v[190:193], v[58:61]
	v_mfma_f32_16x16x32_bf16 v[46:49], v[156:159], v[198:201], v[46:49]
	v_mfma_f32_16x16x32_bf16 v[42:45], v[164:167], v[198:201], v[42:45]
	v_mfma_f32_16x16x32_bf16 v[30:33], v[156:159], v[206:209], v[30:33]
	v_mfma_f32_16x16x32_bf16 v[26:29], v[164:167], v[206:209], v[26:29]
	v_mfma_f32_16x16x32_bf16 v[14:17], v[156:159], v[214:217], v[14:17]
	v_mfma_f32_16x16x32_bf16 v[10:13], v[164:167], v[214:217], v[10:13]
	v_mfma_f32_16x16x32_bf16 v[54:57], v[168:171], v[186:189], v[54:57]
	v_mfma_f32_16x16x32_bf16 v[50:53], v[178:181], v[186:189], v[50:53]
	v_mfma_f32_16x16x32_bf16 v[38:41], v[168:171], v[194:197], v[38:41]
	v_mfma_f32_16x16x32_bf16 v[34:37], v[178:181], v[194:197], v[34:37]
	v_mfma_f32_16x16x32_bf16 v[22:25], v[168:171], v[202:205], v[22:25]
	v_mfma_f32_16x16x32_bf16 v[18:21], v[178:181], v[202:205], v[18:21]
	v_mfma_f32_16x16x32_bf16 v[6:9], v[168:171], v[210:213], v[6:9]
	v_mfma_f32_16x16x32_bf16 v[2:5], v[178:181], v[210:213], v[2:5]
	v_mfma_f32_16x16x32_bf16 v[54:57], v[174:177], v[190:193], v[54:57]
	v_mfma_f32_16x16x32_bf16 v[50:53], v[182:185], v[190:193], v[50:53]
	v_mfma_f32_16x16x32_bf16 v[38:41], v[174:177], v[198:201], v[38:41]
	v_mfma_f32_16x16x32_bf16 v[34:37], v[182:185], v[198:201], v[34:37]
	v_mfma_f32_16x16x32_bf16 v[22:25], v[174:177], v[206:209], v[22:25]
	v_mfma_f32_16x16x32_bf16 v[18:21], v[182:185], v[206:209], v[18:21]
	v_mfma_f32_16x16x32_bf16 v[6:9], v[174:177], v[214:217], v[6:9]
	v_mfma_f32_16x16x32_bf16 v[2:5], v[182:185], v[214:217], v[2:5]
	s_setprio 0
	s_barrier
	s_add_i32 s57, 0, 0x18000
	s_add_i32 s58, 0, 0x1c000
	v_add_u32_e32 v164, s57, v148
	v_add_u32_e32 v182, s58, v148
	ds_read_b128 v[152:155], v164
	ds_read_b128 v[156:159], v164 offset:1024
	ds_read_b128 v[160:163], v164 offset:2048
	ds_read_b128 v[164:167], v164 offset:3072
	ds_read_b128 v[168:171], v182
	ds_read_b128 v[174:177], v182 offset:1024
	ds_read_b128 v[178:181], v182 offset:2048
	ds_read_b128 v[182:185], v182 offset:3072
	s_add_u32 s24, s24, 0x40000
	s_addc_u32 s25, s25, 0
	s_mov_b32 m0, s38
	v_lshl_add_u64 v[226:227], s[24:25], 0, v[136:137]
	ds_read_b128 v[186:189], v151 offset:32768
	ds_read_b128 v[190:193], v151 offset:33792
	ds_read_b128 v[194:197], v151 offset:34816
	ds_read_b128 v[198:201], v151 offset:35840
	ds_read_b128 v[202:205], v151 offset:36864
	ds_read_b128 v[206:209], v151 offset:37888
	ds_read_b128 v[210:213], v151 offset:38912
	ds_read_b128 v[214:217], v151 offset:39936
	global_load_lds_dwordx4 v[226:227], off
	v_lshl_add_u64 v[226:227], s[24:25], 0, v[132:133]
	s_mov_b32 m0, s39
	s_nop 0
	global_load_lds_dwordx4 v[226:227], off
	s_waitcnt vmcnt(8)
	s_waitcnt lgkmcnt(0)
	s_barrier
	s_setprio 1
	s_waitcnt lgkmcnt(0)
	v_mfma_f32_16x16x32_bf16 v[126:129], v[152:155], v[186:189], v[126:129]
	v_mfma_f32_16x16x32_bf16 v[122:125], v[160:163], v[186:189], v[122:125]
	v_mfma_f32_16x16x32_bf16 v[110:113], v[152:155], v[194:197], v[110:113]
	v_mfma_f32_16x16x32_bf16 v[106:109], v[160:163], v[194:197], v[106:109]
	v_mfma_f32_16x16x32_bf16 v[94:97], v[152:155], v[202:205], v[94:97]
	v_mfma_f32_16x16x32_bf16 v[90:93], v[160:163], v[202:205], v[90:93]
	v_mfma_f32_16x16x32_bf16 v[78:81], v[152:155], v[210:213], v[78:81]
	v_mfma_f32_16x16x32_bf16 v[74:77], v[160:163], v[210:213], v[74:77]
	v_mfma_f32_16x16x32_bf16 v[126:129], v[156:159], v[190:193], v[126:129]
	v_mfma_f32_16x16x32_bf16 v[122:125], v[164:167], v[190:193], v[122:125]
	v_mfma_f32_16x16x32_bf16 v[110:113], v[156:159], v[198:201], v[110:113]
	v_mfma_f32_16x16x32_bf16 v[106:109], v[164:167], v[198:201], v[106:109]
	v_mfma_f32_16x16x32_bf16 v[94:97], v[156:159], v[206:209], v[94:97]
	v_mfma_f32_16x16x32_bf16 v[90:93], v[164:167], v[206:209], v[90:93]
	v_mfma_f32_16x16x32_bf16 v[78:81], v[156:159], v[214:217], v[78:81]
	v_mfma_f32_16x16x32_bf16 v[74:77], v[164:167], v[214:217], v[74:77]
	v_mfma_f32_16x16x32_bf16 v[118:121], v[168:171], v[186:189], v[118:121]
	v_mfma_f32_16x16x32_bf16 v[114:117], v[178:181], v[186:189], v[114:117]
	v_mfma_f32_16x16x32_bf16 v[102:105], v[168:171], v[194:197], v[102:105]
	v_mfma_f32_16x16x32_bf16 v[98:101], v[178:181], v[194:197], v[98:101]
	v_mfma_f32_16x16x32_bf16 v[86:89], v[168:171], v[202:205], v[86:89]
	v_mfma_f32_16x16x32_bf16 v[82:85], v[178:181], v[202:205], v[82:85]
	v_mfma_f32_16x16x32_bf16 v[70:73], v[168:171], v[210:213], v[70:73]
	v_mfma_f32_16x16x32_bf16 v[66:69], v[178:181], v[210:213], v[66:69]
	v_mfma_f32_16x16x32_bf16 v[118:121], v[174:177], v[190:193], v[118:121]
	v_mfma_f32_16x16x32_bf16 v[114:117], v[182:185], v[190:193], v[114:117]
	v_mfma_f32_16x16x32_bf16 v[102:105], v[174:177], v[198:201], v[102:105]
	v_mfma_f32_16x16x32_bf16 v[98:101], v[182:185], v[198:201], v[98:101]
	v_mfma_f32_16x16x32_bf16 v[86:89], v[174:177], v[206:209], v[86:89]
	v_mfma_f32_16x16x32_bf16 v[82:85], v[182:185], v[206:209], v[82:85]
	v_mfma_f32_16x16x32_bf16 v[70:73], v[174:177], v[214:217], v[70:73]
	v_mfma_f32_16x16x32_bf16 v[66:69], v[182:185], v[214:217], v[66:69]
	s_setprio 0
	s_barrier
; #define PG8_STAGE(bufoff, gbase, voff) do { _Pragma("unroll") for (int _i = 0; _i < 2; ++_i) \
;         __builtin_amdgcn_global_load_lds((const unsigned*)((const char*)(gbase) + (voff)[_i]), (PG8_LAS unsigned*)(lds + (bufoff) + ldsw + _i * 8192), 16, 0, 0); } while (0)
; #define PG8_LDA(dst, b, h) do { _Pragma("unroll") for (int m = 0; m < 4; ++m) _Pragma("unroll") for (int k = 0; k < 2; ++k) dst[m][k] = *(const PG8_LAS bf16x8*)(lds + PG8_SA(b, h) + aoff + m * 2048 + k * 1024); } while (0)
; #define PG8_MMA(ai, bj, At, Bt) do { __builtin_amdgcn_s_setprio(1); _Pragma("unroll") for (int m = 0; m < 4; ++m) _Pragma("unroll") for (int n = 0; n < 2; ++n) _Pragma("unroll") for (int k = 0; k < 2; ++k) \
;         acc[ai][bj][m][n] = __builtin_amdgcn_mfma_f32_16x16x32_bf16(Bt[n][k], At[m][k], acc[ai][bj][m][n], 0, 0, 0); __builtin_amdgcn_s_setprio(0); } while (0)
; #define PG8_WAIT_V(n) asm volatile("s_waitcnt vmcnt(" #n ")" ::: "memory")
; #define PG8_WAIT_L(n) asm volatile("s_waitcnt lgkmcnt(" #n ")" ::: "memory")
; #define PG8_BAR __builtin_amdgcn_s_barrier()
; #define PG8_SCHED __builtin_amdgcn_sched_barrier(0)
; template <class Epi, class Sched, bool ALIGN_EPI = false, bool SP2 = false>
; __device__ __forceinline__ void gemm_phase(PG8_LAS unsigned char* lds, const Gemm g, const Sched& S, const Epi& E) {
;     ...
;             PG8_WAIT_V(8); PG8_WAIT_L(0); PG8_BAR; PG8_MMA(0, 0, At, B0); PG8_MMA(0, 1, At, B1); PG8_BAR; PG8_SCHED;
;             PG8_LDA(At, 1, 1); PG8_STAGE(PG8_SB(1, 0), b3, voffB); PG8_STAGE(PG8_SB(1, 1), b3 + hstep, voffB); PG8_STAGE(PG8_SA(1, 0), a3, voffA);
;             PG8_WAIT_V(8); PG8_WAIT_L(0); PG8_BAR; PG8_MMA(1, 0, At, B0); PG8_MMA(1, 1, At, B1); PG8_BAR; PG8_SCHED;
	s_add_i32 s24, s57, s30
	v_lshl_add_u64 v[218:219], v[218:219], 0, s[6:7]
	s_mov_b32 m0, s24
	ds_read_b128 v[186:189], v151 offset:49152
	ds_read_b128 v[190:193], v151 offset:50176
	ds_read_b128 v[194:197], v151 offset:51200
	ds_read_b128 v[198:201], v151 offset:52224
	ds_read_b128 v[202:205], v151 offset:53248
	ds_read_b128 v[206:209], v151 offset:54272
	ds_read_b128 v[210:213], v151 offset:55296
	ds_read_b128 v[214:217], v151 offset:56320
	global_load_lds_dwordx4 v[218:219], off
	s_add_i32 m0, s24, 0x2000
	s_add_u32 s22, s22, 0x40080
	v_lshl_add_u64 v[218:219], v[220:221], 0, s[6:7]
	s_addc_u32 s23, s23, 0
	s_add_i32 s24, s58, s30
	global_load_lds_dwordx4 v[218:219], off
	v_lshl_add_u64 v[218:219], s[22:23], 0, v[134:135]
	s_mov_b32 m0, s24
	s_nop 0
	global_load_lds_dwordx4 v[218:219], off
	v_lshl_add_u64 v[218:219], s[22:23], 0, v[130:131]
	s_add_i32 m0, s24, 0x2000
	s_nop 0
	global_load_lds_dwordx4 v[218:219], off
	v_lshl_add_u64 v[218:219], v[222:223], 0, s[6:7]
	s_mov_b32 m0, s41
	s_nop 0
	global_load_lds_dwordx4 v[218:219], off
	v_lshl_add_u64 v[218:219], v[224:225], 0, s[6:7]
	s_mov_b32 m0, s42
	s_nop 0
	global_load_lds_dwordx4 v[218:219], off
	s_waitcnt vmcnt(8)
	s_waitcnt lgkmcnt(0)
	s_barrier
	s_setprio 1
	s_waitcnt lgkmcnt(0)
	v_mfma_f32_16x16x32_bf16 v[62:65], v[152:155], v[186:189], v[62:65]
	v_mfma_f32_16x16x32_bf16 v[58:61], v[160:163], v[186:189], v[58:61]
	v_mfma_f32_16x16x32_bf16 v[46:49], v[152:155], v[194:197], v[46:49]
	v_mfma_f32_16x16x32_bf16 v[42:45], v[160:163], v[194:197], v[42:45]
	v_mfma_f32_16x16x32_bf16 v[30:33], v[152:155], v[202:205], v[30:33]
	v_mfma_f32_16x16x32_bf16 v[26:29], v[160:163], v[202:205], v[26:29]
	v_mfma_f32_16x16x32_bf16 v[14:17], v[152:155], v[210:213], v[14:17]
	v_mfma_f32_16x16x32_bf16 v[10:13], v[160:163], v[210:213], v[10:13]
	v_mfma_f32_16x16x32_bf16 v[62:65], v[156:159], v[190:193], v[62:65]
	v_mfma_f32_16x16x32_bf16 v[58:61], v[164:167], v[190:193], v[58:61]
	v_mfma_f32_16x16x32_bf16 v[46:49], v[156:159], v[198:201], v[46:49]
	v_mfma_f32_16x16x32_bf16 v[42:45], v[164:167], v[198:201], v[42:45]
	v_mfma_f32_16x16x32_bf16 v[30:33], v[156:159], v[206:209], v[30:33]
	v_mfma_f32_16x16x32_bf16 v[26:29], v[164:167], v[206:209], v[26:29]
	v_mfma_f32_16x16x32_bf16 v[14:17], v[156:159], v[214:217], v[14:17]
	v_mfma_f32_16x16x32_bf16 v[10:13], v[164:167], v[214:217], v[10:13]
	v_mfma_f32_16x16x32_bf16 v[54:57], v[168:171], v[186:189], v[54:57]
	v_mfma_f32_16x16x32_bf16 v[50:53], v[178:181], v[186:189], v[50:53]
	v_mfma_f32_16x16x32_bf16 v[38:41], v[168:171], v[194:197], v[38:41]
	v_mfma_f32_16x16x32_bf16 v[34:37], v[178:181], v[194:197], v[34:37]
	v_mfma_f32_16x16x32_bf16 v[22:25], v[168:171], v[202:205], v[22:25]
	v_mfma_f32_16x16x32_bf16 v[18:21], v[178:181], v[202:205], v[18:21]
	v_mfma_f32_16x16x32_bf16 v[6:9], v[168:171], v[210:213], v[6:9]
	v_mfma_f32_16x16x32_bf16 v[2:5], v[178:181], v[210:213], v[2:5]
	v_mfma_f32_16x16x32_bf16 v[54:57], v[174:177], v[190:193], v[54:57]
	v_mfma_f32_16x16x32_bf16 v[50:53], v[182:185], v[190:193], v[50:53]
	v_mfma_f32_16x16x32_bf16 v[38:41], v[174:177], v[198:201], v[38:41]
	v_mfma_f32_16x16x32_bf16 v[34:37], v[182:185], v[198:201], v[34:37]
	v_mfma_f32_16x16x32_bf16 v[22:25], v[174:177], v[206:209], v[22:25]
	v_mfma_f32_16x16x32_bf16 v[18:21], v[182:185], v[206:209], v[18:21]
	v_mfma_f32_16x16x32_bf16 v[6:9], v[174:177], v[214:217], v[6:9]
	v_mfma_f32_16x16x32_bf16 v[2:5], v[182:185], v[214:217], v[2:5]
	s_setprio 0
	s_barrier
	s_add_i32 s56, s56, 2
	s_add_u32 s20, s20, 0x100
	s_addc_u32 s21, s21, 0
	s_add_u32 s54, s54, 0x100
	s_addc_u32 s55, s55, 0
	s_cmp_gt_u32 s56, 13
	s_cbranch_scc0 .LBB0_1591
	s_and_b64 vcc, exec, s[8:9]
	s_cbranch_vccz .LBB0_1594
	s_barrier

; #define PG8_STAGE(bufoff, gbase, voff) do { _Pragma("unroll") for (int _i = 0; _i < 2; ++_i) \
;         __builtin_amdgcn_global_load_lds((const unsigned*)((const char*)(gbase) + (voff)[_i]), (PG8_LAS unsigned*)(lds + (bufoff) + ldsw + _i * 8192), 16, 0, 0); } while (0)
; #define PG8_LDA(dst, b, h) do { _Pragma("unroll") for (int m = 0; m < 4; ++m) _Pragma("unroll") for (int k = 0; k < 2; ++k) dst[m][k] = *(const PG8_LAS bf16x8*)(lds + PG8_SA(b, h) + aoff + m * 2048 + k * 1024); } while (0)
; #define PG8_LDB(dst, b, h) do { _Pragma("unroll") for (int n = 0; n < 2; ++n) _Pragma("unroll") for (int k = 0; k < 2; ++k) dst[n][k] = *(const PG8_LAS bf16x8*)(lds + PG8_SB(b, h) + boff + n * 2048 + k * 1024); } while (0)
; #define PG8_SCHED __builtin_amdgcn_sched_barrier(0)
; template <class Epi, class Sched, bool ALIGN_EPI = false, bool SP2 = false>
; __device__ __forceinline__ void gemm_phase(PG8_LAS unsigned char* lds, const Gemm g, const Sched& S, const Epi& E) {
;     ...
;         const bool has_next = S.next(ui + 1, nxt);
;         const char* nA = has_next ? (const char*)g.A + (size_t)nxt.pm * tstep : cA; const char* nB = has_next ? (const char*)g.Bt + (size_t)nxt.pn * tstep : cB;
; #pragma nounroll
;         for (int t = 0; t < nt; t += 2) {
;             const bool last = (t == nt - 2);
;             const char* a1 = cA + (size_t)(t + 1) * kstep;
;             const char* a2 = last ? nA : cA + (size_t)(t + 2) * kstep; const char* b2 = last ? nB : cB + (size_t)(t + 2) * kstep;
;             const char* a3 = a2 + kstep; const char* b3 = b2 + kstep;
;             if (last && has_next) S.a_ready(nxt);
;             if constexpr (SP2) {
;             PG8_LDB(B0, 0, 0); PG8_LDB(B1, 0, 1); PG8_SCHED; PG8_LDA(At, 0, 0); PG8_STAGE(PG8_SA(1, 1), a1 + hstep, voffA);
.LBB0_1687:
	s_add_u32 s22, s22, 0xb0080
	s_addc_u32 s23, s23, 0
	s_add_u32 s60, s24, 0x100
	s_addc_u32 s61, s25, 0
	s_mov_b32 s62, -2
	ds_read_b128 v[154:157], v150
	ds_read_b128 v[158:161], v150 offset:1024
	ds_read_b128 v[162:165], v150 offset:2048
	ds_read_b128 v[166:169], v150 offset:3072
	ds_read_b128 v[174:177], v151
	ds_read_b128 v[178:181], v151 offset:1024
	ds_read_b128 v[182:185], v151 offset:2048
	ds_read_b128 v[186:189], v151 offset:3072
	s_add_u32 s24, s22, 0xfff50080
	s_addc_u32 s25, s23, -1
	s_cmp_eq_u32 s62, 40
	s_cselect_b32 s27, s5, s25
	s_cselect_b32 s26, s4, s24
	s_cselect_b32 s25, s21, s61
	s_cselect_b32 s24, s20, s60

; #define PG8_STAGE(bufoff, gbase, voff) do { _Pragma("unroll") for (int _i = 0; _i < 2; ++_i) \
;         __builtin_amdgcn_global_load_lds((const unsigned*)((const char*)(gbase) + (voff)[_i]), (PG8_LAS unsigned*)(lds + (bufoff) + ldsw + _i * 8192), 16, 0, 0); } while (0)
; #define PG8_LDA(dst, b, h) do { _Pragma("unroll") for (int m = 0; m < 4; ++m) _Pragma("unroll") for (int k = 0; k < 2; ++k) dst[m][k] = *(const PG8_LAS bf16x8*)(lds + PG8_SA(b, h) + aoff + m * 2048 + k * 1024); } while (0)
; #define PG8_LDB(dst, b, h) do { _Pragma("unroll") for (int n = 0; n < 2; ++n) _Pragma("unroll") for (int k = 0; k < 2; ++k) dst[n][k] = *(const PG8_LAS bf16x8*)(lds + PG8_SB(b, h) + boff + n * 2048 + k * 1024); } while (0)
; #define PG8_MMA(ai, bj, At, Bt) do { __builtin_amdgcn_s_setprio(1); _Pragma("unroll") for (int m = 0; m < 4; ++m) _Pragma("unroll") for (int n = 0; n < 2; ++n) _Pragma("unroll") for (int k = 0; k < 2; ++k) \
;         acc[ai][bj][m][n] = __builtin_amdgcn_mfma_f32_16x16x32_bf16(Bt[n][k], At[m][k], acc[ai][bj][m][n], 0, 0, 0); __builtin_amdgcn_s_setprio(0); } while (0)
; #define PG8_WAIT_V(n) asm volatile("s_waitcnt vmcnt(" #n ")" ::: "memory")
; #define PG8_WAIT_L(n) asm volatile("s_waitcnt lgkmcnt(" #n ")" ::: "memory")
; #define PG8_BAR __builtin_amdgcn_s_barrier()
; #define PG8_SCHED __builtin_amdgcn_sched_barrier(0)
; template <class Epi, class Sched, bool ALIGN_EPI = false, bool SP2 = false>
; __device__ __forceinline__ void gemm_phase(PG8_LAS unsigned char* lds, const Gemm g, const Sched& S, const Epi& E) {
;     ...
;             PG8_LDB(B0, 0, 0); PG8_LDB(B1, 0, 1); PG8_SCHED; PG8_LDA(At, 0, 0); PG8_STAGE(PG8_SA(1, 1), a1 + hstep, voffA);
;             PG8_WAIT_V(8); PG8_WAIT_L(0); PG8_BAR; PG8_MMA(0, 0, At, B0); PG8_MMA(0, 1, At, B1); PG8_BAR; PG8_SCHED;
	v_lshl_add_u64 v[146:147], s[22:23], 0, v[138:139]
	s_add_i32 m0, s35, 0xc000
	ds_read_b128 v[190:193], v152
	ds_read_b128 v[194:197], v152 offset:1024
	ds_read_b128 v[198:201], v152 offset:2048
	ds_read_b128 v[202:205], v152 offset:3072
	ds_read_b128 v[206:209], v152 offset:4096
	ds_read_b128 v[210:213], v152 offset:5120
	ds_read_b128 v[214:217], v152 offset:6144
	ds_read_b128 v[218:221], v152 offset:7168
	global_load_lds_dwordx4 v[146:147], off
	v_lshl_add_u64 v[146:147], s[22:23], 0, v[140:141]
	s_add_i32 m0, s35, 0xe000
	s_nop 0
	global_load_lds_dwordx4 v[146:147], off
	s_waitcnt vmcnt(24)
	s_waitcnt lgkmcnt(0)
	s_barrier
	s_setprio 1
	s_waitcnt lgkmcnt(0)
	v_mfma_f32_16x16x32_bf16 v[126:129], v[154:157], v[190:193], 0
	v_mfma_f32_16x16x32_bf16 v[122:125], v[162:165], v[190:193], 0
	v_mfma_f32_16x16x32_bf16 v[118:121], v[154:157], v[198:201], 0
	v_mfma_f32_16x16x32_bf16 v[110:113], v[162:165], v[198:201], 0
	v_mfma_f32_16x16x32_bf16 v[102:105], v[154:157], v[206:209], 0
	v_mfma_f32_16x16x32_bf16 v[94:97], v[162:165], v[206:209], 0
	v_mfma_f32_16x16x32_bf16 v[86:89], v[154:157], v[214:217], 0
	v_mfma_f32_16x16x32_bf16 v[78:81], v[162:165], v[214:217], 0
	v_mfma_f32_16x16x32_bf16 v[126:129], v[158:161], v[194:197], v[126:129]
	v_mfma_f32_16x16x32_bf16 v[122:125], v[166:169], v[194:197], v[122:125]
	v_mfma_f32_16x16x32_bf16 v[118:121], v[158:161], v[202:205], v[118:121]
	v_mfma_f32_16x16x32_bf16 v[110:113], v[166:169], v[202:205], v[110:113]
	v_mfma_f32_16x16x32_bf16 v[102:105], v[158:161], v[210:213], v[102:105]
	v_mfma_f32_16x16x32_bf16 v[94:97], v[166:169], v[210:213], v[94:97]
	v_mfma_f32_16x16x32_bf16 v[86:89], v[158:161], v[218:221], v[86:89]
	v_mfma_f32_16x16x32_bf16 v[78:81], v[166:169], v[218:221], v[78:81]
	v_mfma_f32_16x16x32_bf16 v[114:117], v[174:177], v[190:193], 0
	v_mfma_f32_16x16x32_bf16 v[106:109], v[182:185], v[190:193], 0
	v_mfma_f32_16x16x32_bf16 v[98:101], v[174:177], v[198:201], 0
	v_mfma_f32_16x16x32_bf16 v[90:93], v[182:185], v[198:201], 0
	v_mfma_f32_16x16x32_bf16 v[82:85], v[174:177], v[206:209], 0
	v_mfma_f32_16x16x32_bf16 v[74:77], v[182:185], v[206:209], 0
	v_mfma_f32_16x16x32_bf16 v[70:73], v[174:177], v[214:217], 0
	v_mfma_f32_16x16x32_bf16 v[66:69], v[182:185], v[214:217], 0
	v_mfma_f32_16x16x32_bf16 v[114:117], v[178:181], v[194:197], v[114:117]
	v_mfma_f32_16x16x32_bf16 v[106:109], v[186:189], v[194:197], v[106:109]
	v_mfma_f32_16x16x32_bf16 v[98:101], v[178:181], v[202:205], v[98:101]
	v_mfma_f32_16x16x32_bf16 v[90:93], v[186:189], v[202:205], v[90:93]
	v_mfma_f32_16x16x32_bf16 v[82:85], v[178:181], v[210:213], v[82:85]
	v_mfma_f32_16x16x32_bf16 v[74:77], v[186:189], v[210:213], v[74:77]
	v_mfma_f32_16x16x32_bf16 v[70:73], v[178:181], v[218:221], v[70:73]
	v_mfma_f32_16x16x32_bf16 v[66:69], v[186:189], v[218:221], v[66:69]
	s_setprio 0
	s_barrier

; #define PG8_STAGE(bufoff, gbase, voff) do { _Pragma("unroll") for (int _i = 0; _i < 2; ++_i) \
;         __builtin_amdgcn_global_load_lds((const unsigned*)((const char*)(gbase) + (voff)[_i]), (PG8_LAS unsigned*)(lds + (bufoff) + ldsw + _i * 8192), 16, 0, 0); } while (0)
; #define PG8_LDA(dst, b, h) do { _Pragma("unroll") for (int m = 0; m < 4; ++m) _Pragma("unroll") for (int k = 0; k < 2; ++k) dst[m][k] = *(const PG8_LAS bf16x8*)(lds + PG8_SA(b, h) + aoff + m * 2048 + k * 1024); } while (0)
; #define PG8_MMA(ai, bj, At, Bt) do { __builtin_amdgcn_s_setprio(1); _Pragma("unroll") for (int m = 0; m < 4; ++m) _Pragma("unroll") for (int n = 0; n < 2; ++n) _Pragma("unroll") for (int k = 0; k < 2; ++k) \
;         acc[ai][bj][m][n] = __builtin_amdgcn_mfma_f32_16x16x32_bf16(Bt[n][k], At[m][k], acc[ai][bj][m][n], 0, 0, 0); __builtin_amdgcn_s_setprio(0); } while (0)
; #define PG8_WAIT_V(n) asm volatile("s_waitcnt vmcnt(" #n ")" ::: "memory")
; #define PG8_WAIT_L(n) asm volatile("s_waitcnt lgkmcnt(" #n ")" ::: "memory")
; #define PG8_BAR __builtin_amdgcn_s_barrier()
; #define PG8_SCHED __builtin_amdgcn_sched_barrier(0)
; template <class Epi, class Sched, bool ALIGN_EPI = false, bool SP2 = false>
; __device__ __forceinline__ void gemm_phase(PG8_LAS unsigned char* lds, const Gemm g, const Sched& S, const Epi& E) {
;     ...
;             PG8_LDA(At, 0, 1); PG8_STAGE(PG8_SB(0, 0), b2, voffB); PG8_STAGE(PG8_SB(0, 1), b2 + hstep, voffB); PG8_STAGE(PG8_SA(0, 0), a2, voffA);
;             PG8_WAIT_V(8); PG8_WAIT_L(0); PG8_BAR; PG8_MMA(1, 0, At, B0); PG8_MMA(1, 1, At, B1); PG8_BAR; PG8_SCHED;
	s_add_i32 s63, s48, s34
	v_lshl_add_u64 v[146:147], s[24:25], 0, v[132:133]
	s_mov_b32 m0, s63
	ds_read_b128 v[190:193], v152 offset:16384
	ds_read_b128 v[194:197], v152 offset:17408
	ds_read_b128 v[198:201], v152 offset:18432
	ds_read_b128 v[202:205], v152 offset:19456
	ds_read_b128 v[206:209], v152 offset:20480
	ds_read_b128 v[210:213], v152 offset:21504
	ds_read_b128 v[214:217], v152 offset:22528
	ds_read_b128 v[218:221], v152 offset:23552
	global_load_lds_dwordx4 v[146:147], off
	s_add_i32 m0, s63, 0x2000
	s_add_u32 s64, s24, 0xb0000
	v_lshl_add_u64 v[170:171], s[24:25], 0, v[136:137]
	s_addc_u32 s65, s25, 0
	s_add_i32 s63, s49, s34
	global_load_lds_dwordx4 v[170:171], off
	v_lshl_add_u64 v[222:223], s[64:65], 0, v[132:133]
	s_mov_b32 m0, s63
	v_lshl_add_u64 v[224:225], s[26:27], 0, v[134:135]
	global_load_lds_dwordx4 v[222:223], off
	v_lshl_add_u64 v[222:223], s[64:65], 0, v[136:137]
	s_add_i32 m0, s63, 0x2000
	s_nop 0
	global_load_lds_dwordx4 v[222:223], off
	v_lshl_add_u64 v[222:223], s[26:27], 0, v[130:131]
	s_mov_b32 m0, s35
	s_nop 0
	global_load_lds_dwordx4 v[222:223], off
	s_mov_b32 m0, s38
	s_nop 0
	global_load_lds_dwordx4 v[224:225], off
	s_waitcnt vmcnt(24)
	s_waitcnt lgkmcnt(0)
	s_barrier
	s_setprio 1
	s_waitcnt lgkmcnt(0)
	v_mfma_f32_16x16x32_bf16 v[62:65], v[154:157], v[190:193], 0
	v_mfma_f32_16x16x32_bf16 v[58:61], v[162:165], v[190:193], 0
	v_mfma_f32_16x16x32_bf16 v[54:57], v[154:157], v[198:201], 0
	v_mfma_f32_16x16x32_bf16 v[46:49], v[162:165], v[198:201], 0
	v_mfma_f32_16x16x32_bf16 v[38:41], v[154:157], v[206:209], 0
	v_mfma_f32_16x16x32_bf16 v[30:33], v[162:165], v[206:209], 0
	v_mfma_f32_16x16x32_bf16 v[22:25], v[154:157], v[214:217], 0
	v_mfma_f32_16x16x32_bf16 v[14:17], v[162:165], v[214:217], 0
	v_mfma_f32_16x16x32_bf16 v[62:65], v[158:161], v[194:197], v[62:65]
	v_mfma_f32_16x16x32_bf16 v[58:61], v[166:169], v[194:197], v[58:61]
	v_mfma_f32_16x16x32_bf16 v[54:57], v[158:161], v[202:205], v[54:57]
	v_mfma_f32_16x16x32_bf16 v[46:49], v[166:169], v[202:205], v[46:49]
	v_mfma_f32_16x16x32_bf16 v[38:41], v[158:161], v[210:213], v[38:41]
	v_mfma_f32_16x16x32_bf16 v[30:33], v[166:169], v[210:213], v[30:33]
	v_mfma_f32_16x16x32_bf16 v[22:25], v[158:161], v[218:221], v[22:25]
	v_mfma_f32_16x16x32_bf16 v[14:17], v[166:169], v[218:221], v[14:17]
	v_mfma_f32_16x16x32_bf16 v[50:53], v[174:177], v[190:193], 0
	v_mfma_f32_16x16x32_bf16 v[42:45], v[182:185], v[190:193], 0
	v_mfma_f32_16x16x32_bf16 v[34:37], v[174:177], v[198:201], 0
	v_mfma_f32_16x16x32_bf16 v[26:29], v[182:185], v[198:201], 0
	v_mfma_f32_16x16x32_bf16 v[18:21], v[174:177], v[206:209], 0
	v_mfma_f32_16x16x32_bf16 v[10:13], v[182:185], v[206:209], 0
	v_mfma_f32_16x16x32_bf16 v[6:9], v[174:177], v[214:217], 0
	v_mfma_f32_16x16x32_bf16 v[2:5], v[182:185], v[214:217], 0
	v_mfma_f32_16x16x32_bf16 v[50:53], v[178:181], v[194:197], v[50:53]
	v_mfma_f32_16x16x32_bf16 v[42:45], v[186:189], v[194:197], v[42:45]
	v_mfma_f32_16x16x32_bf16 v[34:37], v[178:181], v[202:205], v[34:37]
	v_mfma_f32_16x16x32_bf16 v[26:29], v[186:189], v[202:205], v[26:29]
	v_mfma_f32_16x16x32_bf16 v[18:21], v[178:181], v[210:213], v[18:21]
	v_mfma_f32_16x16x32_bf16 v[10:13], v[186:189], v[210:213], v[10:13]
	v_mfma_f32_16x16x32_bf16 v[6:9], v[178:181], v[218:221], v[6:9]
	v_mfma_f32_16x16x32_bf16 v[2:5], v[186:189], v[218:221], v[2:5]
	s_setprio 0
	s_barrier

; #define PG8_STAGE(bufoff, gbase, voff) do { _Pragma("unroll") for (int _i = 0; _i < 2; ++_i) \
;         __builtin_amdgcn_global_load_lds((const unsigned*)((const char*)(gbase) + (voff)[_i]), (PG8_LAS unsigned*)(lds + (bufoff) + ldsw + _i * 8192), 16, 0, 0); } while (0)
; #define PG8_LDA(dst, b, h) do { _Pragma("unroll") for (int m = 0; m < 4; ++m) _Pragma("unroll") for (int k = 0; k < 2; ++k) dst[m][k] = *(const PG8_LAS bf16x8*)(lds + PG8_SA(b, h) + aoff + m * 2048 + k * 1024); } while (0)
; #define PG8_LDB(dst, b, h) do { _Pragma("unroll") for (int n = 0; n < 2; ++n) _Pragma("unroll") for (int k = 0; k < 2; ++k) dst[n][k] = *(const PG8_LAS bf16x8*)(lds + PG8_SB(b, h) + boff + n * 2048 + k * 1024); } while (0)
; #define PG8_SCHED __builtin_amdgcn_sched_barrier(0)
; template <class Epi, class Sched, bool ALIGN_EPI = false, bool SP2 = false>
; __device__ __forceinline__ void gemm_phase(PG8_LAS unsigned char* lds, const Gemm g, const Sched& S, const Epi& E) {
;     ...
;             PG8_LDB(B0, 1, 0); PG8_LDB(B1, 1, 1); PG8_SCHED; PG8_LDA(At, 1, 0); PG8_STAGE(PG8_SA(0, 1), a2 + hstep, voffA);
	s_add_i32 s63, 0, 0x18000
	v_add_u32_e32 v153, s63, v148
	s_add_i32 s64, 0, 0x1c000
	ds_read_b128 v[154:157], v153
	ds_read_b128 v[158:161], v153 offset:1024
	ds_read_b128 v[162:165], v153 offset:2048
	ds_read_b128 v[166:169], v153 offset:3072
	v_add_u32_e32 v153, s64, v148
	ds_read_b128 v[174:177], v153
	ds_read_b128 v[178:181], v153 offset:1024
	ds_read_b128 v[182:185], v153 offset:2048
	ds_read_b128 v[186:189], v153 offset:3072

; #define PG8_STAGE(bufoff, gbase, voff) do { _Pragma("unroll") for (int _i = 0; _i < 2; ++_i) \
;         __builtin_amdgcn_global_load_lds((const unsigned*)((const char*)(gbase) + (voff)[_i]), (PG8_LAS unsigned*)(lds + (bufoff) + ldsw + _i * 8192), 16, 0, 0); } while (0)
; #define PG8_LDA(dst, b, h) do { _Pragma("unroll") for (int m = 0; m < 4; ++m) _Pragma("unroll") for (int k = 0; k < 2; ++k) dst[m][k] = *(const PG8_LAS bf16x8*)(lds + PG8_SA(b, h) + aoff + m * 2048 + k * 1024); } while (0)
; #define PG8_LDB(dst, b, h) do { _Pragma("unroll") for (int n = 0; n < 2; ++n) _Pragma("unroll") for (int k = 0; k < 2; ++k) dst[n][k] = *(const PG8_LAS bf16x8*)(lds + PG8_SB(b, h) + boff + n * 2048 + k * 1024); } while (0)
; #define PG8_MMA(ai, bj, At, Bt) do { __builtin_amdgcn_s_setprio(1); _Pragma("unroll") for (int m = 0; m < 4; ++m) _Pragma("unroll") for (int n = 0; n < 2; ++n) _Pragma("unroll") for (int k = 0; k < 2; ++k) \
;         acc[ai][bj][m][n] = __builtin_amdgcn_mfma_f32_16x16x32_bf16(Bt[n][k], At[m][k], acc[ai][bj][m][n], 0, 0, 0); __builtin_amdgcn_s_setprio(0); } while (0)
; #define PG8_WAIT_V(n) asm volatile("s_waitcnt vmcnt(" #n ")" ::: "memory")
; #define PG8_WAIT_L(n) asm volatile("s_waitcnt lgkmcnt(" #n ")" ::: "memory")
; #define PG8_BAR __builtin_amdgcn_s_barrier()
; #define PG8_SCHED __builtin_amdgcn_sched_barrier(0)
; template <class Epi, class Sched, bool ALIGN_EPI = false, bool SP2 = false>
; __device__ __forceinline__ void gemm_phase(PG8_LAS unsigned char* lds, const Gemm g, const Sched& S, const Epi& E) {
;     ...
;             PG8_LDB(B0, 1, 0); PG8_LDB(B1, 1, 1); PG8_SCHED; PG8_LDA(At, 1, 0); PG8_STAGE(PG8_SA(0, 1), a2 + hstep, voffA);
;             PG8_WAIT_V(8); PG8_WAIT_L(0); PG8_BAR; PG8_MMA(0, 0, At, B0); PG8_MMA(0, 1, At, B1); PG8_BAR; PG8_SCHED;
	s_add_u32 s26, s26, 0xb0000
	s_addc_u32 s27, s27, 0
	s_mov_b32 m0, s39
	v_lshl_add_u64 v[226:227], s[26:27], 0, v[130:131]
	ds_read_b128 v[190:193], v152 offset:32768
	ds_read_b128 v[194:197], v152 offset:33792
	ds_read_b128 v[198:201], v152 offset:34816
	ds_read_b128 v[202:205], v152 offset:35840
	ds_read_b128 v[206:209], v152 offset:36864
	ds_read_b128 v[210:213], v152 offset:37888
	ds_read_b128 v[214:217], v152 offset:38912
	ds_read_b128 v[218:221], v152 offset:39936
	global_load_lds_dwordx4 v[226:227], off
	v_lshl_add_u64 v[226:227], s[26:27], 0, v[134:135]
	s_mov_b32 m0, s40
	s_nop 0
	global_load_lds_dwordx4 v[226:227], off
	s_waitcnt vmcnt(8)
	s_waitcnt lgkmcnt(0)
	s_barrier
	s_setprio 1
	s_waitcnt lgkmcnt(0)
	v_mfma_f32_16x16x32_bf16 v[126:129], v[154:157], v[190:193], v[126:129]
	v_mfma_f32_16x16x32_bf16 v[122:125], v[162:165], v[190:193], v[122:125]
	v_mfma_f32_16x16x32_bf16 v[118:121], v[154:157], v[198:201], v[118:121]
	v_mfma_f32_16x16x32_bf16 v[110:113], v[162:165], v[198:201], v[110:113]
	v_mfma_f32_16x16x32_bf16 v[102:105], v[154:157], v[206:209], v[102:105]
	v_mfma_f32_16x16x32_bf16 v[94:97], v[162:165], v[206:209], v[94:97]
	v_mfma_f32_16x16x32_bf16 v[86:89], v[154:157], v[214:217], v[86:89]
	v_mfma_f32_16x16x32_bf16 v[78:81], v[162:165], v[214:217], v[78:81]
	v_mfma_f32_16x16x32_bf16 v[126:129], v[158:161], v[194:197], v[126:129]
	v_mfma_f32_16x16x32_bf16 v[122:125], v[166:169], v[194:197], v[122:125]
	v_mfma_f32_16x16x32_bf16 v[118:121], v[158:161], v[202:205], v[118:121]
	v_mfma_f32_16x16x32_bf16 v[110:113], v[166:169], v[202:205], v[110:113]
	v_mfma_f32_16x16x32_bf16 v[102:105], v[158:161], v[210:213], v[102:105]
	v_mfma_f32_16x16x32_bf16 v[94:97], v[166:169], v[210:213], v[94:97]
	v_mfma_f32_16x16x32_bf16 v[86:89], v[158:161], v[218:221], v[86:89]
	v_mfma_f32_16x16x32_bf16 v[78:81], v[166:169], v[218:221], v[78:81]
	v_mfma_f32_16x16x32_bf16 v[114:117], v[174:177], v[190:193], v[114:117]
	v_mfma_f32_16x16x32_bf16 v[106:109], v[182:185], v[190:193], v[106:109]
	v_mfma_f32_16x16x32_bf16 v[98:101], v[174:177], v[198:201], v[98:101]
	v_mfma_f32_16x16x32_bf16 v[90:93], v[182:185], v[198:201], v[90:93]
	v_mfma_f32_16x16x32_bf16 v[82:85], v[174:177], v[206:209], v[82:85]
	v_mfma_f32_16x16x32_bf16 v[74:77], v[182:185], v[206:209], v[74:77]
	v_mfma_f32_16x16x32_bf16 v[70:73], v[174:177], v[214:217], v[70:73]
	v_mfma_f32_16x16x32_bf16 v[66:69], v[182:185], v[214:217], v[66:69]
	v_mfma_f32_16x16x32_bf16 v[114:117], v[178:181], v[194:197], v[114:117]
	v_mfma_f32_16x16x32_bf16 v[106:109], v[186:189], v[194:197], v[106:109]
	v_mfma_f32_16x16x32_bf16 v[98:101], v[178:181], v[202:205], v[98:101]
	v_mfma_f32_16x16x32_bf16 v[90:93], v[186:189], v[202:205], v[90:93]
	v_mfma_f32_16x16x32_bf16 v[82:85], v[178:181], v[210:213], v[82:85]
	v_mfma_f32_16x16x32_bf16 v[74:77], v[186:189], v[210:213], v[74:77]
	v_mfma_f32_16x16x32_bf16 v[70:73], v[178:181], v[218:221], v[70:73]
	v_mfma_f32_16x16x32_bf16 v[66:69], v[186:189], v[218:221], v[66:69]
	s_setprio 0
	s_barrier

; #define PG8_STAGE(bufoff, gbase, voff) do { _Pragma("unroll") for (int _i = 0; _i < 2; ++_i) \
;         __builtin_amdgcn_global_load_lds((const unsigned*)((const char*)(gbase) + (voff)[_i]), (PG8_LAS unsigned*)(lds + (bufoff) + ldsw + _i * 8192), 16, 0, 0); } while (0)
; #define PG8_LDA(dst, b, h) do { _Pragma("unroll") for (int m = 0; m < 4; ++m) _Pragma("unroll") for (int k = 0; k < 2; ++k) dst[m][k] = *(const PG8_LAS bf16x8*)(lds + PG8_SA(b, h) + aoff + m * 2048 + k * 1024); } while (0)
; #define PG8_MMA(ai, bj, At, Bt) do { __builtin_amdgcn_s_setprio(1); _Pragma("unroll") for (int m = 0; m < 4; ++m) _Pragma("unroll") for (int n = 0; n < 2; ++n) _Pragma("unroll") for (int k = 0; k < 2; ++k) \
;         acc[ai][bj][m][n] = __builtin_amdgcn_mfma_f32_16x16x32_bf16(Bt[n][k], At[m][k], acc[ai][bj][m][n], 0, 0, 0); __builtin_amdgcn_s_setprio(0); } while (0)
; #define PG8_WAIT_V(n) asm volatile("s_waitcnt vmcnt(" #n ")" ::: "memory")
; #define PG8_WAIT_L(n) asm volatile("s_waitcnt lgkmcnt(" #n ")" ::: "memory")
; #define PG8_BAR __builtin_amdgcn_s_barrier()
; #define PG8_SCHED __builtin_amdgcn_sched_barrier(0)
; template <class Epi, class Sched, bool ALIGN_EPI = false, bool SP2 = false>
; __device__ __forceinline__ void gemm_phase(PG8_LAS unsigned char* lds, const Gemm g, const Sched& S, const Epi& E) {
;     ...
;             PG8_LDA(At, 1, 1); PG8_STAGE(PG8_SB(1, 0), b3, voffB); PG8_STAGE(PG8_SB(1, 1), b3 + hstep, voffB); PG8_STAGE(PG8_SA(1, 0), a3, voffA);
;             PG8_WAIT_V(8); PG8_WAIT_L(0); PG8_BAR; PG8_MMA(1, 0, At, B0); PG8_MMA(1, 1, At, B1); PG8_BAR; PG8_SCHED;
	s_add_i32 s26, s63, s34
	v_lshl_add_u64 v[146:147], v[146:147], 0, s[8:9]
	s_mov_b32 m0, s26
	ds_read_b128 v[190:193], v152 offset:49152
	ds_read_b128 v[194:197], v152 offset:50176
	ds_read_b128 v[198:201], v152 offset:51200
	ds_read_b128 v[202:205], v152 offset:52224
	ds_read_b128 v[206:209], v152 offset:53248
	ds_read_b128 v[210:213], v152 offset:54272
	ds_read_b128 v[214:217], v152 offset:55296
	ds_read_b128 v[218:221], v152 offset:56320
	global_load_lds_dwordx4 v[146:147], off
	s_add_i32 m0, s26, 0x2000
	s_add_u32 s24, s24, 0xb0080
	v_lshl_add_u64 v[146:147], v[170:171], 0, s[8:9]
	s_addc_u32 s25, s25, 0
	s_add_i32 s26, s64, s34
	global_load_lds_dwordx4 v[146:147], off
	v_lshl_add_u64 v[146:147], s[24:25], 0, v[132:133]
	s_mov_b32 m0, s26
	s_nop 0
	global_load_lds_dwordx4 v[146:147], off
	v_lshl_add_u64 v[146:147], s[24:25], 0, v[136:137]
	s_add_i32 m0, s26, 0x2000
	s_nop 0
	global_load_lds_dwordx4 v[146:147], off
	v_lshl_add_u64 v[146:147], v[222:223], 0, s[8:9]
	s_mov_b32 m0, s42
	s_nop 0
	global_load_lds_dwordx4 v[146:147], off
	v_lshl_add_u64 v[146:147], v[224:225], 0, s[8:9]
	s_mov_b32 m0, s43
	s_nop 0
	global_load_lds_dwordx4 v[146:147], off
	s_waitcnt vmcnt(8)
	s_waitcnt lgkmcnt(0)
	s_barrier
	s_setprio 1
	s_waitcnt lgkmcnt(0)
	v_mfma_f32_16x16x32_bf16 v[62:65], v[154:157], v[190:193], v[62:65]
	v_mfma_f32_16x16x32_bf16 v[58:61], v[162:165], v[190:193], v[58:61]
	v_mfma_f32_16x16x32_bf16 v[54:57], v[154:157], v[198:201], v[54:57]
	v_mfma_f32_16x16x32_bf16 v[46:49], v[162:165], v[198:201], v[46:49]
	v_mfma_f32_16x16x32_bf16 v[38:41], v[154:157], v[206:209], v[38:41]
	v_mfma_f32_16x16x32_bf16 v[30:33], v[162:165], v[206:209], v[30:33]
	v_mfma_f32_16x16x32_bf16 v[22:25], v[154:157], v[214:217], v[22:25]
	v_mfma_f32_16x16x32_bf16 v[14:17], v[162:165], v[214:217], v[14:17]
	v_mfma_f32_16x16x32_bf16 v[62:65], v[158:161], v[194:197], v[62:65]
	v_mfma_f32_16x16x32_bf16 v[58:61], v[166:169], v[194:197], v[58:61]
	v_mfma_f32_16x16x32_bf16 v[54:57], v[158:161], v[202:205], v[54:57]
	v_mfma_f32_16x16x32_bf16 v[46:49], v[166:169], v[202:205], v[46:49]
	v_mfma_f32_16x16x32_bf16 v[38:41], v[158:161], v[210:213], v[38:41]
	v_mfma_f32_16x16x32_bf16 v[30:33], v[166:169], v[210:213], v[30:33]
	v_mfma_f32_16x16x32_bf16 v[22:25], v[158:161], v[218:221], v[22:25]
	v_mfma_f32_16x16x32_bf16 v[14:17], v[166:169], v[218:221], v[14:17]
	v_mfma_f32_16x16x32_bf16 v[50:53], v[174:177], v[190:193], v[50:53]
	v_mfma_f32_16x16x32_bf16 v[42:45], v[182:185], v[190:193], v[42:45]
	v_mfma_f32_16x16x32_bf16 v[34:37], v[174:177], v[198:201], v[34:37]
	v_mfma_f32_16x16x32_bf16 v[26:29], v[182:185], v[198:201], v[26:29]
	v_mfma_f32_16x16x32_bf16 v[18:21], v[174:177], v[206:209], v[18:21]
	v_mfma_f32_16x16x32_bf16 v[10:13], v[182:185], v[206:209], v[10:13]
	v_mfma_f32_16x16x32_bf16 v[6:9], v[174:177], v[214:217], v[6:9]
	v_mfma_f32_16x16x32_bf16 v[2:5], v[182:185], v[214:217], v[2:5]
	v_mfma_f32_16x16x32_bf16 v[50:53], v[178:181], v[194:197], v[50:53]
	v_mfma_f32_16x16x32_bf16 v[42:45], v[186:189], v[194:197], v[42:45]
	v_mfma_f32_16x16x32_bf16 v[34:37], v[178:181], v[202:205], v[34:37]
	v_mfma_f32_16x16x32_bf16 v[26:29], v[186:189], v[202:205], v[26:29]
	v_mfma_f32_16x16x32_bf16 v[18:21], v[178:181], v[210:213], v[18:21]
	v_mfma_f32_16x16x32_bf16 v[10:13], v[186:189], v[210:213], v[10:13]
	v_mfma_f32_16x16x32_bf16 v[6:9], v[178:181], v[218:221], v[6:9]
	v_mfma_f32_16x16x32_bf16 v[2:5], v[186:189], v[218:221], v[2:5]
	s_setprio 0
	s_barrier

; #define PG8_STAGE(bufoff, gbase, voff) do { _Pragma("unroll") for (int _i = 0; _i < 2; ++_i) \
;         __builtin_amdgcn_global_load_lds((const unsigned*)((const char*)(gbase) + (voff)[_i]), (PG8_LAS unsigned*)(lds + (bufoff) + ldsw + _i * 8192), 16, 0, 0); } while (0)
; #define PG8_LDA(dst, b, h) do { _Pragma("unroll") for (int m = 0; m < 4; ++m) _Pragma("unroll") for (int k = 0; k < 2; ++k) dst[m][k] = *(const PG8_LAS bf16x8*)(lds + PG8_SA(b, h) + aoff + m * 2048 + k * 1024); } while (0)
; #define PG8_LDB(dst, b, h) do { _Pragma("unroll") for (int n = 0; n < 2; ++n) _Pragma("unroll") for (int k = 0; k < 2; ++k) dst[n][k] = *(const PG8_LAS bf16x8*)(lds + PG8_SB(b, h) + boff + n * 2048 + k * 1024); } while (0)
; #define PG8_MMA(ai, bj, At, Bt) do { __builtin_amdgcn_s_setprio(1); _Pragma("unroll") for (int m = 0; m < 4; ++m) _Pragma("unroll") for (int n = 0; n < 2; ++n) _Pragma("unroll") for (int k = 0; k < 2; ++k) \
;         acc[ai][bj][m][n] = __builtin_amdgcn_mfma_f32_16x16x32_bf16(Bt[n][k], At[m][k], acc[ai][bj][m][n], 0, 0, 0); __builtin_amdgcn_s_setprio(0); } while (0)
; #define PG8_WAIT_V(n) asm volatile("s_waitcnt vmcnt(" #n ")" ::: "memory")
; #define PG8_BAR __builtin_amdgcn_s_barrier()
; template <class Epi, class Sched, bool ALIGN_EPI = false, bool SP2 = false>
; __device__ __forceinline__ void gemm_phase(PG8_LAS unsigned char* lds, const Gemm g, const Sched& S, const Epi& E) {
;     ...
;         for (int t = 0; t < nt; t += 2) {
;             const bool last = (t == nt - 2);
;             const char* a1 = cA + (size_t)(t + 1) * kstep;
;             const char* a2 = last ? nA : cA + (size_t)(t + 2) * kstep; const char* b2 = last ? nB : cB + (size_t)(t + 2) * kstep;
;             const char* a3 = a2 + kstep; const char* b3 = b2 + kstep;
;             if (last && has_next) S.a_ready(nxt);
;             if constexpr (SP2) {
;             PG8_LDB(B0, 0, 0); PG8_LDB(B1, 0, 1); PG8_SCHED; PG8_LDA(At, 0, 0); PG8_STAGE(PG8_SA(1, 1), a1 + hstep, voffA);
;             PG8_WAIT_V(8); PG8_WAIT_L(0); PG8_BAR; PG8_MMA(0, 0, At, B0); PG8_MMA(0, 1, At, B1); PG8_BAR; PG8_SCHED;
;             PG8_LDA(At, 0, 1); PG8_STAGE(PG8_SB(0, 0), b2, voffB); PG8_STAGE(PG8_SB(0, 1), b2 + hstep, voffB); PG8_STAGE(PG8_SA(0, 0), a2, voffA);
;             PG8_WAIT_V(8); PG8_WAIT_L(0); PG8_BAR; PG8_MMA(1, 0, At, B0); PG8_MMA(1, 1, At, B1); PG8_BAR; PG8_SCHED;
	s_add_i32 s62, s62, 2
	s_add_u32 s22, s22, 0x100
	s_addc_u32 s23, s23, 0
	s_add_u32 s60, s60, 0x100
	s_addc_u32 s61, s61, 0
.LBB0_1688:
	ds_read_b128 v[154:157], v150
	ds_read_b128 v[158:161], v150 offset:1024
	ds_read_b128 v[162:165], v150 offset:2048
	ds_read_b128 v[166:169], v150 offset:3072
	ds_read_b128 v[174:177], v151
	ds_read_b128 v[178:181], v151 offset:1024
	ds_read_b128 v[182:185], v151 offset:2048
	ds_read_b128 v[186:189], v151 offset:3072
	s_add_u32 s24, s22, 0xfff50080
	s_addc_u32 s25, s23, -1
	s_cmp_eq_u32 s62, 40
	s_cselect_b32 s27, s5, s25
	s_cselect_b32 s26, s4, s24
	s_cselect_b32 s25, s21, s61
	s_cselect_b32 s24, s20, s60
	v_lshl_add_u64 v[146:147], s[22:23], 0, v[138:139]
	s_add_i32 m0, s35, 0xc000
	ds_read_b128 v[190:193], v152
	ds_read_b128 v[194:197], v152 offset:1024
	ds_read_b128 v[198:201], v152 offset:2048
	ds_read_b128 v[202:205], v152 offset:3072
	ds_read_b128 v[206:209], v152 offset:4096
	ds_read_b128 v[210:213], v152 offset:5120
	ds_read_b128 v[214:217], v152 offset:6144
	ds_read_b128 v[218:221], v152 offset:7168
	global_load_lds_dwordx4 v[146:147], off
	v_lshl_add_u64 v[146:147], s[22:23], 0, v[140:141]
	s_add_i32 m0, s35, 0xe000
	s_nop 0
	global_load_lds_dwordx4 v[146:147], off
	s_waitcnt vmcnt(8)
	s_waitcnt lgkmcnt(0)
	s_barrier
	s_setprio 1
	s_waitcnt lgkmcnt(0)
	v_mfma_f32_16x16x32_bf16 v[126:129], v[154:157], v[190:193], v[126:129]
	v_mfma_f32_16x16x32_bf16 v[122:125], v[162:165], v[190:193], v[122:125]
	v_mfma_f32_16x16x32_bf16 v[118:121], v[154:157], v[198:201], v[118:121]
	v_mfma_f32_16x16x32_bf16 v[110:113], v[162:165], v[198:201], v[110:113]
	v_mfma_f32_16x16x32_bf16 v[102:105], v[154:157], v[206:209], v[102:105]
	v_mfma_f32_16x16x32_bf16 v[94:97], v[162:165], v[206:209], v[94:97]
	v_mfma_f32_16x16x32_bf16 v[86:89], v[154:157], v[214:217], v[86:89]
	v_mfma_f32_16x16x32_bf16 v[78:81], v[162:165], v[214:217], v[78:81]
	v_mfma_f32_16x16x32_bf16 v[126:129], v[158:161], v[194:197], v[126:129]
	v_mfma_f32_16x16x32_bf16 v[122:125], v[166:169], v[194:197], v[122:125]
	v_mfma_f32_16x16x32_bf16 v[118:121], v[158:161], v[202:205], v[118:121]
	v_mfma_f32_16x16x32_bf16 v[110:113], v[166:169], v[202:205], v[110:113]
	v_mfma_f32_16x16x32_bf16 v[102:105], v[158:161], v[210:213], v[102:105]
	v_mfma_f32_16x16x32_bf16 v[94:97], v[166:169], v[210:213], v[94:97]
	v_mfma_f32_16x16x32_bf16 v[86:89], v[158:161], v[218:221], v[86:89]
	v_mfma_f32_16x16x32_bf16 v[78:81], v[166:169], v[218:221], v[78:81]
	v_mfma_f32_16x16x32_bf16 v[114:117], v[174:177], v[190:193], v[114:117]
	v_mfma_f32_16x16x32_bf16 v[106:109], v[182:185], v[190:193], v[106:109]
	v_mfma_f32_16x16x32_bf16 v[98:101], v[174:177], v[198:201], v[98:101]
	v_mfma_f32_16x16x32_bf16 v[90:93], v[182:185], v[198:201], v[90:93]
	v_mfma_f32_16x16x32_bf16 v[82:85], v[174:177], v[206:209], v[82:85]
	v_mfma_f32_16x16x32_bf16 v[74:77], v[182:185], v[206:209], v[74:77]
	v_mfma_f32_16x16x32_bf16 v[70:73], v[174:177], v[214:217], v[70:73]
	v_mfma_f32_16x16x32_bf16 v[66:69], v[182:185], v[214:217], v[66:69]
	v_mfma_f32_16x16x32_bf16 v[114:117], v[178:181], v[194:197], v[114:117]
	v_mfma_f32_16x16x32_bf16 v[106:109], v[186:189], v[194:197], v[106:109]
	v_mfma_f32_16x16x32_bf16 v[98:101], v[178:181], v[202:205], v[98:101]
	v_mfma_f32_16x16x32_bf16 v[90:93], v[186:189], v[202:205], v[90:93]
	v_mfma_f32_16x16x32_bf16 v[82:85], v[178:181], v[210:213], v[82:85]
	v_mfma_f32_16x16x32_bf16 v[74:77], v[186:189], v[210:213], v[74:77]
	v_mfma_f32_16x16x32_bf16 v[70:73], v[178:181], v[218:221], v[70:73]
	v_mfma_f32_16x16x32_bf16 v[66:69], v[186:189], v[218:221], v[66:69]
	s_setprio 0
	s_barrier
	s_add_i32 s63, s48, s34
	v_lshl_add_u64 v[146:147], s[24:25], 0, v[132:133]
	s_mov_b32 m0, s63
	ds_read_b128 v[190:193], v152 offset:16384
	ds_read_b128 v[194:197], v152 offset:17408
	ds_read_b128 v[198:201], v152 offset:18432
	ds_read_b128 v[202:205], v152 offset:19456
	ds_read_b128 v[206:209], v152 offset:20480
	ds_read_b128 v[210:213], v152 offset:21504
	ds_read_b128 v[214:217], v152 offset:22528
	ds_read_b128 v[218:221], v152 offset:23552
	global_load_lds_dwordx4 v[146:147], off
	s_add_i32 m0, s63, 0x2000
	s_add_u32 s64, s24, 0xb0000
	v_lshl_add_u64 v[170:171], s[24:25], 0, v[136:137]
	s_addc_u32 s65, s25, 0
	s_add_i32 s63, s49, s34
	global_load_lds_dwordx4 v[170:171], off
	v_lshl_add_u64 v[222:223], s[64:65], 0, v[132:133]
	s_mov_b32 m0, s63
	v_lshl_add_u64 v[224:225], s[26:27], 0, v[134:135]
	global_load_lds_dwordx4 v[222:223], off
	v_lshl_add_u64 v[222:223], s[64:65], 0, v[136:137]
	s_add_i32 m0, s63, 0x2000
	s_nop 0
	global_load_lds_dwordx4 v[222:223], off
	v_lshl_add_u64 v[222:223], s[26:27], 0, v[130:131]
	s_mov_b32 m0, s35
	s_nop 0
	global_load_lds_dwordx4 v[222:223], off
	s_mov_b32 m0, s38
	s_nop 0
	global_load_lds_dwordx4 v[224:225], off
	s_waitcnt vmcnt(8)
	s_waitcnt lgkmcnt(0)
	s_barrier
; #define PG8_STAGE(bufoff, gbase, voff) do { _Pragma("unroll") for (int _i = 0; _i < 2; ++_i) \
;         __builtin_amdgcn_global_load_lds((const unsigned*)((const char*)(gbase) + (voff)[_i]), (PG8_LAS unsigned*)(lds + (bufoff) + ldsw + _i * 8192), 16, 0, 0); } while (0)
; #define PG8_LDA(dst, b, h) do { _Pragma("unroll") for (int m = 0; m < 4; ++m) _Pragma("unroll") for (int k = 0; k < 2; ++k) dst[m][k] = *(const PG8_LAS bf16x8*)(lds + PG8_SA(b, h) + aoff + m * 2048 + k * 1024); } while (0)
; #define PG8_LDB(dst, b, h) do { _Pragma("unroll") for (int n = 0; n < 2; ++n) _Pragma("unroll") for (int k = 0; k < 2; ++k) dst[n][k] = *(const PG8_LAS bf16x8*)(lds + PG8_SB(b, h) + boff + n * 2048 + k * 1024); } while (0)
; #define PG8_MMA(ai, bj, At, Bt) do { __builtin_amdgcn_s_setprio(1); _Pragma("unroll") for (int m = 0; m < 4; ++m) _Pragma("unroll") for (int n = 0; n < 2; ++n) _Pragma("unroll") for (int k = 0; k < 2; ++k) \
;         acc[ai][bj][m][n] = __builtin_amdgcn_mfma_f32_16x16x32_bf16(Bt[n][k], At[m][k], acc[ai][bj][m][n], 0, 0, 0); __builtin_amdgcn_s_setprio(0); } while (0)
; #define PG8_WAIT_V(n) asm volatile("s_waitcnt vmcnt(" #n ")" ::: "memory")
; #define PG8_WAIT_L(n) asm volatile("s_waitcnt lgkmcnt(" #n ")" ::: "memory")
; #define PG8_BAR __builtin_amdgcn_s_barrier()
; #define PG8_SCHED __builtin_amdgcn_sched_barrier(0)
; template <class Epi, class Sched, bool ALIGN_EPI = false, bool SP2 = false>
; __device__ __forceinline__ void gemm_phase(PG8_LAS unsigned char* lds, const Gemm g, const Sched& S, const Epi& E) {
;     ...
;             PG8_WAIT_V(8); PG8_WAIT_L(0); PG8_BAR; PG8_MMA(1, 0, At, B0); PG8_MMA(1, 1, At, B1); PG8_BAR; PG8_SCHED;
;             PG8_LDB(B0, 1, 0); PG8_LDB(B1, 1, 1); PG8_SCHED; PG8_LDA(At, 1, 0); PG8_STAGE(PG8_SA(0, 1), a2 + hstep, voffA);
;             PG8_WAIT_V(8); PG8_WAIT_L(0); PG8_BAR; PG8_MMA(0, 0, At, B0); PG8_MMA(0, 1, At, B1); PG8_BAR; PG8_SCHED;
	s_setprio 1
	s_waitcnt lgkmcnt(0)
	v_mfma_f32_16x16x32_bf16 v[62:65], v[154:157], v[190:193], v[62:65]
	v_mfma_f32_16x16x32_bf16 v[58:61], v[162:165], v[190:193], v[58:61]
	v_mfma_f32_16x16x32_bf16 v[54:57], v[154:157], v[198:201], v[54:57]
	v_mfma_f32_16x16x32_bf16 v[46:49], v[162:165], v[198:201], v[46:49]
	v_mfma_f32_16x16x32_bf16 v[38:41], v[154:157], v[206:209], v[38:41]
	v_mfma_f32_16x16x32_bf16 v[30:33], v[162:165], v[206:209], v[30:33]
	v_mfma_f32_16x16x32_bf16 v[22:25], v[154:157], v[214:217], v[22:25]
	v_mfma_f32_16x16x32_bf16 v[14:17], v[162:165], v[214:217], v[14:17]
	v_mfma_f32_16x16x32_bf16 v[62:65], v[158:161], v[194:197], v[62:65]
	v_mfma_f32_16x16x32_bf16 v[58:61], v[166:169], v[194:197], v[58:61]
	v_mfma_f32_16x16x32_bf16 v[54:57], v[158:161], v[202:205], v[54:57]
	v_mfma_f32_16x16x32_bf16 v[46:49], v[166:169], v[202:205], v[46:49]
	v_mfma_f32_16x16x32_bf16 v[38:41], v[158:161], v[210:213], v[38:41]
	v_mfma_f32_16x16x32_bf16 v[30:33], v[166:169], v[210:213], v[30:33]
	v_mfma_f32_16x16x32_bf16 v[22:25], v[158:161], v[218:221], v[22:25]
	v_mfma_f32_16x16x32_bf16 v[14:17], v[166:169], v[218:221], v[14:17]
	v_mfma_f32_16x16x32_bf16 v[50:53], v[174:177], v[190:193], v[50:53]
	v_mfma_f32_16x16x32_bf16 v[42:45], v[182:185], v[190:193], v[42:45]
	v_mfma_f32_16x16x32_bf16 v[34:37], v[174:177], v[198:201], v[34:37]
	v_mfma_f32_16x16x32_bf16 v[26:29], v[182:185], v[198:201], v[26:29]
	v_mfma_f32_16x16x32_bf16 v[18:21], v[174:177], v[206:209], v[18:21]
	v_mfma_f32_16x16x32_bf16 v[10:13], v[182:185], v[206:209], v[10:13]
	v_mfma_f32_16x16x32_bf16 v[6:9], v[174:177], v[214:217], v[6:9]
	v_mfma_f32_16x16x32_bf16 v[2:5], v[182:185], v[214:217], v[2:5]
	v_mfma_f32_16x16x32_bf16 v[50:53], v[178:181], v[194:197], v[50:53]
	v_mfma_f32_16x16x32_bf16 v[42:45], v[186:189], v[194:197], v[42:45]
	v_mfma_f32_16x16x32_bf16 v[34:37], v[178:181], v[202:205], v[34:37]
	v_mfma_f32_16x16x32_bf16 v[26:29], v[186:189], v[202:205], v[26:29]
	v_mfma_f32_16x16x32_bf16 v[18:21], v[178:181], v[210:213], v[18:21]
	v_mfma_f32_16x16x32_bf16 v[10:13], v[186:189], v[210:213], v[10:13]
	v_mfma_f32_16x16x32_bf16 v[6:9], v[178:181], v[218:221], v[6:9]
	v_mfma_f32_16x16x32_bf16 v[2:5], v[186:189], v[218:221], v[2:5]
	s_setprio 0
	s_barrier
	s_add_i32 s63, 0, 0x18000
	v_add_u32_e32 v153, s63, v148
	s_add_i32 s64, 0, 0x1c000
	ds_read_b128 v[154:157], v153
	ds_read_b128 v[158:161], v153 offset:1024
	ds_read_b128 v[162:165], v153 offset:2048
	ds_read_b128 v[166:169], v153 offset:3072
	v_add_u32_e32 v153, s64, v148
	ds_read_b128 v[174:177], v153
	ds_read_b128 v[178:181], v153 offset:1024
	ds_read_b128 v[182:185], v153 offset:2048
	ds_read_b128 v[186:189], v153 offset:3072
	s_add_u32 s26, s26, 0xb0000
	s_addc_u32 s27, s27, 0
	s_mov_b32 m0, s39
	v_lshl_add_u64 v[226:227], s[26:27], 0, v[130:131]
	ds_read_b128 v[190:193], v152 offset:32768
	ds_read_b128 v[194:197], v152 offset:33792
	ds_read_b128 v[198:201], v152 offset:34816
	ds_read_b128 v[202:205], v152 offset:35840
	ds_read_b128 v[206:209], v152 offset:36864
	ds_read_b128 v[210:213], v152 offset:37888
	ds_read_b128 v[214:217], v152 offset:38912
	ds_read_b128 v[218:221], v152 offset:39936
	global_load_lds_dwordx4 v[226:227], off
	v_lshl_add_u64 v[226:227], s[26:27], 0, v[134:135]
	s_mov_b32 m0, s40
	s_nop 0
	global_load_lds_dwordx4 v[226:227], off
	s_waitcnt vmcnt(8)
	s_waitcnt lgkmcnt(0)
	s_barrier
	s_setprio 1
	s_waitcnt lgkmcnt(0)
	v_mfma_f32_16x16x32_bf16 v[126:129], v[154:157], v[190:193], v[126:129]
	v_mfma_f32_16x16x32_bf16 v[122:125], v[162:165], v[190:193], v[122:125]
	v_mfma_f32_16x16x32_bf16 v[118:121], v[154:157], v[198:201], v[118:121]
	v_mfma_f32_16x16x32_bf16 v[110:113], v[162:165], v[198:201], v[110:113]
	v_mfma_f32_16x16x32_bf16 v[102:105], v[154:157], v[206:209], v[102:105]
	v_mfma_f32_16x16x32_bf16 v[94:97], v[162:165], v[206:209], v[94:97]
	v_mfma_f32_16x16x32_bf16 v[86:89], v[154:157], v[214:217], v[86:89]
	v_mfma_f32_16x16x32_bf16 v[78:81], v[162:165], v[214:217], v[78:81]
	v_mfma_f32_16x16x32_bf16 v[126:129], v[158:161], v[194:197], v[126:129]
	v_mfma_f32_16x16x32_bf16 v[122:125], v[166:169], v[194:197], v[122:125]
	v_mfma_f32_16x16x32_bf16 v[118:121], v[158:161], v[202:205], v[118:121]
	v_mfma_f32_16x16x32_bf16 v[110:113], v[166:169], v[202:205], v[110:113]
	v_mfma_f32_16x16x32_bf16 v[102:105], v[158:161], v[210:213], v[102:105]
	v_mfma_f32_16x16x32_bf16 v[94:97], v[166:169], v[210:213], v[94:97]
	v_mfma_f32_16x16x32_bf16 v[86:89], v[158:161], v[218:221], v[86:89]
	v_mfma_f32_16x16x32_bf16 v[78:81], v[166:169], v[218:221], v[78:81]
	v_mfma_f32_16x16x32_bf16 v[114:117], v[174:177], v[190:193], v[114:117]
	v_mfma_f32_16x16x32_bf16 v[106:109], v[182:185], v[190:193], v[106:109]
	v_mfma_f32_16x16x32_bf16 v[98:101], v[174:177], v[198:201], v[98:101]
	v_mfma_f32_16x16x32_bf16 v[90:93], v[182:185], v[198:201], v[90:93]
	v_mfma_f32_16x16x32_bf16 v[82:85], v[174:177], v[206:209], v[82:85]
	v_mfma_f32_16x16x32_bf16 v[74:77], v[182:185], v[206:209], v[74:77]
	v_mfma_f32_16x16x32_bf16 v[70:73], v[174:177], v[214:217], v[70:73]
	v_mfma_f32_16x16x32_bf16 v[66:69], v[182:185], v[214:217], v[66:69]
	v_mfma_f32_16x16x32_bf16 v[114:117], v[178:181], v[194:197], v[114:117]
	v_mfma_f32_16x16x32_bf16 v[106:109], v[186:189], v[194:197], v[106:109]
	v_mfma_f32_16x16x32_bf16 v[98:101], v[178:181], v[202:205], v[98:101]
	v_mfma_f32_16x16x32_bf16 v[90:93], v[186:189], v[202:205], v[90:93]
	v_mfma_f32_16x16x32_bf16 v[82:85], v[178:181], v[210:213], v[82:85]
	v_mfma_f32_16x16x32_bf16 v[74:77], v[186:189], v[210:213], v[74:77]
	v_mfma_f32_16x16x32_bf16 v[70:73], v[178:181], v[218:221], v[70:73]
	v_mfma_f32_16x16x32_bf16 v[66:69], v[186:189], v[218:221], v[66:69]
	s_setprio 0
	s_barrier
; #define PG8_STAGE(bufoff, gbase, voff) do { _Pragma("unroll") for (int _i = 0; _i < 2; ++_i) \
;         __builtin_amdgcn_global_load_lds((const unsigned*)((const char*)(gbase) + (voff)[_i]), (PG8_LAS unsigned*)(lds + (bufoff) + ldsw + _i * 8192), 16, 0, 0); } while (0)
; #define PG8_LDA(dst, b, h) do { _Pragma("unroll") for (int m = 0; m < 4; ++m) _Pragma("unroll") for (int k = 0; k < 2; ++k) dst[m][k] = *(const PG8_LAS bf16x8*)(lds + PG8_SA(b, h) + aoff + m * 2048 + k * 1024); } while (0)
; #define PG8_MMA(ai, bj, At, Bt) do { __builtin_amdgcn_s_setprio(1); _Pragma("unroll") for (int m = 0; m < 4; ++m) _Pragma("unroll") for (int n = 0; n < 2; ++n) _Pragma("unroll") for (int k = 0; k < 2; ++k) \
;         acc[ai][bj][m][n] = __builtin_amdgcn_mfma_f32_16x16x32_bf16(Bt[n][k], At[m][k], acc[ai][bj][m][n], 0, 0, 0); __builtin_amdgcn_s_setprio(0); } while (0)
; #define PG8_WAIT_V(n) asm volatile("s_waitcnt vmcnt(" #n ")" ::: "memory")
; #define PG8_WAIT_L(n) asm volatile("s_waitcnt lgkmcnt(" #n ")" ::: "memory")
; #define PG8_BAR __builtin_amdgcn_s_barrier()
; #define PG8_SCHED __builtin_amdgcn_sched_barrier(0)
; template <class Epi, class Sched, bool ALIGN_EPI = false, bool SP2 = false>
; __device__ __forceinline__ void gemm_phase(PG8_LAS unsigned char* lds, const Gemm g, const Sched& S, const Epi& E) {
;     ...
;             PG8_WAIT_V(8); PG8_WAIT_L(0); PG8_BAR; PG8_MMA(0, 0, At, B0); PG8_MMA(0, 1, At, B1); PG8_BAR; PG8_SCHED;
;             PG8_LDA(At, 1, 1); PG8_STAGE(PG8_SB(1, 0), b3, voffB); PG8_STAGE(PG8_SB(1, 1), b3 + hstep, voffB); PG8_STAGE(PG8_SA(1, 0), a3, voffA);
;             PG8_WAIT_V(8); PG8_WAIT_L(0); PG8_BAR; PG8_MMA(1, 0, At, B0); PG8_MMA(1, 1, At, B1); PG8_BAR; PG8_SCHED;
;     ...
;         if constexpr (ALIGN_EPI) { if (wr == 0) PG8_BAR; }
	s_add_i32 s26, s63, s34
	v_lshl_add_u64 v[146:147], v[146:147], 0, s[8:9]
	s_mov_b32 m0, s26
	ds_read_b128 v[190:193], v152 offset:49152
	ds_read_b128 v[194:197], v152 offset:50176
	ds_read_b128 v[198:201], v152 offset:51200
	ds_read_b128 v[202:205], v152 offset:52224
	ds_read_b128 v[206:209], v152 offset:53248
	ds_read_b128 v[210:213], v152 offset:54272
	ds_read_b128 v[214:217], v152 offset:55296
	ds_read_b128 v[218:221], v152 offset:56320
	global_load_lds_dwordx4 v[146:147], off
	s_add_i32 m0, s26, 0x2000
	s_add_u32 s24, s24, 0xb0080
	v_lshl_add_u64 v[146:147], v[170:171], 0, s[8:9]
	s_addc_u32 s25, s25, 0
	s_add_i32 s26, s64, s34
	global_load_lds_dwordx4 v[146:147], off
	v_lshl_add_u64 v[146:147], s[24:25], 0, v[132:133]
	s_mov_b32 m0, s26
	s_nop 0
	global_load_lds_dwordx4 v[146:147], off
	v_lshl_add_u64 v[146:147], s[24:25], 0, v[136:137]
	s_add_i32 m0, s26, 0x2000
	s_nop 0
	global_load_lds_dwordx4 v[146:147], off
	v_lshl_add_u64 v[146:147], v[222:223], 0, s[8:9]
	s_mov_b32 m0, s42
	s_nop 0
	global_load_lds_dwordx4 v[146:147], off
	v_lshl_add_u64 v[146:147], v[224:225], 0, s[8:9]
	s_mov_b32 m0, s43
	s_nop 0
	global_load_lds_dwordx4 v[146:147], off
	s_waitcnt vmcnt(8)
	s_waitcnt lgkmcnt(0)
	s_barrier
	s_setprio 1
	s_waitcnt lgkmcnt(0)
	v_mfma_f32_16x16x32_bf16 v[62:65], v[154:157], v[190:193], v[62:65]
	v_mfma_f32_16x16x32_bf16 v[58:61], v[162:165], v[190:193], v[58:61]
	v_mfma_f32_16x16x32_bf16 v[54:57], v[154:157], v[198:201], v[54:57]
	v_mfma_f32_16x16x32_bf16 v[46:49], v[162:165], v[198:201], v[46:49]
	v_mfma_f32_16x16x32_bf16 v[38:41], v[154:157], v[206:209], v[38:41]
	v_mfma_f32_16x16x32_bf16 v[30:33], v[162:165], v[206:209], v[30:33]
	v_mfma_f32_16x16x32_bf16 v[22:25], v[154:157], v[214:217], v[22:25]
	v_mfma_f32_16x16x32_bf16 v[14:17], v[162:165], v[214:217], v[14:17]
	v_mfma_f32_16x16x32_bf16 v[62:65], v[158:161], v[194:197], v[62:65]
	v_mfma_f32_16x16x32_bf16 v[58:61], v[166:169], v[194:197], v[58:61]
	v_mfma_f32_16x16x32_bf16 v[54:57], v[158:161], v[202:205], v[54:57]
	v_mfma_f32_16x16x32_bf16 v[46:49], v[166:169], v[202:205], v[46:49]
	v_mfma_f32_16x16x32_bf16 v[38:41], v[158:161], v[210:213], v[38:41]
	v_mfma_f32_16x16x32_bf16 v[30:33], v[166:169], v[210:213], v[30:33]
	v_mfma_f32_16x16x32_bf16 v[22:25], v[158:161], v[218:221], v[22:25]
	v_mfma_f32_16x16x32_bf16 v[14:17], v[166:169], v[218:221], v[14:17]
	v_mfma_f32_16x16x32_bf16 v[50:53], v[174:177], v[190:193], v[50:53]
	v_mfma_f32_16x16x32_bf16 v[42:45], v[182:185], v[190:193], v[42:45]
	v_mfma_f32_16x16x32_bf16 v[34:37], v[174:177], v[198:201], v[34:37]
	v_mfma_f32_16x16x32_bf16 v[26:29], v[182:185], v[198:201], v[26:29]
	v_mfma_f32_16x16x32_bf16 v[18:21], v[174:177], v[206:209], v[18:21]
	v_mfma_f32_16x16x32_bf16 v[10:13], v[182:185], v[206:209], v[10:13]
	v_mfma_f32_16x16x32_bf16 v[6:9], v[174:177], v[214:217], v[6:9]
	v_mfma_f32_16x16x32_bf16 v[2:5], v[182:185], v[214:217], v[2:5]
	v_mfma_f32_16x16x32_bf16 v[50:53], v[178:181], v[194:197], v[50:53]
	v_mfma_f32_16x16x32_bf16 v[42:45], v[186:189], v[194:197], v[42:45]
	v_mfma_f32_16x16x32_bf16 v[34:37], v[178:181], v[202:205], v[34:37]
	v_mfma_f32_16x16x32_bf16 v[26:29], v[186:189], v[202:205], v[26:29]
	v_mfma_f32_16x16x32_bf16 v[18:21], v[178:181], v[210:213], v[18:21]
	v_mfma_f32_16x16x32_bf16 v[10:13], v[186:189], v[210:213], v[10:13]
	v_mfma_f32_16x16x32_bf16 v[6:9], v[178:181], v[218:221], v[6:9]
	v_mfma_f32_16x16x32_bf16 v[2:5], v[186:189], v[218:221], v[2:5]
	s_setprio 0
	s_barrier
	s_add_i32 s62, s62, 2
	s_add_u32 s22, s22, 0x100
	s_addc_u32 s23, s23, 0
	s_add_u32 s60, s60, 0x100
	s_addc_u32 s61, s61, 0
	s_cmp_gt_u32 s62, 41
	s_cbranch_scc0 .LBB0_1688
	s_and_b64 vcc, exec, s[10:11]
	s_cbranch_vccz .LBB0_1691
	s_barrier
